# GEMM K-loops: B-fragment LDS reads issued one segment earlier (balances LDS read bursts; counted vmcnt(10) guards, in-place DMA address temps)
# speedup vs baseline: 1.0122x; 1.0104x over previous
.LBB0_253:
	s_ashr_i32 s45, s44, 31
	s_lshl_b64 s[8:9], s[44:45], 20
	s_add_u32 s50, s31, s8
	s_addc_u32 s51, s35, s9
	s_andn2_b64 vcc, exec, s[24:25]
	s_cbranch_vccnz .LBB0_259
	s_and_b64 s[6:7], s[6:7], exec
	s_cselect_b32 s33, s51, s17
	s_cselect_b32 s45, s50, s16
	s_lshl_b32 s6, s52, 8
	s_ashr_i32 s7, s6, 31
	s_add_u32 s56, s14, 0x100
	v_lshl_add_u64 v[4:5], s[6:7], 2, v[144:145]
	s_addc_u32 s57, s15, 0
	v_lshl_add_u64 v[150:151], s[16:17], 0, v[146:147]
	v_lshl_add_u64 v[152:153], s[16:17], 0, v[148:149]
	s_mov_b32 s54, 0
	s_mov_b64 s[6:7], 0
	v_add_u32_e32 v3, 0x10000, v190
	ds_read_b128 v[154:157], v3
	ds_read_b128 v[158:161], v3 offset:1024
	ds_read_b128 v[162:165], v3 offset:2048
	ds_read_b128 v[166:169], v3 offset:3072

.LBB0_257:
	s_or_b64 exec, exec, s[52:53]
	s_add_i32 s58, s54, 2
	s_add_u32 s52, s16, s6
	s_addc_u32 s53, s17, s7
	s_add_u32 s52, s52, 0x100
	s_addc_u32 s53, s53, 0
	s_add_u32 s59, s56, s6
	s_addc_u32 s55, s57, s7
	s_cmp_eq_u32 s65, s54
	s_cselect_b32 s53, s33, s53
	s_cselect_b32 s52, s45, s52
	s_cselect_b32 s55, s49, s55
	s_cselect_b32 s54, s48, s59
	v_lshl_add_u64 v[174:175], v[150:151], 0, s[6:7]
	s_add_i32 m0, s39, 0xc000
	ds_read_b128 v[170:173], v192
	ds_read_b128 v[204:207], v192 offset:1024
	ds_read_b128 v[208:211], v192 offset:2048
	ds_read_b128 v[212:215], v192 offset:3072
	ds_read_b128 v[216:219], v192 offset:4096
	ds_read_b128 v[220:223], v192 offset:5120
	ds_read_b128 v[224:227], v192 offset:6144
	ds_read_b128 v[228:231], v192 offset:7168
	global_load_lds_dwordx4 v[174:175], off
	v_lshl_add_u64 v[174:175], v[152:153], 0, s[6:7]
	s_add_i32 m0, s39, 0xe000
	s_nop 0
	global_load_lds_dwordx4 v[174:175], off
	s_waitcnt lgkmcnt(8)
	s_barrier
	s_waitcnt lgkmcnt(0)
	s_waitcnt lgkmcnt(0)
	v_mfma_f32_16x16x32_bf16 v[130:133], v[154:157], v[170:173], v[130:133]
	v_mfma_f32_16x16x32_bf16 v[126:129], v[162:165], v[170:173], v[126:129]
	v_mfma_f32_16x16x32_bf16 v[122:125], v[154:157], v[208:211], v[122:125]
	v_mfma_f32_16x16x32_bf16 v[118:121], v[162:165], v[208:211], v[118:121]
	v_mfma_f32_16x16x32_bf16 v[114:117], v[154:157], v[216:219], v[114:117]
	v_mfma_f32_16x16x32_bf16 v[110:113], v[162:165], v[216:219], v[110:113]
	v_mfma_f32_16x16x32_bf16 v[106:109], v[154:157], v[224:227], v[106:109]
	v_mfma_f32_16x16x32_bf16 v[98:101], v[162:165], v[224:227], v[98:101]
	v_mfma_f32_16x16x32_bf16 v[130:133], v[158:161], v[204:207], v[130:133]
	v_mfma_f32_16x16x32_bf16 v[126:129], v[166:169], v[204:207], v[126:129]
	v_mfma_f32_16x16x32_bf16 v[122:125], v[158:161], v[212:215], v[122:125]
	v_mfma_f32_16x16x32_bf16 v[118:121], v[166:169], v[212:215], v[118:121]
	v_mfma_f32_16x16x32_bf16 v[114:117], v[158:161], v[220:223], v[114:117]
	v_mfma_f32_16x16x32_bf16 v[110:113], v[166:169], v[220:223], v[110:113]
	v_mfma_f32_16x16x32_bf16 v[106:109], v[158:161], v[228:231], v[106:109]
	v_mfma_f32_16x16x32_bf16 v[98:101], v[166:169], v[228:231], v[98:101]
	s_barrier
	s_add_i32 s59, s67, s37
	v_add_u32_e32 v3, s68, v190
	v_lshl_add_u64 v[174:175], s[54:55], 0, v[138:139]
	s_mov_b32 m0, s59
	ds_read_b128 v[232:235], v3
	ds_read_b128 v[236:239], v3 offset:1024
	ds_read_b128 v[240:243], v3 offset:2048
	ds_read_b128 v[244:247], v3 offset:3072
	global_load_lds_dwordx4 v[174:175], off
	v_lshl_add_u64 v[248:249], s[54:55], 0, v[142:143]
	s_add_i32 m0, s59, 0x2000
	s_nop 0
	global_load_lds_dwordx4 v[248:249], off
	s_barrier
	s_waitcnt lgkmcnt(0)
	s_waitcnt lgkmcnt(0)
	v_mfma_f32_16x16x32_bf16 v[102:105], v[232:235], v[170:173], v[102:105]
	v_mfma_f32_16x16x32_bf16 v[94:97], v[240:243], v[170:173], v[94:97]
	v_mfma_f32_16x16x32_bf16 v[90:93], v[232:235], v[208:211], v[90:93]
	v_mfma_f32_16x16x32_bf16 v[86:89], v[240:243], v[208:211], v[86:89]
	v_mfma_f32_16x16x32_bf16 v[82:85], v[232:235], v[216:219], v[82:85]
	v_mfma_f32_16x16x32_bf16 v[78:81], v[240:243], v[216:219], v[78:81]
	v_mfma_f32_16x16x32_bf16 v[74:77], v[232:235], v[224:227], v[74:77]
	v_mfma_f32_16x16x32_bf16 v[70:73], v[240:243], v[224:227], v[70:73]
	v_mfma_f32_16x16x32_bf16 v[102:105], v[236:239], v[204:207], v[102:105]
	v_mfma_f32_16x16x32_bf16 v[94:97], v[244:247], v[204:207], v[94:97]
	v_mfma_f32_16x16x32_bf16 v[90:93], v[236:239], v[212:215], v[90:93]
	v_mfma_f32_16x16x32_bf16 v[86:89], v[244:247], v[212:215], v[86:89]
	v_mfma_f32_16x16x32_bf16 v[82:85], v[236:239], v[220:223], v[82:85]
	v_mfma_f32_16x16x32_bf16 v[78:81], v[244:247], v[220:223], v[78:81]
	v_mfma_f32_16x16x32_bf16 v[74:77], v[236:239], v[228:231], v[74:77]
	v_mfma_f32_16x16x32_bf16 v[70:73], v[244:247], v[228:231], v[70:73]
	s_mov_b32 m0, s39
	v_lshl_add_u64 v[250:251], s[52:53], 0, v[136:137]
	s_barrier
	ds_read_b128 v[170:173], v192 offset:16384
	ds_read_b128 v[204:207], v192 offset:17408
	ds_read_b128 v[208:211], v192 offset:18432
	ds_read_b128 v[212:215], v192 offset:19456
	ds_read_b128 v[216:219], v192 offset:20480
	ds_read_b128 v[220:223], v192 offset:21504
	ds_read_b128 v[224:227], v192 offset:22528
	ds_read_b128 v[228:231], v192 offset:23552
	global_load_lds_dwordx4 v[250:251], off
	v_lshl_add_u64 v[252:253], s[52:53], 0, v[140:141]
	s_mov_b32 m0, s41
	s_nop 0
	global_load_lds_dwordx4 v[252:253], off
	s_waitcnt vmcnt(10)
	s_barrier
	s_waitcnt lgkmcnt(0)
	s_waitcnt lgkmcnt(0)
	v_mfma_f32_16x16x32_bf16 v[66:69], v[154:157], v[170:173], v[66:69]
	v_mfma_f32_16x16x32_bf16 v[62:65], v[162:165], v[170:173], v[62:65]
	v_mfma_f32_16x16x32_bf16 v[58:61], v[154:157], v[208:211], v[58:61]
	v_mfma_f32_16x16x32_bf16 v[54:57], v[162:165], v[208:211], v[54:57]
	v_mfma_f32_16x16x32_bf16 v[50:53], v[154:157], v[216:219], v[50:53]
	v_mfma_f32_16x16x32_bf16 v[46:49], v[162:165], v[216:219], v[46:49]
	v_mfma_f32_16x16x32_bf16 v[42:45], v[154:157], v[224:227], v[42:45]
	v_mfma_f32_16x16x32_bf16 v[38:41], v[162:165], v[224:227], v[38:41]
	v_mfma_f32_16x16x32_bf16 v[66:69], v[158:161], v[204:207], v[66:69]
	v_mfma_f32_16x16x32_bf16 v[62:65], v[166:169], v[204:207], v[62:65]
	v_mfma_f32_16x16x32_bf16 v[58:61], v[158:161], v[212:215], v[58:61]
	v_mfma_f32_16x16x32_bf16 v[54:57], v[166:169], v[212:215], v[54:57]
	v_mfma_f32_16x16x32_bf16 v[50:53], v[158:161], v[220:223], v[50:53]
	v_mfma_f32_16x16x32_bf16 v[46:49], v[166:169], v[220:223], v[46:49]
	v_mfma_f32_16x16x32_bf16 v[42:45], v[158:161], v[228:231], v[42:45]
	v_mfma_f32_16x16x32_bf16 v[38:41], v[166:169], v[228:231], v[38:41]
	s_barrier
	v_add_u32_e32 v3, 0x18000, v190
	ds_read_b128 v[154:157], v3
	ds_read_b128 v[158:161], v3 offset:1024
	ds_read_b128 v[162:165], v3 offset:2048
	ds_read_b128 v[166:169], v3 offset:3072
	s_add_u32 s54, s54, s10
	s_addc_u32 s55, s55, s11
	s_add_i32 s59, s68, s37
	v_lshl_add_u64 v[180:181], s[54:55], 0, v[138:139]
	s_mov_b32 m0, s59
	v_lshl_add_u64 v[184:185], s[54:55], 0, v[142:143]
	global_load_lds_dwordx4 v[180:181], off
	s_add_i32 m0, s59, 0x2000
	s_nop 0
	global_load_lds_dwordx4 v[184:185], off
	s_waitcnt vmcnt(6)
	s_barrier
	v_mfma_f32_16x16x32_bf16 v[34:37], v[232:235], v[170:173], v[34:37]
	v_mfma_f32_16x16x32_bf16 v[30:33], v[240:243], v[170:173], v[30:33]
	v_mfma_f32_16x16x32_bf16 v[26:29], v[232:235], v[208:211], v[26:29]
	v_mfma_f32_16x16x32_bf16 v[22:25], v[240:243], v[208:211], v[22:25]
	v_mfma_f32_16x16x32_bf16 v[18:21], v[232:235], v[216:219], v[18:21]
	v_mfma_f32_16x16x32_bf16 v[14:17], v[240:243], v[216:219], v[14:17]
	v_mfma_f32_16x16x32_bf16 v[10:13], v[232:235], v[224:227], v[10:13]
	v_mfma_f32_16x16x32_bf16 v[6:9], v[240:243], v[224:227], v[6:9]
	v_mfma_f32_16x16x32_bf16 v[34:37], v[236:239], v[204:207], v[34:37]
	v_mfma_f32_16x16x32_bf16 v[30:33], v[244:247], v[204:207], v[30:33]
	v_mfma_f32_16x16x32_bf16 v[26:29], v[236:239], v[212:215], v[26:29]
	v_mfma_f32_16x16x32_bf16 v[22:25], v[244:247], v[212:215], v[22:25]
	v_mfma_f32_16x16x32_bf16 v[18:21], v[236:239], v[220:223], v[18:21]
	v_mfma_f32_16x16x32_bf16 v[14:17], v[244:247], v[220:223], v[14:17]
	v_mfma_f32_16x16x32_bf16 v[10:13], v[236:239], v[228:231], v[10:13]
	v_mfma_f32_16x16x32_bf16 v[6:9], v[244:247], v[228:231], v[6:9]
	s_add_i32 s54, 0, 0x18000
	s_barrier
	s_add_u32 s52, s52, 0x80000
	s_addc_u32 s53, s53, 0
	s_mov_b32 m0, s43
	v_lshl_add_u64 v[232:233], s[52:53], 0, v[136:137]
	ds_read_b128 v[170:173], v192 offset:32768
	ds_read_b128 v[204:207], v192 offset:33792
	ds_read_b128 v[208:211], v192 offset:34816
	ds_read_b128 v[212:215], v192 offset:35840
	ds_read_b128 v[216:219], v192 offset:36864
	ds_read_b128 v[220:223], v192 offset:37888
	ds_read_b128 v[224:227], v192 offset:38912
	ds_read_b128 v[228:231], v192 offset:39936
	global_load_lds_dwordx4 v[232:233], off
	v_lshl_add_u64 v[232:233], s[52:53], 0, v[140:141]
	s_mov_b32 m0, s60
	s_nop 0
	global_load_lds_dwordx4 v[232:233], off
	s_waitcnt lgkmcnt(8)
	s_barrier
	s_waitcnt lgkmcnt(0)
	s_waitcnt lgkmcnt(0)
	v_mfma_f32_16x16x32_bf16 v[130:133], v[154:157], v[170:173], v[130:133]
	v_mfma_f32_16x16x32_bf16 v[126:129], v[162:165], v[170:173], v[126:129]
	v_mfma_f32_16x16x32_bf16 v[122:125], v[154:157], v[208:211], v[122:125]
	v_mfma_f32_16x16x32_bf16 v[118:121], v[162:165], v[208:211], v[118:121]
	v_mfma_f32_16x16x32_bf16 v[114:117], v[154:157], v[216:219], v[114:117]
	v_mfma_f32_16x16x32_bf16 v[110:113], v[162:165], v[216:219], v[110:113]
	v_mfma_f32_16x16x32_bf16 v[106:109], v[154:157], v[224:227], v[106:109]
	v_mfma_f32_16x16x32_bf16 v[98:101], v[162:165], v[224:227], v[98:101]
	v_mfma_f32_16x16x32_bf16 v[130:133], v[158:161], v[204:207], v[130:133]
	v_mfma_f32_16x16x32_bf16 v[126:129], v[166:169], v[204:207], v[126:129]
	v_mfma_f32_16x16x32_bf16 v[122:125], v[158:161], v[212:215], v[122:125]
	v_mfma_f32_16x16x32_bf16 v[118:121], v[166:169], v[212:215], v[118:121]
	v_mfma_f32_16x16x32_bf16 v[114:117], v[158:161], v[220:223], v[114:117]
	v_mfma_f32_16x16x32_bf16 v[110:113], v[166:169], v[220:223], v[110:113]
	v_mfma_f32_16x16x32_bf16 v[106:109], v[158:161], v[228:231], v[106:109]
	v_mfma_f32_16x16x32_bf16 v[98:101], v[166:169], v[228:231], v[98:101]
	s_barrier
	s_add_i32 s52, 0, 0x1c000
	s_add_i32 s53, s54, s37
	v_add_u32_e32 v3, s52, v190
	v_lshl_add_u64 v[174:175], v[174:175], 0, s[22:23]
	s_mov_b32 m0, s53
	ds_read_b128 v[232:235], v3
	ds_read_b128 v[236:239], v3 offset:1024
	ds_read_b128 v[240:243], v3 offset:2048
	ds_read_b128 v[244:247], v3 offset:3072
	global_load_lds_dwordx4 v[174:175], off
	v_lshl_add_u64 v[174:175], v[248:249], 0, s[22:23]
	s_add_i32 m0, s53, 0x2000
	s_nop 0
	global_load_lds_dwordx4 v[174:175], off
	s_barrier
	s_waitcnt lgkmcnt(0)
	s_waitcnt lgkmcnt(0)
	v_mfma_f32_16x16x32_bf16 v[102:105], v[232:235], v[170:173], v[102:105]
	v_mfma_f32_16x16x32_bf16 v[94:97], v[240:243], v[170:173], v[94:97]
	v_mfma_f32_16x16x32_bf16 v[90:93], v[232:235], v[208:211], v[90:93]
	v_mfma_f32_16x16x32_bf16 v[86:89], v[240:243], v[208:211], v[86:89]
	v_mfma_f32_16x16x32_bf16 v[82:85], v[232:235], v[216:219], v[82:85]
	v_mfma_f32_16x16x32_bf16 v[78:81], v[240:243], v[216:219], v[78:81]
	v_mfma_f32_16x16x32_bf16 v[74:77], v[232:235], v[224:227], v[74:77]
	v_mfma_f32_16x16x32_bf16 v[70:73], v[240:243], v[224:227], v[70:73]
	v_mfma_f32_16x16x32_bf16 v[102:105], v[236:239], v[204:207], v[102:105]
	v_mfma_f32_16x16x32_bf16 v[94:97], v[244:247], v[204:207], v[94:97]
	v_mfma_f32_16x16x32_bf16 v[90:93], v[236:239], v[212:215], v[90:93]
	v_mfma_f32_16x16x32_bf16 v[86:89], v[244:247], v[212:215], v[86:89]
	v_mfma_f32_16x16x32_bf16 v[82:85], v[236:239], v[220:223], v[82:85]
	v_mfma_f32_16x16x32_bf16 v[78:81], v[244:247], v[220:223], v[78:81]
	v_mfma_f32_16x16x32_bf16 v[74:77], v[236:239], v[228:231], v[74:77]
	v_mfma_f32_16x16x32_bf16 v[70:73], v[244:247], v[228:231], v[70:73]
	s_mov_b32 m0, s63
	v_lshl_add_u64 v[174:175], v[250:251], 0, s[22:23]
	s_barrier
	ds_read_b128 v[170:173], v192 offset:49152
	ds_read_b128 v[204:207], v192 offset:50176
	ds_read_b128 v[208:211], v192 offset:51200
	ds_read_b128 v[212:215], v192 offset:52224
	ds_read_b128 v[216:219], v192 offset:53248
	ds_read_b128 v[220:223], v192 offset:54272
	ds_read_b128 v[224:227], v192 offset:55296
	ds_read_b128 v[228:231], v192 offset:56320
	global_load_lds_dwordx4 v[174:175], off
	v_lshl_add_u64 v[174:175], v[252:253], 0, s[22:23]
	s_mov_b32 m0, s64
	s_nop 0
	global_load_lds_dwordx4 v[174:175], off
	s_waitcnt vmcnt(10)
	s_barrier
	s_waitcnt lgkmcnt(0)
	s_waitcnt lgkmcnt(0)
	v_mfma_f32_16x16x32_bf16 v[66:69], v[154:157], v[170:173], v[66:69]
	v_mfma_f32_16x16x32_bf16 v[62:65], v[162:165], v[170:173], v[62:65]
	v_mfma_f32_16x16x32_bf16 v[58:61], v[154:157], v[208:211], v[58:61]
	v_mfma_f32_16x16x32_bf16 v[54:57], v[162:165], v[208:211], v[54:57]
	v_mfma_f32_16x16x32_bf16 v[50:53], v[154:157], v[216:219], v[50:53]
	v_mfma_f32_16x16x32_bf16 v[46:49], v[162:165], v[216:219], v[46:49]
	v_mfma_f32_16x16x32_bf16 v[42:45], v[154:157], v[224:227], v[42:45]
	v_mfma_f32_16x16x32_bf16 v[38:41], v[162:165], v[224:227], v[38:41]
	v_mfma_f32_16x16x32_bf16 v[66:69], v[158:161], v[204:207], v[66:69]
	v_mfma_f32_16x16x32_bf16 v[62:65], v[166:169], v[204:207], v[62:65]
	v_mfma_f32_16x16x32_bf16 v[58:61], v[158:161], v[212:215], v[58:61]
	v_mfma_f32_16x16x32_bf16 v[54:57], v[166:169], v[212:215], v[54:57]
	v_mfma_f32_16x16x32_bf16 v[50:53], v[158:161], v[220:223], v[50:53]
	v_mfma_f32_16x16x32_bf16 v[46:49], v[166:169], v[220:223], v[46:49]
	v_mfma_f32_16x16x32_bf16 v[42:45], v[158:161], v[228:231], v[42:45]
	v_mfma_f32_16x16x32_bf16 v[38:41], v[166:169], v[228:231], v[38:41]
	s_barrier
	v_add_u32_e32 v3, 0x10000, v190
	ds_read_b128 v[154:157], v3
	ds_read_b128 v[158:161], v3 offset:1024
	ds_read_b128 v[162:165], v3 offset:2048
	ds_read_b128 v[166:169], v3 offset:3072
	s_add_i32 s52, s52, s37
	v_lshl_add_u64 v[180:181], v[180:181], 0, s[22:23]
	s_mov_b32 m0, s52
	s_nop 0
	global_load_lds_dwordx4 v[180:181], off
	v_lshl_add_u64 v[184:185], v[184:185], 0, s[22:23]
	s_add_i32 m0, s52, 0x2000
	s_nop 0
	global_load_lds_dwordx4 v[184:185], off
	s_waitcnt vmcnt(6)
	s_barrier
	v_mfma_f32_16x16x32_bf16 v[34:37], v[232:235], v[170:173], v[34:37]
	v_mfma_f32_16x16x32_bf16 v[30:33], v[240:243], v[170:173], v[30:33]
	v_mfma_f32_16x16x32_bf16 v[26:29], v[232:235], v[208:211], v[26:29]
	v_mfma_f32_16x16x32_bf16 v[22:25], v[240:243], v[208:211], v[22:25]
	v_mfma_f32_16x16x32_bf16 v[18:21], v[232:235], v[216:219], v[18:21]
	v_mfma_f32_16x16x32_bf16 v[14:17], v[240:243], v[216:219], v[14:17]
	v_mfma_f32_16x16x32_bf16 v[10:13], v[232:235], v[224:227], v[10:13]
	v_mfma_f32_16x16x32_bf16 v[6:9], v[240:243], v[224:227], v[6:9]
	v_mfma_f32_16x16x32_bf16 v[34:37], v[236:239], v[204:207], v[34:37]
	v_mfma_f32_16x16x32_bf16 v[30:33], v[244:247], v[204:207], v[30:33]
	v_mfma_f32_16x16x32_bf16 v[26:29], v[236:239], v[212:215], v[26:29]
	v_mfma_f32_16x16x32_bf16 v[22:25], v[244:247], v[212:215], v[22:25]
	v_mfma_f32_16x16x32_bf16 v[18:21], v[236:239], v[220:223], v[18:21]
	v_mfma_f32_16x16x32_bf16 v[14:17], v[244:247], v[220:223], v[14:17]
	v_mfma_f32_16x16x32_bf16 v[10:13], v[236:239], v[228:231], v[10:13]
	v_mfma_f32_16x16x32_bf16 v[6:9], v[244:247], v[228:231], v[6:9]
	s_add_u32 s6, s6, 0x100
	s_addc_u32 s7, s7, 0
	s_andn2_b64 s[46:47], s[46:47], exec
	s_and_b64 s[52:53], s[8:9], exec
	s_or_b64 s[46:47], s[46:47], s[52:53]
	s_cmp_ge_i32 s58, s61
	s_barrier
	s_cbranch_scc1 .LBB0_259
	s_mov_b32 s54, s58
	s_branch .LBB0_255
.LBB0_259:
	s_waitcnt lgkmcnt(0)
	s_cmp_lt_i32 s29, 4
	s_mov_b32 s45, 0
	s_cbranch_scc1 .LBB0_261
	s_cmp_lt_u32 s29, 17
	s_cselect_b32 s6, 4, 2
	s_cmp_gt_u32 s29, 12
	s_cselect_b32 s6, s6, 3
	s_cmp_gt_u32 s29, 8
	s_cselect_b32 s6, s6, 2
	s_cmp_lg_u32 s29, 4
	s_cselect_b32 s45, s6, 1

.LBB0_510:
	s_ashr_i32 s25, s24, 31
	s_lshl_b64 s[28:29], s[24:25], 17
	s_add_u32 s28, s43, s28
	s_addc_u32 s29, s44, s29
	s_andn2_b64 vcc, exec, s[22:23]
	s_cbranch_vccnz .LBB0_515
	s_and_b64 s[6:7], s[6:7], exec
	s_cselect_b32 s25, s29, s17
	s_cselect_b32 s61, s28, s16
	s_lshl_b32 s6, s34, 8
	s_ashr_i32 s7, s6, 31
	s_add_u32 s62, s14, 0x100
	v_lshl_add_u64 v[4:5], s[6:7], 2, v[142:143]
	s_addc_u32 s63, s15, 0
	v_lshl_add_u64 v[160:161], s[16:17], 0, v[144:145]
	v_lshl_add_u64 v[162:163], s[16:17], 0, v[146:147]
	s_mov_b32 s38, 0
	s_mov_b64 s[6:7], 0
	v_add_u32_e32 v3, 0x10000, v165
	ds_read_b128 v[170:173], v3
	ds_read_b128 v[174:177], v3 offset:1024
	ds_read_b128 v[178:181], v3 offset:2048
	ds_read_b128 v[182:185], v3 offset:3072
	s_branch .LBB0_513
.LBB0_512:
	s_or_b64 exec, exec, s[36:37]
	s_add_i32 s64, s38, 2
	s_add_u32 s36, s16, s6
	s_addc_u32 s37, s17, s7
	s_add_u32 s36, s36, 0x100
	s_addc_u32 s37, s37, 0
	s_add_u32 s65, s62, s6
	s_addc_u32 s39, s63, s7
	s_cmp_eq_u32 s54, s38
	s_cselect_b32 s38, s26, s65
	s_cselect_b32 s37, s25, s37
	s_cselect_b32 s36, s61, s36
	s_cselect_b32 s39, s27, s39
	v_lshl_add_u64 v[218:219], v[160:161], 0, s[6:7]
	s_add_i32 m0, s46, 0xc000
	ds_read_b128 v[186:189], v167
	ds_read_b128 v[190:193], v167 offset:1024
	ds_read_b128 v[194:197], v167 offset:2048
	ds_read_b128 v[198:201], v167 offset:3072
	ds_read_b128 v[202:205], v167 offset:4096
	ds_read_b128 v[206:209], v167 offset:5120
	ds_read_b128 v[210:213], v167 offset:6144
	ds_read_b128 v[214:217], v167 offset:7168
	global_load_lds_dwordx4 v[218:219], off
	v_lshl_add_u64 v[218:219], v[162:163], 0, s[6:7]
	s_add_i32 m0, s46, 0xe000
	s_nop 0
	global_load_lds_dwordx4 v[218:219], off
	s_waitcnt lgkmcnt(8)
	s_barrier
	s_waitcnt lgkmcnt(0)
	s_waitcnt lgkmcnt(0)
	v_mfma_f32_16x16x32_bf16 v[130:133], v[170:173], v[186:189], v[130:133]
	v_mfma_f32_16x16x32_bf16 v[126:129], v[178:181], v[186:189], v[126:129]
	v_mfma_f32_16x16x32_bf16 v[122:125], v[170:173], v[194:197], v[122:125]
	v_mfma_f32_16x16x32_bf16 v[118:121], v[178:181], v[194:197], v[118:121]
	v_mfma_f32_16x16x32_bf16 v[114:117], v[170:173], v[202:205], v[114:117]
	v_mfma_f32_16x16x32_bf16 v[110:113], v[178:181], v[202:205], v[110:113]
	v_mfma_f32_16x16x32_bf16 v[106:109], v[170:173], v[210:213], v[106:109]
	v_mfma_f32_16x16x32_bf16 v[98:101], v[178:181], v[210:213], v[98:101]
	v_mfma_f32_16x16x32_bf16 v[130:133], v[174:177], v[190:193], v[130:133]
	v_mfma_f32_16x16x32_bf16 v[126:129], v[182:185], v[190:193], v[126:129]
	v_mfma_f32_16x16x32_bf16 v[122:125], v[174:177], v[198:201], v[122:125]
	v_mfma_f32_16x16x32_bf16 v[118:121], v[182:185], v[198:201], v[118:121]
	v_mfma_f32_16x16x32_bf16 v[114:117], v[174:177], v[206:209], v[114:117]
	v_mfma_f32_16x16x32_bf16 v[110:113], v[182:185], v[206:209], v[110:113]
	v_mfma_f32_16x16x32_bf16 v[106:109], v[174:177], v[214:217], v[106:109]
	v_mfma_f32_16x16x32_bf16 v[98:101], v[182:185], v[214:217], v[98:101]
	s_barrier
	s_add_i32 s65, s56, s45
	v_add_u32_e32 v3, s57, v165
	v_lshl_add_u64 v[234:235], s[38:39], 0, v[138:139]
	s_mov_b32 m0, s65
	ds_read_b128 v[218:221], v3
	ds_read_b128 v[222:225], v3 offset:1024
	ds_read_b128 v[226:229], v3 offset:2048
	ds_read_b128 v[230:233], v3 offset:3072
	global_load_lds_dwordx4 v[234:235], off
	v_lshl_add_u64 v[236:237], s[38:39], 0, v[134:135]
	s_add_i32 m0, s65, 0x2000
	s_nop 0
	global_load_lds_dwordx4 v[236:237], off
	s_barrier
	s_waitcnt lgkmcnt(0)
	s_waitcnt lgkmcnt(0)
	v_mfma_f32_16x16x32_bf16 v[102:105], v[218:221], v[186:189], v[102:105]
	v_mfma_f32_16x16x32_bf16 v[94:97], v[226:229], v[186:189], v[94:97]
	v_mfma_f32_16x16x32_bf16 v[90:93], v[218:221], v[194:197], v[90:93]
	v_mfma_f32_16x16x32_bf16 v[86:89], v[226:229], v[194:197], v[86:89]
	v_mfma_f32_16x16x32_bf16 v[82:85], v[218:221], v[202:205], v[82:85]
	v_mfma_f32_16x16x32_bf16 v[78:81], v[226:229], v[202:205], v[78:81]
	v_mfma_f32_16x16x32_bf16 v[74:77], v[218:221], v[210:213], v[74:77]
	v_mfma_f32_16x16x32_bf16 v[70:73], v[226:229], v[210:213], v[70:73]
	v_mfma_f32_16x16x32_bf16 v[102:105], v[222:225], v[190:193], v[102:105]
	v_mfma_f32_16x16x32_bf16 v[94:97], v[230:233], v[190:193], v[94:97]
	v_mfma_f32_16x16x32_bf16 v[90:93], v[222:225], v[198:201], v[90:93]
	v_mfma_f32_16x16x32_bf16 v[86:89], v[230:233], v[198:201], v[86:89]
	v_mfma_f32_16x16x32_bf16 v[82:85], v[222:225], v[206:209], v[82:85]
	v_mfma_f32_16x16x32_bf16 v[78:81], v[230:233], v[206:209], v[78:81]
	v_mfma_f32_16x16x32_bf16 v[74:77], v[222:225], v[214:217], v[74:77]
	v_mfma_f32_16x16x32_bf16 v[70:73], v[230:233], v[214:217], v[70:73]
	s_mov_b32 m0, s46
	v_lshl_add_u64 v[238:239], s[36:37], 0, v[136:137]
	s_barrier
	ds_read_b128 v[186:189], v167 offset:16384
	ds_read_b128 v[190:193], v167 offset:17408
	ds_read_b128 v[194:197], v167 offset:18432
	ds_read_b128 v[198:201], v167 offset:19456
	ds_read_b128 v[202:205], v167 offset:20480
	ds_read_b128 v[206:209], v167 offset:21504
	ds_read_b128 v[210:213], v167 offset:22528
	ds_read_b128 v[214:217], v167 offset:23552
	global_load_lds_dwordx4 v[238:239], off
	v_lshl_add_u64 v[240:241], s[36:37], 0, v[140:141]
	s_mov_b32 m0, s47
	s_nop 0
	global_load_lds_dwordx4 v[240:241], off
	s_waitcnt vmcnt(10)
	s_barrier
	s_waitcnt lgkmcnt(0)
	s_waitcnt lgkmcnt(0)
	v_mfma_f32_16x16x32_bf16 v[66:69], v[170:173], v[186:189], v[66:69]
	v_mfma_f32_16x16x32_bf16 v[62:65], v[178:181], v[186:189], v[62:65]
	v_mfma_f32_16x16x32_bf16 v[58:61], v[170:173], v[194:197], v[58:61]
	v_mfma_f32_16x16x32_bf16 v[54:57], v[178:181], v[194:197], v[54:57]
	v_mfma_f32_16x16x32_bf16 v[50:53], v[170:173], v[202:205], v[50:53]
	v_mfma_f32_16x16x32_bf16 v[46:49], v[178:181], v[202:205], v[46:49]
	v_mfma_f32_16x16x32_bf16 v[42:45], v[170:173], v[210:213], v[42:45]
	v_mfma_f32_16x16x32_bf16 v[38:41], v[178:181], v[210:213], v[38:41]
	v_mfma_f32_16x16x32_bf16 v[66:69], v[174:177], v[190:193], v[66:69]
	v_mfma_f32_16x16x32_bf16 v[62:65], v[182:185], v[190:193], v[62:65]
	v_mfma_f32_16x16x32_bf16 v[58:61], v[174:177], v[198:201], v[58:61]
	v_mfma_f32_16x16x32_bf16 v[54:57], v[182:185], v[198:201], v[54:57]
	v_mfma_f32_16x16x32_bf16 v[50:53], v[174:177], v[206:209], v[50:53]
	v_mfma_f32_16x16x32_bf16 v[46:49], v[182:185], v[206:209], v[46:49]
	v_mfma_f32_16x16x32_bf16 v[42:45], v[174:177], v[214:217], v[42:45]
	v_mfma_f32_16x16x32_bf16 v[38:41], v[182:185], v[214:217], v[38:41]
	s_barrier
	v_add_u32_e32 v3, 0x18000, v165
	ds_read_b128 v[170:173], v3
	ds_read_b128 v[174:177], v3 offset:1024
	ds_read_b128 v[178:181], v3 offset:2048
	ds_read_b128 v[182:185], v3 offset:3072
	s_add_u32 s38, s38, s10
	s_addc_u32 s39, s39, s11
	s_add_i32 s65, s57, s45
	v_lshl_add_u64 v[242:243], s[38:39], 0, v[138:139]
	s_mov_b32 m0, s65
	v_lshl_add_u64 v[244:245], s[38:39], 0, v[134:135]
	global_load_lds_dwordx4 v[242:243], off
	s_add_i32 m0, s65, 0x2000
	s_nop 0
	global_load_lds_dwordx4 v[244:245], off
	s_waitcnt vmcnt(6)
	s_barrier
	v_mfma_f32_16x16x32_bf16 v[34:37], v[218:221], v[186:189], v[34:37]
	v_mfma_f32_16x16x32_bf16 v[30:33], v[226:229], v[186:189], v[30:33]
	v_mfma_f32_16x16x32_bf16 v[26:29], v[218:221], v[194:197], v[26:29]
	v_mfma_f32_16x16x32_bf16 v[22:25], v[226:229], v[194:197], v[22:25]
	v_mfma_f32_16x16x32_bf16 v[18:21], v[218:221], v[202:205], v[18:21]
	v_mfma_f32_16x16x32_bf16 v[14:17], v[226:229], v[202:205], v[14:17]
	v_mfma_f32_16x16x32_bf16 v[10:13], v[218:221], v[210:213], v[10:13]
	v_mfma_f32_16x16x32_bf16 v[6:9], v[226:229], v[210:213], v[6:9]
	v_mfma_f32_16x16x32_bf16 v[34:37], v[222:225], v[190:193], v[34:37]
	v_mfma_f32_16x16x32_bf16 v[30:33], v[230:233], v[190:193], v[30:33]
	v_mfma_f32_16x16x32_bf16 v[26:29], v[222:225], v[198:201], v[26:29]
	v_mfma_f32_16x16x32_bf16 v[22:25], v[230:233], v[198:201], v[22:25]
	v_mfma_f32_16x16x32_bf16 v[18:21], v[222:225], v[206:209], v[18:21]
	v_mfma_f32_16x16x32_bf16 v[14:17], v[230:233], v[206:209], v[14:17]
	v_mfma_f32_16x16x32_bf16 v[10:13], v[222:225], v[214:217], v[10:13]
	v_mfma_f32_16x16x32_bf16 v[6:9], v[230:233], v[214:217], v[6:9]
	s_add_i32 s38, 0, 0x18000
	s_barrier
	s_add_u32 s36, s36, 0x10000
	s_addc_u32 s37, s37, 0
	s_mov_b32 m0, s48
	v_lshl_add_u64 v[218:219], s[36:37], 0, v[136:137]
	ds_read_b128 v[186:189], v167 offset:32768
	ds_read_b128 v[190:193], v167 offset:33792
	ds_read_b128 v[194:197], v167 offset:34816
	ds_read_b128 v[198:201], v167 offset:35840
	ds_read_b128 v[202:205], v167 offset:36864
	ds_read_b128 v[206:209], v167 offset:37888
	ds_read_b128 v[210:213], v167 offset:38912
	ds_read_b128 v[214:217], v167 offset:39936
	global_load_lds_dwordx4 v[218:219], off
	v_lshl_add_u64 v[218:219], s[36:37], 0, v[140:141]
	s_mov_b32 m0, s49
	s_nop 0
	global_load_lds_dwordx4 v[218:219], off
	s_waitcnt lgkmcnt(8)
	s_barrier
	s_waitcnt lgkmcnt(0)
	s_waitcnt lgkmcnt(0)
	v_mfma_f32_16x16x32_bf16 v[130:133], v[170:173], v[186:189], v[130:133]
	v_mfma_f32_16x16x32_bf16 v[126:129], v[178:181], v[186:189], v[126:129]
	v_mfma_f32_16x16x32_bf16 v[122:125], v[170:173], v[194:197], v[122:125]
	v_mfma_f32_16x16x32_bf16 v[118:121], v[178:181], v[194:197], v[118:121]
	v_mfma_f32_16x16x32_bf16 v[114:117], v[170:173], v[202:205], v[114:117]
	v_mfma_f32_16x16x32_bf16 v[110:113], v[178:181], v[202:205], v[110:113]
	v_mfma_f32_16x16x32_bf16 v[106:109], v[170:173], v[210:213], v[106:109]
	v_mfma_f32_16x16x32_bf16 v[98:101], v[178:181], v[210:213], v[98:101]
	v_mfma_f32_16x16x32_bf16 v[130:133], v[174:177], v[190:193], v[130:133]
	v_mfma_f32_16x16x32_bf16 v[126:129], v[182:185], v[190:193], v[126:129]
	v_mfma_f32_16x16x32_bf16 v[122:125], v[174:177], v[198:201], v[122:125]
	v_mfma_f32_16x16x32_bf16 v[118:121], v[182:185], v[198:201], v[118:121]
	v_mfma_f32_16x16x32_bf16 v[114:117], v[174:177], v[206:209], v[114:117]
	v_mfma_f32_16x16x32_bf16 v[110:113], v[182:185], v[206:209], v[110:113]
	v_mfma_f32_16x16x32_bf16 v[106:109], v[174:177], v[214:217], v[106:109]
	v_mfma_f32_16x16x32_bf16 v[98:101], v[182:185], v[214:217], v[98:101]
	s_barrier
	s_add_i32 s36, 0, 0x1c000
	s_add_i32 s37, s38, s45
	v_add_u32_e32 v3, s36, v165
	v_lshl_add_u64 v[234:235], v[234:235], 0, s[20:21]
	s_mov_b32 m0, s37
	ds_read_b128 v[218:221], v3
	ds_read_b128 v[222:225], v3 offset:1024
	ds_read_b128 v[226:229], v3 offset:2048
	ds_read_b128 v[230:233], v3 offset:3072
	global_load_lds_dwordx4 v[234:235], off
	v_lshl_add_u64 v[234:235], v[236:237], 0, s[20:21]
	s_add_i32 m0, s37, 0x2000
	s_nop 0
	global_load_lds_dwordx4 v[234:235], off
	s_barrier
	s_waitcnt lgkmcnt(0)
	s_waitcnt lgkmcnt(0)
	v_mfma_f32_16x16x32_bf16 v[102:105], v[218:221], v[186:189], v[102:105]
	v_mfma_f32_16x16x32_bf16 v[94:97], v[226:229], v[186:189], v[94:97]
	v_mfma_f32_16x16x32_bf16 v[90:93], v[218:221], v[194:197], v[90:93]
	v_mfma_f32_16x16x32_bf16 v[86:89], v[226:229], v[194:197], v[86:89]
	v_mfma_f32_16x16x32_bf16 v[82:85], v[218:221], v[202:205], v[82:85]
	v_mfma_f32_16x16x32_bf16 v[78:81], v[226:229], v[202:205], v[78:81]
	v_mfma_f32_16x16x32_bf16 v[74:77], v[218:221], v[210:213], v[74:77]
	v_mfma_f32_16x16x32_bf16 v[70:73], v[226:229], v[210:213], v[70:73]
	v_mfma_f32_16x16x32_bf16 v[102:105], v[222:225], v[190:193], v[102:105]
	v_mfma_f32_16x16x32_bf16 v[94:97], v[230:233], v[190:193], v[94:97]
	v_mfma_f32_16x16x32_bf16 v[90:93], v[222:225], v[198:201], v[90:93]
	v_mfma_f32_16x16x32_bf16 v[86:89], v[230:233], v[198:201], v[86:89]
	v_mfma_f32_16x16x32_bf16 v[82:85], v[222:225], v[206:209], v[82:85]
	v_mfma_f32_16x16x32_bf16 v[78:81], v[230:233], v[206:209], v[78:81]
	v_mfma_f32_16x16x32_bf16 v[74:77], v[222:225], v[214:217], v[74:77]
	v_mfma_f32_16x16x32_bf16 v[70:73], v[230:233], v[214:217], v[70:73]
	s_mov_b32 m0, s51
	v_lshl_add_u64 v[234:235], v[238:239], 0, s[20:21]
	s_barrier
	ds_read_b128 v[186:189], v167 offset:49152
	ds_read_b128 v[190:193], v167 offset:50176
	ds_read_b128 v[194:197], v167 offset:51200
	ds_read_b128 v[198:201], v167 offset:52224
	ds_read_b128 v[202:205], v167 offset:53248
	ds_read_b128 v[206:209], v167 offset:54272
	ds_read_b128 v[210:213], v167 offset:55296
	ds_read_b128 v[214:217], v167 offset:56320
	global_load_lds_dwordx4 v[234:235], off
	v_lshl_add_u64 v[234:235], v[240:241], 0, s[20:21]
	s_mov_b32 m0, s52
	s_nop 0
	global_load_lds_dwordx4 v[234:235], off
	s_waitcnt vmcnt(10)
	s_barrier
	s_waitcnt lgkmcnt(0)
	s_waitcnt lgkmcnt(0)
	v_mfma_f32_16x16x32_bf16 v[66:69], v[170:173], v[186:189], v[66:69]
	v_mfma_f32_16x16x32_bf16 v[62:65], v[178:181], v[186:189], v[62:65]
	v_mfma_f32_16x16x32_bf16 v[58:61], v[170:173], v[194:197], v[58:61]
	v_mfma_f32_16x16x32_bf16 v[54:57], v[178:181], v[194:197], v[54:57]
	v_mfma_f32_16x16x32_bf16 v[50:53], v[170:173], v[202:205], v[50:53]
	v_mfma_f32_16x16x32_bf16 v[46:49], v[178:181], v[202:205], v[46:49]
	v_mfma_f32_16x16x32_bf16 v[42:45], v[170:173], v[210:213], v[42:45]
	v_mfma_f32_16x16x32_bf16 v[38:41], v[178:181], v[210:213], v[38:41]
	v_mfma_f32_16x16x32_bf16 v[66:69], v[174:177], v[190:193], v[66:69]
	v_mfma_f32_16x16x32_bf16 v[62:65], v[182:185], v[190:193], v[62:65]
	v_mfma_f32_16x16x32_bf16 v[58:61], v[174:177], v[198:201], v[58:61]
	v_mfma_f32_16x16x32_bf16 v[54:57], v[182:185], v[198:201], v[54:57]
	v_mfma_f32_16x16x32_bf16 v[50:53], v[174:177], v[206:209], v[50:53]
	v_mfma_f32_16x16x32_bf16 v[46:49], v[182:185], v[206:209], v[46:49]
	v_mfma_f32_16x16x32_bf16 v[42:45], v[174:177], v[214:217], v[42:45]
	v_mfma_f32_16x16x32_bf16 v[38:41], v[182:185], v[214:217], v[38:41]
	s_barrier
	v_add_u32_e32 v3, 0x10000, v165
	ds_read_b128 v[170:173], v3
	ds_read_b128 v[174:177], v3 offset:1024
	ds_read_b128 v[178:181], v3 offset:2048
	ds_read_b128 v[182:185], v3 offset:3072
	s_add_i32 s36, s36, s45
	v_lshl_add_u64 v[242:243], v[242:243], 0, s[20:21]
	s_mov_b32 m0, s36
	s_nop 0
	global_load_lds_dwordx4 v[242:243], off
	v_lshl_add_u64 v[244:245], v[244:245], 0, s[20:21]
	s_add_i32 m0, s36, 0x2000
	s_nop 0
	global_load_lds_dwordx4 v[244:245], off
	s_waitcnt vmcnt(6)
	s_barrier
	v_mfma_f32_16x16x32_bf16 v[34:37], v[218:221], v[186:189], v[34:37]
	v_mfma_f32_16x16x32_bf16 v[30:33], v[226:229], v[186:189], v[30:33]
	v_mfma_f32_16x16x32_bf16 v[26:29], v[218:221], v[194:197], v[26:29]
	v_mfma_f32_16x16x32_bf16 v[22:25], v[226:229], v[194:197], v[22:25]
	v_mfma_f32_16x16x32_bf16 v[18:21], v[218:221], v[202:205], v[18:21]
	v_mfma_f32_16x16x32_bf16 v[14:17], v[226:229], v[202:205], v[14:17]
	v_mfma_f32_16x16x32_bf16 v[10:13], v[218:221], v[210:213], v[10:13]
	v_mfma_f32_16x16x32_bf16 v[6:9], v[226:229], v[210:213], v[6:9]
	v_mfma_f32_16x16x32_bf16 v[34:37], v[222:225], v[190:193], v[34:37]
	v_mfma_f32_16x16x32_bf16 v[30:33], v[230:233], v[190:193], v[30:33]
	v_mfma_f32_16x16x32_bf16 v[26:29], v[222:225], v[198:201], v[26:29]
	v_mfma_f32_16x16x32_bf16 v[22:25], v[230:233], v[198:201], v[22:25]
	v_mfma_f32_16x16x32_bf16 v[18:21], v[222:225], v[206:209], v[18:21]
	v_mfma_f32_16x16x32_bf16 v[14:17], v[230:233], v[206:209], v[14:17]
	v_mfma_f32_16x16x32_bf16 v[10:13], v[222:225], v[214:217], v[10:13]
	v_mfma_f32_16x16x32_bf16 v[6:9], v[230:233], v[214:217], v[6:9]
	s_add_u32 s6, s6, 0x100
	s_addc_u32 s7, s7, 0
	s_andn2_b64 s[30:31], s[30:31], exec
	s_and_b64 s[36:37], s[34:35], exec
	s_or_b64 s[30:31], s[30:31], s[36:37]
	s_cmp_ge_i32 s64, s50
	s_mov_b32 s38, s64
	s_barrier
	s_cbranch_scc1 .LBB0_515

.LBB0_515:
	s_waitcnt lgkmcnt(0)
	v_and_b32_e32 v5, 64, v168
	v_xor_b32_e32 v3, 16, v168
	v_add_u32_e32 v5, 64, v5
	s_lshl_b32 s6, s58, 8
	v_cmp_lt_i32_e32 vcc, v3, v5
	v_add_u32_e32 v160, s6, v164
	v_lshl_or_b32 v4, s53, 8, v166
	v_cndmask_b32_e32 v3, v168, v3, vcc
	v_lshlrev_b32_e32 v158, 2, v3
	v_xor_b32_e32 v3, 32, v168
	v_ashrrev_i32_e32 v161, 31, v160
	v_cmp_lt_i32_e32 vcc, v3, v5
	v_lshlrev_b64 v[170:171], 12, v[160:161]
	v_ashrrev_i32_e32 v5, 31, v4
	v_mul_f32_e32 v156, v131, v131
	v_lshl_add_u64 v[170:171], s[18:19], 0, v[170:171]
	v_lshlrev_b64 v[172:173], 1, v[4:5]
	v_mul_f32_e32 v157, v123, v123
	v_fmac_f32_e32 v156, v130, v130
	v_lshl_add_u64 v[4:5], v[170:171], 0, v[172:173]
	v_or_b32_e32 v170, 16, v160
	v_fmac_f32_e32 v157, v122, v122
	v_fmac_f32_e32 v156, v132, v132
	v_ashrrev_i32_e32 v171, 31, v170
	v_fmac_f32_e32 v157, v124, v124
	v_fmac_f32_e32 v156, v133, v133
	v_cvt_pk_bf16_f32 v152, v130, v131
	v_cvt_pk_bf16_f32 v153, v132, v133
	v_cvt_pk_bf16_f32 v154, v126, v127
	v_cvt_pk_bf16_f32 v155, v128, v129
	v_fmac_f32_e32 v157, v125, v125
	v_lshlrev_b64 v[170:171], 12, v[170:171]
	v_fmac_f32_e32 v156, v126, v126
	global_store_dwordx4 v[4:5], v[152:155], off
	v_fmac_f32_e32 v157, v118, v118
	v_lshl_add_u64 v[170:171], s[18:19], 0, v[170:171]
	v_cvt_pk_bf16_f32 v152, v102, v103
	v_cvt_pk_bf16_f32 v153, v104, v105
	v_cvt_pk_bf16_f32 v154, v94, v95
	v_cvt_pk_bf16_f32 v155, v96, v97
	v_fmac_f32_e32 v156, v127, v127
	global_store_dwordx4 v[4:5], v[152:155], off offset:256
	v_fmac_f32_e32 v157, v119, v119
	v_lshl_add_u64 v[170:171], v[170:171], 0, v[172:173]
	v_cvt_pk_bf16_f32 v152, v122, v123
	v_cvt_pk_bf16_f32 v153, v124, v125
	v_cvt_pk_bf16_f32 v154, v118, v119
	v_cvt_pk_bf16_f32 v155, v120, v121
	v_fmac_f32_e32 v156, v128, v128
	v_mul_f32_e32 v162, v129, v129
	v_fmac_f32_e32 v157, v120, v120
	v_mul_f32_e32 v163, v121, v121
	global_store_dwordx4 v[170:171], v[152:155], off
	v_cndmask_b32_e32 v3, v168, v3, vcc
	v_lshlrev_b32_e32 v3, 2, v3
	v_cvt_pk_bf16_f32 v152, v90, v91
	v_cvt_pk_bf16_f32 v153, v92, v93
	v_cvt_pk_bf16_f32 v154, v86, v87
	v_cvt_pk_bf16_f32 v155, v88, v89
	global_store_dwordx4 v[170:171], v[152:155], off offset:256
	v_mul_f32_e32 v170, v115, v115
	v_mul_f32_e32 v171, v107, v107
	v_pk_add_f32 v[152:153], v[162:163], v[156:157]
	v_mov_b32_e32 v154, v102
	v_mov_b32_e32 v155, v90
	v_pk_fma_f32 v[152:153], v[154:155], v[154:155], v[152:153]
	v_mov_b32_e32 v154, v103
	v_mov_b32_e32 v155, v91
	v_pk_fma_f32 v[152:153], v[154:155], v[154:155], v[152:153]
	v_mov_b32_e32 v154, v104
	v_mov_b32_e32 v155, v92
	v_pk_fma_f32 v[152:153], v[154:155], v[154:155], v[152:153]
	v_mov_b32_e32 v154, v105
	v_mov_b32_e32 v155, v93
	v_pk_fma_f32 v[152:153], v[154:155], v[154:155], v[152:153]
	v_mov_b32_e32 v154, v94
	v_mov_b32_e32 v155, v86
	v_pk_fma_f32 v[152:153], v[154:155], v[154:155], v[152:153]
	v_mov_b32_e32 v154, v95
	v_mov_b32_e32 v155, v87
	v_pk_fma_f32 v[152:153], v[154:155], v[154:155], v[152:153]
	v_mov_b32_e32 v154, v96
	v_mov_b32_e32 v155, v88
	v_pk_fma_f32 v[152:153], v[154:155], v[154:155], v[152:153]
	v_mov_b32_e32 v154, v97
	v_mov_b32_e32 v155, v89
	v_pk_fma_f32 v[152:153], v[154:155], v[154:155], v[152:153]
	ds_bpermute_b32 v154, v158, v152
	ds_bpermute_b32 v155, v158, v153
	v_or_b32_e32 v162, 32, v160
	v_ashrrev_i32_e32 v163, 31, v162
	v_fmac_f32_e32 v170, v114, v114
	v_lshlrev_b64 v[162:163], 12, v[162:163]
	s_waitcnt lgkmcnt(0)
	v_pk_add_f32 v[152:153], v[152:153], v[154:155]
	ds_bpermute_b32 v154, v3, v152
	ds_bpermute_b32 v155, v3, v153
	v_or_b32_e32 v160, 48, v160
	v_fmac_f32_e32 v171, v106, v106
	v_fmac_f32_e32 v170, v116, v116
	v_lshl_add_u64 v[162:163], s[18:19], 0, v[162:163]
	v_ashrrev_i32_e32 v161, 31, v160
	v_fmac_f32_e32 v171, v108, v108
	s_waitcnt lgkmcnt(0)
	v_pk_add_f32 v[152:153], v[152:153], v[154:155]
	v_fmac_f32_e32 v170, v117, v117
	v_cvt_pk_bf16_f32 v154, v114, v115
	v_cvt_pk_bf16_f32 v155, v116, v117
	v_cvt_pk_bf16_f32 v156, v110, v111
	v_cvt_pk_bf16_f32 v157, v112, v113
	v_lshl_add_u64 v[162:163], v[162:163], 0, v[172:173]
	v_fmac_f32_e32 v171, v109, v109
	v_lshlrev_b64 v[160:161], 12, v[160:161]
	v_fmac_f32_e32 v170, v110, v110
	global_store_dwordx4 v[162:163], v[154:157], off
	v_fmac_f32_e32 v171, v98, v98
	v_lshl_add_u64 v[160:161], s[18:19], 0, v[160:161]
	v_cvt_pk_bf16_f32 v154, v82, v83
	v_cvt_pk_bf16_f32 v155, v84, v85
	v_cvt_pk_bf16_f32 v156, v78, v79
	v_cvt_pk_bf16_f32 v157, v80, v81
	v_fmac_f32_e32 v170, v111, v111
	global_store_dwordx4 v[162:163], v[154:157], off offset:256
	v_fmac_f32_e32 v171, v99, v99
	v_lshl_add_u64 v[160:161], v[160:161], 0, v[172:173]
	v_cvt_pk_bf16_f32 v154, v106, v107
	v_cvt_pk_bf16_f32 v155, v108, v109
	v_cvt_pk_bf16_f32 v156, v98, v99
	v_cvt_pk_bf16_f32 v157, v100, v101
	v_fmac_f32_e32 v170, v112, v112
	v_mul_f32_e32 v174, v113, v113
	v_fmac_f32_e32 v171, v100, v100
	v_mul_f32_e32 v175, v101, v101
	global_store_dwordx4 v[160:161], v[154:157], off
	s_mov_b32 s7, 0x80000
	v_cvt_pk_bf16_f32 v162, v62, v63
	v_cvt_pk_bf16_f32 v154, v74, v75
	v_cvt_pk_bf16_f32 v155, v76, v77
	v_cvt_pk_bf16_f32 v156, v70, v71
	v_cvt_pk_bf16_f32 v157, v72, v73
	global_store_dwordx4 v[160:161], v[154:157], off offset:256
	v_cvt_pk_bf16_f32 v160, v66, v67
	v_cvt_pk_bf16_f32 v161, v68, v69
	v_pk_add_f32 v[154:155], v[174:175], v[170:171]
	v_mov_b32_e32 v156, v82
	v_mov_b32_e32 v157, v74
	v_pk_fma_f32 v[154:155], v[156:157], v[156:157], v[154:155]
	v_mov_b32_e32 v156, v83
	v_mov_b32_e32 v157, v75
	v_pk_fma_f32 v[154:155], v[156:157], v[156:157], v[154:155]
	v_mov_b32_e32 v156, v84
	v_mov_b32_e32 v157, v76
	v_pk_fma_f32 v[154:155], v[156:157], v[156:157], v[154:155]
	v_mov_b32_e32 v156, v85
	v_mov_b32_e32 v157, v77
	v_pk_fma_f32 v[154:155], v[156:157], v[156:157], v[154:155]
	v_mov_b32_e32 v156, v78
	v_mov_b32_e32 v157, v70
	v_pk_fma_f32 v[154:155], v[156:157], v[156:157], v[154:155]
	v_mov_b32_e32 v156, v79
	v_mov_b32_e32 v157, v71
	v_pk_fma_f32 v[154:155], v[156:157], v[156:157], v[154:155]
	v_mov_b32_e32 v156, v80
	v_mov_b32_e32 v157, v72
	v_pk_fma_f32 v[154:155], v[156:157], v[156:157], v[154:155]
	v_mov_b32_e32 v156, v81
	v_mov_b32_e32 v157, v73
	v_pk_fma_f32 v[154:155], v[156:157], v[156:157], v[154:155]
	ds_bpermute_b32 v156, v158, v154
	ds_bpermute_b32 v157, v158, v155
	v_add_co_u32_e32 v174, vcc, s7, v4
	v_cvt_pk_bf16_f32 v163, v64, v65
	s_mov_b64 s[30:31], 0x80000
	s_waitcnt lgkmcnt(0)
	v_pk_add_f32 v[154:155], v[154:155], v[156:157]
	ds_bpermute_b32 v156, v3, v154
	ds_bpermute_b32 v157, v3, v155
	v_addc_co_u32_e32 v175, vcc, 0, v5, vcc
	s_mov_b32 s7, 0x90000
	v_lshl_add_u64 v[172:173], v[4:5], 0, s[30:31]
	s_waitcnt lgkmcnt(0)
	v_pk_add_f32 v[154:155], v[154:155], v[156:157]
	v_mul_f32_e32 v156, v67, v67
	v_mul_f32_e32 v157, v59, v59
	v_fmac_f32_e32 v156, v66, v66
	v_fmac_f32_e32 v157, v58, v58
	v_fmac_f32_e32 v156, v68, v68
	v_fmac_f32_e32 v157, v60, v60
	v_fmac_f32_e32 v156, v69, v69
	v_fmac_f32_e32 v157, v61, v61
	v_fmac_f32_e32 v156, v62, v62
	global_store_dwordx4 v[174:175], v[160:163], off
	v_fmac_f32_e32 v157, v54, v54
	v_add_co_u32_e32 v174, vcc, s7, v4
	v_cvt_pk_bf16_f32 v160, v34, v35
	v_cvt_pk_bf16_f32 v161, v36, v37
	v_cvt_pk_bf16_f32 v162, v30, v31
	v_cvt_pk_bf16_f32 v163, v32, v33
	v_fmac_f32_e32 v156, v63, v63
	global_store_dwordx4 v[172:173], v[160:163], off offset:256
	v_fmac_f32_e32 v157, v55, v55
	s_mov_b64 s[30:31], 0x90000
	v_cvt_pk_bf16_f32 v160, v58, v59
	v_cvt_pk_bf16_f32 v161, v60, v61
	v_cvt_pk_bf16_f32 v162, v54, v55
	v_cvt_pk_bf16_f32 v163, v56, v57
	v_addc_co_u32_e32 v175, vcc, 0, v5, vcc
	v_fmac_f32_e32 v156, v64, v64
	v_mul_f32_e32 v170, v65, v65
	v_fmac_f32_e32 v157, v56, v56
	v_mul_f32_e32 v171, v57, v57
	v_lshl_add_u64 v[172:173], v[4:5], 0, s[30:31]
	global_store_dwordx4 v[174:175], v[160:163], off
	v_pk_add_f32 v[156:157], v[170:171], v[156:157]
	v_mul_f32_e32 v170, v51, v51
	v_cvt_pk_bf16_f32 v160, v26, v27
	v_cvt_pk_bf16_f32 v161, v28, v29
	v_cvt_pk_bf16_f32 v162, v22, v23
	v_cvt_pk_bf16_f32 v163, v24, v25
	global_store_dwordx4 v[172:173], v[160:163], off offset:256
	s_mov_b32 s7, 0xa0000
	v_mul_f32_e32 v171, v43, v43
	v_mov_b32_e32 v160, v34
	v_mov_b32_e32 v161, v26
	v_pk_fma_f32 v[156:157], v[160:161], v[160:161], v[156:157]
	v_mov_b32_e32 v160, v35
	v_mov_b32_e32 v161, v27
	v_pk_fma_f32 v[156:157], v[160:161], v[160:161], v[156:157]
	v_mov_b32_e32 v160, v36
	v_mov_b32_e32 v161, v28
	v_pk_fma_f32 v[156:157], v[160:161], v[160:161], v[156:157]
	v_mov_b32_e32 v160, v37
	v_mov_b32_e32 v161, v29
	v_pk_fma_f32 v[156:157], v[160:161], v[160:161], v[156:157]
	v_mov_b32_e32 v160, v30
	v_mov_b32_e32 v161, v22
	v_pk_fma_f32 v[156:157], v[160:161], v[160:161], v[156:157]
	v_mov_b32_e32 v160, v31
	v_mov_b32_e32 v161, v23
	v_pk_fma_f32 v[156:157], v[160:161], v[160:161], v[156:157]
	v_mov_b32_e32 v160, v32
	v_mov_b32_e32 v161, v24
	v_pk_fma_f32 v[156:157], v[160:161], v[160:161], v[156:157]
	v_mov_b32_e32 v160, v33
	v_mov_b32_e32 v161, v25
	v_pk_fma_f32 v[156:157], v[160:161], v[160:161], v[156:157]
	ds_bpermute_b32 v160, v158, v156
	ds_bpermute_b32 v161, v158, v157
	v_fmac_f32_e32 v170, v50, v50
	v_add_co_u32_e32 v176, vcc, s7, v4
	v_fmac_f32_e32 v171, v42, v42
	s_waitcnt lgkmcnt(0)
	v_pk_add_f32 v[156:157], v[156:157], v[160:161]
	ds_bpermute_b32 v160, v3, v156
	ds_bpermute_b32 v161, v3, v157
	v_fmac_f32_e32 v170, v52, v52
	v_cvt_pk_bf16_f32 v162, v46, v47
	v_cvt_pk_bf16_f32 v163, v48, v49
	s_mov_b64 s[30:31], 0xa0000
	s_waitcnt lgkmcnt(0)
	v_pk_add_f32 v[156:157], v[156:157], v[160:161]
	v_cvt_pk_bf16_f32 v160, v50, v51
	v_cvt_pk_bf16_f32 v161, v52, v53
	v_addc_co_u32_e32 v177, vcc, 0, v5, vcc
	v_fmac_f32_e32 v171, v44, v44
	v_fmac_f32_e32 v170, v53, v53
	v_lshl_add_u64 v[174:175], v[4:5], 0, s[30:31]
	global_store_dwordx4 v[176:177], v[160:163], off
	s_mov_b64 s[30:31], 0xb0000
	s_mov_b32 s7, 0xb0000
	v_cvt_pk_bf16_f32 v160, v18, v19
	v_cvt_pk_bf16_f32 v161, v20, v21
	v_cvt_pk_bf16_f32 v162, v14, v15
	v_cvt_pk_bf16_f32 v163, v16, v17
	v_fmac_f32_e32 v171, v45, v45
	v_fmac_f32_e32 v170, v46, v46
	global_store_dwordx4 v[174:175], v[160:163], off offset:256
	v_lshl_add_u64 v[174:175], v[4:5], 0, s[30:31]
	v_add_co_u32_e32 v4, vcc, s7, v4
	v_fmac_f32_e32 v171, v38, v38
	v_fmac_f32_e32 v170, v47, v47
	v_cvt_pk_bf16_f32 v160, v42, v43
	v_cvt_pk_bf16_f32 v161, v44, v45
	v_cvt_pk_bf16_f32 v162, v38, v39
	v_cvt_pk_bf16_f32 v163, v40, v41
	v_addc_co_u32_e32 v5, vcc, 0, v5, vcc
	v_fmac_f32_e32 v171, v39, v39
	v_fmac_f32_e32 v170, v48, v48
	v_mul_f32_e32 v172, v49, v49
	global_store_dwordx4 v[4:5], v[160:163], off
	v_fmac_f32_e32 v171, v40, v40
	v_mul_f32_e32 v173, v41, v41
	v_cvt_pk_bf16_f32 v160, v10, v11
	v_cvt_pk_bf16_f32 v161, v12, v13
	v_cvt_pk_bf16_f32 v162, v6, v7
	v_cvt_pk_bf16_f32 v163, v8, v9
	global_store_dwordx4 v[174:175], v[160:163], off offset:256
	v_pk_add_f32 v[4:5], v[172:173], v[170:171]
	s_and_b64 vcc, exec, s[4:5]
	v_mov_b32_e32 v160, v18
	v_mov_b32_e32 v161, v10
	v_pk_fma_f32 v[4:5], v[160:161], v[160:161], v[4:5]
	v_mov_b32_e32 v160, v19
	v_mov_b32_e32 v161, v11
	v_pk_fma_f32 v[4:5], v[160:161], v[160:161], v[4:5]
	v_mov_b32_e32 v160, v20
	v_mov_b32_e32 v161, v12
	v_pk_fma_f32 v[4:5], v[160:161], v[160:161], v[4:5]
	v_mov_b32_e32 v160, v21
	v_mov_b32_e32 v161, v13
	v_pk_fma_f32 v[4:5], v[160:161], v[160:161], v[4:5]
	v_mov_b32_e32 v160, v14
	v_mov_b32_e32 v161, v6
	v_pk_fma_f32 v[4:5], v[160:161], v[160:161], v[4:5]
	v_mov_b32_e32 v160, v15
	v_mov_b32_e32 v161, v7
	v_pk_fma_f32 v[4:5], v[160:161], v[160:161], v[4:5]
	v_mov_b32_e32 v160, v16
	v_mov_b32_e32 v161, v8
	v_pk_fma_f32 v[4:5], v[160:161], v[160:161], v[4:5]
	v_mov_b32_e32 v160, v17
	v_mov_b32_e32 v161, v9
	v_pk_fma_f32 v[4:5], v[160:161], v[160:161], v[4:5]
	ds_bpermute_b32 v160, v158, v4
	ds_bpermute_b32 v161, v158, v5
	s_waitcnt lgkmcnt(0)
	v_pk_add_f32 v[4:5], v[4:5], v[160:161]
	ds_bpermute_b32 v158, v3, v4
	ds_bpermute_b32 v159, v3, v5
	s_waitcnt lgkmcnt(0)
	v_pk_add_f32 v[158:159], v[4:5], v[158:159]
	s_cbranch_vccz .LBB0_518
	s_and_saveexec_b64 s[26:27], s[2:3]
	s_cbranch_execz .LBB0_501
	s_ashr_i32 s7, s6, 31
	v_lshl_add_u64 v[4:5], s[6:7], 2, v[142:143]
	global_atomic_add_f32 v[4:5], v152, off
	global_atomic_add_f32 v[4:5], v153, off offset:64
	global_atomic_add_f32 v[4:5], v154, off offset:128
	global_atomic_add_f32 v[4:5], v155, off offset:192
	global_atomic_add_f32 v[4:5], v156, off offset:512
	global_atomic_add_f32 v[4:5], v157, off offset:576
	global_atomic_add_f32 v[4:5], v158, off offset:640
	global_atomic_add_f32 v[4:5], v159, off offset:704
	s_branch .LBB0_501

.LBB0_872:
	s_ashr_i32 s23, s22, 31
	s_lshl_b64 s[26:27], s[22:23], 20
	s_add_u32 s26, s40, s26
	s_addc_u32 s27, s41, s27
	s_andn2_b64 vcc, exec, s[20:21]
	s_cbranch_vccnz .LBB0_877
	s_and_b64 s[6:7], s[6:7], exec
	s_cselect_b32 s23, s27, s15
	s_cselect_b32 s33, s26, s14
	s_lshl_b32 s6, s30, 8
	s_ashr_i32 s7, s6, 31
	s_add_u32 s60, s12, 0x100
	v_lshl_add_u64 v[4:5], s[6:7], 2, v[154:155]
	s_addc_u32 s61, s13, 0
	v_lshl_add_u64 v[136:137], s[14:15], 0, v[156:157]
	v_lshl_add_u64 v[138:139], s[14:15], 0, v[158:159]
	s_mov_b32 s36, 0
	s_mov_b64 s[6:7], 0
	v_add_u32_e32 v3, 0x10000, v198
	ds_read_b128 v[168:171], v3
	ds_read_b128 v[172:175], v3 offset:1024
	ds_read_b128 v[176:179], v3 offset:2048
	ds_read_b128 v[180:183], v3 offset:3072
	s_branch .LBB0_875
.LBB0_874:
	s_or_b64 exec, exec, s[34:35]
	s_add_i32 s62, s36, 2
	s_add_u32 s34, s14, s6
	s_addc_u32 s35, s15, s7
	s_add_u32 s34, s34, 0x100
	s_addc_u32 s35, s35, 0
	s_add_u32 s63, s60, s6
	s_addc_u32 s37, s61, s7
	s_cmp_eq_u32 s54, s36
	s_cselect_b32 s36, s24, s63
	s_cselect_b32 s35, s23, s35
	s_cselect_b32 s34, s33, s34
	s_cselect_b32 s37, s25, s37
	v_lshl_add_u64 v[140:141], v[136:137], 0, s[6:7]
	s_add_i32 m0, s45, 0xc000
	ds_read_b128 v[184:187], v200
	ds_read_b128 v[188:191], v200 offset:1024
	ds_read_b128 v[192:195], v200 offset:2048
	ds_read_b128 v[202:205], v200 offset:3072
	ds_read_b128 v[206:209], v200 offset:4096
	ds_read_b128 v[210:213], v200 offset:5120
	ds_read_b128 v[214:217], v200 offset:6144
	ds_read_b128 v[218:221], v200 offset:7168
	global_load_lds_dwordx4 v[140:141], off
	v_lshl_add_u64 v[140:141], v[138:139], 0, s[6:7]
	s_add_i32 m0, s45, 0xe000
	s_nop 0
	global_load_lds_dwordx4 v[140:141], off
	s_waitcnt lgkmcnt(8)
	s_barrier
	s_waitcnt lgkmcnt(0)
	s_waitcnt lgkmcnt(0)
	v_mfma_f32_16x16x32_bf16 v[130:133], v[168:171], v[184:187], v[130:133]
	v_mfma_f32_16x16x32_bf16 v[126:129], v[176:179], v[184:187], v[126:129]
	v_mfma_f32_16x16x32_bf16 v[122:125], v[168:171], v[192:195], v[122:125]
	v_mfma_f32_16x16x32_bf16 v[118:121], v[176:179], v[192:195], v[118:121]
	v_mfma_f32_16x16x32_bf16 v[114:117], v[168:171], v[206:209], v[114:117]
	v_mfma_f32_16x16x32_bf16 v[110:113], v[176:179], v[206:209], v[110:113]
	v_mfma_f32_16x16x32_bf16 v[106:109], v[168:171], v[214:217], v[106:109]
	v_mfma_f32_16x16x32_bf16 v[98:101], v[176:179], v[214:217], v[98:101]
	v_mfma_f32_16x16x32_bf16 v[130:133], v[172:175], v[188:191], v[130:133]
	v_mfma_f32_16x16x32_bf16 v[126:129], v[180:183], v[188:191], v[126:129]
	v_mfma_f32_16x16x32_bf16 v[122:125], v[172:175], v[202:205], v[122:125]
	v_mfma_f32_16x16x32_bf16 v[118:121], v[180:183], v[202:205], v[118:121]
	v_mfma_f32_16x16x32_bf16 v[114:117], v[172:175], v[210:213], v[114:117]
	v_mfma_f32_16x16x32_bf16 v[110:113], v[180:183], v[210:213], v[110:113]
	v_mfma_f32_16x16x32_bf16 v[106:109], v[172:175], v[218:221], v[106:109]
	v_mfma_f32_16x16x32_bf16 v[98:101], v[180:183], v[218:221], v[98:101]
	s_barrier
	s_add_i32 s63, s55, s44
	v_add_u32_e32 v3, s56, v198
	v_lshl_add_u64 v[140:141], s[36:37], 0, v[148:149]
	s_mov_b32 m0, s63
	ds_read_b128 v[222:225], v3
	ds_read_b128 v[226:229], v3 offset:1024
	ds_read_b128 v[230:233], v3 offset:2048
	ds_read_b128 v[234:237], v3 offset:3072
	global_load_lds_dwordx4 v[140:141], off
	v_lshl_add_u64 v[144:145], s[36:37], 0, v[152:153]
	s_add_i32 m0, s63, 0x2000
	s_nop 0
	global_load_lds_dwordx4 v[144:145], off
	s_barrier
	s_waitcnt lgkmcnt(0)
	s_waitcnt lgkmcnt(0)
	v_mfma_f32_16x16x32_bf16 v[102:105], v[222:225], v[184:187], v[102:105]
	v_mfma_f32_16x16x32_bf16 v[94:97], v[230:233], v[184:187], v[94:97]
	v_mfma_f32_16x16x32_bf16 v[90:93], v[222:225], v[192:195], v[90:93]
	v_mfma_f32_16x16x32_bf16 v[86:89], v[230:233], v[192:195], v[86:89]
	v_mfma_f32_16x16x32_bf16 v[82:85], v[222:225], v[206:209], v[82:85]
	v_mfma_f32_16x16x32_bf16 v[78:81], v[230:233], v[206:209], v[78:81]
	v_mfma_f32_16x16x32_bf16 v[74:77], v[222:225], v[214:217], v[74:77]
	v_mfma_f32_16x16x32_bf16 v[70:73], v[230:233], v[214:217], v[70:73]
	v_mfma_f32_16x16x32_bf16 v[102:105], v[226:229], v[188:191], v[102:105]
	v_mfma_f32_16x16x32_bf16 v[94:97], v[234:237], v[188:191], v[94:97]
	v_mfma_f32_16x16x32_bf16 v[90:93], v[226:229], v[202:205], v[90:93]
	v_mfma_f32_16x16x32_bf16 v[86:89], v[234:237], v[202:205], v[86:89]
	v_mfma_f32_16x16x32_bf16 v[82:85], v[226:229], v[210:213], v[82:85]
	v_mfma_f32_16x16x32_bf16 v[78:81], v[234:237], v[210:213], v[78:81]
	v_mfma_f32_16x16x32_bf16 v[74:77], v[226:229], v[218:221], v[74:77]
	v_mfma_f32_16x16x32_bf16 v[70:73], v[234:237], v[218:221], v[70:73]
	s_mov_b32 m0, s45
	v_lshl_add_u64 v[196:197], s[34:35], 0, v[146:147]
	s_barrier
	ds_read_b128 v[184:187], v200 offset:16384
	ds_read_b128 v[188:191], v200 offset:17408
	ds_read_b128 v[192:195], v200 offset:18432
	ds_read_b128 v[202:205], v200 offset:19456
	ds_read_b128 v[206:209], v200 offset:20480
	ds_read_b128 v[210:213], v200 offset:21504
	ds_read_b128 v[214:217], v200 offset:22528
	ds_read_b128 v[218:221], v200 offset:23552
	global_load_lds_dwordx4 v[196:197], off
	v_lshl_add_u64 v[238:239], s[34:35], 0, v[150:151]
	s_mov_b32 m0, s46
	s_nop 0
	global_load_lds_dwordx4 v[238:239], off
	s_waitcnt vmcnt(10)
	s_barrier
	s_waitcnt lgkmcnt(0)
	s_waitcnt lgkmcnt(0)
	v_mfma_f32_16x16x32_bf16 v[66:69], v[168:171], v[184:187], v[66:69]
	v_mfma_f32_16x16x32_bf16 v[62:65], v[176:179], v[184:187], v[62:65]
	v_mfma_f32_16x16x32_bf16 v[58:61], v[168:171], v[192:195], v[58:61]
	v_mfma_f32_16x16x32_bf16 v[54:57], v[176:179], v[192:195], v[54:57]
	v_mfma_f32_16x16x32_bf16 v[50:53], v[168:171], v[206:209], v[50:53]
	v_mfma_f32_16x16x32_bf16 v[46:49], v[176:179], v[206:209], v[46:49]
	v_mfma_f32_16x16x32_bf16 v[42:45], v[168:171], v[214:217], v[42:45]
	v_mfma_f32_16x16x32_bf16 v[38:41], v[176:179], v[214:217], v[38:41]
	v_mfma_f32_16x16x32_bf16 v[66:69], v[172:175], v[188:191], v[66:69]
	v_mfma_f32_16x16x32_bf16 v[62:65], v[180:183], v[188:191], v[62:65]
	v_mfma_f32_16x16x32_bf16 v[58:61], v[172:175], v[202:205], v[58:61]
	v_mfma_f32_16x16x32_bf16 v[54:57], v[180:183], v[202:205], v[54:57]
	v_mfma_f32_16x16x32_bf16 v[50:53], v[172:175], v[210:213], v[50:53]
	v_mfma_f32_16x16x32_bf16 v[46:49], v[180:183], v[210:213], v[46:49]
	v_mfma_f32_16x16x32_bf16 v[42:45], v[172:175], v[218:221], v[42:45]
	v_mfma_f32_16x16x32_bf16 v[38:41], v[180:183], v[218:221], v[38:41]
	s_barrier
	v_add_u32_e32 v3, 0x18000, v198
	ds_read_b128 v[168:171], v3
	ds_read_b128 v[172:175], v3 offset:1024
	ds_read_b128 v[176:179], v3 offset:2048
	ds_read_b128 v[180:183], v3 offset:3072
	s_add_u32 s36, s36, s8
	s_addc_u32 s37, s37, s9
	s_add_i32 s63, s56, s44
	v_lshl_add_u64 v[240:241], s[36:37], 0, v[148:149]
	s_mov_b32 m0, s63
	v_lshl_add_u64 v[242:243], s[36:37], 0, v[152:153]
	global_load_lds_dwordx4 v[240:241], off
	s_add_i32 m0, s63, 0x2000
	s_nop 0
	global_load_lds_dwordx4 v[242:243], off
	s_waitcnt vmcnt(6)
	s_barrier
	v_mfma_f32_16x16x32_bf16 v[34:37], v[222:225], v[184:187], v[34:37]
	v_mfma_f32_16x16x32_bf16 v[30:33], v[230:233], v[184:187], v[30:33]
	v_mfma_f32_16x16x32_bf16 v[26:29], v[222:225], v[192:195], v[26:29]
	v_mfma_f32_16x16x32_bf16 v[22:25], v[230:233], v[192:195], v[22:25]
	v_mfma_f32_16x16x32_bf16 v[18:21], v[222:225], v[206:209], v[18:21]
	v_mfma_f32_16x16x32_bf16 v[14:17], v[230:233], v[206:209], v[14:17]
	v_mfma_f32_16x16x32_bf16 v[10:13], v[222:225], v[214:217], v[10:13]
	v_mfma_f32_16x16x32_bf16 v[6:9], v[230:233], v[214:217], v[6:9]
	v_mfma_f32_16x16x32_bf16 v[34:37], v[226:229], v[188:191], v[34:37]
	v_mfma_f32_16x16x32_bf16 v[30:33], v[234:237], v[188:191], v[30:33]
	v_mfma_f32_16x16x32_bf16 v[26:29], v[226:229], v[202:205], v[26:29]
	v_mfma_f32_16x16x32_bf16 v[22:25], v[234:237], v[202:205], v[22:25]
	v_mfma_f32_16x16x32_bf16 v[18:21], v[226:229], v[210:213], v[18:21]
	v_mfma_f32_16x16x32_bf16 v[14:17], v[234:237], v[210:213], v[14:17]
	v_mfma_f32_16x16x32_bf16 v[10:13], v[226:229], v[218:221], v[10:13]
	v_mfma_f32_16x16x32_bf16 v[6:9], v[234:237], v[218:221], v[6:9]
	s_add_i32 s36, 0, 0x18000
	s_barrier
	s_add_u32 s34, s34, 0x80000
	s_addc_u32 s35, s35, 0
	s_mov_b32 m0, s47
	v_lshl_add_u64 v[222:223], s[34:35], 0, v[146:147]
	ds_read_b128 v[184:187], v200 offset:32768
	ds_read_b128 v[188:191], v200 offset:33792
	ds_read_b128 v[192:195], v200 offset:34816
	ds_read_b128 v[202:205], v200 offset:35840
	ds_read_b128 v[206:209], v200 offset:36864
	ds_read_b128 v[210:213], v200 offset:37888
	ds_read_b128 v[214:217], v200 offset:38912
	ds_read_b128 v[218:221], v200 offset:39936
	global_load_lds_dwordx4 v[222:223], off
	v_lshl_add_u64 v[222:223], s[34:35], 0, v[150:151]
	s_mov_b32 m0, s48
	s_nop 0
	global_load_lds_dwordx4 v[222:223], off
	s_waitcnt lgkmcnt(8)
	s_barrier
	s_waitcnt lgkmcnt(0)
	s_waitcnt lgkmcnt(0)
	v_mfma_f32_16x16x32_bf16 v[130:133], v[168:171], v[184:187], v[130:133]
	v_mfma_f32_16x16x32_bf16 v[126:129], v[176:179], v[184:187], v[126:129]
	v_mfma_f32_16x16x32_bf16 v[122:125], v[168:171], v[192:195], v[122:125]
	v_mfma_f32_16x16x32_bf16 v[118:121], v[176:179], v[192:195], v[118:121]
	v_mfma_f32_16x16x32_bf16 v[114:117], v[168:171], v[206:209], v[114:117]
	v_mfma_f32_16x16x32_bf16 v[110:113], v[176:179], v[206:209], v[110:113]
	v_mfma_f32_16x16x32_bf16 v[106:109], v[168:171], v[214:217], v[106:109]
	v_mfma_f32_16x16x32_bf16 v[98:101], v[176:179], v[214:217], v[98:101]
	v_mfma_f32_16x16x32_bf16 v[130:133], v[172:175], v[188:191], v[130:133]
	v_mfma_f32_16x16x32_bf16 v[126:129], v[180:183], v[188:191], v[126:129]
	v_mfma_f32_16x16x32_bf16 v[122:125], v[172:175], v[202:205], v[122:125]
	v_mfma_f32_16x16x32_bf16 v[118:121], v[180:183], v[202:205], v[118:121]
	v_mfma_f32_16x16x32_bf16 v[114:117], v[172:175], v[210:213], v[114:117]
	v_mfma_f32_16x16x32_bf16 v[110:113], v[180:183], v[210:213], v[110:113]
	v_mfma_f32_16x16x32_bf16 v[106:109], v[172:175], v[218:221], v[106:109]
	v_mfma_f32_16x16x32_bf16 v[98:101], v[180:183], v[218:221], v[98:101]
	s_barrier
	s_add_i32 s34, 0, 0x1c000
	s_add_i32 s35, s36, s44
	v_add_u32_e32 v3, s34, v198
	v_lshl_add_u64 v[140:141], v[140:141], 0, s[18:19]
	s_mov_b32 m0, s35
	ds_read_b128 v[222:225], v3
	ds_read_b128 v[226:229], v3 offset:1024
	ds_read_b128 v[230:233], v3 offset:2048
	ds_read_b128 v[234:237], v3 offset:3072
	global_load_lds_dwordx4 v[140:141], off
	v_lshl_add_u64 v[140:141], v[144:145], 0, s[18:19]
	s_add_i32 m0, s35, 0x2000
	s_nop 0
	global_load_lds_dwordx4 v[140:141], off
	s_barrier
	s_waitcnt lgkmcnt(0)
	s_waitcnt lgkmcnt(0)
	v_mfma_f32_16x16x32_bf16 v[102:105], v[222:225], v[184:187], v[102:105]
	v_mfma_f32_16x16x32_bf16 v[94:97], v[230:233], v[184:187], v[94:97]
	v_mfma_f32_16x16x32_bf16 v[90:93], v[222:225], v[192:195], v[90:93]
	v_mfma_f32_16x16x32_bf16 v[86:89], v[230:233], v[192:195], v[86:89]
	v_mfma_f32_16x16x32_bf16 v[82:85], v[222:225], v[206:209], v[82:85]
	v_mfma_f32_16x16x32_bf16 v[78:81], v[230:233], v[206:209], v[78:81]
	v_mfma_f32_16x16x32_bf16 v[74:77], v[222:225], v[214:217], v[74:77]
	v_mfma_f32_16x16x32_bf16 v[70:73], v[230:233], v[214:217], v[70:73]
	v_mfma_f32_16x16x32_bf16 v[102:105], v[226:229], v[188:191], v[102:105]
	v_mfma_f32_16x16x32_bf16 v[94:97], v[234:237], v[188:191], v[94:97]
	v_mfma_f32_16x16x32_bf16 v[90:93], v[226:229], v[202:205], v[90:93]
	v_mfma_f32_16x16x32_bf16 v[86:89], v[234:237], v[202:205], v[86:89]
	v_mfma_f32_16x16x32_bf16 v[82:85], v[226:229], v[210:213], v[82:85]
	v_mfma_f32_16x16x32_bf16 v[78:81], v[234:237], v[210:213], v[78:81]
	v_mfma_f32_16x16x32_bf16 v[74:77], v[226:229], v[218:221], v[74:77]
	v_mfma_f32_16x16x32_bf16 v[70:73], v[234:237], v[218:221], v[70:73]
	s_mov_b32 m0, s52
	v_lshl_add_u64 v[140:141], v[196:197], 0, s[18:19]
	s_barrier
	ds_read_b128 v[184:187], v200 offset:49152
	ds_read_b128 v[188:191], v200 offset:50176
	ds_read_b128 v[192:195], v200 offset:51200
	ds_read_b128 v[202:205], v200 offset:52224
	ds_read_b128 v[206:209], v200 offset:53248
	ds_read_b128 v[210:213], v200 offset:54272
	ds_read_b128 v[214:217], v200 offset:55296
	ds_read_b128 v[218:221], v200 offset:56320
	global_load_lds_dwordx4 v[140:141], off
	v_lshl_add_u64 v[140:141], v[238:239], 0, s[18:19]
	s_mov_b32 m0, s53
	s_nop 0
	global_load_lds_dwordx4 v[140:141], off
	s_waitcnt vmcnt(10)
	s_barrier
	s_waitcnt lgkmcnt(0)
	s_waitcnt lgkmcnt(0)
	v_mfma_f32_16x16x32_bf16 v[66:69], v[168:171], v[184:187], v[66:69]
	v_mfma_f32_16x16x32_bf16 v[62:65], v[176:179], v[184:187], v[62:65]
	v_mfma_f32_16x16x32_bf16 v[58:61], v[168:171], v[192:195], v[58:61]
	v_mfma_f32_16x16x32_bf16 v[54:57], v[176:179], v[192:195], v[54:57]
	v_mfma_f32_16x16x32_bf16 v[50:53], v[168:171], v[206:209], v[50:53]
	v_mfma_f32_16x16x32_bf16 v[46:49], v[176:179], v[206:209], v[46:49]
	v_mfma_f32_16x16x32_bf16 v[42:45], v[168:171], v[214:217], v[42:45]
	v_mfma_f32_16x16x32_bf16 v[38:41], v[176:179], v[214:217], v[38:41]
	v_mfma_f32_16x16x32_bf16 v[66:69], v[172:175], v[188:191], v[66:69]
	v_mfma_f32_16x16x32_bf16 v[62:65], v[180:183], v[188:191], v[62:65]
	v_mfma_f32_16x16x32_bf16 v[58:61], v[172:175], v[202:205], v[58:61]
	v_mfma_f32_16x16x32_bf16 v[54:57], v[180:183], v[202:205], v[54:57]
	v_mfma_f32_16x16x32_bf16 v[50:53], v[172:175], v[210:213], v[50:53]
	v_mfma_f32_16x16x32_bf16 v[46:49], v[180:183], v[210:213], v[46:49]
	v_mfma_f32_16x16x32_bf16 v[42:45], v[172:175], v[218:221], v[42:45]
	v_mfma_f32_16x16x32_bf16 v[38:41], v[180:183], v[218:221], v[38:41]
	s_barrier
	v_add_u32_e32 v3, 0x10000, v198
	ds_read_b128 v[168:171], v3
	ds_read_b128 v[172:175], v3 offset:1024
	ds_read_b128 v[176:179], v3 offset:2048
	ds_read_b128 v[180:183], v3 offset:3072
	s_add_i32 s34, s34, s44
	v_lshl_add_u64 v[140:141], v[240:241], 0, s[18:19]
	s_mov_b32 m0, s34
	s_nop 0
	global_load_lds_dwordx4 v[140:141], off
	v_lshl_add_u64 v[140:141], v[242:243], 0, s[18:19]
	s_add_i32 m0, s34, 0x2000
	s_nop 0
	global_load_lds_dwordx4 v[140:141], off
	s_waitcnt vmcnt(6)
	s_barrier
	v_mfma_f32_16x16x32_bf16 v[34:37], v[222:225], v[184:187], v[34:37]
	v_mfma_f32_16x16x32_bf16 v[30:33], v[230:233], v[184:187], v[30:33]
	v_mfma_f32_16x16x32_bf16 v[26:29], v[222:225], v[192:195], v[26:29]
	v_mfma_f32_16x16x32_bf16 v[22:25], v[230:233], v[192:195], v[22:25]
	v_mfma_f32_16x16x32_bf16 v[18:21], v[222:225], v[206:209], v[18:21]
	v_mfma_f32_16x16x32_bf16 v[14:17], v[230:233], v[206:209], v[14:17]
	v_mfma_f32_16x16x32_bf16 v[10:13], v[222:225], v[214:217], v[10:13]
	v_mfma_f32_16x16x32_bf16 v[6:9], v[230:233], v[214:217], v[6:9]
	v_mfma_f32_16x16x32_bf16 v[34:37], v[226:229], v[188:191], v[34:37]
	v_mfma_f32_16x16x32_bf16 v[30:33], v[234:237], v[188:191], v[30:33]
	v_mfma_f32_16x16x32_bf16 v[26:29], v[226:229], v[202:205], v[26:29]
	v_mfma_f32_16x16x32_bf16 v[22:25], v[234:237], v[202:205], v[22:25]
	v_mfma_f32_16x16x32_bf16 v[18:21], v[226:229], v[210:213], v[18:21]
	v_mfma_f32_16x16x32_bf16 v[14:17], v[234:237], v[210:213], v[14:17]
	v_mfma_f32_16x16x32_bf16 v[10:13], v[226:229], v[218:221], v[10:13]
	v_mfma_f32_16x16x32_bf16 v[6:9], v[234:237], v[218:221], v[6:9]
	s_add_u32 s6, s6, 0x100
	s_addc_u32 s7, s7, 0
	s_andn2_b64 s[28:29], s[28:29], exec
	s_and_b64 s[34:35], s[30:31], exec
	s_or_b64 s[28:29], s[28:29], s[34:35]
	s_cmp_ge_i32 s62, s49
	s_mov_b32 s36, s62
	s_barrier
	s_cbranch_scc1 .LBB0_877

.LBB0_877:
	s_waitcnt lgkmcnt(0)
	v_and_b32_e32 v134, 64, v201
	v_xor_b32_e32 v3, 16, v201
	v_add_u32_e32 v134, 64, v134
	s_lshl_b32 s6, s57, 8
	v_cmp_lt_i32_e32 vcc, v3, v134
	v_add_u32_e32 v168, s6, v1
	v_lshl_or_b32 v4, s51, 8, v199
	v_cndmask_b32_e32 v3, v201, v3, vcc
	v_lshlrev_b32_e32 v202, 2, v3
	v_xor_b32_e32 v3, 32, v201
	v_ashrrev_i32_e32 v169, 31, v168
	v_ashrrev_i32_e32 v5, 31, v4
	v_cmp_lt_i32_e32 vcc, v3, v134
	v_lshlrev_b64 v[134:135], 13, v[168:169]
	v_or_b32_e32 v188, 16, v168
	v_lshl_add_u64 v[134:135], s[72:73], 0, v[134:135]
	v_lshlrev_b64 v[170:171], 2, v[4:5]
	v_ashrrev_i32_e32 v189, 31, v188
	v_lshl_add_u64 v[164:165], v[134:135], 0, v[170:171]
	v_lshlrev_b64 v[172:173], 13, v[188:189]
	global_load_dwordx4 v[134:137], v[164:165], off offset:16 nt
	global_load_dwordx4 v[138:141], v[164:165], off nt
	global_load_dwordx4 v[142:145], v[164:165], off offset:528 nt
	s_nop 0
	global_load_dwordx4 v[164:167], v[164:165], off offset:512 nt
	v_lshl_add_u64 v[172:173], s[72:73], 0, v[172:173]
	v_lshl_add_u64 v[184:185], v[172:173], 0, v[170:171]
	global_load_dwordx4 v[172:175], v[184:185], off offset:16 nt
	global_load_dwordx4 v[176:179], v[184:185], off nt
	global_load_dwordx4 v[180:183], v[184:185], off offset:528 nt
	s_nop 0
	global_load_dwordx4 v[184:187], v[184:185], off offset:512 nt
	v_lshlrev_b64 v[194:195], 12, v[168:169]
	v_lshl_add_u64 v[194:195], s[16:17], 0, v[194:195]
	v_lshlrev_b64 v[4:5], 1, v[4:5]
	v_lshl_add_u64 v[194:195], v[194:195], 0, v[4:5]
	v_lshlrev_b64 v[188:189], 12, v[188:189]
	v_lshl_add_u64 v[188:189], s[16:17], 0, v[188:189]
	v_lshl_add_u64 v[188:189], v[188:189], 0, v[4:5]
	v_cndmask_b32_e32 v3, v201, v3, vcc
	v_lshlrev_b32_e32 v3, 2, v3
	s_and_b64 vcc, exec, s[4:5]
	s_waitcnt vmcnt(0)
	v_pk_add_f32 v[190:191], v[128:129], v[136:137]
	v_pk_add_f32 v[140:141], v[132:133], v[140:141]
	v_pk_add_f32 v[138:139], v[130:131], v[138:139]
	v_pk_add_f32 v[192:193], v[126:127], v[134:135]
	v_cvt_pk_bf16_f32 v134, v138, v139
	v_cvt_pk_bf16_f32 v135, v140, v141
	v_cvt_pk_bf16_f32 v136, v192, v193
	v_cvt_pk_bf16_f32 v137, v190, v191
	v_pk_add_f32 v[166:167], v[104:105], v[166:167]
	v_pk_add_f32 v[164:165], v[102:103], v[164:165]
	v_pk_add_f32 v[144:145], v[96:97], v[144:145]
	v_pk_add_f32 v[142:143], v[94:95], v[142:143]
	global_store_dwordx4 v[194:195], v[134:137], off
	v_pk_add_f32 v[178:179], v[124:125], v[178:179]
	v_pk_add_f32 v[176:177], v[122:123], v[176:177]
	v_cvt_pk_bf16_f32 v134, v164, v165
	v_cvt_pk_bf16_f32 v135, v166, v167
	v_cvt_pk_bf16_f32 v136, v142, v143
	v_cvt_pk_bf16_f32 v137, v144, v145
	v_pk_add_f32 v[174:175], v[120:121], v[174:175]
	v_pk_add_f32 v[172:173], v[118:119], v[172:173]
	global_store_dwordx4 v[194:195], v[134:137], off offset:256
	v_pk_add_f32 v[186:187], v[92:93], v[186:187]
	v_pk_add_f32 v[184:185], v[90:91], v[184:185]
	v_cvt_pk_bf16_f32 v134, v176, v177
	v_cvt_pk_bf16_f32 v135, v178, v179
	v_cvt_pk_bf16_f32 v136, v172, v173
	v_cvt_pk_bf16_f32 v137, v174, v175
	v_pk_add_f32 v[182:183], v[88:89], v[182:183]
	v_pk_add_f32 v[180:181], v[86:87], v[180:181]
	global_store_dwordx4 v[188:189], v[134:137], off
	s_nop 1
	v_cvt_pk_bf16_f32 v134, v184, v185
	v_cvt_pk_bf16_f32 v135, v186, v187
	v_cvt_pk_bf16_f32 v136, v180, v181
	v_cvt_pk_bf16_f32 v137, v182, v183
	global_store_dwordx4 v[188:189], v[134:137], off offset:256
	s_nop 1
	v_mov_b32_e32 v135, v175
	v_mov_b32_e32 v175, v176
	v_mov_b32_e32 v176, v139
	v_mov_b32_e32 v134, v191
	v_mov_b32_e32 v191, v174
	v_mov_b32_e32 v174, v138
	v_pk_mul_f32 v[138:139], v[176:177], v[176:177]
	v_mov_b32_e32 v136, v193
	v_mov_b32_e32 v193, v172
	v_mov_b32_e32 v172, v141
	v_mov_b32_e32 v141, v178
	v_pk_fma_f32 v[138:139], v[174:175], v[174:175], v[138:139]
	v_mov_b32_e32 v137, v173
	v_mov_b32_e32 v173, v179
	v_pk_fma_f32 v[138:139], v[140:141], v[140:141], v[138:139]
	s_nop 0
	v_pk_fma_f32 v[138:139], v[172:173], v[172:173], v[138:139]
	s_nop 0
	v_pk_fma_f32 v[138:139], v[192:193], v[192:193], v[138:139]
	v_or_b32_e32 v192, 48, v168
	v_pk_fma_f32 v[136:137], v[136:137], v[136:137], v[138:139]
	v_ashrrev_i32_e32 v193, 31, v192
	v_pk_fma_f32 v[136:137], v[190:191], v[190:191], v[136:137]
	v_lshlrev_b64 v[176:177], 13, v[192:193]
	v_pk_fma_f32 v[134:135], v[134:135], v[134:135], v[136:137]
	v_mov_b32_e32 v136, v164
	v_mov_b32_e32 v137, v184
	v_pk_fma_f32 v[134:135], v[136:137], v[136:137], v[134:135]
	v_mov_b32_e32 v184, v165
	v_pk_fma_f32 v[134:135], v[184:185], v[184:185], v[134:135]
	v_mov_b32_e32 v136, v166
	v_mov_b32_e32 v137, v186
	v_pk_fma_f32 v[134:135], v[136:137], v[136:137], v[134:135]
	v_mov_b32_e32 v186, v167
	v_pk_fma_f32 v[134:135], v[186:187], v[186:187], v[134:135]
	v_mov_b32_e32 v136, v142
	v_mov_b32_e32 v137, v180
	v_pk_fma_f32 v[134:135], v[136:137], v[136:137], v[134:135]
	v_mov_b32_e32 v180, v143
	v_pk_fma_f32 v[134:135], v[180:181], v[180:181], v[134:135]
	v_mov_b32_e32 v136, v144
	v_mov_b32_e32 v137, v182
	v_pk_fma_f32 v[134:135], v[136:137], v[136:137], v[134:135]
	v_mov_b32_e32 v182, v145
	v_pk_fma_f32 v[134:135], v[182:183], v[182:183], v[134:135]
	ds_bpermute_b32 v136, v202, v134
	ds_bpermute_b32 v137, v202, v135
	v_or_b32_e32 v166, 32, v168
	v_ashrrev_i32_e32 v167, 31, v166
	v_lshl_add_u64 v[176:177], s[72:73], 0, v[176:177]
	v_lshl_add_u64 v[188:189], v[176:177], 0, v[170:171]
	s_waitcnt lgkmcnt(0)
	v_pk_add_f32 v[134:135], v[134:135], v[136:137]
	ds_bpermute_b32 v136, v3, v134
	ds_bpermute_b32 v137, v3, v135
	s_waitcnt lgkmcnt(0)
	v_pk_add_f32 v[164:165], v[134:135], v[136:137]
	v_lshlrev_b64 v[134:135], 13, v[166:167]
	v_lshl_add_u64 v[134:135], s[72:73], 0, v[134:135]
	v_lshl_add_u64 v[172:173], v[134:135], 0, v[170:171]
	global_load_dwordx4 v[134:137], v[172:173], off offset:16 nt
	global_load_dwordx4 v[138:141], v[172:173], off nt
	global_load_dwordx4 v[142:145], v[172:173], off offset:528 nt
	s_nop 0
	global_load_dwordx4 v[172:175], v[172:173], off offset:512 nt
	s_nop 0
	global_load_dwordx4 v[176:179], v[188:189], off offset:16 nt
	global_load_dwordx4 v[180:183], v[188:189], off nt
	global_load_dwordx4 v[184:187], v[188:189], off offset:528 nt
	s_nop 0
	global_load_dwordx4 v[188:191], v[188:189], off offset:512 nt
	v_lshlrev_b64 v[166:167], 12, v[166:167]
	v_lshl_add_u64 v[166:167], s[16:17], 0, v[166:167]
	v_lshl_add_u64 v[166:167], v[166:167], 0, v[4:5]
	s_waitcnt vmcnt(7)
	v_pk_add_f32 v[194:195], v[112:113], v[136:137]
	s_waitcnt vmcnt(6)
	v_pk_add_f32 v[140:141], v[116:117], v[140:141]
	v_pk_add_f32 v[138:139], v[114:115], v[138:139]
	v_pk_add_f32 v[196:197], v[110:111], v[134:135]
	v_cvt_pk_bf16_f32 v134, v138, v139
	v_cvt_pk_bf16_f32 v135, v140, v141
	v_cvt_pk_bf16_f32 v136, v196, v197
	v_cvt_pk_bf16_f32 v137, v194, v195
	s_waitcnt vmcnt(4)
	v_pk_add_f32 v[174:175], v[84:85], v[174:175]
	v_pk_add_f32 v[172:173], v[82:83], v[172:173]
	v_pk_add_f32 v[144:145], v[80:81], v[144:145]
	v_pk_add_f32 v[142:143], v[78:79], v[142:143]
	global_store_dwordx4 v[166:167], v[134:137], off
	s_waitcnt vmcnt(3)
	v_pk_add_f32 v[180:181], v[106:107], v[180:181]
	v_pk_add_f32 v[178:179], v[100:101], v[178:179]
	v_cvt_pk_bf16_f32 v134, v172, v173
	v_cvt_pk_bf16_f32 v135, v174, v175
	v_cvt_pk_bf16_f32 v136, v142, v143
	v_cvt_pk_bf16_f32 v137, v144, v145
	global_store_dwordx4 v[166:167], v[134:137], off offset:256
	v_pk_add_f32 v[166:167], v[108:109], v[182:183]
	v_lshlrev_b64 v[182:183], 12, v[192:193]
	v_pk_add_f32 v[176:177], v[98:99], v[176:177]
	v_lshl_add_u64 v[182:183], s[16:17], 0, v[182:183]
	v_cvt_pk_bf16_f32 v134, v180, v181
	v_cvt_pk_bf16_f32 v135, v166, v167
	v_cvt_pk_bf16_f32 v136, v176, v177
	v_cvt_pk_bf16_f32 v137, v178, v179
	v_lshl_add_u64 v[182:183], v[182:183], 0, v[4:5]
	s_waitcnt vmcnt(2)
	v_pk_add_f32 v[190:191], v[76:77], v[190:191]
	v_pk_add_f32 v[188:189], v[74:75], v[188:189]
	v_pk_add_f32 v[186:187], v[72:73], v[186:187]
	v_pk_add_f32 v[184:185], v[70:71], v[184:185]
	global_store_dwordx4 v[182:183], v[134:137], off
	s_nop 1
	v_cvt_pk_bf16_f32 v134, v188, v189
	v_cvt_pk_bf16_f32 v135, v190, v191
	v_cvt_pk_bf16_f32 v136, v184, v185
	v_cvt_pk_bf16_f32 v137, v186, v187
	global_store_dwordx4 v[182:183], v[134:137], off offset:256
	s_nop 1
	v_mov_b32_e32 v137, v177
	v_mov_b32_e32 v177, v167
	v_mov_b32_e32 v167, v180
	v_mov_b32_e32 v180, v139
	v_mov_b32_e32 v136, v197
	v_mov_b32_e32 v197, v176
	v_mov_b32_e32 v176, v141
	v_mov_b32_e32 v141, v166
	v_mov_b32_e32 v166, v138
	v_pk_mul_f32 v[138:139], v[180:181], v[180:181]
	v_mov_b32_e32 v134, v195
	v_pk_fma_f32 v[138:139], v[166:167], v[166:167], v[138:139]
	v_mov_b32_e32 v195, v178
	v_pk_fma_f32 v[138:139], v[140:141], v[140:141], v[138:139]
	v_mov_b32_e32 v135, v179
	v_pk_fma_f32 v[138:139], v[176:177], v[176:177], v[138:139]
	s_nop 0
	v_pk_fma_f32 v[138:139], v[196:197], v[196:197], v[138:139]
	v_add_u32_e32 v196, 0x90, v168
	v_pk_fma_f32 v[136:137], v[136:137], v[136:137], v[138:139]
	v_ashrrev_i32_e32 v197, 31, v196
	v_pk_fma_f32 v[136:137], v[194:195], v[194:195], v[136:137]
	s_nop 0
	v_pk_fma_f32 v[134:135], v[134:135], v[134:135], v[136:137]
	v_mov_b32_e32 v136, v172
	v_mov_b32_e32 v137, v188
	v_pk_fma_f32 v[134:135], v[136:137], v[136:137], v[134:135]
	v_mov_b32_e32 v188, v173
	v_pk_fma_f32 v[134:135], v[188:189], v[188:189], v[134:135]
	v_mov_b32_e32 v136, v174
	v_mov_b32_e32 v137, v190
	v_pk_fma_f32 v[134:135], v[136:137], v[136:137], v[134:135]
	v_mov_b32_e32 v190, v175
	v_pk_fma_f32 v[134:135], v[190:191], v[190:191], v[134:135]
	v_mov_b32_e32 v136, v142
	v_mov_b32_e32 v137, v184
	v_pk_fma_f32 v[134:135], v[136:137], v[136:137], v[134:135]
	v_mov_b32_e32 v184, v143
	v_pk_fma_f32 v[134:135], v[184:185], v[184:185], v[134:135]
	v_mov_b32_e32 v136, v144
	v_mov_b32_e32 v137, v186
	v_pk_fma_f32 v[134:135], v[136:137], v[136:137], v[134:135]
	v_mov_b32_e32 v186, v145
	v_pk_fma_f32 v[134:135], v[186:187], v[186:187], v[134:135]
	ds_bpermute_b32 v136, v202, v134
	ds_bpermute_b32 v137, v202, v135
	v_add_u32_e32 v184, 0x80, v168
	v_ashrrev_i32_e32 v185, 31, v184
	s_waitcnt lgkmcnt(0)
	v_pk_add_f32 v[134:135], v[134:135], v[136:137]
	ds_bpermute_b32 v136, v3, v134
	ds_bpermute_b32 v137, v3, v135
	s_waitcnt lgkmcnt(0)
	v_pk_add_f32 v[166:167], v[134:135], v[136:137]
	v_lshlrev_b64 v[134:135], 13, v[184:185]
	v_lshl_add_u64 v[134:135], s[72:73], 0, v[134:135]
	v_lshl_add_u64 v[134:135], v[134:135], 0, v[170:171]
	global_load_dwordx4 v[142:145], v[134:135], off offset:16 nt
	global_load_dwordx4 v[172:175], v[134:135], off nt
	global_load_dwordx4 v[188:191], v[134:135], off offset:528 nt
	global_load_dwordx4 v[180:183], v[134:135], off offset:512 nt
	v_lshlrev_b64 v[134:135], 13, v[196:197]
	v_lshl_add_u64 v[134:135], s[72:73], 0, v[134:135]
	v_lshl_add_u64 v[138:139], v[134:135], 0, v[170:171]
	global_load_dwordx4 v[192:195], v[138:139], off offset:16 nt
	global_load_dwordx4 v[204:207], v[138:139], off nt
	global_load_dwordx4 v[134:137], v[138:139], off offset:528 nt
	s_nop 0
	global_load_dwordx4 v[138:141], v[138:139], off offset:512 nt
	v_lshlrev_b64 v[184:185], 12, v[184:185]
	v_lshl_add_u64 v[184:185], s[16:17], 0, v[184:185]
	v_lshl_add_u64 v[208:209], v[184:185], 0, v[4:5]
	v_lshlrev_b64 v[196:197], 12, v[196:197]
	v_lshl_add_u64 v[196:197], s[16:17], 0, v[196:197]
	v_lshl_add_u64 v[196:197], v[196:197], 0, v[4:5]
	s_waitcnt vmcnt(7)
	v_pk_add_f32 v[176:177], v[62:63], v[142:143]
	s_waitcnt vmcnt(6)
	v_pk_add_f32 v[174:175], v[68:69], v[174:175]
	v_pk_add_f32 v[178:179], v[66:67], v[172:173]
	v_pk_add_f32 v[172:173], v[64:65], v[144:145]
	v_cvt_pk_bf16_f32 v142, v178, v179
	v_cvt_pk_bf16_f32 v143, v174, v175
	v_cvt_pk_bf16_f32 v144, v176, v177
	v_cvt_pk_bf16_f32 v145, v172, v173
	s_waitcnt vmcnt(4)
	v_pk_add_f32 v[184:185], v[36:37], v[182:183]
	v_pk_add_f32 v[186:187], v[34:35], v[180:181]
	v_pk_add_f32 v[180:181], v[32:33], v[190:191]
	v_pk_add_f32 v[182:183], v[30:31], v[188:189]
	global_store_dwordx4 v[208:209], v[142:145], off
	s_waitcnt vmcnt(3)
	v_pk_add_f32 v[190:191], v[60:61], v[206:207]
	v_pk_add_f32 v[188:189], v[58:59], v[204:205]
	v_cvt_pk_bf16_f32 v142, v186, v187
	v_cvt_pk_bf16_f32 v143, v184, v185
	v_cvt_pk_bf16_f32 v144, v182, v183
	v_cvt_pk_bf16_f32 v145, v180, v181
	v_pk_add_f32 v[194:195], v[56:57], v[194:195]
	v_pk_add_f32 v[192:193], v[54:55], v[192:193]
	global_store_dwordx4 v[208:209], v[142:145], off offset:256
	s_waitcnt vmcnt(2)
	v_pk_add_f32 v[140:141], v[28:29], v[140:141]
	v_pk_add_f32 v[138:139], v[26:27], v[138:139]
	v_cvt_pk_bf16_f32 v142, v188, v189
	v_cvt_pk_bf16_f32 v143, v190, v191
	v_cvt_pk_bf16_f32 v144, v192, v193
	v_cvt_pk_bf16_f32 v145, v194, v195
	global_store_dwordx4 v[196:197], v[142:145], off
	s_nop 1
	v_pk_add_f32 v[142:143], v[24:25], v[136:137]
	v_pk_add_f32 v[144:145], v[22:23], v[134:135]
	v_cvt_pk_bf16_f32 v134, v138, v139
	v_cvt_pk_bf16_f32 v135, v140, v141
	v_cvt_pk_bf16_f32 v136, v144, v145
	v_cvt_pk_bf16_f32 v137, v142, v143
	global_store_dwordx4 v[196:197], v[134:137], off offset:256
	s_nop 1
	v_mov_b32_e32 v137, v193
	v_mov_b32_e32 v193, v191
	v_mov_b32_e32 v191, v188
	v_mov_b32_e32 v188, v179
	v_mov_b32_e32 v136, v177
	v_mov_b32_e32 v177, v192
	v_mov_b32_e32 v192, v175
	v_mov_b32_e32 v175, v190
	v_mov_b32_e32 v190, v178
	v_pk_mul_f32 v[178:179], v[188:189], v[188:189]
	v_mov_b32_e32 v134, v173
	v_pk_fma_f32 v[178:179], v[190:191], v[190:191], v[178:179]
	v_mov_b32_e32 v173, v194
	v_pk_fma_f32 v[174:175], v[174:175], v[174:175], v[178:179]
	v_mov_b32_e32 v135, v195
	v_pk_fma_f32 v[174:175], v[192:193], v[192:193], v[174:175]
	v_add_u32_e32 v192, 0xb0, v168
	v_pk_fma_f32 v[174:175], v[176:177], v[176:177], v[174:175]
	v_ashrrev_i32_e32 v193, 31, v192
	v_pk_fma_f32 v[136:137], v[136:137], v[136:137], v[174:175]
	s_nop 0
	v_pk_fma_f32 v[136:137], v[172:173], v[172:173], v[136:137]
	s_nop 0
	v_pk_fma_f32 v[134:135], v[134:135], v[134:135], v[136:137]
	v_mov_b32_e32 v136, v186
	v_mov_b32_e32 v137, v138
	v_pk_fma_f32 v[134:135], v[136:137], v[136:137], v[134:135]
	v_mov_b32_e32 v138, v187
	v_pk_fma_f32 v[134:135], v[138:139], v[138:139], v[134:135]
	v_mov_b32_e32 v136, v184
	v_mov_b32_e32 v137, v140
	v_pk_fma_f32 v[134:135], v[136:137], v[136:137], v[134:135]
	v_mov_b32_e32 v140, v185
	v_pk_fma_f32 v[134:135], v[140:141], v[140:141], v[134:135]
	v_mov_b32_e32 v136, v182
	v_mov_b32_e32 v137, v144
	v_pk_fma_f32 v[134:135], v[136:137], v[136:137], v[134:135]
	v_mov_b32_e32 v144, v183
	v_pk_fma_f32 v[134:135], v[144:145], v[144:145], v[134:135]
	v_mov_b32_e32 v136, v180
	v_mov_b32_e32 v137, v142
	v_pk_fma_f32 v[134:135], v[136:137], v[136:137], v[134:135]
	v_mov_b32_e32 v142, v181
	v_pk_fma_f32 v[134:135], v[142:143], v[142:143], v[134:135]
	ds_bpermute_b32 v136, v202, v134
	ds_bpermute_b32 v137, v202, v135
	v_add_u32_e32 v144, 0xa0, v168
	v_ashrrev_i32_e32 v145, 31, v144
	s_waitcnt lgkmcnt(0)
	v_pk_add_f32 v[134:135], v[134:135], v[136:137]
	ds_bpermute_b32 v136, v3, v134
	ds_bpermute_b32 v137, v3, v135
	s_waitcnt lgkmcnt(0)
	v_pk_add_f32 v[142:143], v[134:135], v[136:137]
	v_lshlrev_b64 v[134:135], 13, v[144:145]
	v_lshl_add_u64 v[134:135], s[72:73], 0, v[134:135]
	v_lshl_add_u64 v[134:135], v[134:135], 0, v[170:171]
	global_load_dwordx4 v[172:175], v[134:135], off offset:16 nt
	global_load_dwordx4 v[176:179], v[134:135], off nt
	global_load_dwordx4 v[180:183], v[134:135], off offset:528 nt
	global_load_dwordx4 v[184:187], v[134:135], off offset:512 nt
	v_lshlrev_b64 v[134:135], 13, v[192:193]
	v_lshl_add_u64 v[134:135], s[72:73], 0, v[134:135]
	v_lshl_add_u64 v[138:139], v[134:135], 0, v[170:171]
	global_load_dwordx4 v[168:171], v[138:139], off offset:16 nt
	global_load_dwordx4 v[188:191], v[138:139], off nt
	global_load_dwordx4 v[134:137], v[138:139], off offset:528 nt
	s_nop 0
	global_load_dwordx4 v[138:141], v[138:139], off offset:512 nt
	v_lshlrev_b64 v[144:145], 12, v[144:145]
	v_lshl_add_u64 v[144:145], s[16:17], 0, v[144:145]
	v_lshl_add_u64 v[144:145], v[144:145], 0, v[4:5]
	s_waitcnt vmcnt(7)
	v_pk_add_f32 v[194:195], v[48:49], v[174:175]
	s_waitcnt vmcnt(6)
	v_pk_add_f32 v[178:179], v[52:53], v[178:179]
	v_pk_add_f32 v[176:177], v[50:51], v[176:177]
	v_pk_add_f32 v[196:197], v[46:47], v[172:173]
	v_cvt_pk_bf16_f32 v172, v176, v177
	v_cvt_pk_bf16_f32 v173, v178, v179
	v_cvt_pk_bf16_f32 v174, v196, v197
	v_cvt_pk_bf16_f32 v175, v194, v195
	s_waitcnt vmcnt(4)
	v_pk_add_f32 v[186:187], v[20:21], v[186:187]
	v_pk_add_f32 v[184:185], v[18:19], v[184:185]
	v_pk_add_f32 v[182:183], v[16:17], v[182:183]
	v_pk_add_f32 v[180:181], v[14:15], v[180:181]
	global_store_dwordx4 v[144:145], v[172:175], off
	s_waitcnt vmcnt(1)
	v_pk_add_f32 v[140:141], v[12:13], v[140:141]
	v_pk_add_f32 v[138:139], v[10:11], v[138:139]
	v_cvt_pk_bf16_f32 v172, v184, v185
	v_cvt_pk_bf16_f32 v173, v186, v187
	v_cvt_pk_bf16_f32 v174, v180, v181
	v_cvt_pk_bf16_f32 v175, v182, v183
	global_store_dwordx4 v[144:145], v[172:175], off offset:256
	v_pk_add_f32 v[144:145], v[44:45], v[190:191]
	v_lshlrev_b64 v[190:191], 12, v[192:193]
	v_pk_add_f32 v[172:173], v[42:43], v[188:189]
	v_pk_add_f32 v[174:175], v[40:41], v[170:171]
	v_pk_add_f32 v[188:189], v[38:39], v[168:169]
	v_lshl_add_u64 v[190:191], s[16:17], 0, v[190:191]
	v_cvt_pk_bf16_f32 v168, v172, v173
	v_cvt_pk_bf16_f32 v169, v144, v145
	v_cvt_pk_bf16_f32 v170, v188, v189
	v_cvt_pk_bf16_f32 v171, v174, v175
	v_lshl_add_u64 v[4:5], v[190:191], 0, v[4:5]
	global_store_dwordx4 v[4:5], v[168:171], off
	s_nop 1
	v_pk_add_f32 v[168:169], v[8:9], v[136:137]
	v_pk_add_f32 v[170:171], v[6:7], v[134:135]
	v_cvt_pk_bf16_f32 v134, v138, v139
	v_cvt_pk_bf16_f32 v135, v140, v141
	v_cvt_pk_bf16_f32 v136, v170, v171
	v_cvt_pk_bf16_f32 v137, v168, v169
	global_store_dwordx4 v[4:5], v[134:137], off offset:256
	v_mov_b32_e32 v4, v195
	v_mov_b32_e32 v195, v174
	v_mov_b32_e32 v137, v145
	v_mov_b32_e32 v145, v172
	v_mov_b32_e32 v172, v177
	v_mov_b32_e32 v136, v179
	v_mov_b32_e32 v179, v144
	v_mov_b32_e32 v144, v176
	v_pk_mul_f32 v[172:173], v[172:173], v[172:173]
	v_mov_b32_e32 v134, v197
	v_pk_fma_f32 v[144:145], v[144:145], v[144:145], v[172:173]
	v_mov_b32_e32 v197, v188
	v_pk_fma_f32 v[144:145], v[178:179], v[178:179], v[144:145]
	v_mov_b32_e32 v135, v189
	v_pk_fma_f32 v[136:137], v[136:137], v[136:137], v[144:145]
	v_mov_b32_e32 v5, v175
	v_pk_fma_f32 v[136:137], v[196:197], v[196:197], v[136:137]
	s_nop 0
	v_pk_fma_f32 v[134:135], v[134:135], v[134:135], v[136:137]
	s_nop 0
	v_pk_fma_f32 v[134:135], v[194:195], v[194:195], v[134:135]
	s_nop 0
	v_pk_fma_f32 v[4:5], v[4:5], v[4:5], v[134:135]
	v_mov_b32_e32 v134, v184
	v_mov_b32_e32 v135, v138
	v_pk_fma_f32 v[4:5], v[134:135], v[134:135], v[4:5]
	v_mov_b32_e32 v138, v185
	v_pk_fma_f32 v[4:5], v[138:139], v[138:139], v[4:5]
	v_mov_b32_e32 v134, v186
	v_mov_b32_e32 v135, v140
	v_pk_fma_f32 v[4:5], v[134:135], v[134:135], v[4:5]
	v_mov_b32_e32 v140, v187
	v_pk_fma_f32 v[4:5], v[140:141], v[140:141], v[4:5]
	v_mov_b32_e32 v134, v180
	v_mov_b32_e32 v135, v170
	v_pk_fma_f32 v[4:5], v[134:135], v[134:135], v[4:5]
	v_mov_b32_e32 v170, v181
	v_pk_fma_f32 v[4:5], v[170:171], v[170:171], v[4:5]
	v_mov_b32_e32 v134, v182
	v_mov_b32_e32 v135, v168
	v_pk_fma_f32 v[4:5], v[134:135], v[134:135], v[4:5]
	v_mov_b32_e32 v168, v183
	v_pk_fma_f32 v[4:5], v[168:169], v[168:169], v[4:5]
	ds_bpermute_b32 v134, v202, v4
	ds_bpermute_b32 v135, v202, v5
	s_waitcnt lgkmcnt(0)
	v_pk_add_f32 v[4:5], v[4:5], v[134:135]
	ds_bpermute_b32 v134, v3, v4
	ds_bpermute_b32 v135, v3, v5
	s_waitcnt lgkmcnt(0)
	v_pk_add_f32 v[134:135], v[4:5], v[134:135]
	s_cbranch_vccz .LBB0_880
	s_and_saveexec_b64 s[24:25], s[2:3]
	s_cbranch_execz .LBB0_863
	s_ashr_i32 s7, s6, 31
	v_lshl_add_u64 v[4:5], s[6:7], 2, v[154:155]
	global_atomic_add_f32 v[4:5], v164, off
	global_atomic_add_f32 v[4:5], v165, off offset:64
	global_atomic_add_f32 v[4:5], v166, off offset:128
	global_atomic_add_f32 v[4:5], v167, off offset:192
	global_atomic_add_f32 v[4:5], v142, off offset:512
	global_atomic_add_f32 v[4:5], v143, off offset:576
	global_atomic_add_f32 v[4:5], v134, off offset:640
	global_atomic_add_f32 v[4:5], v135, off offset:704
	s_branch .LBB0_863

.LBB0_956:
	s_ashr_i32 s43, s42, 31
	s_lshl_b64 s[8:9], s[42:43], 20
	s_add_u32 s46, s18, s8
	s_addc_u32 s47, s19, s9
	s_andn2_b64 vcc, exec, s[40:41]
	s_cbranch_vccnz .LBB0_962
	s_and_b64 s[6:7], s[6:7], exec
	s_cselect_b32 s14, s47, s27
	s_cselect_b32 s15, s46, s26
	s_lshl_b32 s6, s10, 8
	s_ashr_i32 s7, s6, 31
	s_add_u32 s33, s24, 0x100
	v_lshl_add_u64 v[4:5], s[6:7], 2, v[174:175]
	s_addc_u32 s43, s25, 0
	v_lshl_add_u64 v[136:137], s[26:27], 0, v[176:177]
	v_lshl_add_u64 v[138:139], s[26:27], 0, v[178:179]
	s_mov_b32 s12, 0
	s_mov_b64 s[6:7], 0
	v_add_u32_e32 v3, 0x10000, v230
	ds_read_b128 v[140:143], v3
	ds_read_b128 v[144:147], v3 offset:1024
	ds_read_b128 v[148:151], v3 offset:2048
	ds_read_b128 v[152:155], v3 offset:3072

.LBB0_960:
	s_or_b64 exec, exec, s[10:11]
	s_add_i32 s48, s12, 2
	s_add_u32 s10, s26, s6
	s_addc_u32 s11, s27, s7
	s_add_u32 s10, s10, 0x100
	s_addc_u32 s11, s11, 0
	s_add_u32 s70, s33, s6
	s_addc_u32 s13, s43, s7
	s_cmp_eq_u32 s64, s12
	s_cselect_b32 s11, s14, s11
	s_cselect_b32 s10, s15, s10
	s_cselect_b32 s13, s45, s13
	s_cselect_b32 s12, s44, s70
	v_lshl_add_u64 v[164:165], v[136:137], 0, s[6:7]
	s_add_i32 m0, s55, 0xc000
	ds_read_b128 v[156:159], v232
	ds_read_b128 v[160:163], v232 offset:1024
	ds_read_b128 v[184:187], v232 offset:2048
	ds_read_b128 v[188:191], v232 offset:3072
	ds_read_b128 v[198:201], v232 offset:4096
	ds_read_b128 v[202:205], v232 offset:5120
	ds_read_b128 v[206:209], v232 offset:6144
	ds_read_b128 v[210:213], v232 offset:7168
	global_load_lds_dwordx4 v[164:165], off
	v_lshl_add_u64 v[164:165], v[138:139], 0, s[6:7]
	s_add_i32 m0, s55, 0xe000
	s_nop 0
	global_load_lds_dwordx4 v[164:165], off
	s_waitcnt lgkmcnt(8)
	s_barrier
	s_waitcnt lgkmcnt(0)
	s_waitcnt lgkmcnt(0)
	v_mfma_f32_16x16x32_bf16 v[130:133], v[140:143], v[156:159], v[130:133]
	v_mfma_f32_16x16x32_bf16 v[126:129], v[148:151], v[156:159], v[126:129]
	v_mfma_f32_16x16x32_bf16 v[122:125], v[140:143], v[184:187], v[122:125]
	v_mfma_f32_16x16x32_bf16 v[118:121], v[148:151], v[184:187], v[118:121]
	v_mfma_f32_16x16x32_bf16 v[114:117], v[140:143], v[198:201], v[114:117]
	v_mfma_f32_16x16x32_bf16 v[110:113], v[148:151], v[198:201], v[110:113]
	v_mfma_f32_16x16x32_bf16 v[106:109], v[140:143], v[206:209], v[106:109]
	v_mfma_f32_16x16x32_bf16 v[102:105], v[148:151], v[206:209], v[102:105]
	v_mfma_f32_16x16x32_bf16 v[130:133], v[144:147], v[160:163], v[130:133]
	v_mfma_f32_16x16x32_bf16 v[126:129], v[152:155], v[160:163], v[126:129]
	v_mfma_f32_16x16x32_bf16 v[122:125], v[144:147], v[188:191], v[122:125]
	v_mfma_f32_16x16x32_bf16 v[118:121], v[152:155], v[188:191], v[118:121]
	v_mfma_f32_16x16x32_bf16 v[114:117], v[144:147], v[202:205], v[114:117]
	v_mfma_f32_16x16x32_bf16 v[110:113], v[152:155], v[202:205], v[110:113]
	v_mfma_f32_16x16x32_bf16 v[106:109], v[144:147], v[210:213], v[106:109]
	v_mfma_f32_16x16x32_bf16 v[102:105], v[152:155], v[210:213], v[102:105]
	s_barrier
	s_add_i32 s70, s65, s54
	v_add_u32_e32 v3, s66, v230
	v_lshl_add_u64 v[164:165], s[12:13], 0, v[168:169]
	s_mov_b32 m0, s70
	ds_read_b128 v[214:217], v3
	ds_read_b128 v[218:221], v3 offset:1024
	ds_read_b128 v[222:225], v3 offset:2048
	ds_read_b128 v[226:229], v3 offset:3072
	global_load_lds_dwordx4 v[164:165], off
	v_lshl_add_u64 v[236:237], s[12:13], 0, v[172:173]
	s_add_i32 m0, s70, 0x2000
	s_nop 0
	global_load_lds_dwordx4 v[236:237], off
	s_barrier
	s_waitcnt lgkmcnt(0)
	s_waitcnt lgkmcnt(0)
	v_mfma_f32_16x16x32_bf16 v[98:101], v[214:217], v[156:159], v[98:101]
	v_mfma_f32_16x16x32_bf16 v[94:97], v[222:225], v[156:159], v[94:97]
	v_mfma_f32_16x16x32_bf16 v[90:93], v[214:217], v[184:187], v[90:93]
	v_mfma_f32_16x16x32_bf16 v[86:89], v[222:225], v[184:187], v[86:89]
	v_mfma_f32_16x16x32_bf16 v[82:85], v[214:217], v[198:201], v[82:85]
	v_mfma_f32_16x16x32_bf16 v[78:81], v[222:225], v[198:201], v[78:81]
	v_mfma_f32_16x16x32_bf16 v[74:77], v[214:217], v[206:209], v[74:77]
	v_mfma_f32_16x16x32_bf16 v[70:73], v[222:225], v[206:209], v[70:73]
	v_mfma_f32_16x16x32_bf16 v[98:101], v[218:221], v[160:163], v[98:101]
	v_mfma_f32_16x16x32_bf16 v[94:97], v[226:229], v[160:163], v[94:97]
	v_mfma_f32_16x16x32_bf16 v[90:93], v[218:221], v[188:191], v[90:93]
	v_mfma_f32_16x16x32_bf16 v[86:89], v[226:229], v[188:191], v[86:89]
	v_mfma_f32_16x16x32_bf16 v[82:85], v[218:221], v[202:205], v[82:85]
	v_mfma_f32_16x16x32_bf16 v[78:81], v[226:229], v[202:205], v[78:81]
	v_mfma_f32_16x16x32_bf16 v[74:77], v[218:221], v[210:213], v[74:77]
	v_mfma_f32_16x16x32_bf16 v[70:73], v[226:229], v[210:213], v[70:73]
	s_mov_b32 m0, s55
	v_lshl_add_u64 v[238:239], s[10:11], 0, v[166:167]
	s_barrier
	ds_read_b128 v[156:159], v232 offset:16384
	ds_read_b128 v[160:163], v232 offset:17408
	ds_read_b128 v[184:187], v232 offset:18432
	ds_read_b128 v[188:191], v232 offset:19456
	ds_read_b128 v[198:201], v232 offset:20480
	ds_read_b128 v[202:205], v232 offset:21504
	ds_read_b128 v[206:209], v232 offset:22528
	ds_read_b128 v[210:213], v232 offset:23552
	global_load_lds_dwordx4 v[238:239], off
	v_lshl_add_u64 v[240:241], s[10:11], 0, v[170:171]
	s_mov_b32 m0, s56
	s_nop 0
	global_load_lds_dwordx4 v[240:241], off
	s_waitcnt vmcnt(10)
	s_barrier
	s_waitcnt lgkmcnt(0)
	s_waitcnt lgkmcnt(0)
	v_mfma_f32_16x16x32_bf16 v[66:69], v[140:143], v[156:159], v[66:69]
	v_mfma_f32_16x16x32_bf16 v[62:65], v[148:151], v[156:159], v[62:65]
	v_mfma_f32_16x16x32_bf16 v[58:61], v[140:143], v[184:187], v[58:61]
	v_mfma_f32_16x16x32_bf16 v[54:57], v[148:151], v[184:187], v[54:57]
	v_mfma_f32_16x16x32_bf16 v[50:53], v[140:143], v[198:201], v[50:53]
	v_mfma_f32_16x16x32_bf16 v[46:49], v[148:151], v[198:201], v[46:49]
	v_mfma_f32_16x16x32_bf16 v[42:45], v[140:143], v[206:209], v[42:45]
	v_mfma_f32_16x16x32_bf16 v[38:41], v[148:151], v[206:209], v[38:41]
	v_mfma_f32_16x16x32_bf16 v[66:69], v[144:147], v[160:163], v[66:69]
	v_mfma_f32_16x16x32_bf16 v[62:65], v[152:155], v[160:163], v[62:65]
	v_mfma_f32_16x16x32_bf16 v[58:61], v[144:147], v[188:191], v[58:61]
	v_mfma_f32_16x16x32_bf16 v[54:57], v[152:155], v[188:191], v[54:57]
	v_mfma_f32_16x16x32_bf16 v[50:53], v[144:147], v[202:205], v[50:53]
	v_mfma_f32_16x16x32_bf16 v[46:49], v[152:155], v[202:205], v[46:49]
	v_mfma_f32_16x16x32_bf16 v[42:45], v[144:147], v[210:213], v[42:45]
	v_mfma_f32_16x16x32_bf16 v[38:41], v[152:155], v[210:213], v[38:41]
	s_barrier
	v_add_u32_e32 v3, 0x18000, v230
	ds_read_b128 v[140:143], v3
	ds_read_b128 v[144:147], v3 offset:1024
	ds_read_b128 v[148:151], v3 offset:2048
	ds_read_b128 v[152:155], v3 offset:3072
	s_add_u32 s12, s12, s20
	s_addc_u32 s13, s13, s21
	s_add_i32 s70, s66, s54
	v_lshl_add_u64 v[242:243], s[12:13], 0, v[168:169]
	s_mov_b32 m0, s70
	v_lshl_add_u64 v[244:245], s[12:13], 0, v[172:173]
	global_load_lds_dwordx4 v[242:243], off
	s_add_i32 m0, s70, 0x2000
	s_nop 0
	global_load_lds_dwordx4 v[244:245], off
	s_waitcnt vmcnt(6)
	s_barrier
	v_mfma_f32_16x16x32_bf16 v[34:37], v[214:217], v[156:159], v[34:37]
	v_mfma_f32_16x16x32_bf16 v[30:33], v[222:225], v[156:159], v[30:33]
	v_mfma_f32_16x16x32_bf16 v[26:29], v[214:217], v[184:187], v[26:29]
	v_mfma_f32_16x16x32_bf16 v[22:25], v[222:225], v[184:187], v[22:25]
	v_mfma_f32_16x16x32_bf16 v[18:21], v[214:217], v[198:201], v[18:21]
	v_mfma_f32_16x16x32_bf16 v[14:17], v[222:225], v[198:201], v[14:17]
	v_mfma_f32_16x16x32_bf16 v[10:13], v[214:217], v[206:209], v[10:13]
	v_mfma_f32_16x16x32_bf16 v[6:9], v[222:225], v[206:209], v[6:9]
	v_mfma_f32_16x16x32_bf16 v[34:37], v[218:221], v[160:163], v[34:37]
	v_mfma_f32_16x16x32_bf16 v[30:33], v[226:229], v[160:163], v[30:33]
	v_mfma_f32_16x16x32_bf16 v[26:29], v[218:221], v[188:191], v[26:29]
	v_mfma_f32_16x16x32_bf16 v[22:25], v[226:229], v[188:191], v[22:25]
	v_mfma_f32_16x16x32_bf16 v[18:21], v[218:221], v[202:205], v[18:21]
	v_mfma_f32_16x16x32_bf16 v[14:17], v[226:229], v[202:205], v[14:17]
	v_mfma_f32_16x16x32_bf16 v[10:13], v[218:221], v[210:213], v[10:13]
	v_mfma_f32_16x16x32_bf16 v[6:9], v[226:229], v[210:213], v[6:9]
	s_add_i32 s12, 0, 0x18000
	s_barrier
	s_add_u32 s10, s10, 0x80000
	s_addc_u32 s11, s11, 0
	s_mov_b32 m0, s57
	v_lshl_add_u64 v[214:215], s[10:11], 0, v[166:167]
	ds_read_b128 v[156:159], v232 offset:32768
	ds_read_b128 v[160:163], v232 offset:33792
	ds_read_b128 v[184:187], v232 offset:34816
	ds_read_b128 v[188:191], v232 offset:35840
	ds_read_b128 v[198:201], v232 offset:36864
	ds_read_b128 v[202:205], v232 offset:37888
	ds_read_b128 v[206:209], v232 offset:38912
	ds_read_b128 v[210:213], v232 offset:39936
	global_load_lds_dwordx4 v[214:215], off
	v_lshl_add_u64 v[214:215], s[10:11], 0, v[170:171]
	s_mov_b32 m0, s58
	s_nop 0
	global_load_lds_dwordx4 v[214:215], off
	s_waitcnt lgkmcnt(8)
	s_barrier
	s_waitcnt lgkmcnt(0)
	s_waitcnt lgkmcnt(0)
	v_mfma_f32_16x16x32_bf16 v[130:133], v[140:143], v[156:159], v[130:133]
	v_mfma_f32_16x16x32_bf16 v[126:129], v[148:151], v[156:159], v[126:129]
	v_mfma_f32_16x16x32_bf16 v[122:125], v[140:143], v[184:187], v[122:125]
	v_mfma_f32_16x16x32_bf16 v[118:121], v[148:151], v[184:187], v[118:121]
	v_mfma_f32_16x16x32_bf16 v[114:117], v[140:143], v[198:201], v[114:117]
	v_mfma_f32_16x16x32_bf16 v[110:113], v[148:151], v[198:201], v[110:113]
	v_mfma_f32_16x16x32_bf16 v[106:109], v[140:143], v[206:209], v[106:109]
	v_mfma_f32_16x16x32_bf16 v[102:105], v[148:151], v[206:209], v[102:105]
	v_mfma_f32_16x16x32_bf16 v[130:133], v[144:147], v[160:163], v[130:133]
	v_mfma_f32_16x16x32_bf16 v[126:129], v[152:155], v[160:163], v[126:129]
	v_mfma_f32_16x16x32_bf16 v[122:125], v[144:147], v[188:191], v[122:125]
	v_mfma_f32_16x16x32_bf16 v[118:121], v[152:155], v[188:191], v[118:121]
	v_mfma_f32_16x16x32_bf16 v[114:117], v[144:147], v[202:205], v[114:117]
	v_mfma_f32_16x16x32_bf16 v[110:113], v[152:155], v[202:205], v[110:113]
	v_mfma_f32_16x16x32_bf16 v[106:109], v[144:147], v[210:213], v[106:109]
	v_mfma_f32_16x16x32_bf16 v[102:105], v[152:155], v[210:213], v[102:105]
	s_barrier
	s_add_i32 s10, 0, 0x1c000
	s_add_i32 s11, s12, s54
	v_add_u32_e32 v3, s10, v230
	v_lshl_add_u64 v[164:165], v[164:165], 0, s[38:39]
	s_mov_b32 m0, s11
	ds_read_b128 v[214:217], v3
	ds_read_b128 v[218:221], v3 offset:1024
	ds_read_b128 v[222:225], v3 offset:2048
	ds_read_b128 v[226:229], v3 offset:3072
	global_load_lds_dwordx4 v[164:165], off
	v_lshl_add_u64 v[164:165], v[236:237], 0, s[38:39]
	s_add_i32 m0, s11, 0x2000
	s_nop 0
	global_load_lds_dwordx4 v[164:165], off
	s_barrier
	s_waitcnt lgkmcnt(0)
	s_waitcnt lgkmcnt(0)
	v_mfma_f32_16x16x32_bf16 v[98:101], v[214:217], v[156:159], v[98:101]
	v_mfma_f32_16x16x32_bf16 v[94:97], v[222:225], v[156:159], v[94:97]
	v_mfma_f32_16x16x32_bf16 v[90:93], v[214:217], v[184:187], v[90:93]
	v_mfma_f32_16x16x32_bf16 v[86:89], v[222:225], v[184:187], v[86:89]
	v_mfma_f32_16x16x32_bf16 v[82:85], v[214:217], v[198:201], v[82:85]
	v_mfma_f32_16x16x32_bf16 v[78:81], v[222:225], v[198:201], v[78:81]
	v_mfma_f32_16x16x32_bf16 v[74:77], v[214:217], v[206:209], v[74:77]
	v_mfma_f32_16x16x32_bf16 v[70:73], v[222:225], v[206:209], v[70:73]
	v_mfma_f32_16x16x32_bf16 v[98:101], v[218:221], v[160:163], v[98:101]
	v_mfma_f32_16x16x32_bf16 v[94:97], v[226:229], v[160:163], v[94:97]
	v_mfma_f32_16x16x32_bf16 v[90:93], v[218:221], v[188:191], v[90:93]
	v_mfma_f32_16x16x32_bf16 v[86:89], v[226:229], v[188:191], v[86:89]
	v_mfma_f32_16x16x32_bf16 v[82:85], v[218:221], v[202:205], v[82:85]
	v_mfma_f32_16x16x32_bf16 v[78:81], v[226:229], v[202:205], v[78:81]
	v_mfma_f32_16x16x32_bf16 v[74:77], v[218:221], v[210:213], v[74:77]
	v_mfma_f32_16x16x32_bf16 v[70:73], v[226:229], v[210:213], v[70:73]
	s_mov_b32 m0, s62
	v_lshl_add_u64 v[164:165], v[238:239], 0, s[38:39]
	s_barrier
	ds_read_b128 v[156:159], v232 offset:49152
	ds_read_b128 v[160:163], v232 offset:50176
	ds_read_b128 v[184:187], v232 offset:51200
	ds_read_b128 v[188:191], v232 offset:52224
	ds_read_b128 v[198:201], v232 offset:53248
	ds_read_b128 v[202:205], v232 offset:54272
	ds_read_b128 v[206:209], v232 offset:55296
	ds_read_b128 v[210:213], v232 offset:56320
	global_load_lds_dwordx4 v[164:165], off
	v_lshl_add_u64 v[164:165], v[240:241], 0, s[38:39]
	s_mov_b32 m0, s63
	s_nop 0
	global_load_lds_dwordx4 v[164:165], off
	s_waitcnt vmcnt(10)
	s_barrier
	s_waitcnt lgkmcnt(0)
	s_waitcnt lgkmcnt(0)
	v_mfma_f32_16x16x32_bf16 v[66:69], v[140:143], v[156:159], v[66:69]
	v_mfma_f32_16x16x32_bf16 v[62:65], v[148:151], v[156:159], v[62:65]
	v_mfma_f32_16x16x32_bf16 v[58:61], v[140:143], v[184:187], v[58:61]
	v_mfma_f32_16x16x32_bf16 v[54:57], v[148:151], v[184:187], v[54:57]
	v_mfma_f32_16x16x32_bf16 v[50:53], v[140:143], v[198:201], v[50:53]
	v_mfma_f32_16x16x32_bf16 v[46:49], v[148:151], v[198:201], v[46:49]
	v_mfma_f32_16x16x32_bf16 v[42:45], v[140:143], v[206:209], v[42:45]
	v_mfma_f32_16x16x32_bf16 v[38:41], v[148:151], v[206:209], v[38:41]
	v_mfma_f32_16x16x32_bf16 v[66:69], v[144:147], v[160:163], v[66:69]
	v_mfma_f32_16x16x32_bf16 v[62:65], v[152:155], v[160:163], v[62:65]
	v_mfma_f32_16x16x32_bf16 v[58:61], v[144:147], v[188:191], v[58:61]
	v_mfma_f32_16x16x32_bf16 v[54:57], v[152:155], v[188:191], v[54:57]
	v_mfma_f32_16x16x32_bf16 v[50:53], v[144:147], v[202:205], v[50:53]
	v_mfma_f32_16x16x32_bf16 v[46:49], v[152:155], v[202:205], v[46:49]
	v_mfma_f32_16x16x32_bf16 v[42:45], v[144:147], v[210:213], v[42:45]
	v_mfma_f32_16x16x32_bf16 v[38:41], v[152:155], v[210:213], v[38:41]
	s_barrier
	v_add_u32_e32 v3, 0x10000, v230
	ds_read_b128 v[140:143], v3
	ds_read_b128 v[144:147], v3 offset:1024
	ds_read_b128 v[148:151], v3 offset:2048
	ds_read_b128 v[152:155], v3 offset:3072
	s_add_i32 s10, s10, s54
	v_lshl_add_u64 v[242:243], v[242:243], 0, s[38:39]
	s_mov_b32 m0, s10
	s_nop 0
	global_load_lds_dwordx4 v[242:243], off
	v_lshl_add_u64 v[244:245], v[244:245], 0, s[38:39]
	s_add_i32 m0, s10, 0x2000
	s_nop 0
	global_load_lds_dwordx4 v[244:245], off
	s_waitcnt vmcnt(6)
	s_barrier
	v_mfma_f32_16x16x32_bf16 v[34:37], v[214:217], v[156:159], v[34:37]
	v_mfma_f32_16x16x32_bf16 v[30:33], v[222:225], v[156:159], v[30:33]
	v_mfma_f32_16x16x32_bf16 v[26:29], v[214:217], v[184:187], v[26:29]
	v_mfma_f32_16x16x32_bf16 v[22:25], v[222:225], v[184:187], v[22:25]
	v_mfma_f32_16x16x32_bf16 v[18:21], v[214:217], v[198:201], v[18:21]
	v_mfma_f32_16x16x32_bf16 v[14:17], v[222:225], v[198:201], v[14:17]
	v_mfma_f32_16x16x32_bf16 v[10:13], v[214:217], v[206:209], v[10:13]
	v_mfma_f32_16x16x32_bf16 v[6:9], v[222:225], v[206:209], v[6:9]
	v_mfma_f32_16x16x32_bf16 v[34:37], v[218:221], v[160:163], v[34:37]
	v_mfma_f32_16x16x32_bf16 v[30:33], v[226:229], v[160:163], v[30:33]
	v_mfma_f32_16x16x32_bf16 v[26:29], v[218:221], v[188:191], v[26:29]
	v_mfma_f32_16x16x32_bf16 v[22:25], v[226:229], v[188:191], v[22:25]
	v_mfma_f32_16x16x32_bf16 v[18:21], v[218:221], v[202:205], v[18:21]
	v_mfma_f32_16x16x32_bf16 v[14:17], v[226:229], v[202:205], v[14:17]
	v_mfma_f32_16x16x32_bf16 v[10:13], v[218:221], v[210:213], v[10:13]
	v_mfma_f32_16x16x32_bf16 v[6:9], v[226:229], v[210:213], v[6:9]
	s_add_u32 s6, s6, 0x100
	s_addc_u32 s7, s7, 0
	s_andn2_b64 s[0:1], s[0:1], exec
	s_and_b64 s[10:11], s[8:9], exec
	s_or_b64 s[0:1], s[0:1], s[10:11]
	s_cmp_ge_i32 s48, s59
	s_barrier
	s_cbranch_scc1 .LBB0_962
	s_mov_b32 s12, s48
	s_branch .LBB0_958
.LBB0_962:
	s_waitcnt lgkmcnt(0)
	s_lshl_b32 s48, s68, 8
	v_add_u32_e32 v184, s48, v1
	v_ashrrev_i32_e32 v185, 31, v184
	v_lshlrev_b64 v[4:5], 2, v[184:185]
	v_lshl_add_u64 v[150:151], s[30:31], 0, v[4:5]
	v_or_b32_e32 v208, 16, v184
	v_lshl_add_u64 v[152:153], s[28:29], 0, v[4:5]
	global_load_dword v3, v[150:151], off
	global_load_dword v154, v[152:153], off
	v_ashrrev_i32_e32 v209, 31, v208
	v_or_b32_e32 v204, 32, v184
	v_or_b32_e32 v200, 48, v184
	v_lshlrev_b64 v[4:5], 2, v[208:209]
	v_ashrrev_i32_e32 v205, 31, v204
	v_ashrrev_i32_e32 v201, 31, v200
	v_lshl_add_u64 v[134:135], s[30:31], 0, v[4:5]
	v_lshlrev_b64 v[136:137], 2, v[204:205]
	v_lshlrev_b64 v[140:141], 2, v[200:201]
	v_lshl_add_u64 v[4:5], s[28:29], 0, v[4:5]
	v_lshl_add_u64 v[138:139], s[30:31], 0, v[136:137]
	v_lshl_add_u64 v[136:137], s[28:29], 0, v[136:137]
	v_lshl_add_u64 v[142:143], s[30:31], 0, v[140:141]
	global_load_dword v155, v[134:135], off
	global_load_dword v156, v[4:5], off
	global_load_dword v157, v[138:139], off
	global_load_dword v158, v[136:137], off
	global_load_dword v159, v[142:143], off
	v_lshl_add_u64 v[4:5], s[28:29], 0, v[140:141]
	global_load_dword v160, v[4:5], off
	global_load_dword v161, v[150:151], off offset:512
	v_lshl_or_b32 v188, s61, 8, v231
	v_readlane_b32 s8, v255, 0
	v_ashrrev_i32_e32 v189, 31, v188
	v_readlane_b32 s10, v255, 2
	v_readlane_b32 s11, v255, 3
	v_readlane_b32 s14, v255, 6
	v_readlane_b32 s15, v255, 7
	v_lshl_add_u64 v[138:139], v[188:189], 2, s[10:11]
	global_load_dword v162, v[152:153], off offset:512
	global_load_dwordx4 v[142:145], v[138:139], off offset:16
	global_load_dwordx4 v[146:149], v[138:139], off
	global_load_dwordx4 v[134:137], v[138:139], off offset:528
	s_nop 0
	global_load_dwordx4 v[138:141], v[138:139], off offset:512
	s_nop 0
	global_load_dword v163, v[150:151], off offset:576
	global_load_dword v164, v[152:153], off offset:576
	global_load_dword v165, v[150:151], off offset:640
	global_load_dword v190, v[150:151], off offset:704
	global_load_dword v191, v[152:153], off offset:640
	global_load_dword v212, v[152:153], off offset:704
	v_readlane_b32 s9, v255, 1
	v_readlane_b32 s12, v255, 4
	v_readlane_b32 s13, v255, 5
	v_add_u32_e32 v196, 0x80, v184
	v_add_u32_e32 v192, 0x90, v184
	v_add_u32_e32 v186, 0xa0, v184
	v_add_u32_e32 v4, 0xb0, v184
	v_ashrrev_i32_e32 v197, 31, v196
	v_ashrrev_i32_e32 v193, 31, v192
	v_ashrrev_i32_e32 v187, 31, v186
	v_ashrrev_i32_e32 v5, 31, v4
	s_waitcnt vmcnt(0)
	v_fmamk_f32 v3, v3, 0x3a000000, v233
	v_fmamk_f32 v150, v154, 0x3a000000, v233
	v_mul_f32_e32 v152, 0x4b800000, v150
	v_cmp_gt_f32_e64 s[6:7], s67, v150
	v_mul_f32_e32 v151, 0x4b800000, v3
	v_cmp_gt_f32_e64 s[0:1], s67, v3
	v_cndmask_b32_e64 v150, v150, v152, s[6:7]
	v_rsq_f32_e32 v150, v150
	v_cndmask_b32_e64 v3, v3, v151, s[0:1]
	v_rsq_f32_e32 v3, v3
	v_fmamk_f32 v153, v155, 0x3a000000, v233
	v_fmamk_f32 v154, v156, 0x3a000000, v233
	v_mul_f32_e32 v152, 0x4b800000, v154
	v_fmamk_f32 v156, v158, 0x3a000000, v233
	v_cmp_gt_f32_e64 s[10:11], s67, v154
	v_fmamk_f32 v155, v157, 0x3a000000, v233
	v_fmamk_f32 v157, v159, 0x3a000000, v233
	v_mul_f32_e32 v159, 0x4b800000, v156
	v_cndmask_b32_e64 v152, v154, v152, s[10:11]
	v_cmp_gt_f32_e64 s[14:15], s67, v156
	v_mul_f32_e32 v151, 0x4b800000, v153
	v_cmp_gt_f32_e64 s[8:9], s67, v153
	v_cndmask_b32_e64 v154, v156, v159, s[14:15]
	v_rsq_f32_e32 v152, v152
	v_cndmask_b32_e64 v151, v153, v151, s[8:9]
	v_rsq_f32_e32 v154, v154
	v_mul_f32_e32 v158, 0x4b800000, v155
	v_mul_f32_e32 v194, 0x4b800000, v157
	v_cmp_gt_f32_e64 s[12:13], s67, v155
	v_cmp_gt_f32_e32 vcc, s67, v157
	v_rsq_f32_e32 v151, v151
	v_cndmask_b32_e64 v153, v155, v158, s[12:13]
	v_cndmask_b32_e32 v155, v157, v194, vcc
	v_mul_f32_e32 v157, 0x45800000, v150
	v_cndmask_b32_e64 v224, v150, v157, s[6:7]
	v_mul_f32_e32 v150, 0x45800000, v152
	v_mul_f32_e32 v156, 0x45800000, v3
	v_cndmask_b32_e64 v210, v152, v150, s[10:11]
	v_mul_f32_e32 v150, 0x45800000, v154
	v_cndmask_b32_e64 v225, v3, v156, s[0:1]
	v_mul_f32_e32 v3, 0x45800000, v151
	v_cndmask_b32_e64 v206, v154, v150, s[14:15]
	v_fmamk_f32 v150, v160, 0x3a000000, v233
	v_rsq_f32_e32 v153, v153
	v_cndmask_b32_e64 v211, v151, v3, s[8:9]
	v_mul_f32_e32 v151, 0x4b800000, v150
	v_cmp_gt_f32_e64 s[0:1], s67, v150
	v_rsq_f32_e32 v3, v155
	v_mul_f32_e32 v156, 0x45800000, v153
	v_cndmask_b32_e64 v150, v150, v151, s[0:1]
	v_rsq_f32_e32 v157, v150
	v_lshlrev_b64 v[150:151], 11, v[184:185]
	v_lshl_add_u64 v[150:151], v[150:151], 0, v[188:189]
	v_lshlrev_b64 v[150:151], 1, v[150:151]
	v_cndmask_b32_e64 v207, v153, v156, s[12:13]
	v_lshl_add_u64 v[152:153], s[18:19], 0, v[150:151]
	v_fmamk_f32 v158, v161, 0x3a000000, v233
	v_lshl_add_u64 v[154:155], s[36:37], 0, v[150:151]
	global_load_dwordx4 v[216:219], v[152:153], off
	global_load_dwordx4 v[220:223], v[154:155], off nt
	v_mul_f32_e32 v156, 0x45800000, v3
	v_mul_f32_e32 v159, 0x4b800000, v158
	v_cmp_gt_f32_e64 s[6:7], s67, v158
	v_fmamk_f32 v153, v162, 0x3a000000, v233
	v_cndmask_b32_e32 v203, v3, v156, vcc
	v_cndmask_b32_e64 v152, v158, v159, s[6:7]
	v_mul_f32_e32 v154, 0x4b800000, v153
	v_cmp_gt_f32_e32 vcc, s67, v153
	v_rsq_f32_e32 v152, v152
	v_mul_f32_e32 v3, 0x45800000, v157
	v_cndmask_b32_e32 v153, v153, v154, vcc
	v_rsq_f32_e32 v153, v153
	v_cndmask_b32_e64 v202, v157, v3, s[0:1]
	v_mul_f32_e32 v3, 0x45800000, v152
	v_fmamk_f32 v154, v163, 0x3a000000, v233
	v_mul_f32_e32 v155, 0x4b800000, v154
	v_cmp_gt_f32_e64 s[0:1], s67, v154
	v_cndmask_b32_e64 v199, v152, v3, s[6:7]
	v_mul_f32_e32 v3, 0x45800000, v153
	v_fmamk_f32 v152, v164, 0x3a000000, v233
	v_cndmask_b32_e64 v154, v154, v155, s[0:1]
	v_cndmask_b32_e32 v198, v153, v3, vcc
	v_mul_f32_e32 v153, 0x4b800000, v152
	v_cmp_gt_f32_e32 vcc, s67, v152
	v_rsq_f32_e32 v154, v154
	v_or_b32_e32 v150, 0x100, v150
	v_cndmask_b32_e32 v152, v152, v153, vcc
	v_rsq_f32_e32 v152, v152
	v_mul_f32_e32 v3, 0x45800000, v154
	v_fmamk_f32 v153, v165, 0x3a000000, v233
	v_cndmask_b32_e64 v195, v154, v3, s[0:1]
	v_mul_f32_e32 v3, 0x45800000, v152
	v_mul_f32_e32 v155, 0x4b800000, v153
	v_cmp_gt_f32_e64 s[6:7], s67, v153
	v_cndmask_b32_e32 v194, v152, v3, vcc
	v_fmamk_f32 v152, v191, 0x3a000000, v233
	v_cndmask_b32_e64 v153, v153, v155, s[6:7]
	v_mul_f32_e32 v154, 0x4b800000, v152
	v_cmp_gt_f32_e32 vcc, s67, v152
	v_rsq_f32_e32 v153, v153
	v_fmamk_f32 v235, v212, 0x3a000000, v233
	v_cndmask_b32_e32 v152, v152, v154, vcc
	v_rsq_f32_e32 v152, v152
	v_mul_f32_e32 v3, 0x45800000, v153
	v_cndmask_b32_e64 v191, v153, v3, s[6:7]
	v_fmamk_f32 v154, v190, 0x3a000000, v233
	v_mul_f32_e32 v3, 0x45800000, v152
	v_cndmask_b32_e32 v190, v152, v3, vcc
	v_lshl_add_u64 v[152:153], s[18:19], 0, v[150:151]
	v_lshl_add_u64 v[150:151], s[36:37], 0, v[150:151]
	global_load_dwordx4 v[226:229], v[152:153], off
	global_load_dwordx4 v[236:239], v[150:151], off nt
	v_mul_f32_e32 v155, 0x4b800000, v154
	v_cmp_gt_f32_e64 s[0:1], s67, v154
	v_lshlrev_b64 v[150:151], 11, v[208:209]
	v_lshl_add_u64 v[150:151], v[150:151], 0, v[188:189]
	v_cndmask_b32_e64 v154, v154, v155, s[0:1]
	v_rsq_f32_e32 v154, v154
	v_lshlrev_b64 v[150:151], 1, v[150:151]
	v_lshl_add_u64 v[152:153], s[18:19], 0, v[150:151]
	v_mul_f32_e32 v242, v98, v225
	v_mul_f32_e32 v3, 0x45800000, v154
	v_cndmask_b32_e64 v3, v154, v3, s[0:1]
	v_lshl_add_u64 v[154:155], s[36:37], 0, v[150:151]
	global_load_dwordx4 v[162:165], v[152:153], off
	global_load_dwordx4 v[158:161], v[154:155], off nt
	v_mul_f32_e32 v154, v130, v225
	v_mul_f32_e32 v154, 0xbfb8aa3b, v154
	v_exp_f32_e32 v212, v154
	v_mul_f32_e32 v154, v131, v225
	v_mul_f32_e32 v154, 0xbfb8aa3b, v154
	v_or_b32_e32 v150, 0x100, v150
	v_exp_f32_e32 v213, v154
	v_lshl_add_u64 v[152:153], s[18:19], 0, v[150:151]
	v_lshl_add_u64 v[150:151], s[36:37], 0, v[150:151]
	global_load_dwordx4 v[154:157], v[152:153], off
	s_nop 0
	global_load_dwordx4 v[150:153], v[150:151], off nt
	v_add_f32_e32 v212, 1.0, v212
	v_add_f32_e32 v213, 1.0, v213
	v_rcp_f32_e32 v212, v212
	v_rcp_f32_e32 v213, v213
	s_waitcnt vmcnt(0)
	v_lshlrev_b32_e32 v214, 16, v216
	v_and_b32_e32 v215, 0xffff0000, v216
	v_lshlrev_b32_e32 v240, 16, v220
	v_and_b32_e32 v241, 0xffff0000, v220
	v_mul_f32_e32 v216, v132, v225
	v_mul_f32_e32 v220, v133, v225
	v_mul_f32_e32 v216, 0xbfb8aa3b, v216
	v_mul_f32_e32 v220, 0xbfb8aa3b, v220
	v_exp_f32_e32 v216, v216
	v_exp_f32_e32 v220, v220
	v_pk_mul_f32 v[240:241], v[224:225], v[240:241] op_sel_hi:[0,1]
	v_pk_mul_f32 v[240:241], v[146:147], v[240:241]
	v_mul_f32_e32 v243, v99, v225
	v_pk_fma_f32 v[212:213], v[212:213], v[240:241], v[214:215]
	v_add_f32_e32 v214, 1.0, v216
	v_add_f32_e32 v215, 1.0, v220
	v_mul_f32_e32 v240, v126, v225
	v_mul_f32_e32 v241, v127, v225
	v_rcp_f32_e32 v214, v214
	v_rcp_f32_e32 v215, v215
	v_mul_f32_e32 v240, 0xbfb8aa3b, v240
	v_mul_f32_e32 v241, 0xbfb8aa3b, v241
	v_lshlrev_b32_e32 v220, 16, v221
	v_and_b32_e32 v221, 0xffff0000, v221
	v_exp_f32_e32 v240, v240
	v_exp_f32_e32 v241, v241
	v_pk_mul_f32 v[220:221], v[224:225], v[220:221] op_sel_hi:[0,1]
	v_lshlrev_b32_e32 v216, 16, v217
	v_and_b32_e32 v217, 0xffff0000, v217
	v_pk_mul_f32 v[220:221], v[148:149], v[220:221]
	v_mul_f32_e32 v242, 0xbfb8aa3b, v242
	v_pk_fma_f32 v[214:215], v[214:215], v[220:221], v[216:217]
	v_lshlrev_b32_e32 v220, 16, v218
	v_and_b32_e32 v221, 0xffff0000, v218
	v_mul_f32_e32 v218, v128, v225
	v_add_f32_e32 v216, 1.0, v240
	v_add_f32_e32 v217, 1.0, v241
	v_lshlrev_b32_e32 v240, 16, v222
	v_and_b32_e32 v241, 0xffff0000, v222
	v_mul_f32_e32 v218, 0xbfb8aa3b, v218
	v_mul_f32_e32 v222, v129, v225
	v_exp_f32_e32 v218, v218
	v_mul_f32_e32 v222, 0xbfb8aa3b, v222
	v_rcp_f32_e32 v216, v216
	v_rcp_f32_e32 v217, v217
	v_exp_f32_e32 v222, v222
	v_pk_mul_f32 v[240:241], v[224:225], v[240:241] op_sel_hi:[0,1]
	v_pk_mul_f32 v[240:241], v[142:143], v[240:241]
	v_add_f32_e32 v218, 1.0, v218
	v_pk_fma_f32 v[216:217], v[216:217], v[240:241], v[220:221]
	v_rcp_f32_e32 v220, v218
	v_add_f32_e32 v218, 1.0, v222
	v_rcp_f32_e32 v221, v218
	v_lshlrev_b32_e32 v222, 16, v223
	v_and_b32_e32 v223, 0xffff0000, v223
	v_mul_f32_e32 v243, 0xbfb8aa3b, v243
	v_pk_mul_f32 v[222:223], v[224:225], v[222:223] op_sel_hi:[0,1]
	v_exp_f32_e32 v242, v242
	v_exp_f32_e32 v243, v243
	v_lshlrev_b32_e32 v218, 16, v219
	v_and_b32_e32 v219, 0xffff0000, v219
	v_pk_mul_f32 v[222:223], v[144:145], v[222:223]
	v_lshlrev_b64 v[184:185], 12, v[184:185]
	v_pk_fma_f32 v[218:219], v[220:221], v[222:223], v[218:219]
	v_lshl_add_u64 v[240:241], s[34:35], 0, v[184:185]
	v_lshlrev_b64 v[184:185], 1, v[188:189]
	v_cvt_pk_bf16_f32 v220, v212, v213
	v_cvt_pk_bf16_f32 v221, v214, v215
	v_cvt_pk_bf16_f32 v222, v216, v217
	v_cvt_pk_bf16_f32 v223, v218, v219
	v_lshl_add_u64 v[240:241], v[240:241], 0, v[184:185]
	global_store_dwordx4 v[240:241], v[220:223], off
	v_lshlrev_b64 v[208:209], 12, v[208:209]
	v_lshl_add_u64 v[208:209], s[34:35], 0, v[208:209]
	v_add_f32_e32 v220, 1.0, v242
	v_add_f32_e32 v221, 1.0, v243
	v_lshlrev_b32_e32 v222, 16, v226
	v_and_b32_e32 v223, 0xffff0000, v226
	v_lshlrev_b32_e32 v242, 16, v236
	v_and_b32_e32 v243, 0xffff0000, v236
	v_mul_f32_e32 v226, v100, v225
	v_mul_f32_e32 v236, v101, v225
	v_rcp_f32_e32 v220, v220
	v_rcp_f32_e32 v221, v221
	v_mul_f32_e32 v226, 0xbfb8aa3b, v226
	v_mul_f32_e32 v236, 0xbfb8aa3b, v236
	v_exp_f32_e32 v226, v226
	v_exp_f32_e32 v236, v236
	v_pk_mul_f32 v[242:243], v[224:225], v[242:243] op_sel_hi:[0,1]
	v_pk_mul_f32 v[242:243], v[138:139], v[242:243]
	v_lshl_add_u64 v[208:209], v[208:209], 0, v[184:185]
	v_pk_fma_f32 v[220:221], v[220:221], v[242:243], v[222:223]
	v_mul_f32_e32 v242, v94, v225
	v_mul_f32_e32 v243, v95, v225
	v_add_f32_e32 v222, 1.0, v226
	v_add_f32_e32 v223, 1.0, v236
	v_mul_f32_e32 v242, 0xbfb8aa3b, v242
	v_mul_f32_e32 v243, 0xbfb8aa3b, v243
	v_rcp_f32_e32 v222, v222
	v_rcp_f32_e32 v223, v223
	v_exp_f32_e32 v242, v242
	v_exp_f32_e32 v243, v243
	v_lshlrev_b32_e32 v236, 16, v237
	v_and_b32_e32 v237, 0xffff0000, v237
	v_pk_mul_f32 v[236:237], v[224:225], v[236:237] op_sel_hi:[0,1]
	v_lshlrev_b32_e32 v226, 16, v227
	v_and_b32_e32 v227, 0xffff0000, v227
	v_pk_mul_f32 v[236:237], v[140:141], v[236:237]
	v_cmp_gt_f32_e32 vcc, s67, v235
	v_pk_fma_f32 v[222:223], v[222:223], v[236:237], v[226:227]
	v_add_f32_e32 v226, 1.0, v242
	v_add_f32_e32 v227, 1.0, v243
	v_lshlrev_b32_e32 v242, 16, v238
	v_and_b32_e32 v243, 0xffff0000, v238
	v_lshlrev_b32_e32 v236, 16, v228
	v_and_b32_e32 v237, 0xffff0000, v228
	v_pk_mul_f32 v[242:243], v[224:225], v[242:243] op_sel_hi:[0,1]
	v_mul_f32_e32 v228, v96, v225
	v_mul_f32_e32 v225, v97, v225
	v_mul_f32_e32 v228, 0xbfb8aa3b, v228
	v_mul_f32_e32 v225, 0xbfb8aa3b, v225
	v_exp_f32_e32 v228, v228
	v_exp_f32_e32 v225, v225
	v_rcp_f32_e32 v226, v226
	v_rcp_f32_e32 v227, v227
	v_pk_mul_f32 v[242:243], v[134:135], v[242:243]
	v_add_f32_e32 v228, 1.0, v228
	v_add_f32_e32 v225, 1.0, v225
	v_pk_fma_f32 v[226:227], v[226:227], v[242:243], v[236:237]
	v_rcp_f32_e32 v236, v228
	v_rcp_f32_e32 v237, v225
	v_lshlrev_b32_e32 v238, 16, v239
	v_and_b32_e32 v239, 0xffff0000, v239
	v_pk_mul_f32 v[224:225], v[224:225], v[238:239] op_sel_hi:[0,1]
	v_lshlrev_b32_e32 v228, 16, v229
	v_and_b32_e32 v229, 0xffff0000, v229
	v_pk_mul_f32 v[224:225], v[136:137], v[224:225]
	v_cvt_pk_bf16_f32 v238, v226, v227
	v_pk_fma_f32 v[224:225], v[236:237], v[224:225], v[228:229]
	v_mul_f32_e32 v228, v122, v211
	v_mul_f32_e32 v229, v123, v211
	v_mul_f32_e32 v228, 0xbfb8aa3b, v228
	v_mul_f32_e32 v229, 0xbfb8aa3b, v229
	v_exp_f32_e32 v228, v228
	v_exp_f32_e32 v229, v229
	v_cvt_pk_bf16_f32 v236, v220, v221
	v_cvt_pk_bf16_f32 v237, v222, v223
	v_cvt_pk_bf16_f32 v239, v224, v225
	global_store_dwordx4 v[240:241], v[236:239], off offset:256
	v_add_f32_e32 v228, 1.0, v228
	v_add_f32_e32 v229, 1.0, v229
	v_lshlrev_b32_e32 v238, 16, v158
	v_and_b32_e32 v239, 0xffff0000, v158
	v_mul_f32_e32 v158, v124, v211
	v_lshlrev_b32_e32 v236, 16, v162
	v_and_b32_e32 v237, 0xffff0000, v162
	v_mul_f32_e32 v158, 0xbfb8aa3b, v158
	v_mul_f32_e32 v162, v125, v211
	v_rcp_f32_e32 v228, v228
	v_rcp_f32_e32 v229, v229
	v_exp_f32_e32 v158, v158
	v_mul_f32_e32 v162, 0xbfb8aa3b, v162
	v_exp_f32_e32 v162, v162
	v_pk_mul_f32 v[238:239], v[210:211], v[238:239] op_sel_hi:[0,1]
	v_pk_mul_f32 v[238:239], v[146:147], v[238:239]
	v_add_f32_e32 v158, 1.0, v158
	v_pk_fma_f32 v[228:229], v[228:229], v[238:239], v[236:237]
	v_mul_f32_e32 v238, v118, v211
	v_mul_f32_e32 v239, v119, v211
	v_rcp_f32_e32 v236, v158
	v_add_f32_e32 v158, 1.0, v162
	v_mul_f32_e32 v238, 0xbfb8aa3b, v238
	v_mul_f32_e32 v239, 0xbfb8aa3b, v239
	v_rcp_f32_e32 v237, v158
	v_exp_f32_e32 v238, v238
	v_exp_f32_e32 v239, v239
	v_lshlrev_b32_e32 v158, 16, v159
	v_and_b32_e32 v159, 0xffff0000, v159
	v_pk_mul_f32 v[158:159], v[210:211], v[158:159] op_sel_hi:[0,1]
	v_lshlrev_b32_e32 v162, 16, v163
	v_and_b32_e32 v163, 0xffff0000, v163
	v_pk_mul_f32 v[158:159], v[148:149], v[158:159]
	s_nop 0
	v_pk_fma_f32 v[158:159], v[236:237], v[158:159], v[162:163]
	v_add_f32_e32 v162, 1.0, v238
	v_add_f32_e32 v163, 1.0, v239
	v_lshlrev_b32_e32 v238, 16, v160
	v_and_b32_e32 v239, 0xffff0000, v160
	v_mul_f32_e32 v160, v120, v211
	v_lshlrev_b32_e32 v236, 16, v164
	v_and_b32_e32 v237, 0xffff0000, v164
	v_mul_f32_e32 v160, 0xbfb8aa3b, v160
	v_mul_f32_e32 v164, v121, v211
	v_exp_f32_e32 v160, v160
	v_mul_f32_e32 v164, 0xbfb8aa3b, v164
	v_rcp_f32_e32 v162, v162
	v_rcp_f32_e32 v163, v163
	v_exp_f32_e32 v164, v164
	v_pk_mul_f32 v[238:239], v[210:211], v[238:239] op_sel_hi:[0,1]
	v_pk_mul_f32 v[238:239], v[142:143], v[238:239]
	v_add_f32_e32 v160, 1.0, v160
	v_pk_fma_f32 v[246:247], v[162:163], v[238:239], v[236:237]
	v_rcp_f32_e32 v162, v160
	v_add_f32_e32 v160, 1.0, v164
	v_rcp_f32_e32 v163, v160
	v_mul_f32_e32 v236, v90, v211
	v_mul_f32_e32 v237, v91, v211
	v_lshlrev_b32_e32 v160, 16, v161
	v_and_b32_e32 v161, 0xffff0000, v161
	v_mul_f32_e32 v236, 0xbfb8aa3b, v236
	v_mul_f32_e32 v237, 0xbfb8aa3b, v237
	v_pk_mul_f32 v[160:161], v[210:211], v[160:161] op_sel_hi:[0,1]
	v_exp_f32_e32 v236, v236
	v_exp_f32_e32 v237, v237
	v_lshlrev_b32_e32 v164, 16, v165
	v_and_b32_e32 v165, 0xffff0000, v165
	v_pk_mul_f32 v[160:161], v[144:145], v[160:161]
	s_nop 0
	v_pk_fma_f32 v[164:165], v[162:163], v[160:161], v[164:165]
	v_cvt_pk_bf16_f32 v160, v228, v229
	v_cvt_pk_bf16_f32 v161, v158, v159
	v_cvt_pk_bf16_f32 v162, v246, v247
	v_cvt_pk_bf16_f32 v163, v164, v165
	global_store_dwordx4 v[208:209], v[160:163], off
	s_nop 1
	v_add_f32_e32 v160, 1.0, v236
	v_add_f32_e32 v161, 1.0, v237
	v_lshlrev_b32_e32 v236, 16, v150
	v_and_b32_e32 v237, 0xffff0000, v150
	v_mul_f32_e32 v150, v92, v211
	v_lshlrev_b32_e32 v162, 16, v154
	v_and_b32_e32 v163, 0xffff0000, v154
	v_mul_f32_e32 v150, 0xbfb8aa3b, v150
	v_mul_f32_e32 v154, v93, v211
	v_rcp_f32_e32 v160, v160
	v_rcp_f32_e32 v161, v161
	v_exp_f32_e32 v150, v150
	v_mul_f32_e32 v154, 0xbfb8aa3b, v154
	v_exp_f32_e32 v154, v154
	v_pk_mul_f32 v[236:237], v[210:211], v[236:237] op_sel_hi:[0,1]
	v_pk_mul_f32 v[236:237], v[138:139], v[236:237]
	v_add_f32_e32 v150, 1.0, v150
	v_pk_fma_f32 v[160:161], v[160:161], v[236:237], v[162:163]
	v_mul_f32_e32 v236, v86, v211
	v_mul_f32_e32 v237, v87, v211
	v_rcp_f32_e32 v162, v150
	v_add_f32_e32 v150, 1.0, v154
	v_mul_f32_e32 v236, 0xbfb8aa3b, v236
	v_mul_f32_e32 v237, 0xbfb8aa3b, v237
	v_rcp_f32_e32 v163, v150
	v_exp_f32_e32 v236, v236
	v_exp_f32_e32 v237, v237
	v_lshlrev_b32_e32 v150, 16, v151
	v_and_b32_e32 v151, 0xffff0000, v151
	v_pk_mul_f32 v[150:151], v[210:211], v[150:151] op_sel_hi:[0,1]
	v_lshlrev_b32_e32 v154, 16, v155
	v_and_b32_e32 v155, 0xffff0000, v155
	v_pk_mul_f32 v[150:151], v[140:141], v[150:151]
	s_nop 0
	v_pk_fma_f32 v[154:155], v[162:163], v[150:151], v[154:155]
	v_add_f32_e32 v150, 1.0, v236
	v_add_f32_e32 v151, 1.0, v237
	v_lshlrev_b32_e32 v162, 16, v156
	v_and_b32_e32 v163, 0xffff0000, v156
	v_lshlrev_b32_e32 v236, 16, v152
	v_and_b32_e32 v237, 0xffff0000, v152
	v_mul_f32_e32 v152, v88, v211
	v_mul_f32_e32 v156, v89, v211
	v_mul_f32_e32 v152, 0xbfb8aa3b, v152
	v_mul_f32_e32 v156, 0xbfb8aa3b, v156
	v_rcp_f32_e32 v150, v150
	v_rcp_f32_e32 v151, v151
	v_exp_f32_e32 v152, v152
	v_exp_f32_e32 v156, v156
	v_pk_mul_f32 v[236:237], v[210:211], v[236:237] op_sel_hi:[0,1]
	v_pk_mul_f32 v[236:237], v[134:135], v[236:237]
	s_nop 0
	v_pk_fma_f32 v[162:163], v[150:151], v[236:237], v[162:163]
	v_add_f32_e32 v150, 1.0, v152
	v_add_f32_e32 v151, 1.0, v156
	v_rcp_f32_e32 v150, v150
	v_rcp_f32_e32 v151, v151
	v_lshlrev_b32_e32 v152, 16, v153
	v_and_b32_e32 v153, 0xffff0000, v153
	v_pk_mul_f32 v[152:153], v[210:211], v[152:153] op_sel_hi:[0,1]
	v_lshlrev_b32_e32 v156, 16, v157
	v_and_b32_e32 v157, 0xffff0000, v157
	v_pk_mul_f32 v[152:153], v[136:137], v[152:153]
	s_nop 0
	v_pk_fma_f32 v[156:157], v[150:151], v[152:153], v[156:157]
	v_cvt_pk_bf16_f32 v150, v160, v161
	v_cvt_pk_bf16_f32 v151, v154, v155
	v_cvt_pk_bf16_f32 v152, v162, v163
	v_cvt_pk_bf16_f32 v153, v156, v157
	global_store_dwordx4 v[208:209], v[150:153], off offset:256
	v_mov_b32_e32 v209, v159
	v_mov_b32_e32 v159, v228
	v_lshlrev_b64 v[150:151], 11, v[204:205]
	v_lshl_add_u64 v[150:151], v[150:151], 0, v[188:189]
	v_lshlrev_b64 v[150:151], 1, v[150:151]
	v_lshl_add_u64 v[152:153], s[18:19], 0, v[150:151]
	global_load_dwordx4 v[238:241], v[152:153], off
	v_lshl_add_u64 v[152:153], s[36:37], 0, v[150:151]
	global_load_dwordx4 v[242:245], v[152:153], off nt
	v_mul_f32_e32 v152, 0x4b800000, v235
	v_cndmask_b32_e32 v152, v235, v152, vcc
	v_and_b32_e32 v153, 64, v234
	v_mov_b32_e32 v228, v213
	v_rsq_f32_e32 v236, v152
	v_xor_b32_e32 v152, 16, v234
	v_add_u32_e32 v237, 64, v153
	v_mov_b32_e32 v208, v215
	v_mov_b32_e32 v215, v158
	v_mov_b32_e32 v158, v212
	v_pk_mul_f32 v[210:211], v[228:229], v[228:229]
	v_cmp_lt_i32_e64 s[0:1], v152, v237
	v_pk_fma_f32 v[158:159], v[158:159], v[158:159], v[210:211]
	v_mov_b32_e32 v153, v165
	v_cndmask_b32_e64 v152, v234, v152, s[0:1]
	v_pk_fma_f32 v[158:159], v[214:215], v[214:215], v[158:159]
	v_lshlrev_b32_e32 v235, 2, v152
	v_mov_b32_e32 v152, v219
	v_mov_b32_e32 v219, v164
	v_mov_b32_e32 v164, v217
	v_mov_b32_e32 v217, v246
	v_pk_fma_f32 v[158:159], v[208:209], v[208:209], v[158:159]
	v_mov_b32_e32 v165, v247
	v_pk_fma_f32 v[158:159], v[216:217], v[216:217], v[158:159]
	v_or_b32_e32 v150, 0x100, v150
	v_pk_fma_f32 v[158:159], v[164:165], v[164:165], v[158:159]
	v_mul_f32_e32 v216, v116, v207
	v_pk_fma_f32 v[158:159], v[218:219], v[218:219], v[158:159]
	v_mul_f32_e32 v217, v117, v207
	v_pk_fma_f32 v[152:153], v[152:153], v[152:153], v[158:159]
	v_mov_b32_e32 v158, v220
	v_mov_b32_e32 v159, v160
	v_pk_fma_f32 v[152:153], v[158:159], v[158:159], v[152:153]
	v_mov_b32_e32 v160, v221
	v_pk_fma_f32 v[152:153], v[160:161], v[160:161], v[152:153]
	v_mov_b32_e32 v158, v222
	v_mov_b32_e32 v159, v154
	v_pk_fma_f32 v[152:153], v[158:159], v[158:159], v[152:153]
	v_mov_b32_e32 v154, v223
	v_pk_fma_f32 v[152:153], v[154:155], v[154:155], v[152:153]
	v_mov_b32_e32 v154, v226
	v_mov_b32_e32 v155, v162
	v_pk_fma_f32 v[152:153], v[154:155], v[154:155], v[152:153]
	v_mov_b32_e32 v162, v227
	v_pk_fma_f32 v[152:153], v[162:163], v[162:163], v[152:153]
	v_mov_b32_e32 v154, v224
	v_mov_b32_e32 v155, v156
	v_pk_fma_f32 v[152:153], v[154:155], v[154:155], v[152:153]
	v_mov_b32_e32 v156, v225
	v_pk_fma_f32 v[208:209], v[156:157], v[156:157], v[152:153]
	v_lshl_add_u64 v[152:153], s[18:19], 0, v[150:151]
	v_lshl_add_u64 v[150:151], s[36:37], 0, v[150:151]
	global_load_dwordx4 v[220:223], v[152:153], off
	global_load_dwordx4 v[224:227], v[150:151], off nt
	v_lshlrev_b64 v[150:151], 11, v[200:201]
	v_lshl_add_u64 v[150:151], v[150:151], 0, v[188:189]
	v_lshlrev_b64 v[150:151], 1, v[150:151]
	v_lshl_add_u64 v[152:153], s[18:19], 0, v[150:151]
	v_lshl_add_u64 v[154:155], s[36:37], 0, v[150:151]
	global_load_dwordx4 v[162:165], v[152:153], off
	global_load_dwordx4 v[158:161], v[154:155], off nt
	v_mul_f32_e32 v154, v114, v207
	v_mul_f32_e32 v154, 0xbfb8aa3b, v154
	v_exp_f32_e32 v210, v154
	v_mul_f32_e32 v154, v115, v207
	v_or_b32_e32 v150, 0x100, v150
	v_mul_f32_e32 v154, 0xbfb8aa3b, v154
	v_lshl_add_u64 v[152:153], s[18:19], 0, v[150:151]
	v_lshl_add_u64 v[150:151], s[36:37], 0, v[150:151]
	v_exp_f32_e32 v211, v154
	global_load_dwordx4 v[154:157], v[152:153], off
	s_nop 0
	global_load_dwordx4 v[150:153], v[150:151], off nt
	v_add_f32_e32 v210, 1.0, v210
	v_mul_f32_e32 v216, 0xbfb8aa3b, v216
	v_add_f32_e32 v211, 1.0, v211
	v_mul_f32_e32 v217, 0xbfb8aa3b, v217
	v_rcp_f32_e32 v210, v210
	v_rcp_f32_e32 v211, v211
	v_exp_f32_e32 v216, v216
	v_exp_f32_e32 v217, v217
	s_waitcnt vmcnt(0)
	v_lshlrev_b32_e32 v212, 16, v238
	v_and_b32_e32 v213, 0xffff0000, v238
	v_lshlrev_b32_e32 v214, 16, v242
	v_and_b32_e32 v215, 0xffff0000, v242
	v_pk_mul_f32 v[214:215], v[206:207], v[214:215] op_sel_hi:[0,1]
	v_pk_mul_f32 v[214:215], v[146:147], v[214:215]
	v_mul_f32_e32 v218, v110, v207
	v_mul_f32_e32 v219, v111, v207
	v_pk_fma_f32 v[210:211], v[210:211], v[214:215], v[212:213]
	v_add_f32_e32 v212, 1.0, v216
	v_add_f32_e32 v213, 1.0, v217
	v_mul_f32_e32 v218, 0xbfb8aa3b, v218
	v_mul_f32_e32 v219, 0xbfb8aa3b, v219
	v_rcp_f32_e32 v212, v212
	v_rcp_f32_e32 v213, v213
	v_exp_f32_e32 v218, v218
	v_exp_f32_e32 v219, v219
	v_lshlrev_b32_e32 v216, 16, v243
	v_and_b32_e32 v217, 0xffff0000, v243
	v_pk_mul_f32 v[216:217], v[206:207], v[216:217] op_sel_hi:[0,1]
	v_lshlrev_b32_e32 v214, 16, v239
	v_and_b32_e32 v215, 0xffff0000, v239
	v_pk_mul_f32 v[216:217], v[148:149], v[216:217]
	v_mul_f32_e32 v228, v112, v207
	v_mul_f32_e32 v229, v113, v207
	v_pk_fma_f32 v[212:213], v[212:213], v[216:217], v[214:215]
	v_add_f32_e32 v214, 1.0, v218
	v_add_f32_e32 v215, 1.0, v219
	v_mul_f32_e32 v228, 0xbfb8aa3b, v228
	v_mul_f32_e32 v229, 0xbfb8aa3b, v229
	v_rcp_f32_e32 v214, v214
	v_rcp_f32_e32 v215, v215
	v_exp_f32_e32 v228, v228
	v_exp_f32_e32 v229, v229
	v_lshlrev_b32_e32 v218, 16, v244
	v_and_b32_e32 v219, 0xffff0000, v244
	v_pk_mul_f32 v[218:219], v[206:207], v[218:219] op_sel_hi:[0,1]
	v_lshlrev_b32_e32 v216, 16, v240
	v_and_b32_e32 v217, 0xffff0000, v240
	v_pk_mul_f32 v[218:219], v[142:143], v[218:219]
	v_lshlrev_b64 v[204:205], 12, v[204:205]
	v_pk_fma_f32 v[214:215], v[214:215], v[218:219], v[216:217]
	v_add_f32_e32 v216, 1.0, v228
	v_add_f32_e32 v217, 1.0, v229
	v_rcp_f32_e32 v216, v216
	v_rcp_f32_e32 v217, v217
	v_lshlrev_b32_e32 v228, 16, v245
	v_and_b32_e32 v229, 0xffff0000, v245
	v_pk_mul_f32 v[228:229], v[206:207], v[228:229] op_sel_hi:[0,1]
	v_lshlrev_b32_e32 v218, 16, v241
	v_and_b32_e32 v219, 0xffff0000, v241
	v_pk_mul_f32 v[228:229], v[144:145], v[228:229]
	v_lshl_add_u64 v[204:205], s[34:35], 0, v[204:205]
	v_pk_fma_f32 v[216:217], v[216:217], v[228:229], v[218:219]
	v_lshl_add_u64 v[228:229], v[204:205], 0, v[184:185]
	v_mul_f32_e32 v204, v82, v207
	v_mul_f32_e32 v205, v83, v207
	v_mul_f32_e32 v204, 0xbfb8aa3b, v204
	v_mul_f32_e32 v205, 0xbfb8aa3b, v205
	v_exp_f32_e32 v204, v204
	v_exp_f32_e32 v205, v205
	v_cvt_pk_bf16_f32 v238, v210, v211
	v_cvt_pk_bf16_f32 v239, v212, v213
	v_cvt_pk_bf16_f32 v240, v214, v215
	v_cvt_pk_bf16_f32 v241, v216, v217
	global_store_dwordx4 v[228:229], v[238:241], off
	v_add_f32_e32 v204, 1.0, v204
	v_add_f32_e32 v205, 1.0, v205
	v_lshlrev_b32_e32 v218, 16, v220
	v_and_b32_e32 v219, 0xffff0000, v220
	v_lshlrev_b32_e32 v238, 16, v224
	v_and_b32_e32 v239, 0xffff0000, v224
	v_mul_f32_e32 v220, v84, v207
	v_mul_f32_e32 v224, v85, v207
	v_rcp_f32_e32 v204, v204
	v_rcp_f32_e32 v205, v205
	v_mul_f32_e32 v220, 0xbfb8aa3b, v220
	v_mul_f32_e32 v224, 0xbfb8aa3b, v224
	v_exp_f32_e32 v220, v220
	v_exp_f32_e32 v224, v224
	v_pk_mul_f32 v[238:239], v[206:207], v[238:239] op_sel_hi:[0,1]
	v_pk_mul_f32 v[238:239], v[138:139], v[238:239]
	v_lshlrev_b64 v[200:201], 12, v[200:201]
	v_pk_fma_f32 v[204:205], v[204:205], v[238:239], v[218:219]
	v_mul_f32_e32 v238, v78, v207
	v_mul_f32_e32 v239, v79, v207
	v_add_f32_e32 v218, 1.0, v220
	v_add_f32_e32 v219, 1.0, v224
	v_mul_f32_e32 v238, 0xbfb8aa3b, v238
	v_mul_f32_e32 v239, 0xbfb8aa3b, v239
	v_rcp_f32_e32 v218, v218
	v_rcp_f32_e32 v219, v219
	v_exp_f32_e32 v238, v238
	v_exp_f32_e32 v239, v239
	v_lshlrev_b32_e32 v224, 16, v225
	v_and_b32_e32 v225, 0xffff0000, v225
	v_pk_mul_f32 v[224:225], v[206:207], v[224:225] op_sel_hi:[0,1]
	v_lshlrev_b32_e32 v220, 16, v221
	v_and_b32_e32 v221, 0xffff0000, v221
	v_pk_mul_f32 v[224:225], v[140:141], v[224:225]
	v_lshl_add_u64 v[200:201], s[34:35], 0, v[200:201]
	v_pk_fma_f32 v[218:219], v[218:219], v[224:225], v[220:221]
	v_add_f32_e32 v220, 1.0, v238
	v_add_f32_e32 v221, 1.0, v239
	v_lshlrev_b32_e32 v238, 16, v226
	v_and_b32_e32 v239, 0xffff0000, v226
	v_lshlrev_b32_e32 v224, 16, v222
	v_and_b32_e32 v225, 0xffff0000, v222
	v_pk_mul_f32 v[238:239], v[206:207], v[238:239] op_sel_hi:[0,1]
	v_mul_f32_e32 v222, v80, v207
	v_mul_f32_e32 v207, v81, v207
	v_mul_f32_e32 v222, 0xbfb8aa3b, v222
	v_mul_f32_e32 v207, 0xbfb8aa3b, v207
	v_exp_f32_e32 v222, v222
	v_exp_f32_e32 v207, v207
	v_rcp_f32_e32 v220, v220
	v_rcp_f32_e32 v221, v221
	v_pk_mul_f32 v[238:239], v[134:135], v[238:239]
	v_add_f32_e32 v222, 1.0, v222
	v_add_f32_e32 v207, 1.0, v207
	v_lshlrev_b32_e32 v226, 16, v227
	v_and_b32_e32 v227, 0xffff0000, v227
	v_pk_fma_f32 v[220:221], v[220:221], v[238:239], v[224:225]
	v_rcp_f32_e32 v224, v222
	v_rcp_f32_e32 v225, v207
	v_pk_mul_f32 v[206:207], v[206:207], v[226:227] op_sel_hi:[0,1]
	v_mul_f32_e32 v226, v106, v203
	v_mul_f32_e32 v227, v107, v203
	v_mul_f32_e32 v226, 0xbfb8aa3b, v226
	v_mul_f32_e32 v227, 0xbfb8aa3b, v227
	v_exp_f32_e32 v226, v226
	v_exp_f32_e32 v227, v227
	v_lshlrev_b32_e32 v222, 16, v223
	v_and_b32_e32 v223, 0xffff0000, v223
	v_pk_mul_f32 v[206:207], v[136:137], v[206:207]
	v_lshl_add_u64 v[200:201], v[200:201], 0, v[184:185]
	v_pk_fma_f32 v[206:207], v[224:225], v[206:207], v[222:223]
	v_cvt_pk_bf16_f32 v222, v204, v205
	v_cvt_pk_bf16_f32 v223, v218, v219
	v_cvt_pk_bf16_f32 v224, v220, v221
	v_cvt_pk_bf16_f32 v225, v206, v207
	global_store_dwordx4 v[228:229], v[222:225], off offset:256
	s_nop 1
	v_add_f32_e32 v222, 1.0, v226
	v_add_f32_e32 v223, 1.0, v227
	v_lshlrev_b32_e32 v226, 16, v158
	v_and_b32_e32 v227, 0xffff0000, v158
	v_mul_f32_e32 v158, v108, v203
	v_lshlrev_b32_e32 v224, 16, v162
	v_and_b32_e32 v225, 0xffff0000, v162
	v_mul_f32_e32 v158, 0xbfb8aa3b, v158
	v_mul_f32_e32 v162, v109, v203
	v_rcp_f32_e32 v222, v222
	v_rcp_f32_e32 v223, v223
	v_exp_f32_e32 v158, v158
	v_mul_f32_e32 v162, 0xbfb8aa3b, v162
	v_exp_f32_e32 v162, v162
	v_pk_mul_f32 v[226:227], v[202:203], v[226:227] op_sel_hi:[0,1]
	v_pk_mul_f32 v[226:227], v[146:147], v[226:227]
	v_add_f32_e32 v158, 1.0, v158
	v_pk_fma_f32 v[222:223], v[222:223], v[226:227], v[224:225]
	v_mul_f32_e32 v226, v102, v203
	v_mul_f32_e32 v227, v103, v203
	v_rcp_f32_e32 v224, v158
	v_add_f32_e32 v158, 1.0, v162
	v_mul_f32_e32 v226, 0xbfb8aa3b, v226
	v_mul_f32_e32 v227, 0xbfb8aa3b, v227
	v_rcp_f32_e32 v225, v158
	v_exp_f32_e32 v226, v226
	v_exp_f32_e32 v227, v227
	v_lshlrev_b32_e32 v158, 16, v159
	v_and_b32_e32 v159, 0xffff0000, v159
	v_pk_mul_f32 v[158:159], v[202:203], v[158:159] op_sel_hi:[0,1]
	v_lshlrev_b32_e32 v162, 16, v163
	v_and_b32_e32 v163, 0xffff0000, v163
	v_pk_mul_f32 v[158:159], v[148:149], v[158:159]
	s_nop 0
	v_pk_fma_f32 v[158:159], v[224:225], v[158:159], v[162:163]
	v_add_f32_e32 v162, 1.0, v226
	v_add_f32_e32 v163, 1.0, v227
	v_lshlrev_b32_e32 v226, 16, v160
	v_and_b32_e32 v227, 0xffff0000, v160
	v_mul_f32_e32 v160, v104, v203
	v_lshlrev_b32_e32 v224, 16, v164
	v_and_b32_e32 v225, 0xffff0000, v164
	v_mul_f32_e32 v160, 0xbfb8aa3b, v160
	v_mul_f32_e32 v164, v105, v203
	v_exp_f32_e32 v160, v160
	v_mul_f32_e32 v164, 0xbfb8aa3b, v164
	v_rcp_f32_e32 v162, v162
	v_rcp_f32_e32 v163, v163
	v_exp_f32_e32 v164, v164
	v_pk_mul_f32 v[226:227], v[202:203], v[226:227] op_sel_hi:[0,1]
	v_pk_mul_f32 v[226:227], v[142:143], v[226:227]
	v_add_f32_e32 v160, 1.0, v160
	v_pk_fma_f32 v[242:243], v[162:163], v[226:227], v[224:225]
	v_rcp_f32_e32 v162, v160
	v_add_f32_e32 v160, 1.0, v164
	v_rcp_f32_e32 v163, v160
	v_mul_f32_e32 v224, v74, v203
	v_mul_f32_e32 v225, v75, v203
	v_lshlrev_b32_e32 v160, 16, v161
	v_and_b32_e32 v161, 0xffff0000, v161
	v_mul_f32_e32 v224, 0xbfb8aa3b, v224
	v_mul_f32_e32 v225, 0xbfb8aa3b, v225
	v_pk_mul_f32 v[160:161], v[202:203], v[160:161] op_sel_hi:[0,1]
	v_exp_f32_e32 v224, v224
	v_exp_f32_e32 v225, v225
	v_lshlrev_b32_e32 v164, 16, v165
	v_and_b32_e32 v165, 0xffff0000, v165
	v_pk_mul_f32 v[160:161], v[144:145], v[160:161]
	s_nop 0
	v_pk_fma_f32 v[164:165], v[162:163], v[160:161], v[164:165]
	v_cvt_pk_bf16_f32 v160, v222, v223
	v_cvt_pk_bf16_f32 v161, v158, v159
	v_cvt_pk_bf16_f32 v162, v242, v243
	v_cvt_pk_bf16_f32 v163, v164, v165
	global_store_dwordx4 v[200:201], v[160:163], off
	s_nop 1
	v_add_f32_e32 v160, 1.0, v224
	v_add_f32_e32 v161, 1.0, v225
	v_lshlrev_b32_e32 v224, 16, v150
	v_and_b32_e32 v225, 0xffff0000, v150
	v_mul_f32_e32 v150, v76, v203
	v_lshlrev_b32_e32 v162, 16, v154
	v_and_b32_e32 v163, 0xffff0000, v154
	v_mul_f32_e32 v150, 0xbfb8aa3b, v150
	v_mul_f32_e32 v154, v77, v203
	v_rcp_f32_e32 v160, v160
	v_rcp_f32_e32 v161, v161
	v_exp_f32_e32 v150, v150
	v_mul_f32_e32 v154, 0xbfb8aa3b, v154
	v_exp_f32_e32 v154, v154
	v_pk_mul_f32 v[224:225], v[202:203], v[224:225] op_sel_hi:[0,1]
	v_pk_mul_f32 v[224:225], v[138:139], v[224:225]
	v_add_f32_e32 v150, 1.0, v150
	v_pk_fma_f32 v[160:161], v[160:161], v[224:225], v[162:163]
	v_mul_f32_e32 v224, v70, v203
	v_mul_f32_e32 v225, v71, v203
	v_rcp_f32_e32 v162, v150
	v_add_f32_e32 v150, 1.0, v154
	v_mul_f32_e32 v224, 0xbfb8aa3b, v224
	v_mul_f32_e32 v225, 0xbfb8aa3b, v225
	v_rcp_f32_e32 v163, v150
	v_exp_f32_e32 v224, v224
	v_exp_f32_e32 v225, v225
	v_lshlrev_b32_e32 v150, 16, v151
	v_and_b32_e32 v151, 0xffff0000, v151
	v_pk_mul_f32 v[150:151], v[202:203], v[150:151] op_sel_hi:[0,1]
	v_lshlrev_b32_e32 v154, 16, v155
	v_and_b32_e32 v155, 0xffff0000, v155
	v_pk_mul_f32 v[150:151], v[140:141], v[150:151]
	s_nop 0
	v_pk_fma_f32 v[154:155], v[162:163], v[150:151], v[154:155]
	v_add_f32_e32 v150, 1.0, v224
	v_add_f32_e32 v151, 1.0, v225
	v_lshlrev_b32_e32 v162, 16, v156
	v_and_b32_e32 v163, 0xffff0000, v156
	v_lshlrev_b32_e32 v224, 16, v152
	v_and_b32_e32 v225, 0xffff0000, v152
	v_mul_f32_e32 v152, v72, v203
	v_mul_f32_e32 v156, v73, v203
	v_mul_f32_e32 v152, 0xbfb8aa3b, v152
	v_mul_f32_e32 v156, 0xbfb8aa3b, v156
	v_rcp_f32_e32 v150, v150
	v_rcp_f32_e32 v151, v151
	v_exp_f32_e32 v152, v152
	v_exp_f32_e32 v156, v156
	v_pk_mul_f32 v[224:225], v[202:203], v[224:225] op_sel_hi:[0,1]
	v_pk_mul_f32 v[224:225], v[134:135], v[224:225]
	s_nop 0
	v_pk_fma_f32 v[162:163], v[150:151], v[224:225], v[162:163]
	v_add_f32_e32 v150, 1.0, v152
	v_add_f32_e32 v151, 1.0, v156
	v_rcp_f32_e32 v150, v150
	v_rcp_f32_e32 v151, v151
	v_lshlrev_b32_e32 v152, 16, v153
	v_and_b32_e32 v153, 0xffff0000, v153
	v_pk_mul_f32 v[152:153], v[202:203], v[152:153] op_sel_hi:[0,1]
	v_lshlrev_b32_e32 v156, 16, v157
	v_and_b32_e32 v157, 0xffff0000, v157
	v_pk_mul_f32 v[152:153], v[136:137], v[152:153]
	v_mul_f32_e32 v225, v31, v199
	v_pk_fma_f32 v[156:157], v[150:151], v[152:153], v[156:157]
	v_cvt_pk_bf16_f32 v150, v160, v161
	v_cvt_pk_bf16_f32 v151, v154, v155
	v_cvt_pk_bf16_f32 v152, v162, v163
	v_cvt_pk_bf16_f32 v153, v156, v157
	global_store_dwordx4 v[200:201], v[150:153], off offset:256
	v_xor_b32_e32 v200, 32, v234
	v_cmp_lt_i32_e64 s[0:1], v200, v237
	v_lshlrev_b64 v[150:151], 11, v[196:197]
	v_lshl_add_u64 v[150:151], v[150:151], 0, v[188:189]
	v_lshlrev_b64 v[150:151], 1, v[150:151]
	v_lshl_add_u64 v[152:153], s[18:19], 0, v[150:151]
	global_load_dwordx4 v[226:229], v[152:153], off
	v_lshl_add_u64 v[152:153], s[36:37], 0, v[150:151]
	global_load_dwordx4 v[238:241], v[152:153], off nt
	ds_bpermute_b32 v152, v235, v208
	ds_bpermute_b32 v153, v235, v209
	v_cndmask_b32_e64 v200, v234, v200, s[0:1]
	v_lshlrev_b32_e32 v224, 2, v200
	v_or_b32_e32 v150, 0x100, v150
	v_lshlrev_b64 v[196:197], 12, v[196:197]
	s_waitcnt lgkmcnt(0)
	v_pk_add_f32 v[200:201], v[208:209], v[152:153]
	v_mov_b32_e32 v209, v159
	v_mov_b32_e32 v159, v222
	v_mov_b32_e32 v222, v211
	v_mov_b32_e32 v208, v213
	v_mov_b32_e32 v213, v158
	v_mov_b32_e32 v158, v210
	v_pk_mul_f32 v[210:211], v[222:223], v[222:223]
	v_mov_b32_e32 v152, v217
	v_pk_fma_f32 v[158:159], v[158:159], v[158:159], v[210:211]
	v_mov_b32_e32 v217, v164
	v_pk_fma_f32 v[158:159], v[212:213], v[212:213], v[158:159]
	v_mov_b32_e32 v164, v215
	v_mov_b32_e32 v215, v242
	v_pk_fma_f32 v[158:159], v[208:209], v[208:209], v[158:159]
	v_mov_b32_e32 v153, v165
	v_mov_b32_e32 v165, v243
	v_pk_fma_f32 v[158:159], v[214:215], v[214:215], v[158:159]
	v_mul_f32_e32 v214, v69, v199
	v_pk_fma_f32 v[158:159], v[164:165], v[164:165], v[158:159]
	v_mul_f32_e32 v214, 0xbfb8aa3b, v214
	v_pk_fma_f32 v[158:159], v[216:217], v[216:217], v[158:159]
	v_exp_f32_e32 v214, v214
	v_pk_fma_f32 v[152:153], v[152:153], v[152:153], v[158:159]
	v_mov_b32_e32 v158, v204
	v_mov_b32_e32 v159, v160
	v_pk_fma_f32 v[152:153], v[158:159], v[158:159], v[152:153]
	v_mov_b32_e32 v160, v205
	v_pk_fma_f32 v[152:153], v[160:161], v[160:161], v[152:153]
	v_mov_b32_e32 v158, v218
	v_mov_b32_e32 v159, v154
	v_pk_fma_f32 v[152:153], v[158:159], v[158:159], v[152:153]
	v_mov_b32_e32 v154, v219
	v_pk_fma_f32 v[152:153], v[154:155], v[154:155], v[152:153]
	v_mov_b32_e32 v154, v220
	v_mov_b32_e32 v155, v162
	v_pk_fma_f32 v[152:153], v[154:155], v[154:155], v[152:153]
	v_mov_b32_e32 v162, v221
	v_pk_fma_f32 v[152:153], v[162:163], v[162:163], v[152:153]
	v_mov_b32_e32 v154, v206
	v_mov_b32_e32 v155, v156
	v_pk_fma_f32 v[152:153], v[154:155], v[154:155], v[152:153]
	v_mov_b32_e32 v156, v207
	v_pk_fma_f32 v[204:205], v[156:157], v[156:157], v[152:153]
	v_lshl_add_u64 v[152:153], s[18:19], 0, v[150:151]
	v_lshl_add_u64 v[150:151], s[36:37], 0, v[150:151]
	global_load_dwordx4 v[218:221], v[152:153], off
	global_load_dwordx4 v[242:245], v[150:151], off nt
	v_lshlrev_b64 v[150:151], 11, v[192:193]
	v_lshl_add_u64 v[150:151], v[150:151], 0, v[188:189]
	v_lshlrev_b64 v[150:151], 1, v[150:151]
	v_lshl_add_u64 v[152:153], s[18:19], 0, v[150:151]
	v_lshl_add_u64 v[154:155], s[36:37], 0, v[150:151]
	global_load_dwordx4 v[162:165], v[152:153], off
	global_load_dwordx4 v[158:161], v[154:155], off nt
	v_mul_f32_e32 v154, v66, v199
	v_mul_f32_e32 v154, 0xbfb8aa3b, v154
	v_exp_f32_e32 v203, v154
	v_mul_f32_e32 v154, v67, v199
	v_mul_f32_e32 v154, 0xbfb8aa3b, v154
	v_exp_f32_e32 v209, v154
	v_or_b32_e32 v150, 0x100, v150
	v_lshl_add_u64 v[152:153], s[18:19], 0, v[150:151]
	v_lshl_add_u64 v[150:151], s[36:37], 0, v[150:151]
	v_add_f32_e32 v203, 1.0, v203
	global_load_dwordx4 v[154:157], v[152:153], off
	s_nop 0
	global_load_dwordx4 v[150:153], v[150:151], off nt
	v_rcp_f32_e32 v208, v203
	v_add_f32_e32 v203, 1.0, v209
	v_rcp_f32_e32 v209, v203
	v_mul_f32_e32 v203, v68, v199
	v_mul_f32_e32 v203, 0xbfb8aa3b, v203
	v_exp_f32_e32 v203, v203
	v_mul_f32_e32 v216, v63, v199
	s_waitcnt vmcnt(7)
	v_lshlrev_b32_e32 v210, 16, v226
	v_and_b32_e32 v211, 0xffff0000, v226
	s_waitcnt vmcnt(6)
	v_lshlrev_b32_e32 v212, 16, v238
	v_and_b32_e32 v213, 0xffff0000, v238
	v_pk_mul_f32 v[212:213], v[198:199], v[212:213] op_sel_hi:[0,1]
	v_pk_mul_f32 v[212:213], v[146:147], v[212:213]
	v_add_f32_e32 v203, 1.0, v203
	v_pk_fma_f32 v[208:209], v[208:209], v[212:213], v[210:211]
	v_rcp_f32_e32 v210, v203
	v_add_f32_e32 v203, 1.0, v214
	v_rcp_f32_e32 v211, v203
	v_mul_f32_e32 v203, v62, v199
	v_mul_f32_e32 v203, 0xbfb8aa3b, v203
	v_exp_f32_e32 v203, v203
	v_mul_f32_e32 v216, 0xbfb8aa3b, v216
	v_exp_f32_e32 v216, v216
	v_lshlrev_b32_e32 v214, 16, v239
	v_and_b32_e32 v215, 0xffff0000, v239
	v_pk_mul_f32 v[214:215], v[198:199], v[214:215] op_sel_hi:[0,1]
	v_lshlrev_b32_e32 v212, 16, v227
	v_and_b32_e32 v213, 0xffff0000, v227
	v_pk_mul_f32 v[214:215], v[148:149], v[214:215]
	v_add_f32_e32 v203, 1.0, v203
	v_pk_fma_f32 v[210:211], v[210:211], v[214:215], v[212:213]
	v_rcp_f32_e32 v212, v203
	v_add_f32_e32 v203, 1.0, v216
	v_rcp_f32_e32 v213, v203
	v_mul_f32_e32 v203, v64, v199
	v_mul_f32_e32 v203, 0xbfb8aa3b, v203
	v_mul_f32_e32 v222, v65, v199
	v_exp_f32_e32 v203, v203
	v_mul_f32_e32 v222, 0xbfb8aa3b, v222
	v_exp_f32_e32 v222, v222
	v_lshlrev_b32_e32 v216, 16, v240
	v_and_b32_e32 v217, 0xffff0000, v240
	v_pk_mul_f32 v[216:217], v[198:199], v[216:217] op_sel_hi:[0,1]
	v_lshlrev_b32_e32 v214, 16, v228
	v_and_b32_e32 v215, 0xffff0000, v228
	v_pk_mul_f32 v[216:217], v[142:143], v[216:217]
	v_add_f32_e32 v203, 1.0, v203
	v_lshl_add_u64 v[196:197], s[34:35], 0, v[196:197]
	v_pk_fma_f32 v[212:213], v[212:213], v[216:217], v[214:215]
	v_rcp_f32_e32 v214, v203
	v_add_f32_e32 v203, 1.0, v222
	v_lshl_add_u64 v[238:239], v[196:197], 0, v[184:185]
	v_mul_f32_e32 v196, v34, v199
	v_mul_f32_e32 v197, v35, v199
	v_rcp_f32_e32 v215, v203
	v_mul_f32_e32 v196, 0xbfb8aa3b, v196
	v_mul_f32_e32 v197, 0xbfb8aa3b, v197
	v_lshlrev_b32_e32 v222, 16, v241
	v_and_b32_e32 v223, 0xffff0000, v241
	v_exp_f32_e32 v196, v196
	v_exp_f32_e32 v197, v197
	v_pk_mul_f32 v[222:223], v[198:199], v[222:223] op_sel_hi:[0,1]
	v_lshlrev_b32_e32 v216, 16, v229
	v_and_b32_e32 v217, 0xffff0000, v229
	v_pk_mul_f32 v[222:223], v[144:145], v[222:223]
	v_mul_f32_e32 v203, v36, v199
	v_pk_fma_f32 v[214:215], v[214:215], v[222:223], v[216:217]
	s_waitcnt vmcnt(5)
	v_lshlrev_b32_e32 v216, 16, v218
	v_and_b32_e32 v217, 0xffff0000, v218
	v_mul_f32_e32 v203, 0xbfb8aa3b, v203
	v_mul_f32_e32 v218, v37, v199
	v_add_f32_e32 v196, 1.0, v196
	v_add_f32_e32 v197, 1.0, v197
	v_exp_f32_e32 v203, v203
	v_mul_f32_e32 v218, 0xbfb8aa3b, v218
	v_rcp_f32_e32 v196, v196
	v_rcp_f32_e32 v197, v197
	v_exp_f32_e32 v218, v218
	s_waitcnt vmcnt(4)
	v_lshlrev_b32_e32 v222, 16, v242
	v_and_b32_e32 v223, 0xffff0000, v242
	v_pk_mul_f32 v[222:223], v[198:199], v[222:223] op_sel_hi:[0,1]
	v_pk_mul_f32 v[222:223], v[138:139], v[222:223]
	v_add_f32_e32 v203, 1.0, v203
	v_pk_fma_f32 v[196:197], v[196:197], v[222:223], v[216:217]
	v_rcp_f32_e32 v216, v203
	v_add_f32_e32 v203, 1.0, v218
	v_rcp_f32_e32 v217, v203
	v_mul_f32_e32 v203, v30, v199
	v_mul_f32_e32 v203, 0xbfb8aa3b, v203
	v_exp_f32_e32 v203, v203
	v_mul_f32_e32 v225, 0xbfb8aa3b, v225
	v_exp_f32_e32 v225, v225
	v_lshlrev_b32_e32 v222, 16, v243
	v_and_b32_e32 v223, 0xffff0000, v243
	v_pk_mul_f32 v[222:223], v[198:199], v[222:223] op_sel_hi:[0,1]
	v_cvt_pk_bf16_f32 v226, v208, v209
	v_cvt_pk_bf16_f32 v227, v210, v211
	v_cvt_pk_bf16_f32 v228, v212, v213
	v_cvt_pk_bf16_f32 v229, v214, v215
	v_lshlrev_b32_e32 v218, 16, v219
	v_and_b32_e32 v219, 0xffff0000, v219
	v_pk_mul_f32 v[222:223], v[140:141], v[222:223]
	v_add_f32_e32 v203, 1.0, v203
	global_store_dwordx4 v[238:239], v[226:229], off
	v_pk_fma_f32 v[216:217], v[216:217], v[222:223], v[218:219]
	v_rcp_f32_e32 v218, v203
	v_add_f32_e32 v203, 1.0, v225
	v_lshlrev_b32_e32 v226, 16, v244
	v_and_b32_e32 v227, 0xffff0000, v244
	v_rcp_f32_e32 v219, v203
	v_pk_mul_f32 v[226:227], v[198:199], v[226:227] op_sel_hi:[0,1]
	v_mul_f32_e32 v203, v32, v199
	v_mul_f32_e32 v199, v33, v199
	v_mul_f32_e32 v203, 0xbfb8aa3b, v203
	v_mul_f32_e32 v199, 0xbfb8aa3b, v199
	v_exp_f32_e32 v203, v203
	v_exp_f32_e32 v199, v199
	v_lshlrev_b32_e32 v222, 16, v220
	v_and_b32_e32 v223, 0xffff0000, v220
	v_pk_mul_f32 v[226:227], v[134:135], v[226:227]
	v_add_f32_e32 v203, 1.0, v203
	v_add_f32_e32 v199, 1.0, v199
	v_pk_fma_f32 v[218:219], v[218:219], v[226:227], v[222:223]
	v_rcp_f32_e32 v222, v203
	v_rcp_f32_e32 v223, v199
	v_mul_f32_e32 v203, v58, v195
	v_lshlrev_b32_e32 v226, 16, v245
	v_and_b32_e32 v227, 0xffff0000, v245
	v_mul_f32_e32 v203, 0xbfb8aa3b, v203
	v_mul_f32_e32 v225, v59, v195
	v_pk_mul_f32 v[198:199], v[198:199], v[226:227] op_sel_hi:[0,1]
	v_exp_f32_e32 v203, v203
	v_mul_f32_e32 v225, 0xbfb8aa3b, v225
	v_lshlrev_b32_e32 v220, 16, v221
	v_and_b32_e32 v221, 0xffff0000, v221
	v_pk_mul_f32 v[198:199], v[136:137], v[198:199]
	v_exp_f32_e32 v225, v225
	v_pk_fma_f32 v[198:199], v[222:223], v[198:199], v[220:221]
	v_cvt_pk_bf16_f32 v220, v196, v197
	v_cvt_pk_bf16_f32 v221, v216, v217
	v_cvt_pk_bf16_f32 v222, v218, v219
	v_cvt_pk_bf16_f32 v223, v198, v199
	s_waitcnt vmcnt(3)
	v_lshlrev_b32_e32 v226, 16, v158
	v_and_b32_e32 v227, 0xffff0000, v158
	v_mul_f32_e32 v158, v60, v195
	global_store_dwordx4 v[238:239], v[220:223], off offset:256
	v_add_f32_e32 v203, 1.0, v203
	v_mul_f32_e32 v158, 0xbfb8aa3b, v158
	v_lshlrev_b32_e32 v222, 16, v162
	v_and_b32_e32 v223, 0xffff0000, v162
	v_mul_f32_e32 v162, v61, v195
	v_rcp_f32_e32 v220, v203
	v_add_f32_e32 v203, 1.0, v225
	v_exp_f32_e32 v158, v158
	v_mul_f32_e32 v162, 0xbfb8aa3b, v162
	v_rcp_f32_e32 v221, v203
	v_exp_f32_e32 v162, v162
	v_pk_mul_f32 v[226:227], v[194:195], v[226:227] op_sel_hi:[0,1]
	v_pk_mul_f32 v[226:227], v[146:147], v[226:227]
	v_add_f32_e32 v158, 1.0, v158
	v_pk_fma_f32 v[220:221], v[220:221], v[226:227], v[222:223]
	v_rcp_f32_e32 v222, v158
	v_add_f32_e32 v158, 1.0, v162
	v_mul_f32_e32 v203, v54, v195
	v_mul_f32_e32 v225, v55, v195
	v_rcp_f32_e32 v223, v158
	v_mul_f32_e32 v203, 0xbfb8aa3b, v203
	v_mul_f32_e32 v225, 0xbfb8aa3b, v225
	v_lshlrev_b32_e32 v158, 16, v159
	v_and_b32_e32 v159, 0xffff0000, v159
	v_exp_f32_e32 v203, v203
	v_exp_f32_e32 v225, v225
	v_pk_mul_f32 v[158:159], v[194:195], v[158:159] op_sel_hi:[0,1]
	v_lshlrev_b32_e32 v162, 16, v163
	v_and_b32_e32 v163, 0xffff0000, v163
	v_pk_mul_f32 v[158:159], v[148:149], v[158:159]
	v_lshlrev_b32_e32 v226, 16, v160
	v_pk_fma_f32 v[162:163], v[222:223], v[158:159], v[162:163]
	v_lshlrev_b32_e32 v222, 16, v164
	v_and_b32_e32 v223, 0xffff0000, v164
	v_and_b32_e32 v227, 0xffff0000, v160
	v_mul_f32_e32 v160, v56, v195
	v_mul_f32_e32 v164, v57, v195
	v_add_f32_e32 v158, 1.0, v203
	v_add_f32_e32 v159, 1.0, v225
	v_mul_f32_e32 v160, 0xbfb8aa3b, v160
	v_mul_f32_e32 v164, 0xbfb8aa3b, v164
	v_rcp_f32_e32 v158, v158
	v_rcp_f32_e32 v159, v159
	v_exp_f32_e32 v160, v160
	v_exp_f32_e32 v164, v164
	v_pk_mul_f32 v[226:227], v[194:195], v[226:227] op_sel_hi:[0,1]
	v_pk_mul_f32 v[226:227], v[142:143], v[226:227]
	v_mul_f32_e32 v203, v26, v195
	v_pk_fma_f32 v[222:223], v[158:159], v[226:227], v[222:223]
	v_add_f32_e32 v158, 1.0, v160
	v_add_f32_e32 v159, 1.0, v164
	v_rcp_f32_e32 v158, v158
	v_rcp_f32_e32 v159, v159
	v_lshlrev_b32_e32 v160, 16, v161
	v_and_b32_e32 v161, 0xffff0000, v161
	v_mul_f32_e32 v225, v27, v195
	v_pk_mul_f32 v[160:161], v[194:195], v[160:161] op_sel_hi:[0,1]
	v_mul_f32_e32 v203, 0xbfb8aa3b, v203
	v_mul_f32_e32 v225, 0xbfb8aa3b, v225
	v_lshlrev_b32_e32 v164, 16, v165
	v_and_b32_e32 v165, 0xffff0000, v165
	v_pk_mul_f32 v[160:161], v[144:145], v[160:161]
	v_lshlrev_b64 v[192:193], 12, v[192:193]
	v_exp_f32_e32 v203, v203
	v_exp_f32_e32 v225, v225
	v_pk_fma_f32 v[164:165], v[158:159], v[160:161], v[164:165]
	v_lshl_add_u64 v[192:193], s[34:35], 0, v[192:193]
	v_cvt_pk_bf16_f32 v158, v220, v221
	v_cvt_pk_bf16_f32 v159, v162, v163
	v_cvt_pk_bf16_f32 v160, v222, v223
	v_cvt_pk_bf16_f32 v161, v164, v165
	v_lshl_add_u64 v[192:193], v[192:193], 0, v[184:185]
	s_waitcnt vmcnt(2)
	v_lshlrev_b32_e32 v226, 16, v150
	v_and_b32_e32 v227, 0xffff0000, v150
	v_mul_f32_e32 v150, v28, v195
	global_store_dwordx4 v[192:193], v[158:161], off
	v_mul_f32_e32 v150, 0xbfb8aa3b, v150
	v_exp_f32_e32 v150, v150
	v_lshlrev_b32_e32 v160, 16, v154
	v_and_b32_e32 v161, 0xffff0000, v154
	v_mul_f32_e32 v154, v29, v195
	v_add_f32_e32 v158, 1.0, v203
	v_add_f32_e32 v159, 1.0, v225
	v_mul_f32_e32 v154, 0xbfb8aa3b, v154
	v_rcp_f32_e32 v158, v158
	v_rcp_f32_e32 v159, v159
	v_exp_f32_e32 v154, v154
	v_pk_mul_f32 v[226:227], v[194:195], v[226:227] op_sel_hi:[0,1]
	v_pk_mul_f32 v[226:227], v[138:139], v[226:227]
	v_add_f32_e32 v150, 1.0, v150
	v_pk_fma_f32 v[158:159], v[158:159], v[226:227], v[160:161]
	v_rcp_f32_e32 v160, v150
	v_add_f32_e32 v150, 1.0, v154
	v_mul_f32_e32 v203, v22, v195
	v_mul_f32_e32 v225, v23, v195
	v_rcp_f32_e32 v161, v150
	v_mul_f32_e32 v203, 0xbfb8aa3b, v203
	v_mul_f32_e32 v225, 0xbfb8aa3b, v225
	v_lshlrev_b32_e32 v150, 16, v151
	v_and_b32_e32 v151, 0xffff0000, v151
	v_exp_f32_e32 v203, v203
	v_exp_f32_e32 v225, v225
	v_pk_mul_f32 v[150:151], v[194:195], v[150:151] op_sel_hi:[0,1]
	v_lshlrev_b32_e32 v154, 16, v155
	v_and_b32_e32 v155, 0xffff0000, v155
	v_pk_mul_f32 v[150:151], v[140:141], v[150:151]
	v_lshlrev_b32_e32 v226, 16, v152
	v_pk_fma_f32 v[154:155], v[160:161], v[150:151], v[154:155]
	v_lshlrev_b32_e32 v160, 16, v156
	v_and_b32_e32 v161, 0xffff0000, v156
	v_and_b32_e32 v227, 0xffff0000, v152
	v_mul_f32_e32 v152, v24, v195
	v_mul_f32_e32 v156, v25, v195
	v_add_f32_e32 v150, 1.0, v203
	v_add_f32_e32 v151, 1.0, v225
	v_mul_f32_e32 v152, 0xbfb8aa3b, v152
	v_mul_f32_e32 v156, 0xbfb8aa3b, v156
	v_rcp_f32_e32 v150, v150
	v_rcp_f32_e32 v151, v151
	v_exp_f32_e32 v152, v152
	v_exp_f32_e32 v156, v156
	v_pk_mul_f32 v[226:227], v[194:195], v[226:227] op_sel_hi:[0,1]
	v_pk_mul_f32 v[226:227], v[134:135], v[226:227]
	ds_bpermute_b32 v206, v235, v204
	v_pk_fma_f32 v[160:161], v[150:151], v[226:227], v[160:161]
	v_add_f32_e32 v150, 1.0, v152
	v_add_f32_e32 v151, 1.0, v156
	v_rcp_f32_e32 v150, v150
	v_rcp_f32_e32 v151, v151
	v_lshlrev_b32_e32 v152, 16, v153
	v_and_b32_e32 v153, 0xffff0000, v153
	v_pk_mul_f32 v[152:153], v[194:195], v[152:153] op_sel_hi:[0,1]
	v_lshlrev_b32_e32 v156, 16, v157
	v_and_b32_e32 v157, 0xffff0000, v157
	v_pk_mul_f32 v[152:153], v[136:137], v[152:153]
	ds_bpermute_b32 v207, v235, v205
	v_pk_fma_f32 v[156:157], v[150:151], v[152:153], v[156:157]
	v_cvt_pk_bf16_f32 v150, v158, v159
	v_cvt_pk_bf16_f32 v151, v154, v155
	v_cvt_pk_bf16_f32 v152, v160, v161
	v_cvt_pk_bf16_f32 v153, v156, v157
	global_store_dwordx4 v[192:193], v[150:153], off offset:256
	ds_bpermute_b32 v202, v224, v200
	ds_bpermute_b32 v203, v224, v201
	v_mov_b32_e32 v150, v215
	v_mov_b32_e32 v151, v165
	v_mov_b32_e32 v215, v164
	v_lshlrev_b64 v[164:165], 11, v[186:187]
	v_lshl_add_u64 v[164:165], v[164:165], 0, v[188:189]
	v_lshlrev_b64 v[164:165], 1, v[164:165]
	v_lshl_add_u64 v[192:193], s[18:19], 0, v[164:165]
	global_load_dwordx4 v[226:229], v[192:193], off
	v_lshl_add_u64 v[192:193], s[36:37], 0, v[164:165]
	global_load_dwordx4 v[238:241], v[192:193], off nt
	v_mov_b32_e32 v193, v163
	v_mov_b32_e32 v163, v220
	v_mov_b32_e32 v220, v209
	v_mov_b32_e32 v192, v211
	v_mov_b32_e32 v211, v162
	v_mov_b32_e32 v162, v208
	v_pk_mul_f32 v[194:195], v[220:221], v[220:221]
	v_mov_b32_e32 v152, v213
	v_pk_fma_f32 v[162:163], v[162:163], v[162:163], v[194:195]
	v_mov_b32_e32 v213, v222
	v_pk_fma_f32 v[162:163], v[210:211], v[210:211], v[162:163]
	v_mov_b32_e32 v153, v223
	v_pk_fma_f32 v[162:163], v[192:193], v[192:193], v[162:163]
	v_or_b32_e32 v164, 0x100, v164
	v_pk_fma_f32 v[162:163], v[212:213], v[212:213], v[162:163]
	s_waitcnt lgkmcnt(0)
	v_pk_add_f32 v[192:193], v[200:201], v[202:203]
	v_pk_fma_f32 v[152:153], v[152:153], v[152:153], v[162:163]
	v_lshlrev_b64 v[186:187], 12, v[186:187]
	v_pk_fma_f32 v[152:153], v[214:215], v[214:215], v[152:153]
	v_lshl_add_u64 v[186:187], s[34:35], 0, v[186:187]
	v_pk_fma_f32 v[150:151], v[150:151], v[150:151], v[152:153]
	v_mov_b32_e32 v152, v196
	v_mov_b32_e32 v153, v158
	v_pk_fma_f32 v[150:151], v[152:153], v[152:153], v[150:151]
	v_mov_b32_e32 v158, v197
	v_pk_fma_f32 v[150:151], v[158:159], v[158:159], v[150:151]
	v_mov_b32_e32 v152, v216
	v_mov_b32_e32 v153, v154
	v_pk_fma_f32 v[150:151], v[152:153], v[152:153], v[150:151]
	v_mov_b32_e32 v154, v217
	v_pk_fma_f32 v[150:151], v[154:155], v[154:155], v[150:151]
	v_mov_b32_e32 v152, v218
	v_mov_b32_e32 v153, v160
	v_pk_fma_f32 v[150:151], v[152:153], v[152:153], v[150:151]
	v_mov_b32_e32 v160, v219
	v_pk_fma_f32 v[150:151], v[160:161], v[160:161], v[150:151]
	v_mov_b32_e32 v152, v198
	v_mov_b32_e32 v153, v156
	v_pk_fma_f32 v[150:151], v[152:153], v[152:153], v[150:151]
	v_mov_b32_e32 v156, v199
	v_pk_fma_f32 v[150:151], v[156:157], v[156:157], v[150:151]
	ds_bpermute_b32 v152, v235, v150
	ds_bpermute_b32 v153, v235, v151
	v_pk_add_f32 v[154:155], v[204:205], v[206:207]
	ds_bpermute_b32 v156, v224, v154
	ds_bpermute_b32 v157, v224, v155
	v_mul_f32_e32 v158, 0x45800000, v236
	s_waitcnt lgkmcnt(2)
	v_pk_add_f32 v[150:151], v[150:151], v[152:153]
	ds_bpermute_b32 v152, v224, v150
	ds_bpermute_b32 v153, v224, v151
	v_cndmask_b32_e32 v198, v236, v158, vcc
	s_waitcnt lgkmcnt(2)
	v_pk_add_f32 v[194:195], v[154:155], v[156:157]
	v_mul_f32_e32 v199, v52, v191
	v_mul_f32_e32 v199, 0xbfb8aa3b, v199
	s_waitcnt lgkmcnt(0)
	v_pk_add_f32 v[196:197], v[150:151], v[152:153]
	v_lshl_add_u64 v[150:151], s[18:19], 0, v[164:165]
	v_lshl_add_u64 v[152:153], s[36:37], 0, v[164:165]
	global_load_dwordx4 v[208:211], v[150:151], off
	global_load_dwordx4 v[212:215], v[152:153], off nt
	v_lshlrev_b64 v[150:151], 11, v[4:5]
	v_lshl_add_u64 v[150:151], v[150:151], 0, v[188:189]
	v_lshlrev_b64 v[150:151], 1, v[150:151]
	v_lshl_add_u64 v[152:153], s[18:19], 0, v[150:151]
	v_lshl_add_u64 v[154:155], s[36:37], 0, v[150:151]
	global_load_dwordx4 v[162:165], v[152:153], off
	global_load_dwordx4 v[158:161], v[154:155], off nt
	v_mul_f32_e32 v154, v50, v191
	v_mul_f32_e32 v154, 0xbfb8aa3b, v154
	v_exp_f32_e32 v188, v154
	v_mul_f32_e32 v154, v51, v191
	v_mul_f32_e32 v154, 0xbfb8aa3b, v154
	v_exp_f32_e32 v189, v154
	v_mul_f32_e32 v204, v53, v191
	v_add_f32_e32 v188, 1.0, v188
	v_exp_f32_e32 v199, v199
	v_add_f32_e32 v189, 1.0, v189
	v_mul_f32_e32 v204, 0xbfb8aa3b, v204
	v_rcp_f32_e32 v188, v188
	v_rcp_f32_e32 v189, v189
	v_exp_f32_e32 v204, v204
	s_waitcnt vmcnt(5)
	v_lshlrev_b32_e32 v200, 16, v226
	s_waitcnt vmcnt(4)
	v_lshlrev_b32_e32 v202, 16, v238
	v_and_b32_e32 v203, 0xffff0000, v238
	v_pk_mul_f32 v[202:203], v[190:191], v[202:203] op_sel_hi:[0,1]
	v_and_b32_e32 v201, 0xffff0000, v226
	v_pk_mul_f32 v[202:203], v[146:147], v[202:203]
	v_add_f32_e32 v199, 1.0, v199
	v_pk_fma_f32 v[188:189], v[188:189], v[202:203], v[200:201]
	v_rcp_f32_e32 v200, v199
	v_add_f32_e32 v199, 1.0, v204
	v_rcp_f32_e32 v201, v199
	v_mul_f32_e32 v199, v46, v191
	v_mul_f32_e32 v199, 0xbfb8aa3b, v199
	v_mul_f32_e32 v206, v47, v191
	v_exp_f32_e32 v199, v199
	v_mul_f32_e32 v206, 0xbfb8aa3b, v206
	v_or_b32_e32 v150, 0x100, v150
	v_exp_f32_e32 v206, v206
	v_lshl_add_u64 v[152:153], s[18:19], 0, v[150:151]
	v_lshl_add_u64 v[150:151], s[36:37], 0, v[150:151]
	v_lshlrev_b32_e32 v204, 16, v239
	v_and_b32_e32 v205, 0xffff0000, v239
	global_load_dwordx4 v[154:157], v[152:153], off
	s_nop 0
	global_load_dwordx4 v[150:153], v[150:151], off nt
	v_pk_mul_f32 v[204:205], v[190:191], v[204:205] op_sel_hi:[0,1]
	v_lshlrev_b32_e32 v202, 16, v227
	v_and_b32_e32 v203, 0xffff0000, v227
	v_pk_mul_f32 v[204:205], v[148:149], v[204:205]
	v_add_f32_e32 v199, 1.0, v199
	v_pk_fma_f32 v[200:201], v[200:201], v[204:205], v[202:203]
	v_rcp_f32_e32 v202, v199
	v_add_f32_e32 v199, 1.0, v206
	v_rcp_f32_e32 v203, v199
	v_mul_f32_e32 v199, v48, v191
	v_mul_f32_e32 v199, 0xbfb8aa3b, v199
	v_mul_f32_e32 v216, v49, v191
	v_exp_f32_e32 v199, v199
	v_mul_f32_e32 v216, 0xbfb8aa3b, v216
	v_exp_f32_e32 v216, v216
	v_lshlrev_b32_e32 v206, 16, v240
	v_and_b32_e32 v207, 0xffff0000, v240
	v_pk_mul_f32 v[206:207], v[190:191], v[206:207] op_sel_hi:[0,1]
	v_lshlrev_b32_e32 v204, 16, v228
	v_and_b32_e32 v205, 0xffff0000, v228
	v_pk_mul_f32 v[206:207], v[142:143], v[206:207]
	v_add_f32_e32 v199, 1.0, v199
	v_pk_fma_f32 v[202:203], v[202:203], v[206:207], v[204:205]
	v_rcp_f32_e32 v204, v199
	v_add_f32_e32 v199, 1.0, v216
	v_lshl_add_u64 v[220:221], v[186:187], 0, v[184:185]
	v_mul_f32_e32 v186, v18, v191
	v_mul_f32_e32 v187, v19, v191
	v_rcp_f32_e32 v205, v199
	v_mul_f32_e32 v186, 0xbfb8aa3b, v186
	v_mul_f32_e32 v187, 0xbfb8aa3b, v187
	v_lshlrev_b32_e32 v216, 16, v241
	v_and_b32_e32 v217, 0xffff0000, v241
	v_exp_f32_e32 v186, v186
	v_exp_f32_e32 v187, v187
	v_pk_mul_f32 v[216:217], v[190:191], v[216:217] op_sel_hi:[0,1]
	v_lshlrev_b32_e32 v206, 16, v229
	v_and_b32_e32 v207, 0xffff0000, v229
	v_pk_mul_f32 v[216:217], v[144:145], v[216:217]
	v_mul_f32_e32 v199, v20, v191
	v_pk_fma_f32 v[204:205], v[204:205], v[216:217], v[206:207]
	s_waitcnt vmcnt(5)
	v_lshlrev_b32_e32 v206, 16, v208
	v_and_b32_e32 v207, 0xffff0000, v208
	v_mul_f32_e32 v199, 0xbfb8aa3b, v199
	v_mul_f32_e32 v208, v21, v191
	v_add_f32_e32 v186, 1.0, v186
	v_add_f32_e32 v187, 1.0, v187
	v_exp_f32_e32 v199, v199
	v_mul_f32_e32 v208, 0xbfb8aa3b, v208
	v_cvt_pk_bf16_f32 v216, v188, v189
	v_cvt_pk_bf16_f32 v217, v200, v201
	v_cvt_pk_bf16_f32 v218, v202, v203
	v_cvt_pk_bf16_f32 v219, v204, v205
	v_rcp_f32_e32 v186, v186
	v_rcp_f32_e32 v187, v187
	v_exp_f32_e32 v208, v208
	global_store_dwordx4 v[220:221], v[216:219], off
	v_add_f32_e32 v199, 1.0, v199
	v_lshlrev_b64 v[4:5], 12, v[4:5]
	s_waitcnt vmcnt(5)
	v_lshlrev_b32_e32 v216, 16, v212
	v_and_b32_e32 v217, 0xffff0000, v212
	v_pk_mul_f32 v[216:217], v[190:191], v[216:217] op_sel_hi:[0,1]
	v_pk_mul_f32 v[216:217], v[138:139], v[216:217]
	v_lshlrev_b32_e32 v212, 16, v213
	v_pk_fma_f32 v[186:187], v[186:187], v[216:217], v[206:207]
	v_rcp_f32_e32 v206, v199
	v_add_f32_e32 v199, 1.0, v208
	v_rcp_f32_e32 v207, v199
	v_mul_f32_e32 v199, v14, v191
	v_mul_f32_e32 v199, 0xbfb8aa3b, v199
	v_mul_f32_e32 v216, v15, v191
	v_exp_f32_e32 v199, v199
	v_mul_f32_e32 v216, 0xbfb8aa3b, v216
	v_exp_f32_e32 v216, v216
	v_and_b32_e32 v213, 0xffff0000, v213
	v_pk_mul_f32 v[212:213], v[190:191], v[212:213] op_sel_hi:[0,1]
	v_lshlrev_b32_e32 v208, 16, v209
	v_and_b32_e32 v209, 0xffff0000, v209
	v_pk_mul_f32 v[212:213], v[140:141], v[212:213]
	v_add_f32_e32 v199, 1.0, v199
	v_pk_fma_f32 v[206:207], v[206:207], v[212:213], v[208:209]
	v_rcp_f32_e32 v208, v199
	v_add_f32_e32 v199, 1.0, v216
	v_rcp_f32_e32 v209, v199
	v_lshlrev_b32_e32 v216, 16, v214
	v_and_b32_e32 v217, 0xffff0000, v214
	v_mul_f32_e32 v199, v16, v191
	v_pk_mul_f32 v[216:217], v[190:191], v[216:217] op_sel_hi:[0,1]
	v_mul_f32_e32 v199, 0xbfb8aa3b, v199
	v_mul_f32_e32 v191, v17, v191
	v_exp_f32_e32 v199, v199
	v_mul_f32_e32 v191, 0xbfb8aa3b, v191
	v_exp_f32_e32 v191, v191
	v_lshlrev_b32_e32 v212, 16, v210
	v_and_b32_e32 v213, 0xffff0000, v210
	v_pk_mul_f32 v[216:217], v[134:135], v[216:217]
	v_add_f32_e32 v199, 1.0, v199
	v_pk_fma_f32 v[208:209], v[208:209], v[216:217], v[212:213]
	v_rcp_f32_e32 v212, v199
	v_add_f32_e32 v191, 1.0, v191
	v_lshlrev_b32_e32 v214, 16, v215
	v_and_b32_e32 v215, 0xffff0000, v215
	v_mul_f32_e32 v199, v42, v3
	v_rcp_f32_e32 v213, v191
	v_pk_mul_f32 v[190:191], v[190:191], v[214:215] op_sel_hi:[0,1]
	v_mul_f32_e32 v199, 0xbfb8aa3b, v199
	v_mul_f32_e32 v214, v43, v3
	v_exp_f32_e32 v199, v199
	v_mul_f32_e32 v214, 0xbfb8aa3b, v214
	v_exp_f32_e32 v214, v214
	v_lshlrev_b32_e32 v210, 16, v211
	v_and_b32_e32 v211, 0xffff0000, v211
	v_pk_mul_f32 v[190:191], v[136:137], v[190:191]
	v_add_f32_e32 v199, 1.0, v199
	v_pk_fma_f32 v[190:191], v[212:213], v[190:191], v[210:211]
	v_cvt_pk_bf16_f32 v210, v186, v187
	v_cvt_pk_bf16_f32 v211, v206, v207
	v_cvt_pk_bf16_f32 v212, v208, v209
	v_cvt_pk_bf16_f32 v213, v190, v191
	global_store_dwordx4 v[220:221], v[210:213], off offset:256
	s_waitcnt vmcnt(4)
	v_and_b32_e32 v215, 0xffff0000, v158
	v_lshl_add_u64 v[4:5], s[34:35], 0, v[4:5]
	v_rcp_f32_e32 v210, v199
	v_add_f32_e32 v199, 1.0, v214
	v_lshlrev_b32_e32 v214, 16, v158
	v_mul_f32_e32 v158, v44, v3
	v_lshlrev_b32_e32 v212, 16, v162
	v_and_b32_e32 v213, 0xffff0000, v162
	v_mul_f32_e32 v158, 0xbfb8aa3b, v158
	v_mul_f32_e32 v162, v45, v3
	v_exp_f32_e32 v158, v158
	v_mul_f32_e32 v162, 0xbfb8aa3b, v162
	v_rcp_f32_e32 v211, v199
	v_exp_f32_e32 v162, v162
	v_pk_mul_f32 v[214:215], v[198:199], v[214:215] op_sel_hi:[0,1]
	v_pk_mul_f32 v[146:147], v[146:147], v[214:215]
	v_add_f32_e32 v158, 1.0, v158
	v_pk_fma_f32 v[146:147], v[210:211], v[146:147], v[212:213]
	v_rcp_f32_e32 v210, v158
	v_add_f32_e32 v158, 1.0, v162
	v_rcp_f32_e32 v211, v158
	v_lshlrev_b32_e32 v158, 16, v159
	v_and_b32_e32 v159, 0xffff0000, v159
	v_pk_mul_f32 v[158:159], v[198:199], v[158:159] op_sel_hi:[0,1]
	v_pk_mul_f32 v[148:149], v[148:149], v[158:159]
	v_mul_f32_e32 v158, v38, v3
	v_mul_f32_e32 v159, v39, v3
	v_mul_f32_e32 v158, 0xbfb8aa3b, v158
	v_mul_f32_e32 v159, 0xbfb8aa3b, v159
	v_exp_f32_e32 v158, v158
	v_exp_f32_e32 v159, v159
	v_lshlrev_b32_e32 v162, 16, v163
	v_and_b32_e32 v163, 0xffff0000, v163
	v_pk_fma_f32 v[148:149], v[210:211], v[148:149], v[162:163]
	v_lshlrev_b32_e32 v162, 16, v164
	v_and_b32_e32 v163, 0xffff0000, v164
	v_lshlrev_b32_e32 v210, 16, v160
	v_and_b32_e32 v211, 0xffff0000, v160
	v_mul_f32_e32 v160, v40, v3
	v_mul_f32_e32 v164, v41, v3
	v_add_f32_e32 v158, 1.0, v158
	v_add_f32_e32 v159, 1.0, v159
	v_mul_f32_e32 v160, 0xbfb8aa3b, v160
	v_mul_f32_e32 v164, 0xbfb8aa3b, v164
	v_rcp_f32_e32 v158, v158
	v_rcp_f32_e32 v159, v159
	v_exp_f32_e32 v160, v160
	v_exp_f32_e32 v164, v164
	v_pk_mul_f32 v[210:211], v[198:199], v[210:211] op_sel_hi:[0,1]
	v_pk_mul_f32 v[142:143], v[142:143], v[210:211]
	v_lshl_add_u64 v[4:5], v[4:5], 0, v[184:185]
	v_pk_fma_f32 v[158:159], v[158:159], v[142:143], v[162:163]
	v_add_f32_e32 v142, 1.0, v160
	v_add_f32_e32 v143, 1.0, v164
	v_rcp_f32_e32 v142, v142
	v_rcp_f32_e32 v143, v143
	v_lshlrev_b32_e32 v160, 16, v161
	v_and_b32_e32 v161, 0xffff0000, v161
	v_pk_mul_f32 v[160:161], v[198:199], v[160:161] op_sel_hi:[0,1]
	v_lshlrev_b32_e32 v162, 16, v165
	v_and_b32_e32 v163, 0xffff0000, v165
	v_pk_mul_f32 v[144:145], v[144:145], v[160:161]
	s_waitcnt vmcnt(2)
	v_lshlrev_b32_e32 v164, 16, v150
	v_pk_fma_f32 v[160:161], v[142:143], v[144:145], v[162:163]
	v_mul_f32_e32 v142, v10, v3
	v_mul_f32_e32 v142, 0xbfb8aa3b, v142
	v_exp_f32_e32 v143, v142
	v_mul_f32_e32 v142, v11, v3
	v_mul_f32_e32 v142, 0xbfb8aa3b, v142
	v_exp_f32_e32 v145, v142
	v_add_f32_e32 v143, 1.0, v143
	v_rcp_f32_e32 v144, v143
	v_and_b32_e32 v165, 0xffff0000, v150
	v_add_f32_e32 v143, 1.0, v145
	v_rcp_f32_e32 v145, v143
	v_mul_f32_e32 v143, v12, v3
	v_mul_f32_e32 v143, 0xbfb8aa3b, v143
	v_mul_f32_e32 v150, v13, v3
	v_exp_f32_e32 v143, v143
	v_mul_f32_e32 v150, 0xbfb8aa3b, v150
	v_exp_f32_e32 v150, v150
	v_pk_mul_f32 v[164:165], v[198:199], v[164:165] op_sel_hi:[0,1]
	v_lshlrev_b32_e32 v162, 16, v154
	v_and_b32_e32 v163, 0xffff0000, v154
	v_pk_mul_f32 v[138:139], v[138:139], v[164:165]
	v_add_f32_e32 v143, 1.0, v143
	v_pk_fma_f32 v[138:139], v[144:145], v[138:139], v[162:163]
	v_rcp_f32_e32 v144, v143
	v_add_f32_e32 v143, 1.0, v150
	v_lshlrev_b32_e32 v150, 16, v151
	v_and_b32_e32 v151, 0xffff0000, v151
	v_rcp_f32_e32 v145, v143
	v_pk_mul_f32 v[150:151], v[198:199], v[150:151] op_sel_hi:[0,1]
	v_mul_f32_e32 v143, v6, v3
	v_pk_mul_f32 v[140:141], v[140:141], v[150:151]
	v_mul_f32_e32 v143, 0xbfb8aa3b, v143
	v_mul_f32_e32 v150, v7, v3
	v_exp_f32_e32 v143, v143
	v_mul_f32_e32 v150, 0xbfb8aa3b, v150
	v_exp_f32_e32 v150, v150
	v_lshlrev_b32_e32 v154, 16, v155
	v_and_b32_e32 v155, 0xffff0000, v155
	v_add_f32_e32 v143, 1.0, v143
	v_pk_fma_f32 v[140:141], v[144:145], v[140:141], v[154:155]
	v_rcp_f32_e32 v144, v143
	v_add_f32_e32 v143, 1.0, v150
	v_rcp_f32_e32 v145, v143
	v_mul_f32_e32 v143, v8, v3
	v_mul_f32_e32 v3, v9, v3
	v_mul_f32_e32 v143, 0xbfb8aa3b, v143
	v_mul_f32_e32 v3, 0xbfb8aa3b, v3
	v_cvt_pk_bf16_f32 v142, v146, v147
	v_lshlrev_b32_e32 v154, 16, v152
	v_and_b32_e32 v155, 0xffff0000, v152
	v_exp_f32_e32 v143, v143
	v_exp_f32_e32 v3, v3
	v_mov_b32_e32 v163, v146
	v_mov_b32_e32 v146, v189
	v_pk_mul_f32 v[154:155], v[198:199], v[154:155] op_sel_hi:[0,1]
	v_mov_b32_e32 v162, v188
	v_pk_mul_f32 v[146:147], v[146:147], v[146:147]
	v_lshlrev_b32_e32 v150, 16, v156
	v_and_b32_e32 v151, 0xffff0000, v156
	v_pk_mul_f32 v[134:135], v[134:135], v[154:155]
	v_mov_b32_e32 v156, v201
	v_mov_b32_e32 v201, v148
	v_pk_fma_f32 v[146:147], v[162:163], v[162:163], v[146:147]
	v_pk_fma_f32 v[144:145], v[144:145], v[134:135], v[150:151]
	v_lshlrev_b32_e32 v150, 16, v157
	v_and_b32_e32 v151, 0xffff0000, v157
	v_mov_b32_e32 v157, v149
	v_pk_fma_f32 v[146:147], v[200:201], v[200:201], v[146:147]
	v_add_f32_e32 v134, 1.0, v143
	v_add_f32_e32 v3, 1.0, v3
	v_lshlrev_b32_e32 v152, 16, v153
	v_and_b32_e32 v153, 0xffff0000, v153
	v_mov_b32_e32 v154, v203
	v_mov_b32_e32 v203, v158
	v_pk_fma_f32 v[146:147], v[156:157], v[156:157], v[146:147]
	v_rcp_f32_e32 v134, v134
	v_rcp_f32_e32 v135, v3
	v_pk_mul_f32 v[152:153], v[198:199], v[152:153] op_sel_hi:[0,1]
	v_mov_b32_e32 v155, v159
	v_pk_fma_f32 v[146:147], v[202:203], v[202:203], v[146:147]
	v_pk_mul_f32 v[136:137], v[136:137], v[152:153]
	v_mov_b32_e32 v152, v205
	v_mov_b32_e32 v205, v160
	v_pk_fma_f32 v[146:147], v[154:155], v[154:155], v[146:147]
	v_mov_b32_e32 v153, v161
	v_pk_fma_f32 v[146:147], v[204:205], v[204:205], v[146:147]
	v_pk_fma_f32 v[150:151], v[134:135], v[136:137], v[150:151]
	v_pk_fma_f32 v[146:147], v[152:153], v[152:153], v[146:147]
	v_mov_b32_e32 v152, v186
	v_mov_b32_e32 v153, v138
	v_cvt_pk_bf16_f32 v134, v138, v139
	v_pk_fma_f32 v[146:147], v[152:153], v[152:153], v[146:147]
	v_mov_b32_e32 v138, v187
	v_pk_fma_f32 v[138:139], v[138:139], v[138:139], v[146:147]
	v_mov_b32_e32 v146, v206
	v_mov_b32_e32 v147, v140
	v_cvt_pk_bf16_f32 v135, v140, v141
	v_pk_fma_f32 v[138:139], v[146:147], v[146:147], v[138:139]
	v_mov_b32_e32 v140, v207
	v_pk_fma_f32 v[138:139], v[140:141], v[140:141], v[138:139]
	v_mov_b32_e32 v140, v208
	v_mov_b32_e32 v141, v144
	v_cvt_pk_bf16_f32 v136, v144, v145
	v_pk_fma_f32 v[138:139], v[140:141], v[140:141], v[138:139]
	v_mov_b32_e32 v144, v209
	v_pk_fma_f32 v[138:139], v[144:145], v[144:145], v[138:139]
	v_mov_b32_e32 v140, v190
	v_mov_b32_e32 v141, v150
	v_cvt_pk_bf16_f32 v137, v150, v151
	v_pk_fma_f32 v[138:139], v[140:141], v[140:141], v[138:139]
	v_mov_b32_e32 v150, v191
	v_pk_fma_f32 v[138:139], v[150:151], v[150:151], v[138:139]
	ds_bpermute_b32 v140, v235, v138
	ds_bpermute_b32 v141, v235, v139
	v_cvt_pk_bf16_f32 v143, v148, v149
	v_cvt_pk_bf16_f32 v144, v158, v159
	v_cvt_pk_bf16_f32 v145, v160, v161
	global_store_dwordx4 v[4:5], v[142:145], off
	global_store_dwordx4 v[4:5], v[134:137], off offset:256
	s_waitcnt lgkmcnt(0)
	v_pk_add_f32 v[138:139], v[138:139], v[140:141]
	ds_bpermute_b32 v140, v224, v138
	ds_bpermute_b32 v141, v224, v139
	s_and_b64 vcc, exec, s[4:5]
	s_waitcnt lgkmcnt(0)
	v_pk_add_f32 v[134:135], v[138:139], v[140:141]
	s_cbranch_vccz .LBB0_965
	s_and_saveexec_b64 s[0:1], s[2:3]
	s_cbranch_execz .LBB0_947
	s_ashr_i32 s49, s48, 31
	v_lshl_add_u64 v[4:5], s[48:49], 2, v[174:175]
	global_atomic_add_f32 v[4:5], v192, off
	global_atomic_add_f32 v[4:5], v193, off offset:64
	global_atomic_add_f32 v[4:5], v194, off offset:128
	global_atomic_add_f32 v[4:5], v195, off offset:192
	global_atomic_add_f32 v[4:5], v196, off offset:512
	global_atomic_add_f32 v[4:5], v197, off offset:576
	global_atomic_add_f32 v[4:5], v134, off offset:640
	global_atomic_add_f32 v[4:5], v135, off offset:704
	s_branch .LBB0_947

.LBB0_1035:
	s_ashr_i32 s21, s20, 31
	s_lshl_b64 s[24:25], s[20:21], 20
	s_add_u32 s24, s31, s24
	v_mov_b32_e32 v129, 0
	s_addc_u32 s25, s34, s25
	s_and_b64 vcc, exec, s[2:3]
	v_mov_b32_e32 v128, v129
	v_mov_b32_e32 v127, v129
	v_mov_b32_e32 v126, v129
	v_mov_b32_e32 v125, v129
	v_mov_b32_e32 v124, v129
	v_mov_b32_e32 v123, v129
	v_mov_b32_e32 v122, v129
	v_mov_b32_e32 v113, v129
	v_mov_b32_e32 v112, v129
	v_mov_b32_e32 v111, v129
	v_mov_b32_e32 v110, v129
	v_mov_b32_e32 v109, v129
	v_mov_b32_e32 v108, v129
	v_mov_b32_e32 v107, v129
	v_mov_b32_e32 v106, v129
	v_mov_b32_e32 v97, v129
	v_mov_b32_e32 v96, v129
	v_mov_b32_e32 v95, v129
	v_mov_b32_e32 v94, v129
	v_mov_b32_e32 v93, v129
	v_mov_b32_e32 v92, v129
	v_mov_b32_e32 v91, v129
	v_mov_b32_e32 v90, v129
	v_mov_b32_e32 v81, v129
	v_mov_b32_e32 v80, v129
	v_mov_b32_e32 v79, v129
	v_mov_b32_e32 v78, v129
	v_mov_b32_e32 v77, v129
	v_mov_b32_e32 v76, v129
	v_mov_b32_e32 v75, v129
	v_mov_b32_e32 v74, v129
	v_mov_b32_e32 v121, v129
	v_mov_b32_e32 v120, v129
	v_mov_b32_e32 v119, v129
	v_mov_b32_e32 v118, v129
	v_mov_b32_e32 v117, v129
	v_mov_b32_e32 v116, v129
	v_mov_b32_e32 v115, v129
	v_mov_b32_e32 v114, v129
	v_mov_b32_e32 v105, v129
	v_mov_b32_e32 v104, v129
	v_mov_b32_e32 v103, v129
	v_mov_b32_e32 v102, v129
	v_mov_b32_e32 v101, v129
	v_mov_b32_e32 v100, v129
	v_mov_b32_e32 v99, v129
	v_mov_b32_e32 v98, v129
	v_mov_b32_e32 v89, v129
	v_mov_b32_e32 v88, v129
	v_mov_b32_e32 v87, v129
	v_mov_b32_e32 v86, v129
	v_mov_b32_e32 v85, v129
	v_mov_b32_e32 v84, v129
	v_mov_b32_e32 v83, v129
	v_mov_b32_e32 v82, v129
	v_mov_b32_e32 v73, v129
	v_mov_b32_e32 v72, v129
	v_mov_b32_e32 v71, v129
	v_mov_b32_e32 v70, v129
	v_mov_b32_e32 v69, v129
	v_mov_b32_e32 v68, v129
	v_mov_b32_e32 v67, v129
	v_mov_b32_e32 v66, v129
	v_mov_b32_e32 v65, v129
	v_mov_b32_e32 v64, v129
	v_mov_b32_e32 v63, v129
	v_mov_b32_e32 v62, v129
	v_mov_b32_e32 v61, v129
	v_mov_b32_e32 v60, v129
	v_mov_b32_e32 v59, v129
	v_mov_b32_e32 v58, v129
	v_mov_b32_e32 v49, v129
	v_mov_b32_e32 v48, v129
	v_mov_b32_e32 v47, v129
	v_mov_b32_e32 v46, v129
	v_mov_b32_e32 v45, v129
	v_mov_b32_e32 v44, v129
	v_mov_b32_e32 v43, v129
	v_mov_b32_e32 v42, v129
	v_mov_b32_e32 v33, v129
	v_mov_b32_e32 v32, v129
	v_mov_b32_e32 v31, v129
	v_mov_b32_e32 v30, v129
	v_mov_b32_e32 v29, v129
	v_mov_b32_e32 v28, v129
	v_mov_b32_e32 v27, v129
	v_mov_b32_e32 v26, v129
	v_mov_b32_e32 v17, v129
	v_mov_b32_e32 v16, v129
	v_mov_b32_e32 v15, v129
	v_mov_b32_e32 v14, v129
	v_mov_b32_e32 v13, v129
	v_mov_b32_e32 v12, v129
	v_mov_b32_e32 v11, v129
	v_mov_b32_e32 v10, v129
	v_mov_b32_e32 v57, v129
	v_mov_b32_e32 v56, v129
	v_mov_b32_e32 v55, v129
	v_mov_b32_e32 v54, v129
	v_mov_b32_e32 v53, v129
	v_mov_b32_e32 v52, v129
	v_mov_b32_e32 v51, v129
	v_mov_b32_e32 v50, v129
	v_mov_b32_e32 v41, v129
	v_mov_b32_e32 v40, v129
	v_mov_b32_e32 v39, v129
	v_mov_b32_e32 v38, v129
	v_mov_b32_e32 v37, v129
	v_mov_b32_e32 v36, v129
	v_mov_b32_e32 v35, v129
	v_mov_b32_e32 v34, v129
	v_mov_b32_e32 v25, v129
	v_mov_b32_e32 v24, v129
	v_mov_b32_e32 v23, v129
	v_mov_b32_e32 v22, v129
	v_mov_b32_e32 v21, v129
	v_mov_b32_e32 v20, v129
	v_mov_b32_e32 v19, v129
	v_mov_b32_e32 v18, v129
	v_mov_b32_e32 v9, v129
	v_mov_b32_e32 v8, v129
	v_mov_b32_e32 v7, v129
	v_mov_b32_e32 v6, v129
	v_mov_b32_e32 v5, v129
	v_mov_b32_e32 v4, v129
	v_mov_b32_e32 v3, v129
	v_mov_b32_e32 v2, v129
	s_cbranch_vccnz .LBB0_1038
	s_and_b64 s[6:7], s[6:7], exec
	s_cselect_b32 s1, s25, s29
	s_cselect_b32 s21, s24, s28
	s_add_u32 s6, s28, 0x80080
	s_addc_u32 s7, s29, 0
	s_add_u32 s33, s26, 0x100
	v_mov_b32_e32 v2, 0
	s_addc_u32 s56, s27, 0
	s_mov_b32 s26, 0
	v_mov_b32_e32 v3, v2
	v_mov_b32_e32 v4, v2
	v_mov_b32_e32 v5, v2
	v_mov_b32_e32 v6, v2
	v_mov_b32_e32 v7, v2
	v_mov_b32_e32 v8, v2
	v_mov_b32_e32 v9, v2
	v_mov_b32_e32 v18, v2
	v_mov_b32_e32 v19, v2
	v_mov_b32_e32 v20, v2
	v_mov_b32_e32 v21, v2
	v_mov_b32_e32 v22, v2
	v_mov_b32_e32 v23, v2
	v_mov_b32_e32 v24, v2
	v_mov_b32_e32 v25, v2
	v_mov_b32_e32 v34, v2
	v_mov_b32_e32 v35, v2
	v_mov_b32_e32 v36, v2
	v_mov_b32_e32 v37, v2
	v_mov_b32_e32 v38, v2
	v_mov_b32_e32 v39, v2
	v_mov_b32_e32 v40, v2
	v_mov_b32_e32 v41, v2
	v_mov_b32_e32 v50, v2
	v_mov_b32_e32 v51, v2
	v_mov_b32_e32 v52, v2
	v_mov_b32_e32 v53, v2
	v_mov_b32_e32 v54, v2
	v_mov_b32_e32 v55, v2
	v_mov_b32_e32 v56, v2
	v_mov_b32_e32 v57, v2
	v_mov_b32_e32 v10, v2
	v_mov_b32_e32 v11, v2
	v_mov_b32_e32 v12, v2
	v_mov_b32_e32 v13, v2
	v_mov_b32_e32 v14, v2
	v_mov_b32_e32 v15, v2
	v_mov_b32_e32 v16, v2
	v_mov_b32_e32 v17, v2
	v_mov_b32_e32 v26, v2
	v_mov_b32_e32 v27, v2
	v_mov_b32_e32 v28, v2
	v_mov_b32_e32 v29, v2
	v_mov_b32_e32 v30, v2
	v_mov_b32_e32 v31, v2
	v_mov_b32_e32 v32, v2
	v_mov_b32_e32 v33, v2
	v_mov_b32_e32 v42, v2
	v_mov_b32_e32 v43, v2
	v_mov_b32_e32 v44, v2
	v_mov_b32_e32 v45, v2
	v_mov_b32_e32 v46, v2
	v_mov_b32_e32 v47, v2
	v_mov_b32_e32 v48, v2
	v_mov_b32_e32 v49, v2
	v_mov_b32_e32 v58, v2
	v_mov_b32_e32 v59, v2
	v_mov_b32_e32 v60, v2
	v_mov_b32_e32 v61, v2
	v_mov_b32_e32 v62, v2
	v_mov_b32_e32 v63, v2
	v_mov_b32_e32 v64, v2
	v_mov_b32_e32 v65, v2
	v_mov_b32_e32 v66, v2
	v_mov_b32_e32 v67, v2
	v_mov_b32_e32 v68, v2
	v_mov_b32_e32 v69, v2
	v_mov_b32_e32 v70, v2
	v_mov_b32_e32 v71, v2
	v_mov_b32_e32 v72, v2
	v_mov_b32_e32 v73, v2
	v_mov_b32_e32 v82, v2
	v_mov_b32_e32 v83, v2
	v_mov_b32_e32 v84, v2
	v_mov_b32_e32 v85, v2
	v_mov_b32_e32 v86, v2
	v_mov_b32_e32 v87, v2
	v_mov_b32_e32 v88, v2
	v_mov_b32_e32 v89, v2
	v_mov_b32_e32 v98, v2
	v_mov_b32_e32 v99, v2
	v_mov_b32_e32 v100, v2
	v_mov_b32_e32 v101, v2
	v_mov_b32_e32 v102, v2
	v_mov_b32_e32 v103, v2
	v_mov_b32_e32 v104, v2
	v_mov_b32_e32 v105, v2
	v_mov_b32_e32 v114, v2
	v_mov_b32_e32 v115, v2
	v_mov_b32_e32 v116, v2
	v_mov_b32_e32 v117, v2
	v_mov_b32_e32 v118, v2
	v_mov_b32_e32 v119, v2
	v_mov_b32_e32 v120, v2
	v_mov_b32_e32 v121, v2
	v_mov_b32_e32 v74, v2
	v_mov_b32_e32 v75, v2
	v_mov_b32_e32 v76, v2
	v_mov_b32_e32 v77, v2
	v_mov_b32_e32 v78, v2
	v_mov_b32_e32 v79, v2
	v_mov_b32_e32 v80, v2
	v_mov_b32_e32 v81, v2
	v_mov_b32_e32 v90, v2
	v_mov_b32_e32 v91, v2
	v_mov_b32_e32 v92, v2
	v_mov_b32_e32 v93, v2
	v_mov_b32_e32 v94, v2
	v_mov_b32_e32 v95, v2
	v_mov_b32_e32 v96, v2
	v_mov_b32_e32 v97, v2
	v_mov_b32_e32 v106, v2
	v_mov_b32_e32 v107, v2
	v_mov_b32_e32 v108, v2
	v_mov_b32_e32 v109, v2
	v_mov_b32_e32 v110, v2
	v_mov_b32_e32 v111, v2
	v_mov_b32_e32 v112, v2
	v_mov_b32_e32 v113, v2
	v_mov_b32_e32 v122, v2
	v_mov_b32_e32 v123, v2
	v_mov_b32_e32 v124, v2
	v_mov_b32_e32 v125, v2
	v_mov_b32_e32 v126, v2
	v_mov_b32_e32 v127, v2
	v_mov_b32_e32 v128, v2
	v_mov_b32_e32 v129, v2
	v_lshl_add_u32 v238, s0, 8, v158
	v_mov_b32_e32 v239, 0
	v_lshl_add_u64 v[238:239], v[238:239], 2, s[10:11]
	global_load_dword v230, v[238:239], off
	global_load_dword v231, v[238:239], off offset:64
	global_load_dword v232, v[238:239], off offset:128
	global_load_dword v233, v[238:239], off offset:192
	global_load_dword v234, v[238:239], off offset:512
	global_load_dword v235, v[238:239], off offset:576
	global_load_dword v236, v[238:239], off offset:640
	global_load_dword v237, v[238:239], off offset:704
	ds_read_b128 v[146:149], v161
	ds_read_b128 v[150:153], v161 offset:1024
	ds_read_b128 v[154:157], v161 offset:2048
	ds_read_b128 v[166:169], v161 offset:3072
.LBB0_1037:
	s_add_i32 s57, s26, 2
	s_add_u32 s28, s6, 0xfff80080
	s_addc_u32 s27, s7, -1
	s_cmp_eq_u32 s46, s26
	s_cselect_b32 s26, s21, s28
	s_cselect_b32 s27, s1, s27
	s_cselect_b32 s29, s23, s56
	s_cselect_b32 s28, s22, s33
	v_lshl_add_u64 v[202:203], s[6:7], 0, v[138:139]
	s_add_i32 m0, s38, 0xc000
	ds_read_b128 v[170:173], v162
	ds_read_b128 v[174:177], v162 offset:1024
	ds_read_b128 v[178:181], v162 offset:2048
	ds_read_b128 v[182:185], v162 offset:3072
	ds_read_b128 v[186:189], v162 offset:4096
	ds_read_b128 v[190:193], v162 offset:5120
	ds_read_b128 v[194:197], v162 offset:6144
	ds_read_b128 v[198:201], v162 offset:7168
	global_load_lds_dwordx4 v[202:203], off
	v_lshl_add_u64 v[202:203], s[6:7], 0, v[140:141]
	s_add_i32 m0, s38, 0xe000
	s_nop 0
	global_load_lds_dwordx4 v[202:203], off
	s_waitcnt lgkmcnt(8)
	s_barrier
	s_waitcnt lgkmcnt(0)
	s_waitcnt lgkmcnt(0)
	v_mfma_f32_16x16x32_bf16 v[126:129], v[146:149], v[170:173], v[126:129]
	v_mfma_f32_16x16x32_bf16 v[122:125], v[154:157], v[170:173], v[122:125]
	v_mfma_f32_16x16x32_bf16 v[110:113], v[146:149], v[178:181], v[110:113]
	v_mfma_f32_16x16x32_bf16 v[106:109], v[154:157], v[178:181], v[106:109]
	v_mfma_f32_16x16x32_bf16 v[94:97], v[146:149], v[186:189], v[94:97]
	v_mfma_f32_16x16x32_bf16 v[90:93], v[154:157], v[186:189], v[90:93]
	v_mfma_f32_16x16x32_bf16 v[78:81], v[146:149], v[194:197], v[78:81]
	v_mfma_f32_16x16x32_bf16 v[74:77], v[154:157], v[194:197], v[74:77]
	v_mfma_f32_16x16x32_bf16 v[126:129], v[150:153], v[174:177], v[126:129]
	v_mfma_f32_16x16x32_bf16 v[122:125], v[166:169], v[174:177], v[122:125]
	v_mfma_f32_16x16x32_bf16 v[110:113], v[150:153], v[182:185], v[110:113]
	v_mfma_f32_16x16x32_bf16 v[106:109], v[166:169], v[182:185], v[106:109]
	v_mfma_f32_16x16x32_bf16 v[94:97], v[150:153], v[190:193], v[94:97]
	v_mfma_f32_16x16x32_bf16 v[90:93], v[166:169], v[190:193], v[90:93]
	v_mfma_f32_16x16x32_bf16 v[78:81], v[150:153], v[198:201], v[78:81]
	v_mfma_f32_16x16x32_bf16 v[74:77], v[166:169], v[198:201], v[74:77]
	s_barrier
	s_add_i32 s58, s50, s37
	v_lshl_add_u64 v[218:219], s[28:29], 0, v[132:133]
	s_mov_b32 m0, s58
	ds_read_b128 v[202:205], v163
	ds_read_b128 v[206:209], v163 offset:1024
	ds_read_b128 v[210:213], v163 offset:2048
	ds_read_b128 v[214:217], v163 offset:3072
	global_load_lds_dwordx4 v[218:219], off
	v_lshl_add_u64 v[220:221], s[28:29], 0, v[136:137]
	s_add_i32 m0, s58, 0x2000
	s_nop 0
	global_load_lds_dwordx4 v[220:221], off
	s_barrier
	s_waitcnt lgkmcnt(0)
	s_waitcnt lgkmcnt(0)
	v_mfma_f32_16x16x32_bf16 v[118:121], v[202:205], v[170:173], v[118:121]
	v_mfma_f32_16x16x32_bf16 v[114:117], v[210:213], v[170:173], v[114:117]
	v_mfma_f32_16x16x32_bf16 v[102:105], v[202:205], v[178:181], v[102:105]
	v_mfma_f32_16x16x32_bf16 v[98:101], v[210:213], v[178:181], v[98:101]
	v_mfma_f32_16x16x32_bf16 v[86:89], v[202:205], v[186:189], v[86:89]
	v_mfma_f32_16x16x32_bf16 v[82:85], v[210:213], v[186:189], v[82:85]
	v_mfma_f32_16x16x32_bf16 v[70:73], v[202:205], v[194:197], v[70:73]
	v_mfma_f32_16x16x32_bf16 v[66:69], v[210:213], v[194:197], v[66:69]
	v_mfma_f32_16x16x32_bf16 v[118:121], v[206:209], v[174:177], v[118:121]
	v_mfma_f32_16x16x32_bf16 v[114:117], v[214:217], v[174:177], v[114:117]
	v_mfma_f32_16x16x32_bf16 v[102:105], v[206:209], v[182:185], v[102:105]
	v_mfma_f32_16x16x32_bf16 v[98:101], v[214:217], v[182:185], v[98:101]
	v_mfma_f32_16x16x32_bf16 v[86:89], v[206:209], v[190:193], v[86:89]
	v_mfma_f32_16x16x32_bf16 v[82:85], v[214:217], v[190:193], v[82:85]
	v_mfma_f32_16x16x32_bf16 v[70:73], v[206:209], v[198:201], v[70:73]
	v_mfma_f32_16x16x32_bf16 v[66:69], v[214:217], v[198:201], v[66:69]
	s_mov_b32 m0, s38
	v_lshl_add_u64 v[222:223], s[26:27], 0, v[130:131]
	s_barrier
	ds_read_b128 v[170:173], v162 offset:16384
	ds_read_b128 v[174:177], v162 offset:17408
	ds_read_b128 v[178:181], v162 offset:18432
	ds_read_b128 v[182:185], v162 offset:19456
	ds_read_b128 v[186:189], v162 offset:20480
	ds_read_b128 v[190:193], v162 offset:21504
	ds_read_b128 v[194:197], v162 offset:22528
	ds_read_b128 v[198:201], v162 offset:23552
	global_load_lds_dwordx4 v[222:223], off
	v_lshl_add_u64 v[224:225], s[26:27], 0, v[134:135]
	s_mov_b32 m0, s39
	s_nop 0
	global_load_lds_dwordx4 v[224:225], off
	s_waitcnt vmcnt(10)
	s_barrier
	s_waitcnt lgkmcnt(0)
	s_waitcnt lgkmcnt(0)
	v_mfma_f32_16x16x32_bf16 v[62:65], v[146:149], v[170:173], v[62:65]
	v_mfma_f32_16x16x32_bf16 v[58:61], v[154:157], v[170:173], v[58:61]
	v_mfma_f32_16x16x32_bf16 v[46:49], v[146:149], v[178:181], v[46:49]
	v_mfma_f32_16x16x32_bf16 v[42:45], v[154:157], v[178:181], v[42:45]
	v_mfma_f32_16x16x32_bf16 v[30:33], v[146:149], v[186:189], v[30:33]
	v_mfma_f32_16x16x32_bf16 v[26:29], v[154:157], v[186:189], v[26:29]
	v_mfma_f32_16x16x32_bf16 v[14:17], v[146:149], v[194:197], v[14:17]
	v_mfma_f32_16x16x32_bf16 v[10:13], v[154:157], v[194:197], v[10:13]
	v_mfma_f32_16x16x32_bf16 v[62:65], v[150:153], v[174:177], v[62:65]
	v_mfma_f32_16x16x32_bf16 v[58:61], v[166:169], v[174:177], v[58:61]
	v_mfma_f32_16x16x32_bf16 v[46:49], v[150:153], v[182:185], v[46:49]
	v_mfma_f32_16x16x32_bf16 v[42:45], v[166:169], v[182:185], v[42:45]
	v_mfma_f32_16x16x32_bf16 v[30:33], v[150:153], v[190:193], v[30:33]
	v_mfma_f32_16x16x32_bf16 v[26:29], v[166:169], v[190:193], v[26:29]
	v_mfma_f32_16x16x32_bf16 v[14:17], v[150:153], v[198:201], v[14:17]
	v_mfma_f32_16x16x32_bf16 v[10:13], v[166:169], v[198:201], v[10:13]
	s_barrier
	v_add_u32_e32 v165, 0x18000, v159
	ds_read_b128 v[146:149], v165
	ds_read_b128 v[150:153], v165 offset:1024
	ds_read_b128 v[154:157], v165 offset:2048
	ds_read_b128 v[166:169], v165 offset:3072
	s_add_u32 s28, s28, s12
	s_addc_u32 s29, s29, s13
	s_add_i32 s58, s51, s37
	v_lshl_add_u64 v[226:227], s[28:29], 0, v[132:133]
	s_mov_b32 m0, s58
	v_lshl_add_u64 v[228:229], s[28:29], 0, v[136:137]
	global_load_lds_dwordx4 v[226:227], off
	s_add_i32 m0, s58, 0x2000
	s_nop 0
	global_load_lds_dwordx4 v[228:229], off
	s_waitcnt vmcnt(6)
	s_barrier
	v_mfma_f32_16x16x32_bf16 v[54:57], v[202:205], v[170:173], v[54:57]
	v_mfma_f32_16x16x32_bf16 v[50:53], v[210:213], v[170:173], v[50:53]
	v_mfma_f32_16x16x32_bf16 v[38:41], v[202:205], v[178:181], v[38:41]
	v_mfma_f32_16x16x32_bf16 v[34:37], v[210:213], v[178:181], v[34:37]
	v_mfma_f32_16x16x32_bf16 v[22:25], v[202:205], v[186:189], v[22:25]
	v_mfma_f32_16x16x32_bf16 v[18:21], v[210:213], v[186:189], v[18:21]
	v_mfma_f32_16x16x32_bf16 v[6:9], v[202:205], v[194:197], v[6:9]
	v_mfma_f32_16x16x32_bf16 v[2:5], v[210:213], v[194:197], v[2:5]
	v_mfma_f32_16x16x32_bf16 v[54:57], v[206:209], v[174:177], v[54:57]
	v_mfma_f32_16x16x32_bf16 v[50:53], v[214:217], v[174:177], v[50:53]
	v_mfma_f32_16x16x32_bf16 v[38:41], v[206:209], v[182:185], v[38:41]
	v_mfma_f32_16x16x32_bf16 v[34:37], v[214:217], v[182:185], v[34:37]
	v_mfma_f32_16x16x32_bf16 v[22:25], v[206:209], v[190:193], v[22:25]
	v_mfma_f32_16x16x32_bf16 v[18:21], v[214:217], v[190:193], v[18:21]
	v_mfma_f32_16x16x32_bf16 v[6:9], v[206:209], v[198:201], v[6:9]
	v_mfma_f32_16x16x32_bf16 v[2:5], v[214:217], v[198:201], v[2:5]
	s_add_i32 s28, 0, 0x18000
	s_barrier
	s_add_u32 s26, s26, 0x80000
	s_addc_u32 s27, s27, 0
	s_mov_b32 m0, s40
	v_lshl_add_u64 v[202:203], s[26:27], 0, v[130:131]
	ds_read_b128 v[170:173], v162 offset:32768
	ds_read_b128 v[174:177], v162 offset:33792
	ds_read_b128 v[178:181], v162 offset:34816
	ds_read_b128 v[182:185], v162 offset:35840
	ds_read_b128 v[186:189], v162 offset:36864
	ds_read_b128 v[190:193], v162 offset:37888
	ds_read_b128 v[194:197], v162 offset:38912
	ds_read_b128 v[198:201], v162 offset:39936
	global_load_lds_dwordx4 v[202:203], off
	v_lshl_add_u64 v[202:203], s[26:27], 0, v[134:135]
	s_mov_b32 m0, s41
	s_nop 0
	global_load_lds_dwordx4 v[202:203], off
	s_waitcnt lgkmcnt(8)
	s_barrier
	s_waitcnt lgkmcnt(0)
	s_waitcnt lgkmcnt(0)
	v_mfma_f32_16x16x32_bf16 v[126:129], v[146:149], v[170:173], v[126:129]
	v_mfma_f32_16x16x32_bf16 v[122:125], v[154:157], v[170:173], v[122:125]
	v_mfma_f32_16x16x32_bf16 v[110:113], v[146:149], v[178:181], v[110:113]
	v_mfma_f32_16x16x32_bf16 v[106:109], v[154:157], v[178:181], v[106:109]
	v_mfma_f32_16x16x32_bf16 v[94:97], v[146:149], v[186:189], v[94:97]
	v_mfma_f32_16x16x32_bf16 v[90:93], v[154:157], v[186:189], v[90:93]
	v_mfma_f32_16x16x32_bf16 v[78:81], v[146:149], v[194:197], v[78:81]
	v_mfma_f32_16x16x32_bf16 v[74:77], v[154:157], v[194:197], v[74:77]
	v_mfma_f32_16x16x32_bf16 v[126:129], v[150:153], v[174:177], v[126:129]
	v_mfma_f32_16x16x32_bf16 v[122:125], v[166:169], v[174:177], v[122:125]
	v_mfma_f32_16x16x32_bf16 v[110:113], v[150:153], v[182:185], v[110:113]
	v_mfma_f32_16x16x32_bf16 v[106:109], v[166:169], v[182:185], v[106:109]
	v_mfma_f32_16x16x32_bf16 v[94:97], v[150:153], v[190:193], v[94:97]
	v_mfma_f32_16x16x32_bf16 v[90:93], v[166:169], v[190:193], v[90:93]
	v_mfma_f32_16x16x32_bf16 v[78:81], v[150:153], v[198:201], v[78:81]
	v_mfma_f32_16x16x32_bf16 v[74:77], v[166:169], v[198:201], v[74:77]
	s_barrier
	s_add_i32 s26, 0, 0x1c000
	s_add_i32 s27, s28, s37
	v_add_u32_e32 v165, s26, v159
	v_lshl_add_u64 v[218:219], v[218:219], 0, s[18:19]
	s_mov_b32 m0, s27
	ds_read_b128 v[202:205], v165
	ds_read_b128 v[206:209], v165 offset:1024
	ds_read_b128 v[210:213], v165 offset:2048
	ds_read_b128 v[214:217], v165 offset:3072
	global_load_lds_dwordx4 v[218:219], off
	v_lshl_add_u64 v[218:219], v[220:221], 0, s[18:19]
	s_add_i32 m0, s27, 0x2000
	s_nop 0
	global_load_lds_dwordx4 v[218:219], off
	s_barrier
	s_waitcnt lgkmcnt(0)
	s_waitcnt lgkmcnt(0)
	v_mfma_f32_16x16x32_bf16 v[118:121], v[202:205], v[170:173], v[118:121]
	v_mfma_f32_16x16x32_bf16 v[114:117], v[210:213], v[170:173], v[114:117]
	v_mfma_f32_16x16x32_bf16 v[102:105], v[202:205], v[178:181], v[102:105]
	v_mfma_f32_16x16x32_bf16 v[98:101], v[210:213], v[178:181], v[98:101]
	v_mfma_f32_16x16x32_bf16 v[86:89], v[202:205], v[186:189], v[86:89]
	v_mfma_f32_16x16x32_bf16 v[82:85], v[210:213], v[186:189], v[82:85]
	v_mfma_f32_16x16x32_bf16 v[70:73], v[202:205], v[194:197], v[70:73]
	v_mfma_f32_16x16x32_bf16 v[66:69], v[210:213], v[194:197], v[66:69]
	v_mfma_f32_16x16x32_bf16 v[118:121], v[206:209], v[174:177], v[118:121]
	v_mfma_f32_16x16x32_bf16 v[114:117], v[214:217], v[174:177], v[114:117]
	v_mfma_f32_16x16x32_bf16 v[102:105], v[206:209], v[182:185], v[102:105]
	v_mfma_f32_16x16x32_bf16 v[98:101], v[214:217], v[182:185], v[98:101]
	v_mfma_f32_16x16x32_bf16 v[86:89], v[206:209], v[190:193], v[86:89]
	v_mfma_f32_16x16x32_bf16 v[82:85], v[214:217], v[190:193], v[82:85]
	v_mfma_f32_16x16x32_bf16 v[70:73], v[206:209], v[198:201], v[70:73]
	v_mfma_f32_16x16x32_bf16 v[66:69], v[214:217], v[198:201], v[66:69]
	s_mov_b32 m0, s43
	v_lshl_add_u64 v[218:219], v[222:223], 0, s[18:19]
	s_barrier
	ds_read_b128 v[170:173], v162 offset:49152
	ds_read_b128 v[174:177], v162 offset:50176
	ds_read_b128 v[178:181], v162 offset:51200
	ds_read_b128 v[182:185], v162 offset:52224
	ds_read_b128 v[186:189], v162 offset:53248
	ds_read_b128 v[190:193], v162 offset:54272
	ds_read_b128 v[194:197], v162 offset:55296
	ds_read_b128 v[198:201], v162 offset:56320
	global_load_lds_dwordx4 v[218:219], off
	v_lshl_add_u64 v[218:219], v[224:225], 0, s[18:19]
	s_mov_b32 m0, s44
	s_nop 0
	global_load_lds_dwordx4 v[218:219], off
	s_waitcnt vmcnt(10)
	s_barrier
	s_waitcnt lgkmcnt(0)
	s_waitcnt lgkmcnt(0)
	v_mfma_f32_16x16x32_bf16 v[62:65], v[146:149], v[170:173], v[62:65]
	v_mfma_f32_16x16x32_bf16 v[58:61], v[154:157], v[170:173], v[58:61]
	v_mfma_f32_16x16x32_bf16 v[46:49], v[146:149], v[178:181], v[46:49]
	v_mfma_f32_16x16x32_bf16 v[42:45], v[154:157], v[178:181], v[42:45]
	v_mfma_f32_16x16x32_bf16 v[30:33], v[146:149], v[186:189], v[30:33]
	v_mfma_f32_16x16x32_bf16 v[26:29], v[154:157], v[186:189], v[26:29]
	v_mfma_f32_16x16x32_bf16 v[14:17], v[146:149], v[194:197], v[14:17]
	v_mfma_f32_16x16x32_bf16 v[10:13], v[154:157], v[194:197], v[10:13]
	v_mfma_f32_16x16x32_bf16 v[62:65], v[150:153], v[174:177], v[62:65]
	v_mfma_f32_16x16x32_bf16 v[58:61], v[166:169], v[174:177], v[58:61]
	v_mfma_f32_16x16x32_bf16 v[46:49], v[150:153], v[182:185], v[46:49]
	v_mfma_f32_16x16x32_bf16 v[42:45], v[166:169], v[182:185], v[42:45]
	v_mfma_f32_16x16x32_bf16 v[30:33], v[150:153], v[190:193], v[30:33]
	v_mfma_f32_16x16x32_bf16 v[26:29], v[166:169], v[190:193], v[26:29]
	v_mfma_f32_16x16x32_bf16 v[14:17], v[150:153], v[198:201], v[14:17]
	v_mfma_f32_16x16x32_bf16 v[10:13], v[166:169], v[198:201], v[10:13]
	s_barrier
	ds_read_b128 v[146:149], v161
	ds_read_b128 v[150:153], v161 offset:1024
	ds_read_b128 v[154:157], v161 offset:2048
	ds_read_b128 v[166:169], v161 offset:3072
	s_add_i32 s26, s26, s37
	v_lshl_add_u64 v[226:227], v[226:227], 0, s[18:19]
	s_mov_b32 m0, s26
	s_nop 0
	global_load_lds_dwordx4 v[226:227], off
	v_lshl_add_u64 v[228:229], v[228:229], 0, s[18:19]
	s_add_i32 m0, s26, 0x2000
	s_nop 0
	global_load_lds_dwordx4 v[228:229], off
	s_waitcnt vmcnt(6)
	s_barrier
	v_mfma_f32_16x16x32_bf16 v[54:57], v[202:205], v[170:173], v[54:57]
	v_mfma_f32_16x16x32_bf16 v[50:53], v[210:213], v[170:173], v[50:53]
	v_mfma_f32_16x16x32_bf16 v[38:41], v[202:205], v[178:181], v[38:41]
	v_mfma_f32_16x16x32_bf16 v[34:37], v[210:213], v[178:181], v[34:37]
	v_mfma_f32_16x16x32_bf16 v[22:25], v[202:205], v[186:189], v[22:25]
	v_mfma_f32_16x16x32_bf16 v[18:21], v[210:213], v[186:189], v[18:21]
	v_mfma_f32_16x16x32_bf16 v[6:9], v[202:205], v[194:197], v[6:9]
	v_mfma_f32_16x16x32_bf16 v[2:5], v[210:213], v[194:197], v[2:5]
	v_mfma_f32_16x16x32_bf16 v[54:57], v[206:209], v[174:177], v[54:57]
	v_mfma_f32_16x16x32_bf16 v[50:53], v[214:217], v[174:177], v[50:53]
	v_mfma_f32_16x16x32_bf16 v[38:41], v[206:209], v[182:185], v[38:41]
	v_mfma_f32_16x16x32_bf16 v[34:37], v[214:217], v[182:185], v[34:37]
	v_mfma_f32_16x16x32_bf16 v[22:25], v[206:209], v[190:193], v[22:25]
	v_mfma_f32_16x16x32_bf16 v[18:21], v[214:217], v[190:193], v[18:21]
	v_mfma_f32_16x16x32_bf16 v[6:9], v[206:209], v[198:201], v[6:9]
	v_mfma_f32_16x16x32_bf16 v[2:5], v[214:217], v[198:201], v[2:5]
	s_add_u32 s6, s6, 0x100
	s_addc_u32 s7, s7, 0
	s_add_u32 s33, s33, 0x100
	s_addc_u32 s56, s56, 0
	s_cmp_ge_i32 s57, s45
	s_mov_b32 s26, s57
	s_barrier
	s_cbranch_scc0 .LBB0_1037
	s_waitcnt lgkmcnt(0)

.LBB0_1480:
	s_lshl_b32 s40, s40, 8
	s_ashr_i32 s41, s40, 31
	s_add_u32 s33, s16, 0x100
	v_lshl_add_u64 v[4:5], s[40:41], 2, v[156:157]
	s_addc_u32 s71, s17, 0
	v_lshl_add_u64 v[138:139], s[18:19], 0, v[158:159]
	v_lshl_add_u64 v[140:141], s[18:19], 0, v[160:161]
	s_mov_b32 s46, 0
	s_mov_b64 s[40:41], 0
	v_add_u32_e32 v3, 0x10000, v181
	ds_read_b128 v[162:165], v3
	ds_read_b128 v[186:189], v3 offset:1024
	ds_read_b128 v[190:193], v3 offset:2048
	ds_read_b128 v[194:197], v3 offset:3072
	s_branch .LBB0_1482
.LBB0_1481:
	s_or_b64 exec, exec, s[44:45]
	s_add_i32 s72, s46, 2
	s_add_u32 s44, s18, s40
	s_addc_u32 s45, s19, s41
	s_add_u32 s44, s44, 0x100
	s_addc_u32 s45, s45, 0
	s_add_u32 s73, s33, s40
	s_addc_u32 s47, s71, s41
	s_cmp_eq_u32 s64, s46
	s_cselect_b32 s46, s0, s73
	s_cselect_b32 s45, s7, s45
	s_cselect_b32 s44, s6, s44
	s_cselect_b32 s47, s1, s47
	v_lshl_add_u64 v[166:167], v[138:139], 0, s[40:41]
	s_add_i32 m0, s55, 0xc000
	ds_read_b128 v[198:201], v183
	ds_read_b128 v[202:205], v183 offset:1024
	ds_read_b128 v[206:209], v183 offset:2048
	ds_read_b128 v[210:213], v183 offset:3072
	ds_read_b128 v[214:217], v183 offset:4096
	ds_read_b128 v[218:221], v183 offset:5120
	ds_read_b128 v[222:225], v183 offset:6144
	ds_read_b128 v[226:229], v183 offset:7168
	global_load_lds_dwordx4 v[166:167], off
	v_lshl_add_u64 v[166:167], v[140:141], 0, s[40:41]
	s_add_i32 m0, s55, 0xe000
	s_nop 0
	global_load_lds_dwordx4 v[166:167], off
	s_waitcnt lgkmcnt(8)
	s_barrier
	s_waitcnt lgkmcnt(0)
	s_waitcnt lgkmcnt(0)
	v_mfma_f32_16x16x32_bf16 v[130:133], v[162:165], v[198:201], v[130:133]
	v_mfma_f32_16x16x32_bf16 v[126:129], v[190:193], v[198:201], v[126:129]
	v_mfma_f32_16x16x32_bf16 v[122:125], v[162:165], v[206:209], v[122:125]
	v_mfma_f32_16x16x32_bf16 v[118:121], v[190:193], v[206:209], v[118:121]
	v_mfma_f32_16x16x32_bf16 v[114:117], v[162:165], v[214:217], v[114:117]
	v_mfma_f32_16x16x32_bf16 v[110:113], v[190:193], v[214:217], v[110:113]
	v_mfma_f32_16x16x32_bf16 v[106:109], v[162:165], v[222:225], v[106:109]
	v_mfma_f32_16x16x32_bf16 v[98:101], v[190:193], v[222:225], v[98:101]
	v_mfma_f32_16x16x32_bf16 v[130:133], v[186:189], v[202:205], v[130:133]
	v_mfma_f32_16x16x32_bf16 v[126:129], v[194:197], v[202:205], v[126:129]
	v_mfma_f32_16x16x32_bf16 v[122:125], v[186:189], v[210:213], v[122:125]
	v_mfma_f32_16x16x32_bf16 v[118:121], v[194:197], v[210:213], v[118:121]
	v_mfma_f32_16x16x32_bf16 v[114:117], v[186:189], v[218:221], v[114:117]
	v_mfma_f32_16x16x32_bf16 v[110:113], v[194:197], v[218:221], v[110:113]
	v_mfma_f32_16x16x32_bf16 v[106:109], v[186:189], v[226:229], v[106:109]
	v_mfma_f32_16x16x32_bf16 v[98:101], v[194:197], v[226:229], v[98:101]
	s_barrier
	s_add_i32 s73, s65, s54
	v_add_u32_e32 v3, s66, v181
	v_lshl_add_u64 v[166:167], s[46:47], 0, v[150:151]
	s_mov_b32 m0, s73
	ds_read_b128 v[230:233], v3
	ds_read_b128 v[234:237], v3 offset:1024
	ds_read_b128 v[238:241], v3 offset:2048
	ds_read_b128 v[242:245], v3 offset:3072
	global_load_lds_dwordx4 v[166:167], off
	v_lshl_add_u64 v[246:247], s[46:47], 0, v[154:155]
	s_add_i32 m0, s73, 0x2000
	s_nop 0
	global_load_lds_dwordx4 v[246:247], off
	s_barrier
	s_waitcnt lgkmcnt(0)
	s_waitcnt lgkmcnt(0)
	v_mfma_f32_16x16x32_bf16 v[102:105], v[230:233], v[198:201], v[102:105]
	v_mfma_f32_16x16x32_bf16 v[94:97], v[238:241], v[198:201], v[94:97]
	v_mfma_f32_16x16x32_bf16 v[90:93], v[230:233], v[206:209], v[90:93]
	v_mfma_f32_16x16x32_bf16 v[86:89], v[238:241], v[206:209], v[86:89]
	v_mfma_f32_16x16x32_bf16 v[82:85], v[230:233], v[214:217], v[82:85]
	v_mfma_f32_16x16x32_bf16 v[78:81], v[238:241], v[214:217], v[78:81]
	v_mfma_f32_16x16x32_bf16 v[74:77], v[230:233], v[222:225], v[74:77]
	v_mfma_f32_16x16x32_bf16 v[70:73], v[238:241], v[222:225], v[70:73]
	v_mfma_f32_16x16x32_bf16 v[102:105], v[234:237], v[202:205], v[102:105]
	v_mfma_f32_16x16x32_bf16 v[94:97], v[242:245], v[202:205], v[94:97]
	v_mfma_f32_16x16x32_bf16 v[90:93], v[234:237], v[210:213], v[90:93]
	v_mfma_f32_16x16x32_bf16 v[86:89], v[242:245], v[210:213], v[86:89]
	v_mfma_f32_16x16x32_bf16 v[82:85], v[234:237], v[218:221], v[82:85]
	v_mfma_f32_16x16x32_bf16 v[78:81], v[242:245], v[218:221], v[78:81]
	v_mfma_f32_16x16x32_bf16 v[74:77], v[234:237], v[226:229], v[74:77]
	v_mfma_f32_16x16x32_bf16 v[70:73], v[242:245], v[226:229], v[70:73]
	s_mov_b32 m0, s55
	v_lshl_add_u64 v[248:249], s[44:45], 0, v[148:149]
	s_barrier
	ds_read_b128 v[198:201], v183 offset:16384
	ds_read_b128 v[202:205], v183 offset:17408
	ds_read_b128 v[206:209], v183 offset:18432
	ds_read_b128 v[210:213], v183 offset:19456
	ds_read_b128 v[214:217], v183 offset:20480
	ds_read_b128 v[218:221], v183 offset:21504
	ds_read_b128 v[222:225], v183 offset:22528
	ds_read_b128 v[226:229], v183 offset:23552
	global_load_lds_dwordx4 v[248:249], off
	v_lshl_add_u64 v[250:251], s[44:45], 0, v[152:153]
	s_mov_b32 m0, s56
	s_nop 0
	global_load_lds_dwordx4 v[250:251], off
	s_waitcnt vmcnt(10)
	s_barrier
	s_waitcnt lgkmcnt(0)
	s_waitcnt lgkmcnt(0)
	v_mfma_f32_16x16x32_bf16 v[66:69], v[162:165], v[198:201], v[66:69]
	v_mfma_f32_16x16x32_bf16 v[62:65], v[190:193], v[198:201], v[62:65]
	v_mfma_f32_16x16x32_bf16 v[58:61], v[162:165], v[206:209], v[58:61]
	v_mfma_f32_16x16x32_bf16 v[54:57], v[190:193], v[206:209], v[54:57]
	v_mfma_f32_16x16x32_bf16 v[50:53], v[162:165], v[214:217], v[50:53]
	v_mfma_f32_16x16x32_bf16 v[46:49], v[190:193], v[214:217], v[46:49]
	v_mfma_f32_16x16x32_bf16 v[42:45], v[162:165], v[222:225], v[42:45]
	v_mfma_f32_16x16x32_bf16 v[38:41], v[190:193], v[222:225], v[38:41]
	v_mfma_f32_16x16x32_bf16 v[66:69], v[186:189], v[202:205], v[66:69]
	v_mfma_f32_16x16x32_bf16 v[62:65], v[194:197], v[202:205], v[62:65]
	v_mfma_f32_16x16x32_bf16 v[58:61], v[186:189], v[210:213], v[58:61]
	v_mfma_f32_16x16x32_bf16 v[54:57], v[194:197], v[210:213], v[54:57]
	v_mfma_f32_16x16x32_bf16 v[50:53], v[186:189], v[218:221], v[50:53]
	v_mfma_f32_16x16x32_bf16 v[46:49], v[194:197], v[218:221], v[46:49]
	v_mfma_f32_16x16x32_bf16 v[42:45], v[186:189], v[226:229], v[42:45]
	v_mfma_f32_16x16x32_bf16 v[38:41], v[194:197], v[226:229], v[38:41]
	s_barrier
	v_add_u32_e32 v3, 0x18000, v181
	ds_read_b128 v[162:165], v3
	ds_read_b128 v[186:189], v3 offset:1024
	ds_read_b128 v[190:193], v3 offset:2048
	ds_read_b128 v[194:197], v3 offset:3072
	s_add_u32 s46, s46, s12
	s_addc_u32 s47, s47, s13
	s_add_i32 s73, s66, s54
	v_lshl_add_u64 v[252:253], s[46:47], 0, v[150:151]
	s_mov_b32 m0, s73
	v_lshl_add_u64 v[146:147], s[46:47], 0, v[154:155]
	global_load_lds_dwordx4 v[252:253], off
	s_add_i32 m0, s73, 0x2000
	s_nop 0
	global_load_lds_dwordx4 v[146:147], off
	s_waitcnt vmcnt(6)
	s_barrier
	v_mfma_f32_16x16x32_bf16 v[34:37], v[230:233], v[198:201], v[34:37]
	v_mfma_f32_16x16x32_bf16 v[30:33], v[238:241], v[198:201], v[30:33]
	v_mfma_f32_16x16x32_bf16 v[26:29], v[230:233], v[206:209], v[26:29]
	v_mfma_f32_16x16x32_bf16 v[22:25], v[238:241], v[206:209], v[22:25]
	v_mfma_f32_16x16x32_bf16 v[18:21], v[230:233], v[214:217], v[18:21]
	v_mfma_f32_16x16x32_bf16 v[14:17], v[238:241], v[214:217], v[14:17]
	v_mfma_f32_16x16x32_bf16 v[10:13], v[230:233], v[222:225], v[10:13]
	v_mfma_f32_16x16x32_bf16 v[6:9], v[238:241], v[222:225], v[6:9]
	v_mfma_f32_16x16x32_bf16 v[34:37], v[234:237], v[202:205], v[34:37]
	v_mfma_f32_16x16x32_bf16 v[30:33], v[242:245], v[202:205], v[30:33]
	v_mfma_f32_16x16x32_bf16 v[26:29], v[234:237], v[210:213], v[26:29]
	v_mfma_f32_16x16x32_bf16 v[22:25], v[242:245], v[210:213], v[22:25]
	v_mfma_f32_16x16x32_bf16 v[18:21], v[234:237], v[218:221], v[18:21]
	v_mfma_f32_16x16x32_bf16 v[14:17], v[242:245], v[218:221], v[14:17]
	v_mfma_f32_16x16x32_bf16 v[10:13], v[234:237], v[226:229], v[10:13]
	v_mfma_f32_16x16x32_bf16 v[6:9], v[242:245], v[226:229], v[6:9]
	s_add_i32 s46, 0, 0x18000
	s_barrier
	s_add_u32 s44, s44, 0x1d0000
	s_addc_u32 s45, s45, 0
	s_mov_b32 m0, s57
	v_lshl_add_u64 v[230:231], s[44:45], 0, v[148:149]
	ds_read_b128 v[198:201], v183 offset:32768
	ds_read_b128 v[202:205], v183 offset:33792
	ds_read_b128 v[206:209], v183 offset:34816
	ds_read_b128 v[210:213], v183 offset:35840
	ds_read_b128 v[214:217], v183 offset:36864
	ds_read_b128 v[218:221], v183 offset:37888
	ds_read_b128 v[222:225], v183 offset:38912
	ds_read_b128 v[226:229], v183 offset:39936
	global_load_lds_dwordx4 v[230:231], off
	v_lshl_add_u64 v[230:231], s[44:45], 0, v[152:153]
	s_mov_b32 m0, s58
	s_nop 0
	global_load_lds_dwordx4 v[230:231], off
	s_waitcnt lgkmcnt(8)
	s_barrier
	s_waitcnt lgkmcnt(0)
	s_waitcnt lgkmcnt(0)
	v_mfma_f32_16x16x32_bf16 v[130:133], v[162:165], v[198:201], v[130:133]
	v_mfma_f32_16x16x32_bf16 v[126:129], v[190:193], v[198:201], v[126:129]
	v_mfma_f32_16x16x32_bf16 v[122:125], v[162:165], v[206:209], v[122:125]
	v_mfma_f32_16x16x32_bf16 v[118:121], v[190:193], v[206:209], v[118:121]
	v_mfma_f32_16x16x32_bf16 v[114:117], v[162:165], v[214:217], v[114:117]
	v_mfma_f32_16x16x32_bf16 v[110:113], v[190:193], v[214:217], v[110:113]
	v_mfma_f32_16x16x32_bf16 v[106:109], v[162:165], v[222:225], v[106:109]
	v_mfma_f32_16x16x32_bf16 v[98:101], v[190:193], v[222:225], v[98:101]
	v_mfma_f32_16x16x32_bf16 v[130:133], v[186:189], v[202:205], v[130:133]
	v_mfma_f32_16x16x32_bf16 v[126:129], v[194:197], v[202:205], v[126:129]
	v_mfma_f32_16x16x32_bf16 v[122:125], v[186:189], v[210:213], v[122:125]
	v_mfma_f32_16x16x32_bf16 v[118:121], v[194:197], v[210:213], v[118:121]
	v_mfma_f32_16x16x32_bf16 v[114:117], v[186:189], v[218:221], v[114:117]
	v_mfma_f32_16x16x32_bf16 v[110:113], v[194:197], v[218:221], v[110:113]
	v_mfma_f32_16x16x32_bf16 v[106:109], v[186:189], v[226:229], v[106:109]
	v_mfma_f32_16x16x32_bf16 v[98:101], v[194:197], v[226:229], v[98:101]
	s_barrier
	s_add_i32 s44, 0, 0x1c000
	s_add_i32 s45, s46, s54
	v_add_u32_e32 v3, s44, v181
	v_lshl_add_u64 v[166:167], v[166:167], 0, s[24:25]
	s_mov_b32 m0, s45
	ds_read_b128 v[230:233], v3
	ds_read_b128 v[234:237], v3 offset:1024
	ds_read_b128 v[238:241], v3 offset:2048
	ds_read_b128 v[242:245], v3 offset:3072
	global_load_lds_dwordx4 v[166:167], off
	v_lshl_add_u64 v[166:167], v[246:247], 0, s[24:25]
	s_add_i32 m0, s45, 0x2000
	s_nop 0
	global_load_lds_dwordx4 v[166:167], off
	s_barrier
	s_waitcnt lgkmcnt(0)
	s_waitcnt lgkmcnt(0)
	v_mfma_f32_16x16x32_bf16 v[102:105], v[230:233], v[198:201], v[102:105]
	v_mfma_f32_16x16x32_bf16 v[94:97], v[238:241], v[198:201], v[94:97]
	v_mfma_f32_16x16x32_bf16 v[90:93], v[230:233], v[206:209], v[90:93]
	v_mfma_f32_16x16x32_bf16 v[86:89], v[238:241], v[206:209], v[86:89]
	v_mfma_f32_16x16x32_bf16 v[82:85], v[230:233], v[214:217], v[82:85]
	v_mfma_f32_16x16x32_bf16 v[78:81], v[238:241], v[214:217], v[78:81]
	v_mfma_f32_16x16x32_bf16 v[74:77], v[230:233], v[222:225], v[74:77]
	v_mfma_f32_16x16x32_bf16 v[70:73], v[238:241], v[222:225], v[70:73]
	v_mfma_f32_16x16x32_bf16 v[102:105], v[234:237], v[202:205], v[102:105]
	v_mfma_f32_16x16x32_bf16 v[94:97], v[242:245], v[202:205], v[94:97]
	v_mfma_f32_16x16x32_bf16 v[90:93], v[234:237], v[210:213], v[90:93]
	v_mfma_f32_16x16x32_bf16 v[86:89], v[242:245], v[210:213], v[86:89]
	v_mfma_f32_16x16x32_bf16 v[82:85], v[234:237], v[218:221], v[82:85]
	v_mfma_f32_16x16x32_bf16 v[78:81], v[242:245], v[218:221], v[78:81]
	v_mfma_f32_16x16x32_bf16 v[74:77], v[234:237], v[226:229], v[74:77]
	v_mfma_f32_16x16x32_bf16 v[70:73], v[242:245], v[226:229], v[70:73]
	s_mov_b32 m0, s61
	v_lshl_add_u64 v[166:167], v[248:249], 0, s[24:25]
	s_barrier
	ds_read_b128 v[198:201], v183 offset:49152
	ds_read_b128 v[202:205], v183 offset:50176
	ds_read_b128 v[206:209], v183 offset:51200
	ds_read_b128 v[210:213], v183 offset:52224
	ds_read_b128 v[214:217], v183 offset:53248
	ds_read_b128 v[218:221], v183 offset:54272
	ds_read_b128 v[222:225], v183 offset:55296
	ds_read_b128 v[226:229], v183 offset:56320
	global_load_lds_dwordx4 v[166:167], off
	v_lshl_add_u64 v[166:167], v[250:251], 0, s[24:25]
	s_mov_b32 m0, s62
	s_nop 0
	global_load_lds_dwordx4 v[166:167], off
	s_waitcnt vmcnt(10)
	s_barrier
	s_waitcnt lgkmcnt(0)
	s_waitcnt lgkmcnt(0)
	v_mfma_f32_16x16x32_bf16 v[66:69], v[162:165], v[198:201], v[66:69]
	v_mfma_f32_16x16x32_bf16 v[62:65], v[190:193], v[198:201], v[62:65]
	v_mfma_f32_16x16x32_bf16 v[58:61], v[162:165], v[206:209], v[58:61]
	v_mfma_f32_16x16x32_bf16 v[54:57], v[190:193], v[206:209], v[54:57]
	v_mfma_f32_16x16x32_bf16 v[50:53], v[162:165], v[214:217], v[50:53]
	v_mfma_f32_16x16x32_bf16 v[46:49], v[190:193], v[214:217], v[46:49]
	v_mfma_f32_16x16x32_bf16 v[42:45], v[162:165], v[222:225], v[42:45]
	v_mfma_f32_16x16x32_bf16 v[38:41], v[190:193], v[222:225], v[38:41]
	v_mfma_f32_16x16x32_bf16 v[66:69], v[186:189], v[202:205], v[66:69]
	v_mfma_f32_16x16x32_bf16 v[62:65], v[194:197], v[202:205], v[62:65]
	v_mfma_f32_16x16x32_bf16 v[58:61], v[186:189], v[210:213], v[58:61]
	v_mfma_f32_16x16x32_bf16 v[54:57], v[194:197], v[210:213], v[54:57]
	v_mfma_f32_16x16x32_bf16 v[50:53], v[186:189], v[218:221], v[50:53]
	v_mfma_f32_16x16x32_bf16 v[46:49], v[194:197], v[218:221], v[46:49]
	v_mfma_f32_16x16x32_bf16 v[42:45], v[186:189], v[226:229], v[42:45]
	v_mfma_f32_16x16x32_bf16 v[38:41], v[194:197], v[226:229], v[38:41]
	s_barrier
	v_add_u32_e32 v3, 0x10000, v181
	ds_read_b128 v[162:165], v3
	ds_read_b128 v[186:189], v3 offset:1024
	ds_read_b128 v[190:193], v3 offset:2048
	ds_read_b128 v[194:197], v3 offset:3072
	s_add_i32 s44, s44, s54
	v_lshl_add_u64 v[252:253], v[252:253], 0, s[24:25]
	s_mov_b32 m0, s44
	v_lshl_add_u64 v[146:147], v[146:147], 0, s[24:25]
	global_load_lds_dwordx4 v[252:253], off
	s_add_i32 m0, s44, 0x2000
	s_nop 0
	global_load_lds_dwordx4 v[146:147], off
	s_waitcnt vmcnt(6)
	s_barrier
	v_mfma_f32_16x16x32_bf16 v[34:37], v[230:233], v[198:201], v[34:37]
	v_mfma_f32_16x16x32_bf16 v[30:33], v[238:241], v[198:201], v[30:33]
	v_mfma_f32_16x16x32_bf16 v[26:29], v[230:233], v[206:209], v[26:29]
	v_mfma_f32_16x16x32_bf16 v[22:25], v[238:241], v[206:209], v[22:25]
	v_mfma_f32_16x16x32_bf16 v[18:21], v[230:233], v[214:217], v[18:21]
	v_mfma_f32_16x16x32_bf16 v[14:17], v[238:241], v[214:217], v[14:17]
	v_mfma_f32_16x16x32_bf16 v[10:13], v[230:233], v[222:225], v[10:13]
	v_mfma_f32_16x16x32_bf16 v[6:9], v[238:241], v[222:225], v[6:9]
	v_mfma_f32_16x16x32_bf16 v[34:37], v[234:237], v[202:205], v[34:37]
	v_mfma_f32_16x16x32_bf16 v[30:33], v[242:245], v[202:205], v[30:33]
	v_mfma_f32_16x16x32_bf16 v[26:29], v[234:237], v[210:213], v[26:29]
	v_mfma_f32_16x16x32_bf16 v[22:25], v[242:245], v[210:213], v[22:25]
	v_mfma_f32_16x16x32_bf16 v[18:21], v[234:237], v[218:221], v[18:21]
	v_mfma_f32_16x16x32_bf16 v[14:17], v[242:245], v[218:221], v[14:17]
	v_mfma_f32_16x16x32_bf16 v[10:13], v[234:237], v[226:229], v[10:13]
	v_mfma_f32_16x16x32_bf16 v[6:9], v[242:245], v[226:229], v[6:9]
	s_add_u32 s40, s40, 0x100
	s_addc_u32 s41, s41, 0
	s_andn2_b64 s[38:39], s[38:39], exec
	s_and_b64 s[44:45], s[42:43], exec
	s_or_b64 s[38:39], s[38:39], s[44:45]
	s_cmp_ge_i32 s72, s59
	s_mov_b32 s46, s72
	s_barrier
	s_cbranch_scc1 .LBB0_1484

.LBB0_1484:
	s_waitcnt lgkmcnt(0)
	s_lshl_b32 s38, s67, 8
	v_add_u32_e32 v166, s38, v180
	v_lshl_or_b32 v4, s63, 8, v182
	v_ashrrev_i32_e32 v167, 31, v166
	v_ashrrev_i32_e32 v5, 31, v4
	v_lshlrev_b64 v[162:163], 12, v[166:167]
	v_lshl_add_u64 v[134:135], s[20:21], 0, v[162:163]
	v_lshlrev_b64 v[4:5], 1, v[4:5]
	v_lshl_add_u64 v[134:135], v[134:135], 0, v[4:5]
	global_load_dwordx4 v[186:189], v[134:135], off
	global_load_dwordx4 v[142:145], v[134:135], off offset:256
	v_or_b32_e32 v134, 16, v166
	v_ashrrev_i32_e32 v135, 31, v134
	v_lshlrev_b64 v[164:165], 12, v[134:135]
	v_lshl_add_u64 v[134:135], s[20:21], 0, v[164:165]
	v_lshl_add_u64 v[134:135], v[134:135], 0, v[4:5]
	global_load_dwordx4 v[138:141], v[134:135], off
	s_nop 0
	global_load_dwordx4 v[134:137], v[134:135], off offset:256
	v_or_b32_e32 v190, 32, v166
	v_ashrrev_i32_e32 v191, 31, v190
	v_lshlrev_b64 v[206:207], 12, v[190:191]
	v_lshl_add_u64 v[190:191], s[20:21], 0, v[206:207]
	v_lshl_add_u64 v[192:193], s[22:23], 0, v[162:163]
	v_lshl_add_u64 v[202:203], v[190:191], 0, v[4:5]
	v_lshl_add_u64 v[196:197], v[192:193], 0, v[4:5]
	global_load_dwordx4 v[190:193], v[202:203], off
	v_and_b32_e32 v146, 64, v184
	v_xor_b32_e32 v3, 16, v184
	v_add_u32_e32 v146, 64, v146
	v_cmp_lt_i32_e32 vcc, v3, v146
	v_lshl_add_u64 v[164:165], s[22:23], 0, v[164:165]
	v_lshl_add_u64 v[164:165], v[164:165], 0, v[4:5]
	v_cndmask_b32_e32 v3, v184, v3, vcc
	v_lshlrev_b32_e32 v167, 2, v3
	v_xor_b32_e32 v147, 32, v184
	v_cmp_lt_i32_e32 vcc, v147, v146
	s_waitcnt vmcnt(0)
	v_lshlrev_b32_e32 v194, 16, v186
	v_lshlrev_b32_e32 v204, 16, v144
	v_and_b32_e32 v205, 0xffff0000, v144
	v_pk_add_f32 v[218:219], v[94:95], v[204:205]
	v_lshlrev_b32_e32 v144, 16, v145
	v_and_b32_e32 v145, 0xffff0000, v145
	v_and_b32_e32 v195, 0xffff0000, v186
	v_lshlrev_b32_e32 v204, 16, v134
	v_and_b32_e32 v205, 0xffff0000, v134
	v_lshlrev_b32_e32 v134, 16, v135
	v_and_b32_e32 v135, 0xffff0000, v135
	v_pk_add_f32 v[234:235], v[92:93], v[134:135]
	v_lshlrev_b32_e32 v134, 16, v137
	v_and_b32_e32 v135, 0xffff0000, v137
	v_pk_add_f32 v[236:237], v[88:89], v[134:135]
	v_or_b32_e32 v134, 48, v166
	v_pk_add_f32 v[220:221], v[96:97], v[144:145]
	v_lshlrev_b32_e32 v144, 16, v138
	v_and_b32_e32 v145, 0xffff0000, v138
	v_ashrrev_i32_e32 v135, 31, v134
	v_pk_add_f32 v[208:209], v[130:131], v[194:195]
	v_lshlrev_b32_e32 v194, 16, v139
	v_and_b32_e32 v195, 0xffff0000, v139
	v_pk_add_f32 v[224:225], v[122:123], v[144:145]
	v_lshlrev_b64 v[144:145], 12, v[134:135]
	v_lshlrev_b32_e32 v186, 16, v187
	v_and_b32_e32 v187, 0xffff0000, v187
	v_pk_add_f32 v[226:227], v[124:125], v[194:195]
	v_cvt_pk_bf16_f32 v194, v224, v225
	v_mov_b32_e32 v241, v224
	v_lshl_add_u64 v[134:135], s[20:21], 0, v[144:145]
	v_mov_b32_e32 v224, v209
	v_lshlrev_b32_e32 v198, 16, v188
	v_and_b32_e32 v199, 0xffff0000, v188
	v_lshlrev_b32_e32 v188, 16, v189
	v_and_b32_e32 v189, 0xffff0000, v189
	v_pk_add_f32 v[210:211], v[132:133], v[186:187]
	v_cvt_pk_bf16_f32 v138, v208, v209
	v_mov_b32_e32 v240, v208
	v_lshl_add_u64 v[242:243], v[134:135], 0, v[4:5]
	v_pk_mul_f32 v[208:209], v[224:225], v[224:225]
	v_lshlrev_b32_e32 v200, 16, v142
	v_and_b32_e32 v201, 0xffff0000, v142
	v_pk_add_f32 v[212:213], v[126:127], v[198:199]
	v_pk_add_f32 v[214:215], v[128:129], v[188:189]
	v_lshlrev_b32_e32 v198, 16, v140
	v_and_b32_e32 v199, 0xffff0000, v140
	v_lshlrev_b32_e32 v222, 16, v136
	v_and_b32_e32 v223, 0xffff0000, v136
	v_cvt_pk_bf16_f32 v139, v210, v211
	v_pk_add_f32 v[232:233], v[90:91], v[204:205]
	v_mov_b32_e32 v238, v211
	v_mov_b32_e32 v211, v226
	global_load_dwordx4 v[134:137], v[242:243], off
	v_pk_fma_f32 v[208:209], v[240:241], v[240:241], v[208:209]
	global_load_dwordx4 v[202:205], v[202:203], off offset:256
	v_pk_add_f32 v[216:217], v[102:103], v[200:201]
	v_lshlrev_b32_e32 v200, 16, v141
	v_and_b32_e32 v201, 0xffff0000, v141
	v_cvt_pk_bf16_f32 v140, v212, v213
	v_cvt_pk_bf16_f32 v141, v214, v215
	v_pk_add_f32 v[228:229], v[118:119], v[198:199]
	v_mov_b32_e32 v239, v227
	v_pk_fma_f32 v[208:209], v[210:211], v[210:211], v[208:209]
	global_store_dwordx4 v[196:197], v[138:141], off
	v_pk_fma_f32 v[208:209], v[238:239], v[238:239], v[208:209]
	v_pk_add_f32 v[230:231], v[120:121], v[200:201]
	v_mov_b32_e32 v140, v213
	v_mov_b32_e32 v213, v228
	v_mov_b32_e32 v141, v229
	v_pk_fma_f32 v[208:209], v[212:213], v[212:213], v[208:209]
	v_mov_b32_e32 v138, v215
	v_mov_b32_e32 v215, v230
	v_pk_fma_f32 v[140:141], v[140:141], v[140:141], v[208:209]
	v_mov_b32_e32 v139, v231
	v_pk_fma_f32 v[140:141], v[214:215], v[214:215], v[140:141]
	v_cvt_pk_bf16_f32 v198, v232, v233
	v_pk_fma_f32 v[138:139], v[138:139], v[138:139], v[140:141]
	v_mov_b32_e32 v140, v216
	v_mov_b32_e32 v141, v232
	v_pk_fma_f32 v[138:139], v[140:141], v[140:141], v[138:139]
	v_mov_b32_e32 v232, v217
	v_pk_fma_f32 v[208:209], v[232:233], v[232:233], v[138:139]
	global_load_dwordx4 v[138:141], v[242:243], off offset:256
	v_lshlrev_b32_e32 v142, 16, v143
	v_and_b32_e32 v143, 0xffff0000, v143
	v_pk_add_f32 v[142:143], v[104:105], v[142:143]
	v_mov_b32_e32 v211, v234
	v_mov_b32_e32 v210, v142
	v_pk_add_f32 v[222:223], v[86:87], v[222:223]
	v_cvt_pk_bf16_f32 v199, v234, v235
	v_pk_fma_f32 v[208:209], v[210:211], v[210:211], v[208:209]
	v_mov_b32_e32 v234, v143
	v_cvt_pk_bf16_f32 v187, v142, v143
	v_pk_fma_f32 v[142:143], v[234:235], v[234:235], v[208:209]
	v_mov_b32_e32 v208, v218
	v_mov_b32_e32 v209, v222
	v_cvt_pk_bf16_f32 v200, v222, v223
	v_pk_fma_f32 v[142:143], v[208:209], v[208:209], v[142:143]
	v_mov_b32_e32 v222, v219
	v_pk_fma_f32 v[142:143], v[222:223], v[222:223], v[142:143]
	v_mov_b32_e32 v208, v220
	v_mov_b32_e32 v209, v236
	v_cvt_pk_bf16_f32 v201, v236, v237
	v_pk_fma_f32 v[142:143], v[208:209], v[208:209], v[142:143]
	v_mov_b32_e32 v236, v221
	v_pk_fma_f32 v[142:143], v[236:237], v[236:237], v[142:143]
	ds_bpermute_b32 v208, v167, v142
	ds_bpermute_b32 v209, v167, v143
	v_cvt_pk_bf16_f32 v186, v216, v217
	v_cvt_pk_bf16_f32 v188, v218, v219
	v_cvt_pk_bf16_f32 v189, v220, v221
	global_store_dwordx4 v[196:197], v[186:189], off offset:256
	v_cvt_pk_bf16_f32 v195, v226, v227
	v_cvt_pk_bf16_f32 v196, v228, v229
	v_cvt_pk_bf16_f32 v197, v230, v231
	global_store_dwordx4 v[164:165], v[194:197], off
	global_store_dwordx4 v[164:165], v[198:201], off offset:256
	v_lshlrev_b32_e32 v164, 16, v190
	v_and_b32_e32 v165, 0xffff0000, v190
	v_pk_add_f32 v[196:197], v[114:115], v[164:165]
	v_lshlrev_b32_e32 v164, 16, v191
	v_and_b32_e32 v165, 0xffff0000, v191
	s_waitcnt lgkmcnt(0)
	v_pk_add_f32 v[142:143], v[142:143], v[208:209]
	v_pk_add_f32 v[208:209], v[116:117], v[164:165]
	v_lshlrev_b32_e32 v164, 16, v192
	v_and_b32_e32 v165, 0xffff0000, v192
	v_pk_add_f32 v[210:211], v[110:111], v[164:165]
	v_lshlrev_b32_e32 v164, 16, v193
	v_and_b32_e32 v165, 0xffff0000, v193
	v_pk_add_f32 v[212:213], v[112:113], v[164:165]
	v_lshl_add_u64 v[164:165], s[22:23], 0, v[206:207]
	v_cndmask_b32_e32 v146, v184, v147, vcc
	v_lshl_add_u64 v[206:207], v[164:165], 0, v[4:5]
	v_lshlrev_b32_e32 v3, 2, v146
	ds_bpermute_b32 v186, v3, v142
	s_waitcnt vmcnt(5)
	v_lshlrev_b32_e32 v164, 16, v202
	v_and_b32_e32 v165, 0xffff0000, v202
	v_pk_add_f32 v[214:215], v[82:83], v[164:165]
	v_lshlrev_b32_e32 v164, 16, v203
	v_and_b32_e32 v165, 0xffff0000, v203
	ds_bpermute_b32 v187, v3, v143
	v_pk_add_f32 v[216:217], v[84:85], v[164:165]
	v_lshlrev_b32_e32 v164, 16, v204
	v_and_b32_e32 v165, 0xffff0000, v204
	v_pk_add_f32 v[218:219], v[78:79], v[164:165]
	v_lshlrev_b32_e32 v164, 16, v205
	v_and_b32_e32 v165, 0xffff0000, v205
	v_pk_add_f32 v[220:221], v[80:81], v[164:165]
	v_lshlrev_b32_e32 v164, 16, v134
	v_and_b32_e32 v165, 0xffff0000, v134
	v_pk_add_f32 v[222:223], v[106:107], v[164:165]
	v_lshlrev_b32_e32 v134, 16, v135
	v_and_b32_e32 v135, 0xffff0000, v135
	v_pk_add_f32 v[224:225], v[108:109], v[134:135]
	v_lshlrev_b32_e32 v134, 16, v136
	v_and_b32_e32 v135, 0xffff0000, v136
	v_cvt_pk_bf16_f32 v194, v222, v223
	v_mov_b32_e32 v243, v222
	v_mov_b32_e32 v222, v197
	s_waitcnt lgkmcnt(0)
	v_pk_add_f32 v[142:143], v[142:143], v[186:187]
	v_cvt_pk_bf16_f32 v186, v196, v197
	v_pk_add_f32 v[226:227], v[98:99], v[134:135]
	v_lshlrev_b32_e32 v134, 16, v137
	v_and_b32_e32 v135, 0xffff0000, v137
	v_mov_b32_e32 v242, v196
	v_pk_mul_f32 v[196:197], v[222:223], v[222:223]
	v_cvt_pk_bf16_f32 v187, v208, v209
	v_lshl_add_u64 v[228:229], v[162:163], 0, s[28:29]
	v_pk_add_f32 v[230:231], v[100:101], v[134:135]
	s_waitcnt vmcnt(3)
	v_lshlrev_b32_e32 v134, 16, v138
	v_and_b32_e32 v135, 0xffff0000, v138
	v_mov_b32_e32 v240, v209
	v_mov_b32_e32 v209, v224
	v_pk_fma_f32 v[196:197], v[242:243], v[242:243], v[196:197]
	v_lshl_add_u64 v[164:165], s[20:21], 0, v[228:229]
	v_pk_add_f32 v[232:233], v[74:75], v[134:135]
	v_lshlrev_b32_e32 v134, 16, v139
	v_and_b32_e32 v135, 0xffff0000, v139
	v_mov_b32_e32 v241, v225
	v_pk_fma_f32 v[196:197], v[208:209], v[208:209], v[196:197]
	v_cvt_pk_bf16_f32 v188, v210, v211
	v_lshl_add_u64 v[164:165], v[164:165], 0, v[4:5]
	v_pk_add_f32 v[234:235], v[76:77], v[134:135]
	v_lshlrev_b32_e32 v134, 16, v140
	v_and_b32_e32 v135, 0xffff0000, v140
	v_mov_b32_e32 v140, v211
	v_mov_b32_e32 v211, v226
	v_pk_fma_f32 v[196:197], v[240:241], v[240:241], v[196:197]
	global_load_dwordx4 v[190:193], v[164:165], off
	global_load_dwordx4 v[202:205], v[164:165], off offset:256
	v_pk_add_f32 v[236:237], v[70:71], v[134:135]
	v_lshlrev_b32_e32 v134, 16, v141
	v_and_b32_e32 v135, 0xffff0000, v141
	v_mov_b32_e32 v141, v227
	v_lshl_add_u64 v[164:165], v[162:163], 0, s[30:31]
	v_pk_fma_f32 v[196:197], v[210:211], v[210:211], v[196:197]
	v_cvt_pk_bf16_f32 v189, v212, v213
	v_pk_add_f32 v[238:239], v[72:73], v[134:135]
	v_mov_b32_e32 v138, v213
	v_mov_b32_e32 v213, v230
	v_lshl_add_u64 v[134:135], s[20:21], 0, v[164:165]
	v_pk_fma_f32 v[140:141], v[140:141], v[140:141], v[196:197]
	v_mov_b32_e32 v139, v231
	v_lshl_add_u64 v[244:245], v[134:135], 0, v[4:5]
	v_pk_fma_f32 v[140:141], v[212:213], v[212:213], v[140:141]
	global_load_dwordx4 v[134:137], v[244:245], off
	v_pk_fma_f32 v[138:139], v[138:139], v[138:139], v[140:141]
	v_mov_b32_e32 v140, v214
	v_mov_b32_e32 v141, v232
	v_cvt_pk_bf16_f32 v198, v232, v233
	v_pk_fma_f32 v[138:139], v[140:141], v[140:141], v[138:139]
	v_mov_b32_e32 v232, v215
	v_pk_fma_f32 v[196:197], v[232:233], v[232:233], v[138:139]
	global_load_dwordx4 v[138:141], v[244:245], off offset:256
	v_mov_b32_e32 v208, v216
	v_mov_b32_e32 v209, v234
	v_cvt_pk_bf16_f32 v199, v234, v235
	v_pk_fma_f32 v[196:197], v[208:209], v[208:209], v[196:197]
	v_mov_b32_e32 v234, v217
	v_pk_fma_f32 v[196:197], v[234:235], v[234:235], v[196:197]
	v_mov_b32_e32 v208, v218
	v_mov_b32_e32 v209, v236
	v_cvt_pk_bf16_f32 v200, v236, v237
	v_pk_fma_f32 v[196:197], v[208:209], v[208:209], v[196:197]
	v_mov_b32_e32 v236, v219
	v_pk_fma_f32 v[196:197], v[236:237], v[236:237], v[196:197]
	v_mov_b32_e32 v208, v220
	v_mov_b32_e32 v209, v238
	v_cvt_pk_bf16_f32 v201, v238, v239
	v_pk_fma_f32 v[196:197], v[208:209], v[208:209], v[196:197]
	v_mov_b32_e32 v238, v221
	v_pk_fma_f32 v[208:209], v[238:239], v[238:239], v[196:197]
	ds_bpermute_b32 v210, v167, v208
	ds_bpermute_b32 v211, v167, v209
	global_store_dwordx4 v[206:207], v[186:189], off
	v_lshl_add_u64 v[144:145], s[22:23], 0, v[144:145]
	v_cvt_pk_bf16_f32 v195, v224, v225
	v_cvt_pk_bf16_f32 v186, v214, v215
	v_cvt_pk_bf16_f32 v187, v216, v217
	v_cvt_pk_bf16_f32 v188, v218, v219
	v_cvt_pk_bf16_f32 v189, v220, v221
	global_store_dwordx4 v[206:207], v[186:189], off offset:256
	v_cvt_pk_bf16_f32 v196, v226, v227
	v_cvt_pk_bf16_f32 v197, v230, v231
	s_waitcnt lgkmcnt(0)
	v_pk_add_f32 v[186:187], v[208:209], v[210:211]
	ds_bpermute_b32 v188, v3, v186
	ds_bpermute_b32 v189, v3, v187
	v_lshl_add_u64 v[144:145], v[144:145], 0, v[4:5]
	global_store_dwordx4 v[144:145], v[194:197], off
	global_store_dwordx4 v[144:145], v[198:201], off offset:256
	v_lshl_add_u64 v[226:227], v[162:163], 0, s[34:35]
	v_lshl_add_u64 v[164:165], s[22:23], 0, v[164:165]
	s_waitcnt lgkmcnt(0)
	v_pk_add_f32 v[144:145], v[186:187], v[188:189]
	v_lshl_add_u64 v[164:165], v[164:165], 0, v[4:5]
	s_and_b64 vcc, exec, s[4:5]
	s_waitcnt vmcnt(7)
	v_lshlrev_b32_e32 v186, 16, v190
	v_and_b32_e32 v187, 0xffff0000, v190
	v_pk_add_f32 v[196:197], v[66:67], v[186:187]
	v_lshlrev_b32_e32 v186, 16, v191
	v_and_b32_e32 v187, 0xffff0000, v191
	v_lshl_add_u64 v[190:191], s[22:23], 0, v[228:229]
	v_lshl_add_u64 v[212:213], v[190:191], 0, v[4:5]
	v_pk_add_f32 v[206:207], v[68:69], v[186:187]
	v_lshlrev_b32_e32 v186, 16, v192
	v_and_b32_e32 v187, 0xffff0000, v192
	v_pk_add_f32 v[208:209], v[62:63], v[186:187]
	v_lshlrev_b32_e32 v186, 16, v193
	v_and_b32_e32 v187, 0xffff0000, v193
	v_pk_add_f32 v[210:211], v[64:65], v[186:187]
	v_cvt_pk_bf16_f32 v186, v196, v197
	v_cvt_pk_bf16_f32 v187, v206, v207
	v_cvt_pk_bf16_f32 v188, v208, v209
	s_waitcnt vmcnt(5)
	v_lshlrev_b32_e32 v190, 16, v134
	v_and_b32_e32 v191, 0xffff0000, v134
	v_pk_add_f32 v[222:223], v[58:59], v[190:191]
	v_lshlrev_b32_e32 v190, 16, v136
	v_and_b32_e32 v191, 0xffff0000, v136
	v_lshlrev_b32_e32 v136, 16, v137
	v_and_b32_e32 v137, 0xffff0000, v137
	v_pk_add_f32 v[228:229], v[56:57], v[136:137]
	s_waitcnt vmcnt(4)
	v_lshlrev_b32_e32 v136, 16, v138
	v_and_b32_e32 v137, 0xffff0000, v138
	v_pk_add_f32 v[230:231], v[26:27], v[136:137]
	v_lshlrev_b32_e32 v136, 16, v139
	v_and_b32_e32 v137, 0xffff0000, v139
	v_pk_add_f32 v[232:233], v[28:29], v[136:137]
	v_lshlrev_b32_e32 v136, 16, v140
	v_and_b32_e32 v137, 0xffff0000, v140
	v_cvt_pk_bf16_f32 v189, v210, v211
	v_pk_add_f32 v[234:235], v[22:23], v[136:137]
	v_lshlrev_b32_e32 v136, 16, v141
	v_and_b32_e32 v137, 0xffff0000, v141
	global_store_dwordx4 v[212:213], v[186:189], off
	v_pk_add_f32 v[236:237], v[24:25], v[136:137]
	v_lshl_add_u64 v[136:137], v[162:163], 0, s[36:37]
	v_lshlrev_b32_e32 v186, 16, v202
	v_and_b32_e32 v187, 0xffff0000, v202
	v_pk_add_f32 v[214:215], v[34:35], v[186:187]
	v_lshlrev_b32_e32 v186, 16, v203
	v_and_b32_e32 v187, 0xffff0000, v203
	v_lshl_add_u64 v[162:163], s[20:21], 0, v[136:137]
	v_pk_add_f32 v[216:217], v[36:37], v[186:187]
	v_lshlrev_b32_e32 v186, 16, v204
	v_and_b32_e32 v187, 0xffff0000, v204
	v_pk_add_f32 v[224:225], v[54:55], v[190:191]
	v_lshl_add_u64 v[190:191], s[20:21], 0, v[226:227]
	v_lshl_add_u64 v[162:163], v[162:163], 0, v[4:5]
	v_pk_add_f32 v[218:219], v[30:31], v[186:187]
	v_lshlrev_b32_e32 v186, 16, v205
	v_and_b32_e32 v187, 0xffff0000, v205
	v_lshlrev_b32_e32 v134, 16, v135
	v_and_b32_e32 v135, 0xffff0000, v135
	v_lshl_add_u64 v[198:199], v[190:191], 0, v[4:5]
	v_cvt_pk_bf16_f32 v194, v222, v223
	v_mov_b32_e32 v245, v222
	global_load_dwordx4 v[202:205], v[162:163], off
	v_mov_b32_e32 v222, v197
	v_pk_add_f32 v[134:135], v[60:61], v[134:135]
	global_load_dwordx4 v[190:193], v[198:199], off
	v_mov_b32_e32 v244, v196
	v_pk_mul_f32 v[196:197], v[222:223], v[222:223]
	v_mov_b32_e32 v242, v207
	v_mov_b32_e32 v207, v134
	v_pk_fma_f32 v[196:197], v[244:245], v[244:245], v[196:197]
	v_mov_b32_e32 v243, v135
	v_pk_fma_f32 v[196:197], v[206:207], v[206:207], v[196:197]
	v_mov_b32_e32 v240, v209
	v_mov_b32_e32 v209, v224
	v_pk_fma_f32 v[196:197], v[242:243], v[242:243], v[196:197]
	v_mov_b32_e32 v241, v225
	v_pk_fma_f32 v[196:197], v[208:209], v[208:209], v[196:197]
	v_mov_b32_e32 v238, v211
	v_mov_b32_e32 v211, v228
	v_pk_fma_f32 v[196:197], v[240:241], v[240:241], v[196:197]
	v_mov_b32_e32 v239, v229
	v_pk_fma_f32 v[196:197], v[210:211], v[210:211], v[196:197]
	v_mov_b32_e32 v206, v214
	v_pk_fma_f32 v[196:197], v[238:239], v[238:239], v[196:197]
	v_mov_b32_e32 v207, v230
	v_pk_fma_f32 v[196:197], v[206:207], v[206:207], v[196:197]
	global_load_dwordx4 v[206:209], v[162:163], off offset:256
	v_cvt_pk_bf16_f32 v138, v230, v231
	global_load_dwordx4 v[198:201], v[198:199], off offset:256
	v_mov_b32_e32 v230, v215
	v_pk_fma_f32 v[162:163], v[230:231], v[230:231], v[196:197]
	v_mov_b32_e32 v196, v216
	v_mov_b32_e32 v197, v232
	v_cvt_pk_bf16_f32 v139, v232, v233
	v_pk_fma_f32 v[162:163], v[196:197], v[196:197], v[162:163]
	v_mov_b32_e32 v232, v217
	v_pk_fma_f32 v[162:163], v[232:233], v[232:233], v[162:163]
	v_mov_b32_e32 v196, v218
	v_mov_b32_e32 v197, v234
	v_pk_add_f32 v[220:221], v[32:33], v[186:187]
	v_cvt_pk_bf16_f32 v140, v234, v235
	v_pk_fma_f32 v[162:163], v[196:197], v[196:197], v[162:163]
	v_mov_b32_e32 v234, v219
	v_pk_fma_f32 v[162:163], v[234:235], v[234:235], v[162:163]
	v_mov_b32_e32 v196, v220
	v_mov_b32_e32 v197, v236
	v_cvt_pk_bf16_f32 v141, v236, v237
	v_pk_fma_f32 v[162:163], v[196:197], v[196:197], v[162:163]
	v_mov_b32_e32 v236, v221
	v_pk_fma_f32 v[162:163], v[236:237], v[236:237], v[162:163]
	ds_bpermute_b32 v210, v167, v162
	ds_bpermute_b32 v211, v167, v163
	v_cvt_pk_bf16_f32 v195, v134, v135
	v_cvt_pk_bf16_f32 v186, v214, v215
	v_cvt_pk_bf16_f32 v187, v216, v217
	v_cvt_pk_bf16_f32 v188, v218, v219
	s_waitcnt lgkmcnt(0)
	v_pk_add_f32 v[134:135], v[162:163], v[210:211]
	ds_bpermute_b32 v162, v3, v134
	ds_bpermute_b32 v163, v3, v135
	v_cvt_pk_bf16_f32 v189, v220, v221
	v_cvt_pk_bf16_f32 v196, v224, v225
	v_cvt_pk_bf16_f32 v197, v228, v229
	global_store_dwordx4 v[212:213], v[186:189], off offset:256
	s_waitcnt lgkmcnt(0)
	v_pk_add_f32 v[134:135], v[134:135], v[162:163]
	v_lshl_add_u64 v[162:163], s[22:23], 0, v[226:227]
	global_store_dwordx4 v[164:165], v[194:197], off
	global_store_dwordx4 v[164:165], v[138:141], off offset:256
	v_lshl_add_u64 v[136:137], s[22:23], 0, v[136:137]
	v_lshl_add_u64 v[196:197], v[162:163], 0, v[4:5]
	v_lshl_add_u64 v[4:5], v[136:137], 0, v[4:5]
	s_waitcnt vmcnt(6)
	v_lshlrev_b32_e32 v162, 16, v202
	v_and_b32_e32 v163, 0xffff0000, v202
	v_pk_add_f32 v[214:215], v[42:43], v[162:163]
	s_waitcnt vmcnt(5)
	v_lshlrev_b32_e32 v138, 16, v190
	v_and_b32_e32 v139, 0xffff0000, v190
	v_lshlrev_b32_e32 v162, 16, v203
	v_and_b32_e32 v163, 0xffff0000, v203
	v_pk_add_f32 v[164:165], v[50:51], v[138:139]
	v_lshlrev_b32_e32 v138, 16, v191
	v_and_b32_e32 v139, 0xffff0000, v191
	v_pk_add_f32 v[202:203], v[44:45], v[162:163]
	v_lshlrev_b32_e32 v162, 16, v204
	v_and_b32_e32 v163, 0xffff0000, v204
	v_pk_add_f32 v[190:191], v[52:53], v[138:139]
	v_lshlrev_b32_e32 v138, 16, v192
	v_and_b32_e32 v139, 0xffff0000, v192
	v_pk_add_f32 v[216:217], v[38:39], v[162:163]
	v_lshlrev_b32_e32 v162, 16, v205
	v_and_b32_e32 v163, 0xffff0000, v205
	v_pk_add_f32 v[194:195], v[46:47], v[138:139]
	v_lshlrev_b32_e32 v138, 16, v193
	v_and_b32_e32 v139, 0xffff0000, v193
	v_pk_add_f32 v[204:205], v[40:41], v[162:163]
	v_cvt_pk_bf16_f32 v162, v214, v215
	v_mov_b32_e32 v229, v214
	v_mov_b32_e32 v214, v165
	v_pk_add_f32 v[192:193], v[48:49], v[138:139]
	v_cvt_pk_bf16_f32 v138, v164, v165
	v_mov_b32_e32 v228, v164
	v_pk_mul_f32 v[164:165], v[214:215], v[214:215]
	v_cvt_pk_bf16_f32 v139, v190, v191
	v_mov_b32_e32 v226, v191
	v_mov_b32_e32 v191, v202
	v_pk_fma_f32 v[164:165], v[228:229], v[228:229], v[164:165]
	v_mov_b32_e32 v227, v203
	v_pk_fma_f32 v[164:165], v[190:191], v[190:191], v[164:165]
	v_cvt_pk_bf16_f32 v140, v194, v195
	v_mov_b32_e32 v224, v195
	v_mov_b32_e32 v195, v216
	v_pk_fma_f32 v[164:165], v[226:227], v[226:227], v[164:165]
	v_cvt_pk_bf16_f32 v141, v192, v193
	s_waitcnt vmcnt(4)
	v_lshlrev_b32_e32 v186, 16, v206
	v_and_b32_e32 v187, 0xffff0000, v206
	v_mov_b32_e32 v225, v217
	v_pk_fma_f32 v[164:165], v[194:195], v[194:195], v[164:165]
	global_store_dwordx4 v[196:197], v[138:141], off
	v_pk_add_f32 v[218:219], v[10:11], v[186:187]
	v_lshlrev_b32_e32 v186, 16, v207
	s_waitcnt vmcnt(4)
	v_lshlrev_b32_e32 v138, 16, v198
	v_and_b32_e32 v139, 0xffff0000, v198
	v_and_b32_e32 v187, 0xffff0000, v207
	v_mov_b32_e32 v222, v193
	v_mov_b32_e32 v193, v204
	v_pk_fma_f32 v[164:165], v[224:225], v[224:225], v[164:165]
	v_pk_add_f32 v[210:211], v[18:19], v[138:139]
	v_pk_add_f32 v[206:207], v[12:13], v[186:187]
	v_lshlrev_b32_e32 v186, 16, v208
	v_and_b32_e32 v187, 0xffff0000, v208
	v_mov_b32_e32 v223, v205
	v_pk_fma_f32 v[164:165], v[192:193], v[192:193], v[164:165]
	v_lshlrev_b32_e32 v138, 16, v199
	v_and_b32_e32 v139, 0xffff0000, v199
	v_pk_add_f32 v[220:221], v[6:7], v[186:187]
	v_lshlrev_b32_e32 v186, 16, v209
	v_and_b32_e32 v187, 0xffff0000, v209
	v_pk_fma_f32 v[164:165], v[222:223], v[222:223], v[164:165]
	v_mov_b32_e32 v190, v210
	v_mov_b32_e32 v191, v218
	v_pk_add_f32 v[198:199], v[20:21], v[138:139]
	v_pk_add_f32 v[208:209], v[8:9], v[186:187]
	v_cvt_pk_bf16_f32 v186, v218, v219
	v_pk_fma_f32 v[164:165], v[190:191], v[190:191], v[164:165]
	v_mov_b32_e32 v218, v211
	v_lshlrev_b32_e32 v138, 16, v200
	v_and_b32_e32 v139, 0xffff0000, v200
	v_pk_fma_f32 v[164:165], v[218:219], v[218:219], v[164:165]
	v_mov_b32_e32 v190, v198
	v_mov_b32_e32 v191, v206
	v_pk_add_f32 v[212:213], v[14:15], v[138:139]
	v_cvt_pk_bf16_f32 v187, v206, v207
	v_pk_fma_f32 v[164:165], v[190:191], v[190:191], v[164:165]
	v_mov_b32_e32 v206, v199
	v_lshlrev_b32_e32 v138, 16, v201
	v_and_b32_e32 v139, 0xffff0000, v201
	v_pk_fma_f32 v[164:165], v[206:207], v[206:207], v[164:165]
	v_mov_b32_e32 v190, v212
	v_mov_b32_e32 v191, v220
	v_pk_add_f32 v[200:201], v[16:17], v[138:139]
	v_cvt_pk_bf16_f32 v188, v220, v221
	v_pk_fma_f32 v[164:165], v[190:191], v[190:191], v[164:165]
	v_mov_b32_e32 v220, v213
	v_pk_fma_f32 v[164:165], v[220:221], v[220:221], v[164:165]
	v_mov_b32_e32 v190, v200
	v_mov_b32_e32 v191, v208
	v_cvt_pk_bf16_f32 v189, v208, v209
	v_pk_fma_f32 v[164:165], v[190:191], v[190:191], v[164:165]
	v_mov_b32_e32 v208, v201
	v_pk_fma_f32 v[190:191], v[208:209], v[208:209], v[164:165]
	ds_bpermute_b32 v166, v167, v190
	ds_bpermute_b32 v167, v167, v191
	v_cvt_pk_bf16_f32 v138, v210, v211
	v_cvt_pk_bf16_f32 v139, v198, v199
	v_cvt_pk_bf16_f32 v140, v212, v213
	v_cvt_pk_bf16_f32 v141, v200, v201
	global_store_dwordx4 v[196:197], v[138:141], off offset:256
	v_cvt_pk_bf16_f32 v163, v202, v203
	v_cvt_pk_bf16_f32 v164, v216, v217
	s_waitcnt lgkmcnt(0)
	v_pk_add_f32 v[138:139], v[190:191], v[166:167]
	ds_bpermute_b32 v140, v3, v138
	ds_bpermute_b32 v141, v3, v139
	v_cvt_pk_bf16_f32 v165, v204, v205
	global_store_dwordx4 v[4:5], v[162:165], off
	global_store_dwordx4 v[4:5], v[186:189], off offset:256
	s_waitcnt lgkmcnt(0)
	v_pk_add_f32 v[136:137], v[138:139], v[140:141]
	s_cbranch_vccz .LBB0_1487
	s_and_saveexec_b64 s[0:1], s[2:3]
	s_cbranch_execz .LBB0_1468
	s_ashr_i32 s39, s38, 31
	v_lshl_add_u64 v[4:5], s[38:39], 2, v[156:157]
	global_atomic_add_f32 v[4:5], v142, off
	global_atomic_add_f32 v[4:5], v143, off offset:64
	global_atomic_add_f32 v[4:5], v144, off offset:128
	global_atomic_add_f32 v[4:5], v145, off offset:192
	global_atomic_add_f32 v[4:5], v134, off offset:512
	global_atomic_add_f32 v[4:5], v135, off offset:576
	global_atomic_add_f32 v[4:5], v136, off offset:640
	global_atomic_add_f32 v[4:5], v137, off offset:704
	s_branch .LBB0_1468

.LBB0_1508:
	s_ashr_i32 s29, s28, 31
	s_lshl_b64 s[34:35], s[28:29], 17
	s_add_u32 s34, s45, s34
	s_addc_u32 s35, s46, s35
	s_andn2_b64 vcc, exec, s[18:19]
	s_cbranch_vccnz .LBB0_1513
	s_and_b64 s[6:7], s[6:7], exec
	s_cselect_b32 s29, s35, s15
	s_cselect_b32 s69, s34, s14
	s_lshl_b32 s6, s38, 8
	s_ashr_i32 s7, s6, 31
	s_add_u32 s70, s12, 0x100
	v_lshl_add_u64 v[4:5], s[6:7], 2, v[142:143]
	s_addc_u32 s71, s13, 0
	v_lshl_add_u64 v[160:161], s[14:15], 0, v[144:145]
	v_lshl_add_u64 v[162:163], s[14:15], 0, v[146:147]
	s_mov_b32 s42, 0
	s_mov_b64 s[6:7], 0
	v_add_u32_e32 v3, 0x10000, v165
	ds_read_b128 v[168:171], v3
	ds_read_b128 v[172:175], v3 offset:1024
	ds_read_b128 v[176:179], v3 offset:2048
	ds_read_b128 v[180:183], v3 offset:3072
	s_branch .LBB0_1511
.LBB0_1510:
	s_or_b64 exec, exec, s[40:41]
	s_add_i32 s72, s42, 2
	s_add_u32 s40, s14, s6
	s_addc_u32 s41, s15, s7
	s_add_u32 s40, s40, 0x100
	s_addc_u32 s41, s41, 0
	s_add_u32 s73, s70, s6
	s_addc_u32 s43, s71, s7
	s_cmp_eq_u32 s59, s42
	s_cselect_b32 s42, s30, s73
	s_cselect_b32 s41, s29, s41
	s_cselect_b32 s40, s69, s40
	s_cselect_b32 s43, s31, s43
	v_lshl_add_u64 v[216:217], v[160:161], 0, s[6:7]
	s_add_i32 m0, s50, 0xc000
	ds_read_b128 v[184:187], v1
	ds_read_b128 v[188:191], v1 offset:1024
	ds_read_b128 v[192:195], v1 offset:2048
	ds_read_b128 v[196:199], v1 offset:3072
	ds_read_b128 v[200:203], v1 offset:4096
	ds_read_b128 v[204:207], v1 offset:5120
	ds_read_b128 v[208:211], v1 offset:6144
	ds_read_b128 v[212:215], v1 offset:7168
	global_load_lds_dwordx4 v[216:217], off
	v_lshl_add_u64 v[216:217], v[162:163], 0, s[6:7]
	s_add_i32 m0, s50, 0xe000
	s_nop 0
	global_load_lds_dwordx4 v[216:217], off
	s_waitcnt lgkmcnt(8)
	s_barrier
	s_waitcnt lgkmcnt(0)
	s_waitcnt lgkmcnt(0)
	v_mfma_f32_16x16x32_bf16 v[130:133], v[168:171], v[184:187], v[130:133]
	v_mfma_f32_16x16x32_bf16 v[126:129], v[176:179], v[184:187], v[126:129]
	v_mfma_f32_16x16x32_bf16 v[122:125], v[168:171], v[192:195], v[122:125]
	v_mfma_f32_16x16x32_bf16 v[118:121], v[176:179], v[192:195], v[118:121]
	v_mfma_f32_16x16x32_bf16 v[114:117], v[168:171], v[200:203], v[114:117]
	v_mfma_f32_16x16x32_bf16 v[110:113], v[176:179], v[200:203], v[110:113]
	v_mfma_f32_16x16x32_bf16 v[106:109], v[168:171], v[208:211], v[106:109]
	v_mfma_f32_16x16x32_bf16 v[98:101], v[176:179], v[208:211], v[98:101]
	v_mfma_f32_16x16x32_bf16 v[130:133], v[172:175], v[188:191], v[130:133]
	v_mfma_f32_16x16x32_bf16 v[126:129], v[180:183], v[188:191], v[126:129]
	v_mfma_f32_16x16x32_bf16 v[122:125], v[172:175], v[196:199], v[122:125]
	v_mfma_f32_16x16x32_bf16 v[118:121], v[180:183], v[196:199], v[118:121]
	v_mfma_f32_16x16x32_bf16 v[114:117], v[172:175], v[204:207], v[114:117]
	v_mfma_f32_16x16x32_bf16 v[110:113], v[180:183], v[204:207], v[110:113]
	v_mfma_f32_16x16x32_bf16 v[106:109], v[172:175], v[212:215], v[106:109]
	v_mfma_f32_16x16x32_bf16 v[98:101], v[180:183], v[212:215], v[98:101]
	s_barrier
	s_add_i32 s73, s60, s49
	v_add_u32_e32 v3, s61, v165
	v_lshl_add_u64 v[232:233], s[42:43], 0, v[136:137]
	s_mov_b32 m0, s73
	ds_read_b128 v[216:219], v3
	ds_read_b128 v[220:223], v3 offset:1024
	ds_read_b128 v[224:227], v3 offset:2048
	ds_read_b128 v[228:231], v3 offset:3072
	global_load_lds_dwordx4 v[232:233], off
	v_lshl_add_u64 v[234:235], s[42:43], 0, v[140:141]
	s_add_i32 m0, s73, 0x2000
	s_nop 0
	global_load_lds_dwordx4 v[234:235], off
	s_barrier
	s_waitcnt lgkmcnt(0)
	s_waitcnt lgkmcnt(0)
	v_mfma_f32_16x16x32_bf16 v[102:105], v[216:219], v[184:187], v[102:105]
	v_mfma_f32_16x16x32_bf16 v[94:97], v[224:227], v[184:187], v[94:97]
	v_mfma_f32_16x16x32_bf16 v[90:93], v[216:219], v[192:195], v[90:93]
	v_mfma_f32_16x16x32_bf16 v[86:89], v[224:227], v[192:195], v[86:89]
	v_mfma_f32_16x16x32_bf16 v[82:85], v[216:219], v[200:203], v[82:85]
	v_mfma_f32_16x16x32_bf16 v[78:81], v[224:227], v[200:203], v[78:81]
	v_mfma_f32_16x16x32_bf16 v[74:77], v[216:219], v[208:211], v[74:77]
	v_mfma_f32_16x16x32_bf16 v[70:73], v[224:227], v[208:211], v[70:73]
	v_mfma_f32_16x16x32_bf16 v[102:105], v[220:223], v[188:191], v[102:105]
	v_mfma_f32_16x16x32_bf16 v[94:97], v[228:231], v[188:191], v[94:97]
	v_mfma_f32_16x16x32_bf16 v[90:93], v[220:223], v[196:199], v[90:93]
	v_mfma_f32_16x16x32_bf16 v[86:89], v[228:231], v[196:199], v[86:89]
	v_mfma_f32_16x16x32_bf16 v[82:85], v[220:223], v[204:207], v[82:85]
	v_mfma_f32_16x16x32_bf16 v[78:81], v[228:231], v[204:207], v[78:81]
	v_mfma_f32_16x16x32_bf16 v[74:77], v[220:223], v[212:215], v[74:77]
	v_mfma_f32_16x16x32_bf16 v[70:73], v[228:231], v[212:215], v[70:73]
	s_mov_b32 m0, s50
	v_lshl_add_u64 v[236:237], s[40:41], 0, v[134:135]
	s_barrier
	ds_read_b128 v[184:187], v1 offset:16384
	ds_read_b128 v[188:191], v1 offset:17408
	ds_read_b128 v[192:195], v1 offset:18432
	ds_read_b128 v[196:199], v1 offset:19456
	ds_read_b128 v[200:203], v1 offset:20480
	ds_read_b128 v[204:207], v1 offset:21504
	ds_read_b128 v[208:211], v1 offset:22528
	ds_read_b128 v[212:215], v1 offset:23552
	global_load_lds_dwordx4 v[236:237], off
	v_lshl_add_u64 v[238:239], s[40:41], 0, v[138:139]
	s_mov_b32 m0, s51
	s_nop 0
	global_load_lds_dwordx4 v[238:239], off
	s_waitcnt vmcnt(10)
	s_barrier
	s_waitcnt lgkmcnt(0)
	s_waitcnt lgkmcnt(0)
	v_mfma_f32_16x16x32_bf16 v[66:69], v[168:171], v[184:187], v[66:69]
	v_mfma_f32_16x16x32_bf16 v[62:65], v[176:179], v[184:187], v[62:65]
	v_mfma_f32_16x16x32_bf16 v[58:61], v[168:171], v[192:195], v[58:61]
	v_mfma_f32_16x16x32_bf16 v[54:57], v[176:179], v[192:195], v[54:57]
	v_mfma_f32_16x16x32_bf16 v[50:53], v[168:171], v[200:203], v[50:53]
	v_mfma_f32_16x16x32_bf16 v[46:49], v[176:179], v[200:203], v[46:49]
	v_mfma_f32_16x16x32_bf16 v[42:45], v[168:171], v[208:211], v[42:45]
	v_mfma_f32_16x16x32_bf16 v[38:41], v[176:179], v[208:211], v[38:41]
	v_mfma_f32_16x16x32_bf16 v[66:69], v[172:175], v[188:191], v[66:69]
	v_mfma_f32_16x16x32_bf16 v[62:65], v[180:183], v[188:191], v[62:65]
	v_mfma_f32_16x16x32_bf16 v[58:61], v[172:175], v[196:199], v[58:61]
	v_mfma_f32_16x16x32_bf16 v[54:57], v[180:183], v[196:199], v[54:57]
	v_mfma_f32_16x16x32_bf16 v[50:53], v[172:175], v[204:207], v[50:53]
	v_mfma_f32_16x16x32_bf16 v[46:49], v[180:183], v[204:207], v[46:49]
	v_mfma_f32_16x16x32_bf16 v[42:45], v[172:175], v[212:215], v[42:45]
	v_mfma_f32_16x16x32_bf16 v[38:41], v[180:183], v[212:215], v[38:41]
	s_barrier
	v_add_u32_e32 v3, 0x18000, v165
	ds_read_b128 v[168:171], v3
	ds_read_b128 v[172:175], v3 offset:1024
	ds_read_b128 v[176:179], v3 offset:2048
	ds_read_b128 v[180:183], v3 offset:3072
	s_add_u32 s42, s42, s0
	s_addc_u32 s43, s43, s1
	s_add_i32 s73, s61, s49
	v_lshl_add_u64 v[240:241], s[42:43], 0, v[136:137]
	s_mov_b32 m0, s73
	v_lshl_add_u64 v[242:243], s[42:43], 0, v[140:141]
	global_load_lds_dwordx4 v[240:241], off
	s_add_i32 m0, s73, 0x2000
	s_nop 0
	global_load_lds_dwordx4 v[242:243], off
	s_waitcnt vmcnt(6)
	s_barrier
	v_mfma_f32_16x16x32_bf16 v[34:37], v[216:219], v[184:187], v[34:37]
	v_mfma_f32_16x16x32_bf16 v[30:33], v[224:227], v[184:187], v[30:33]
	v_mfma_f32_16x16x32_bf16 v[26:29], v[216:219], v[192:195], v[26:29]
	v_mfma_f32_16x16x32_bf16 v[22:25], v[224:227], v[192:195], v[22:25]
	v_mfma_f32_16x16x32_bf16 v[18:21], v[216:219], v[200:203], v[18:21]
	v_mfma_f32_16x16x32_bf16 v[14:17], v[224:227], v[200:203], v[14:17]
	v_mfma_f32_16x16x32_bf16 v[10:13], v[216:219], v[208:211], v[10:13]
	v_mfma_f32_16x16x32_bf16 v[6:9], v[224:227], v[208:211], v[6:9]
	v_mfma_f32_16x16x32_bf16 v[34:37], v[220:223], v[188:191], v[34:37]
	v_mfma_f32_16x16x32_bf16 v[30:33], v[228:231], v[188:191], v[30:33]
	v_mfma_f32_16x16x32_bf16 v[26:29], v[220:223], v[196:199], v[26:29]
	v_mfma_f32_16x16x32_bf16 v[22:25], v[228:231], v[196:199], v[22:25]
	v_mfma_f32_16x16x32_bf16 v[18:21], v[220:223], v[204:207], v[18:21]
	v_mfma_f32_16x16x32_bf16 v[14:17], v[228:231], v[204:207], v[14:17]
	v_mfma_f32_16x16x32_bf16 v[10:13], v[220:223], v[212:215], v[10:13]
	v_mfma_f32_16x16x32_bf16 v[6:9], v[228:231], v[212:215], v[6:9]
	s_add_i32 s42, 0, 0x18000
	s_barrier
	s_add_u32 s40, s40, 0x10000
	s_addc_u32 s41, s41, 0
	s_mov_b32 m0, s52
	v_lshl_add_u64 v[216:217], s[40:41], 0, v[134:135]
	ds_read_b128 v[184:187], v1 offset:32768
	ds_read_b128 v[188:191], v1 offset:33792
	ds_read_b128 v[192:195], v1 offset:34816
	ds_read_b128 v[196:199], v1 offset:35840
	ds_read_b128 v[200:203], v1 offset:36864
	ds_read_b128 v[204:207], v1 offset:37888
	ds_read_b128 v[208:211], v1 offset:38912
	ds_read_b128 v[212:215], v1 offset:39936
	global_load_lds_dwordx4 v[216:217], off
	v_lshl_add_u64 v[216:217], s[40:41], 0, v[138:139]
	s_mov_b32 m0, s53
	s_nop 0
	global_load_lds_dwordx4 v[216:217], off
	s_waitcnt lgkmcnt(8)
	s_barrier
	s_waitcnt lgkmcnt(0)
	s_waitcnt lgkmcnt(0)
	v_mfma_f32_16x16x32_bf16 v[130:133], v[168:171], v[184:187], v[130:133]
	v_mfma_f32_16x16x32_bf16 v[126:129], v[176:179], v[184:187], v[126:129]
	v_mfma_f32_16x16x32_bf16 v[122:125], v[168:171], v[192:195], v[122:125]
	v_mfma_f32_16x16x32_bf16 v[118:121], v[176:179], v[192:195], v[118:121]
	v_mfma_f32_16x16x32_bf16 v[114:117], v[168:171], v[200:203], v[114:117]
	v_mfma_f32_16x16x32_bf16 v[110:113], v[176:179], v[200:203], v[110:113]
	v_mfma_f32_16x16x32_bf16 v[106:109], v[168:171], v[208:211], v[106:109]
	v_mfma_f32_16x16x32_bf16 v[98:101], v[176:179], v[208:211], v[98:101]
	v_mfma_f32_16x16x32_bf16 v[130:133], v[172:175], v[188:191], v[130:133]
	v_mfma_f32_16x16x32_bf16 v[126:129], v[180:183], v[188:191], v[126:129]
	v_mfma_f32_16x16x32_bf16 v[122:125], v[172:175], v[196:199], v[122:125]
	v_mfma_f32_16x16x32_bf16 v[118:121], v[180:183], v[196:199], v[118:121]
	v_mfma_f32_16x16x32_bf16 v[114:117], v[172:175], v[204:207], v[114:117]
	v_mfma_f32_16x16x32_bf16 v[110:113], v[180:183], v[204:207], v[110:113]
	v_mfma_f32_16x16x32_bf16 v[106:109], v[172:175], v[212:215], v[106:109]
	v_mfma_f32_16x16x32_bf16 v[98:101], v[180:183], v[212:215], v[98:101]
	s_barrier
	s_add_i32 s40, 0, 0x1c000
	s_add_i32 s41, s42, s49
	v_add_u32_e32 v3, s40, v165
	v_lshl_add_u64 v[232:233], v[232:233], 0, s[16:17]
	s_mov_b32 m0, s41
	ds_read_b128 v[216:219], v3
	ds_read_b128 v[220:223], v3 offset:1024
	ds_read_b128 v[224:227], v3 offset:2048
	ds_read_b128 v[228:231], v3 offset:3072
	global_load_lds_dwordx4 v[232:233], off
	v_lshl_add_u64 v[232:233], v[234:235], 0, s[16:17]
	s_add_i32 m0, s41, 0x2000
	s_nop 0
	global_load_lds_dwordx4 v[232:233], off
	s_barrier
	s_waitcnt lgkmcnt(0)
	s_waitcnt lgkmcnt(0)
	v_mfma_f32_16x16x32_bf16 v[102:105], v[216:219], v[184:187], v[102:105]
	v_mfma_f32_16x16x32_bf16 v[94:97], v[224:227], v[184:187], v[94:97]
	v_mfma_f32_16x16x32_bf16 v[90:93], v[216:219], v[192:195], v[90:93]
	v_mfma_f32_16x16x32_bf16 v[86:89], v[224:227], v[192:195], v[86:89]
	v_mfma_f32_16x16x32_bf16 v[82:85], v[216:219], v[200:203], v[82:85]
	v_mfma_f32_16x16x32_bf16 v[78:81], v[224:227], v[200:203], v[78:81]
	v_mfma_f32_16x16x32_bf16 v[74:77], v[216:219], v[208:211], v[74:77]
	v_mfma_f32_16x16x32_bf16 v[70:73], v[224:227], v[208:211], v[70:73]
	v_mfma_f32_16x16x32_bf16 v[102:105], v[220:223], v[188:191], v[102:105]
	v_mfma_f32_16x16x32_bf16 v[94:97], v[228:231], v[188:191], v[94:97]
	v_mfma_f32_16x16x32_bf16 v[90:93], v[220:223], v[196:199], v[90:93]
	v_mfma_f32_16x16x32_bf16 v[86:89], v[228:231], v[196:199], v[86:89]
	v_mfma_f32_16x16x32_bf16 v[82:85], v[220:223], v[204:207], v[82:85]
	v_mfma_f32_16x16x32_bf16 v[78:81], v[228:231], v[204:207], v[78:81]
	v_mfma_f32_16x16x32_bf16 v[74:77], v[220:223], v[212:215], v[74:77]
	v_mfma_f32_16x16x32_bf16 v[70:73], v[228:231], v[212:215], v[70:73]
	s_mov_b32 m0, s56
	v_lshl_add_u64 v[232:233], v[236:237], 0, s[16:17]
	s_barrier
	ds_read_b128 v[184:187], v1 offset:49152
	ds_read_b128 v[188:191], v1 offset:50176
	ds_read_b128 v[192:195], v1 offset:51200
	ds_read_b128 v[196:199], v1 offset:52224
	ds_read_b128 v[200:203], v1 offset:53248
	ds_read_b128 v[204:207], v1 offset:54272
	ds_read_b128 v[208:211], v1 offset:55296
	ds_read_b128 v[212:215], v1 offset:56320
	global_load_lds_dwordx4 v[232:233], off
	v_lshl_add_u64 v[232:233], v[238:239], 0, s[16:17]
	s_mov_b32 m0, s57
	s_nop 0
	global_load_lds_dwordx4 v[232:233], off
	s_waitcnt vmcnt(10)
	s_barrier
	s_waitcnt lgkmcnt(0)
	s_waitcnt lgkmcnt(0)
	v_mfma_f32_16x16x32_bf16 v[66:69], v[168:171], v[184:187], v[66:69]
	v_mfma_f32_16x16x32_bf16 v[62:65], v[176:179], v[184:187], v[62:65]
	v_mfma_f32_16x16x32_bf16 v[58:61], v[168:171], v[192:195], v[58:61]
	v_mfma_f32_16x16x32_bf16 v[54:57], v[176:179], v[192:195], v[54:57]
	v_mfma_f32_16x16x32_bf16 v[50:53], v[168:171], v[200:203], v[50:53]
	v_mfma_f32_16x16x32_bf16 v[46:49], v[176:179], v[200:203], v[46:49]
	v_mfma_f32_16x16x32_bf16 v[42:45], v[168:171], v[208:211], v[42:45]
	v_mfma_f32_16x16x32_bf16 v[38:41], v[176:179], v[208:211], v[38:41]
	v_mfma_f32_16x16x32_bf16 v[66:69], v[172:175], v[188:191], v[66:69]
	v_mfma_f32_16x16x32_bf16 v[62:65], v[180:183], v[188:191], v[62:65]
	v_mfma_f32_16x16x32_bf16 v[58:61], v[172:175], v[196:199], v[58:61]
	v_mfma_f32_16x16x32_bf16 v[54:57], v[180:183], v[196:199], v[54:57]
	v_mfma_f32_16x16x32_bf16 v[50:53], v[172:175], v[204:207], v[50:53]
	v_mfma_f32_16x16x32_bf16 v[46:49], v[180:183], v[204:207], v[46:49]
	v_mfma_f32_16x16x32_bf16 v[42:45], v[172:175], v[212:215], v[42:45]
	v_mfma_f32_16x16x32_bf16 v[38:41], v[180:183], v[212:215], v[38:41]
	s_barrier
	v_add_u32_e32 v3, 0x10000, v165
	ds_read_b128 v[168:171], v3
	ds_read_b128 v[172:175], v3 offset:1024
	ds_read_b128 v[176:179], v3 offset:2048
	ds_read_b128 v[180:183], v3 offset:3072
	s_add_i32 s40, s40, s49
	v_lshl_add_u64 v[240:241], v[240:241], 0, s[16:17]
	s_mov_b32 m0, s40
	s_nop 0
	global_load_lds_dwordx4 v[240:241], off
	v_lshl_add_u64 v[242:243], v[242:243], 0, s[16:17]
	s_add_i32 m0, s40, 0x2000
	s_nop 0
	global_load_lds_dwordx4 v[242:243], off
	s_waitcnt vmcnt(6)
	s_barrier
	v_mfma_f32_16x16x32_bf16 v[34:37], v[216:219], v[184:187], v[34:37]
	v_mfma_f32_16x16x32_bf16 v[30:33], v[224:227], v[184:187], v[30:33]
	v_mfma_f32_16x16x32_bf16 v[26:29], v[216:219], v[192:195], v[26:29]
	v_mfma_f32_16x16x32_bf16 v[22:25], v[224:227], v[192:195], v[22:25]
	v_mfma_f32_16x16x32_bf16 v[18:21], v[216:219], v[200:203], v[18:21]
	v_mfma_f32_16x16x32_bf16 v[14:17], v[224:227], v[200:203], v[14:17]
	v_mfma_f32_16x16x32_bf16 v[10:13], v[216:219], v[208:211], v[10:13]
	v_mfma_f32_16x16x32_bf16 v[6:9], v[224:227], v[208:211], v[6:9]
	v_mfma_f32_16x16x32_bf16 v[34:37], v[220:223], v[188:191], v[34:37]
	v_mfma_f32_16x16x32_bf16 v[30:33], v[228:231], v[188:191], v[30:33]
	v_mfma_f32_16x16x32_bf16 v[26:29], v[220:223], v[196:199], v[26:29]
	v_mfma_f32_16x16x32_bf16 v[22:25], v[228:231], v[196:199], v[22:25]
	v_mfma_f32_16x16x32_bf16 v[18:21], v[220:223], v[204:207], v[18:21]
	v_mfma_f32_16x16x32_bf16 v[14:17], v[228:231], v[204:207], v[14:17]
	v_mfma_f32_16x16x32_bf16 v[10:13], v[220:223], v[212:215], v[10:13]
	v_mfma_f32_16x16x32_bf16 v[6:9], v[228:231], v[212:215], v[6:9]
	s_add_u32 s6, s6, 0x100
	s_addc_u32 s7, s7, 0
	s_andn2_b64 s[36:37], s[36:37], exec
	s_and_b64 s[40:41], s[38:39], exec
	s_or_b64 s[36:37], s[36:37], s[40:41]
	s_cmp_ge_i32 s72, s54
	s_mov_b32 s42, s72
	s_barrier
	s_cbranch_scc1 .LBB0_1513

.LBB0_1513:
	s_waitcnt lgkmcnt(0)
	v_mul_f32_e32 v156, v131, v131
	v_mul_f32_e32 v157, v123, v123
	v_fmac_f32_e32 v156, v130, v130
	v_fmac_f32_e32 v157, v122, v122
	v_fmac_f32_e32 v156, v132, v132
	v_fmac_f32_e32 v157, v124, v124
	v_fmac_f32_e32 v156, v133, v133
	v_fmac_f32_e32 v157, v125, v125
	v_fmac_f32_e32 v156, v126, v126
	v_fmac_f32_e32 v157, v118, v118
	v_fmac_f32_e32 v156, v127, v127
	v_fmac_f32_e32 v157, v119, v119
	v_fmac_f32_e32 v156, v128, v128
	v_mul_f32_e32 v162, v129, v129
	v_fmac_f32_e32 v157, v120, v120
	v_mul_f32_e32 v163, v121, v121
	v_pk_add_f32 v[156:157], v[162:163], v[156:157]
	v_mov_b32_e32 v162, v102
	v_mov_b32_e32 v163, v90
	v_pk_fma_f32 v[156:157], v[162:163], v[162:163], v[156:157]
	v_mov_b32_e32 v162, v103
	v_mov_b32_e32 v163, v91
	v_pk_fma_f32 v[156:157], v[162:163], v[162:163], v[156:157]
	v_mov_b32_e32 v162, v104
	v_mov_b32_e32 v163, v92
	v_pk_fma_f32 v[156:157], v[162:163], v[162:163], v[156:157]
	v_mov_b32_e32 v162, v105
	v_mov_b32_e32 v163, v93
	v_and_b32_e32 v5, 64, v167
	v_pk_fma_f32 v[156:157], v[162:163], v[162:163], v[156:157]
	v_mov_b32_e32 v162, v94
	v_mov_b32_e32 v163, v86
	v_xor_b32_e32 v3, 16, v167
	v_add_u32_e32 v5, 64, v5
	v_pk_fma_f32 v[156:157], v[162:163], v[162:163], v[156:157]
	v_mov_b32_e32 v162, v95
	v_mov_b32_e32 v163, v87
	v_cmp_lt_i32_e32 vcc, v3, v5
	v_pk_fma_f32 v[156:157], v[162:163], v[162:163], v[156:157]
	v_mov_b32_e32 v162, v96
	v_mov_b32_e32 v163, v88
	v_cndmask_b32_e32 v3, v167, v3, vcc
	v_pk_fma_f32 v[156:157], v[162:163], v[162:163], v[156:157]
	v_mov_b32_e32 v162, v97
	v_mov_b32_e32 v163, v89
	s_lshl_b32 s6, s66, 8
	v_lshlrev_b32_e32 v158, 2, v3
	v_pk_fma_f32 v[156:157], v[162:163], v[162:163], v[156:157]
	v_add_u32_e32 v160, s6, v164
	ds_bpermute_b32 v162, v158, v156
	ds_bpermute_b32 v163, v158, v157
	v_lshl_or_b32 v4, s58, 8, v166
	v_xor_b32_e32 v3, 32, v167
	v_ashrrev_i32_e32 v161, 31, v160
	v_cmp_lt_i32_e32 vcc, v3, v5
	v_lshlrev_b64 v[168:169], 12, v[160:161]
	v_ashrrev_i32_e32 v5, 31, v4
	v_lshl_add_u64 v[168:169], s[90:91], 0, v[168:169]
	v_lshlrev_b64 v[170:171], 1, v[4:5]
	v_cndmask_b32_e32 v3, v167, v3, vcc
	v_lshl_add_u64 v[4:5], v[168:169], 0, v[170:171]
	v_or_b32_e32 v168, 16, v160
	v_lshlrev_b32_e32 v3, 2, v3
	v_ashrrev_i32_e32 v169, 31, v168
	s_waitcnt lgkmcnt(0)
	v_pk_add_f32 v[156:157], v[156:157], v[162:163]
	v_cvt_pk_bf16_f32 v152, v130, v131
	v_cvt_pk_bf16_f32 v153, v132, v133
	v_cvt_pk_bf16_f32 v154, v126, v127
	v_cvt_pk_bf16_f32 v155, v128, v129
	v_lshlrev_b64 v[168:169], 12, v[168:169]
	ds_bpermute_b32 v162, v3, v156
	ds_bpermute_b32 v163, v3, v157
	global_store_dwordx4 v[4:5], v[152:155], off
	v_lshl_add_u64 v[168:169], s[90:91], 0, v[168:169]
	v_lshl_add_u64 v[168:169], v[168:169], 0, v[170:171]
	v_cvt_pk_bf16_f32 v152, v102, v103
	v_cvt_pk_bf16_f32 v153, v104, v105
	v_cvt_pk_bf16_f32 v154, v94, v95
	v_cvt_pk_bf16_f32 v155, v96, v97
	global_store_dwordx4 v[4:5], v[152:155], off offset:256
	v_mul_f32_e32 v172, v113, v113
	v_mul_f32_e32 v173, v101, v101
	v_cvt_pk_bf16_f32 v152, v122, v123
	v_cvt_pk_bf16_f32 v153, v124, v125
	v_cvt_pk_bf16_f32 v154, v118, v119
	v_cvt_pk_bf16_f32 v155, v120, v121
	global_store_dwordx4 v[168:169], v[152:155], off
	v_cvt_pk_bf16_f32 v159, v12, v13
	s_nop 0
	v_cvt_pk_bf16_f32 v152, v90, v91
	v_cvt_pk_bf16_f32 v153, v92, v93
	v_cvt_pk_bf16_f32 v154, v86, v87
	v_cvt_pk_bf16_f32 v155, v88, v89
	global_store_dwordx4 v[168:169], v[152:155], off offset:256
	v_mul_f32_e32 v168, v115, v115
	v_mul_f32_e32 v169, v107, v107
	s_waitcnt lgkmcnt(0)
	v_pk_add_f32 v[152:153], v[156:157], v[162:163]
	v_or_b32_e32 v162, 32, v160
	v_fmac_f32_e32 v168, v114, v114
	v_fmac_f32_e32 v169, v106, v106
	v_ashrrev_i32_e32 v163, 31, v162
	v_fmac_f32_e32 v168, v116, v116
	v_fmac_f32_e32 v169, v108, v108
	v_fmac_f32_e32 v168, v117, v117
	v_lshlrev_b64 v[162:163], 12, v[162:163]
	v_fmac_f32_e32 v169, v109, v109
	v_fmac_f32_e32 v168, v110, v110
	v_lshl_add_u64 v[162:163], s[90:91], 0, v[162:163]
	v_fmac_f32_e32 v169, v98, v98
	v_fmac_f32_e32 v168, v111, v111
	v_cvt_pk_bf16_f32 v154, v114, v115
	v_cvt_pk_bf16_f32 v155, v116, v117
	v_cvt_pk_bf16_f32 v156, v110, v111
	v_cvt_pk_bf16_f32 v157, v112, v113
	v_lshl_add_u64 v[162:163], v[162:163], 0, v[170:171]
	v_fmac_f32_e32 v169, v99, v99
	v_fmac_f32_e32 v168, v112, v112
	global_store_dwordx4 v[162:163], v[154:157], off
	v_fmac_f32_e32 v169, v100, v100
	v_or_b32_e32 v160, 48, v160
	v_cvt_pk_bf16_f32 v154, v82, v83
	v_cvt_pk_bf16_f32 v155, v84, v85
	v_cvt_pk_bf16_f32 v156, v78, v79
	v_cvt_pk_bf16_f32 v157, v80, v81
	global_store_dwordx4 v[162:163], v[154:157], off offset:256
	v_pk_add_f32 v[162:163], v[172:173], v[168:169]
	v_mov_b32_e32 v168, v82
	v_mov_b32_e32 v169, v74
	v_pk_fma_f32 v[162:163], v[168:169], v[168:169], v[162:163]
	v_mov_b32_e32 v168, v83
	v_mov_b32_e32 v169, v75
	v_pk_fma_f32 v[162:163], v[168:169], v[168:169], v[162:163]
	v_mov_b32_e32 v168, v84
	v_mov_b32_e32 v169, v76
	v_pk_fma_f32 v[162:163], v[168:169], v[168:169], v[162:163]
	v_mov_b32_e32 v168, v85
	v_mov_b32_e32 v169, v77
	v_pk_fma_f32 v[162:163], v[168:169], v[168:169], v[162:163]
	v_mov_b32_e32 v168, v78
	v_mov_b32_e32 v169, v70
	v_pk_fma_f32 v[162:163], v[168:169], v[168:169], v[162:163]
	v_mov_b32_e32 v168, v79
	v_mov_b32_e32 v169, v71
	v_pk_fma_f32 v[162:163], v[168:169], v[168:169], v[162:163]
	v_mov_b32_e32 v168, v80
	v_mov_b32_e32 v169, v72
	v_pk_fma_f32 v[162:163], v[168:169], v[168:169], v[162:163]
	v_mov_b32_e32 v168, v81
	v_mov_b32_e32 v169, v73
	v_pk_fma_f32 v[162:163], v[168:169], v[168:169], v[162:163]
	v_ashrrev_i32_e32 v161, 31, v160
	ds_bpermute_b32 v168, v158, v162
	ds_bpermute_b32 v169, v158, v163
	v_lshlrev_b64 v[160:161], 12, v[160:161]
	v_lshl_add_u64 v[160:161], s[90:91], 0, v[160:161]
	v_cvt_pk_bf16_f32 v154, v106, v107
	v_cvt_pk_bf16_f32 v155, v108, v109
	v_cvt_pk_bf16_f32 v156, v98, v99
	v_cvt_pk_bf16_f32 v157, v100, v101
	v_lshl_add_u64 v[160:161], v[160:161], 0, v[170:171]
	global_store_dwordx4 v[160:161], v[154:157], off
	s_waitcnt lgkmcnt(0)
	v_pk_add_f32 v[162:163], v[162:163], v[168:169]
	ds_bpermute_b32 v168, v3, v162
	v_cvt_pk_bf16_f32 v154, v74, v75
	v_cvt_pk_bf16_f32 v155, v76, v77
	v_cvt_pk_bf16_f32 v156, v70, v71
	v_cvt_pk_bf16_f32 v157, v72, v73
	global_store_dwordx4 v[160:161], v[154:157], off offset:256
	ds_bpermute_b32 v169, v3, v163
	v_add_co_u32_e32 v172, vcc, s62, v4
	v_mul_f32_e32 v156, v67, v67
	v_mul_f32_e32 v157, v59, v59
	v_fmac_f32_e32 v156, v66, v66
	v_fmac_f32_e32 v157, v58, v58
	v_fmac_f32_e32 v156, v68, v68
	v_fmac_f32_e32 v157, v60, v60
	v_fmac_f32_e32 v156, v69, v69
	v_fmac_f32_e32 v157, v61, v61
	v_fmac_f32_e32 v156, v62, v62
	v_fmac_f32_e32 v157, v54, v54
	v_fmac_f32_e32 v156, v63, v63
	v_fmac_f32_e32 v157, v55, v55
	s_waitcnt lgkmcnt(0)
	v_pk_add_f32 v[154:155], v[162:163], v[168:169]
	v_fmac_f32_e32 v156, v64, v64
	v_mul_f32_e32 v168, v65, v65
	v_fmac_f32_e32 v157, v56, v56
	v_mul_f32_e32 v169, v57, v57
	v_pk_add_f32 v[156:157], v[168:169], v[156:157]
	v_mov_b32_e32 v168, v34
	v_mov_b32_e32 v169, v26
	v_pk_fma_f32 v[156:157], v[168:169], v[168:169], v[156:157]
	v_mov_b32_e32 v168, v35
	v_mov_b32_e32 v169, v27
	v_pk_fma_f32 v[156:157], v[168:169], v[168:169], v[156:157]
	v_mov_b32_e32 v168, v36
	v_mov_b32_e32 v169, v28
	v_pk_fma_f32 v[156:157], v[168:169], v[168:169], v[156:157]
	v_mov_b32_e32 v168, v37
	v_mov_b32_e32 v169, v29
	v_pk_fma_f32 v[156:157], v[168:169], v[168:169], v[156:157]
	v_mov_b32_e32 v168, v30
	v_mov_b32_e32 v169, v22
	v_pk_fma_f32 v[156:157], v[168:169], v[168:169], v[156:157]
	v_mov_b32_e32 v168, v31
	v_mov_b32_e32 v169, v23
	v_pk_fma_f32 v[156:157], v[168:169], v[168:169], v[156:157]
	v_mov_b32_e32 v168, v32
	v_mov_b32_e32 v169, v24
	v_pk_fma_f32 v[156:157], v[168:169], v[168:169], v[156:157]
	v_mov_b32_e32 v168, v33
	v_mov_b32_e32 v169, v25
	v_pk_fma_f32 v[156:157], v[168:169], v[168:169], v[156:157]
	ds_bpermute_b32 v168, v158, v156
	ds_bpermute_b32 v169, v158, v157
	v_cvt_pk_bf16_f32 v160, v66, v67
	v_cvt_pk_bf16_f32 v161, v68, v69
	v_cvt_pk_bf16_f32 v162, v62, v63
	v_cvt_pk_bf16_f32 v163, v64, v65
	s_waitcnt lgkmcnt(0)
	v_pk_add_f32 v[156:157], v[156:157], v[168:169]
	ds_bpermute_b32 v168, v3, v156
	ds_bpermute_b32 v169, v3, v157
	v_addc_co_u32_e32 v173, vcc, 0, v5, vcc
	v_lshl_add_u64 v[170:171], v[4:5], 0, s[20:21]
	global_store_dwordx4 v[172:173], v[160:163], off
	s_waitcnt lgkmcnt(0)
	v_pk_add_f32 v[156:157], v[156:157], v[168:169]
	v_mul_f32_e32 v168, v51, v51
	v_mul_f32_e32 v169, v43, v43
	v_fmac_f32_e32 v168, v50, v50
	v_fmac_f32_e32 v169, v42, v42
	v_fmac_f32_e32 v168, v52, v52
	v_fmac_f32_e32 v169, v44, v44
	v_cvt_pk_bf16_f32 v160, v34, v35
	v_cvt_pk_bf16_f32 v161, v36, v37
	v_cvt_pk_bf16_f32 v162, v30, v31
	v_cvt_pk_bf16_f32 v163, v32, v33
	v_add_co_u32_e32 v172, vcc, s63, v4
	v_fmac_f32_e32 v168, v53, v53
	v_fmac_f32_e32 v169, v45, v45
	global_store_dwordx4 v[170:171], v[160:163], off offset:256
	v_addc_co_u32_e32 v173, vcc, 0, v5, vcc
	s_nop 0
	v_cvt_pk_bf16_f32 v160, v58, v59
	v_cvt_pk_bf16_f32 v161, v60, v61
	v_cvt_pk_bf16_f32 v162, v54, v55
	v_cvt_pk_bf16_f32 v163, v56, v57
	v_fmac_f32_e32 v168, v46, v46
	v_fmac_f32_e32 v169, v38, v38
	v_lshl_add_u64 v[170:171], v[4:5], 0, s[22:23]
	global_store_dwordx4 v[172:173], v[160:163], off
	v_fmac_f32_e32 v168, v47, v47
	v_fmac_f32_e32 v169, v39, v39
	v_cvt_pk_bf16_f32 v160, v26, v27
	v_cvt_pk_bf16_f32 v161, v28, v29
	v_cvt_pk_bf16_f32 v162, v22, v23
	v_cvt_pk_bf16_f32 v163, v24, v25
	global_store_dwordx4 v[170:171], v[160:163], off offset:256
	v_fmac_f32_e32 v168, v48, v48
	v_mul_f32_e32 v170, v49, v49
	v_fmac_f32_e32 v169, v40, v40
	v_mul_f32_e32 v171, v41, v41
	v_pk_add_f32 v[168:169], v[170:171], v[168:169]
	v_mov_b32_e32 v170, v18
	v_mov_b32_e32 v171, v10
	v_pk_fma_f32 v[168:169], v[170:171], v[170:171], v[168:169]
	v_mov_b32_e32 v170, v19
	v_mov_b32_e32 v171, v11
	v_pk_fma_f32 v[168:169], v[170:171], v[170:171], v[168:169]
	v_mov_b32_e32 v170, v20
	v_mov_b32_e32 v171, v12
	v_pk_fma_f32 v[168:169], v[170:171], v[170:171], v[168:169]
	v_mov_b32_e32 v170, v21
	v_mov_b32_e32 v171, v13
	v_pk_fma_f32 v[168:169], v[170:171], v[170:171], v[168:169]
	v_mov_b32_e32 v170, v14
	v_mov_b32_e32 v171, v6
	v_pk_fma_f32 v[168:169], v[170:171], v[170:171], v[168:169]
	v_mov_b32_e32 v170, v15
	v_mov_b32_e32 v171, v7
	v_pk_fma_f32 v[168:169], v[170:171], v[170:171], v[168:169]
	v_mov_b32_e32 v170, v16
	v_mov_b32_e32 v171, v8
	v_pk_fma_f32 v[168:169], v[170:171], v[170:171], v[168:169]
	v_mov_b32_e32 v170, v17
	v_mov_b32_e32 v171, v9
	v_pk_fma_f32 v[168:169], v[170:171], v[170:171], v[168:169]
	v_add_co_u32_e32 v174, vcc, s64, v4
	ds_bpermute_b32 v170, v158, v168
	ds_bpermute_b32 v171, v158, v169
	v_cvt_pk_bf16_f32 v160, v50, v51
	v_cvt_pk_bf16_f32 v161, v52, v53
	v_cvt_pk_bf16_f32 v162, v46, v47
	v_cvt_pk_bf16_f32 v163, v48, v49
	v_addc_co_u32_e32 v175, vcc, 0, v5, vcc
	v_lshl_add_u64 v[172:173], v[4:5], 0, s[24:25]
	global_store_dwordx4 v[174:175], v[160:163], off
	v_cvt_pk_bf16_f32 v158, v10, v11
	s_nop 0
	v_cvt_pk_bf16_f32 v160, v18, v19
	v_cvt_pk_bf16_f32 v161, v20, v21
	v_cvt_pk_bf16_f32 v162, v14, v15
	v_cvt_pk_bf16_f32 v163, v16, v17
	global_store_dwordx4 v[172:173], v[160:163], off offset:256
	v_lshl_add_u64 v[172:173], v[4:5], 0, s[26:27]
	v_add_co_u32_e32 v4, vcc, s65, v4
	v_cvt_pk_bf16_f32 v160, v42, v43
	v_cvt_pk_bf16_f32 v161, v44, v45
	v_cvt_pk_bf16_f32 v162, v38, v39
	v_cvt_pk_bf16_f32 v163, v40, v41
	v_addc_co_u32_e32 v5, vcc, 0, v5, vcc
	global_store_dwordx4 v[4:5], v[160:163], off
	s_waitcnt lgkmcnt(0)
	v_pk_add_f32 v[4:5], v[168:169], v[170:171]
	ds_bpermute_b32 v162, v3, v4
	ds_bpermute_b32 v163, v3, v5
	v_cvt_pk_bf16_f32 v160, v6, v7
	v_cvt_pk_bf16_f32 v161, v8, v9
	global_store_dwordx4 v[172:173], v[158:161], off offset:256
	s_and_b64 vcc, exec, s[4:5]
	s_waitcnt lgkmcnt(0)
	v_pk_add_f32 v[158:159], v[4:5], v[162:163]
	s_cbranch_vccz .LBB0_1516
	s_and_saveexec_b64 s[30:31], s[2:3]
	s_cbranch_execz .LBB0_1499
	s_ashr_i32 s7, s6, 31
	v_lshl_add_u64 v[4:5], s[6:7], 2, v[142:143]
	global_atomic_add_f32 v[4:5], v152, off
	global_atomic_add_f32 v[4:5], v153, off offset:64
	global_atomic_add_f32 v[4:5], v154, off offset:128
	global_atomic_add_f32 v[4:5], v155, off offset:192
	global_atomic_add_f32 v[4:5], v156, off offset:512
	global_atomic_add_f32 v[4:5], v157, off offset:576
	global_atomic_add_f32 v[4:5], v158, off offset:640
	global_atomic_add_f32 v[4:5], v159, off offset:704
	s_branch .LBB0_1499

.LBB0_1592:
	s_ashr_i32 s41, s40, 31
	s_lshl_b64 s[8:9], s[40:41], 20
	s_add_u32 s44, s16, s8
	s_addc_u32 s45, s17, s9
	s_andn2_b64 vcc, exec, s[38:39]
	s_cbranch_vccnz .LBB0_1598
	s_and_b64 s[6:7], s[6:7], exec
	s_cselect_b32 s33, s45, s25
	s_cselect_b32 s41, s44, s24
	s_lshl_b32 s6, s10, 8
	s_ashr_i32 s7, s6, 31
	s_add_u32 s46, s22, 0x100
	v_lshl_add_u64 v[4:5], s[6:7], 2, v[174:175]
	s_addc_u32 s68, s23, 0
	v_lshl_add_u64 v[136:137], s[24:25], 0, v[176:177]
	v_lshl_add_u64 v[138:139], s[24:25], 0, v[178:179]
	s_mov_b32 s12, 0
	s_mov_b64 s[6:7], 0
	v_add_u32_e32 v3, 0x10000, v228
	ds_read_b128 v[140:143], v3
	ds_read_b128 v[144:147], v3 offset:1024
	ds_read_b128 v[148:151], v3 offset:2048
	ds_read_b128 v[152:155], v3 offset:3072

.LBB0_1596:
	s_or_b64 exec, exec, s[10:11]
	s_add_i32 s69, s12, 2
	s_add_u32 s10, s24, s6
	s_addc_u32 s11, s25, s7
	s_add_u32 s10, s10, 0x100
	s_addc_u32 s11, s11, 0
	s_add_u32 s70, s46, s6
	s_addc_u32 s13, s68, s7
	s_cmp_eq_u32 s62, s12
	s_cselect_b32 s11, s33, s11
	s_cselect_b32 s10, s41, s10
	s_cselect_b32 s13, s43, s13
	s_cselect_b32 s12, s42, s70
	v_lshl_add_u64 v[164:165], v[136:137], 0, s[6:7]
	s_add_i32 m0, s53, 0xc000
	ds_read_b128 v[156:159], v230
	ds_read_b128 v[160:163], v230 offset:1024
	ds_read_b128 v[184:187], v230 offset:2048
	ds_read_b128 v[196:199], v230 offset:3072
	ds_read_b128 v[200:203], v230 offset:4096
	ds_read_b128 v[204:207], v230 offset:5120
	ds_read_b128 v[208:211], v230 offset:6144
	ds_read_b128 v[212:215], v230 offset:7168
	global_load_lds_dwordx4 v[164:165], off
	v_lshl_add_u64 v[164:165], v[138:139], 0, s[6:7]
	s_add_i32 m0, s53, 0xe000
	s_nop 0
	global_load_lds_dwordx4 v[164:165], off
	s_waitcnt lgkmcnt(8)
	s_barrier
	s_waitcnt lgkmcnt(0)
	s_waitcnt lgkmcnt(0)
	v_mfma_f32_16x16x32_bf16 v[130:133], v[140:143], v[156:159], v[130:133]
	v_mfma_f32_16x16x32_bf16 v[126:129], v[148:151], v[156:159], v[126:129]
	v_mfma_f32_16x16x32_bf16 v[122:125], v[140:143], v[184:187], v[122:125]
	v_mfma_f32_16x16x32_bf16 v[118:121], v[148:151], v[184:187], v[118:121]
	v_mfma_f32_16x16x32_bf16 v[114:117], v[140:143], v[200:203], v[114:117]
	v_mfma_f32_16x16x32_bf16 v[110:113], v[148:151], v[200:203], v[110:113]
	v_mfma_f32_16x16x32_bf16 v[106:109], v[140:143], v[208:211], v[106:109]
	v_mfma_f32_16x16x32_bf16 v[102:105], v[148:151], v[208:211], v[102:105]
	v_mfma_f32_16x16x32_bf16 v[130:133], v[144:147], v[160:163], v[130:133]
	v_mfma_f32_16x16x32_bf16 v[126:129], v[152:155], v[160:163], v[126:129]
	v_mfma_f32_16x16x32_bf16 v[122:125], v[144:147], v[196:199], v[122:125]
	v_mfma_f32_16x16x32_bf16 v[118:121], v[152:155], v[196:199], v[118:121]
	v_mfma_f32_16x16x32_bf16 v[114:117], v[144:147], v[204:207], v[114:117]
	v_mfma_f32_16x16x32_bf16 v[110:113], v[152:155], v[204:207], v[110:113]
	v_mfma_f32_16x16x32_bf16 v[106:109], v[144:147], v[212:215], v[106:109]
	v_mfma_f32_16x16x32_bf16 v[102:105], v[152:155], v[212:215], v[102:105]
	s_barrier
	s_add_i32 s70, s63, s52
	v_add_u32_e32 v3, s64, v228
	v_lshl_add_u64 v[164:165], s[12:13], 0, v[168:169]
	s_mov_b32 m0, s70
	ds_read_b128 v[216:219], v3
	ds_read_b128 v[220:223], v3 offset:1024
	ds_read_b128 v[224:227], v3 offset:2048
	ds_read_b128 v[234:237], v3 offset:3072
	global_load_lds_dwordx4 v[164:165], off
	v_lshl_add_u64 v[188:189], s[12:13], 0, v[172:173]
	s_add_i32 m0, s70, 0x2000
	s_nop 0
	global_load_lds_dwordx4 v[188:189], off
	s_barrier
	s_waitcnt lgkmcnt(0)
	s_waitcnt lgkmcnt(0)
	v_mfma_f32_16x16x32_bf16 v[98:101], v[216:219], v[156:159], v[98:101]
	v_mfma_f32_16x16x32_bf16 v[94:97], v[224:227], v[156:159], v[94:97]
	v_mfma_f32_16x16x32_bf16 v[90:93], v[216:219], v[184:187], v[90:93]
	v_mfma_f32_16x16x32_bf16 v[86:89], v[224:227], v[184:187], v[86:89]
	v_mfma_f32_16x16x32_bf16 v[82:85], v[216:219], v[200:203], v[82:85]
	v_mfma_f32_16x16x32_bf16 v[78:81], v[224:227], v[200:203], v[78:81]
	v_mfma_f32_16x16x32_bf16 v[74:77], v[216:219], v[208:211], v[74:77]
	v_mfma_f32_16x16x32_bf16 v[70:73], v[224:227], v[208:211], v[70:73]
	v_mfma_f32_16x16x32_bf16 v[98:101], v[220:223], v[160:163], v[98:101]
	v_mfma_f32_16x16x32_bf16 v[94:97], v[234:237], v[160:163], v[94:97]
	v_mfma_f32_16x16x32_bf16 v[90:93], v[220:223], v[196:199], v[90:93]
	v_mfma_f32_16x16x32_bf16 v[86:89], v[234:237], v[196:199], v[86:89]
	v_mfma_f32_16x16x32_bf16 v[82:85], v[220:223], v[204:207], v[82:85]
	v_mfma_f32_16x16x32_bf16 v[78:81], v[234:237], v[204:207], v[78:81]
	v_mfma_f32_16x16x32_bf16 v[74:77], v[220:223], v[212:215], v[74:77]
	v_mfma_f32_16x16x32_bf16 v[70:73], v[234:237], v[212:215], v[70:73]
	s_mov_b32 m0, s53
	v_lshl_add_u64 v[238:239], s[10:11], 0, v[166:167]
	s_barrier
	ds_read_b128 v[156:159], v230 offset:16384
	ds_read_b128 v[160:163], v230 offset:17408
	ds_read_b128 v[184:187], v230 offset:18432
	ds_read_b128 v[196:199], v230 offset:19456
	ds_read_b128 v[200:203], v230 offset:20480
	ds_read_b128 v[204:207], v230 offset:21504
	ds_read_b128 v[208:211], v230 offset:22528
	ds_read_b128 v[212:215], v230 offset:23552
	global_load_lds_dwordx4 v[238:239], off
	v_lshl_add_u64 v[240:241], s[10:11], 0, v[170:171]
	s_mov_b32 m0, s54
	s_nop 0
	global_load_lds_dwordx4 v[240:241], off
	s_waitcnt vmcnt(10)
	s_barrier
	s_waitcnt lgkmcnt(0)
	s_waitcnt lgkmcnt(0)
	v_mfma_f32_16x16x32_bf16 v[66:69], v[140:143], v[156:159], v[66:69]
	v_mfma_f32_16x16x32_bf16 v[62:65], v[148:151], v[156:159], v[62:65]
	v_mfma_f32_16x16x32_bf16 v[58:61], v[140:143], v[184:187], v[58:61]
	v_mfma_f32_16x16x32_bf16 v[54:57], v[148:151], v[184:187], v[54:57]
	v_mfma_f32_16x16x32_bf16 v[50:53], v[140:143], v[200:203], v[50:53]
	v_mfma_f32_16x16x32_bf16 v[46:49], v[148:151], v[200:203], v[46:49]
	v_mfma_f32_16x16x32_bf16 v[42:45], v[140:143], v[208:211], v[42:45]
	v_mfma_f32_16x16x32_bf16 v[38:41], v[148:151], v[208:211], v[38:41]
	v_mfma_f32_16x16x32_bf16 v[66:69], v[144:147], v[160:163], v[66:69]
	v_mfma_f32_16x16x32_bf16 v[62:65], v[152:155], v[160:163], v[62:65]
	v_mfma_f32_16x16x32_bf16 v[58:61], v[144:147], v[196:199], v[58:61]
	v_mfma_f32_16x16x32_bf16 v[54:57], v[152:155], v[196:199], v[54:57]
	v_mfma_f32_16x16x32_bf16 v[50:53], v[144:147], v[204:207], v[50:53]
	v_mfma_f32_16x16x32_bf16 v[46:49], v[152:155], v[204:207], v[46:49]
	v_mfma_f32_16x16x32_bf16 v[42:45], v[144:147], v[212:215], v[42:45]
	v_mfma_f32_16x16x32_bf16 v[38:41], v[152:155], v[212:215], v[38:41]
	s_barrier
	v_add_u32_e32 v3, 0x18000, v228
	ds_read_b128 v[140:143], v3
	ds_read_b128 v[144:147], v3 offset:1024
	ds_read_b128 v[148:151], v3 offset:2048
	ds_read_b128 v[152:155], v3 offset:3072
	s_add_u32 s12, s12, s18
	s_addc_u32 s13, s13, s19
	s_add_i32 s70, s64, s52
	v_lshl_add_u64 v[242:243], s[12:13], 0, v[168:169]
	s_mov_b32 m0, s70
	v_lshl_add_u64 v[244:245], s[12:13], 0, v[172:173]
	global_load_lds_dwordx4 v[242:243], off
	s_add_i32 m0, s70, 0x2000
	s_nop 0
	global_load_lds_dwordx4 v[244:245], off
	s_waitcnt vmcnt(6)
	s_barrier
	v_mfma_f32_16x16x32_bf16 v[34:37], v[216:219], v[156:159], v[34:37]
	v_mfma_f32_16x16x32_bf16 v[30:33], v[224:227], v[156:159], v[30:33]
	v_mfma_f32_16x16x32_bf16 v[26:29], v[216:219], v[184:187], v[26:29]
	v_mfma_f32_16x16x32_bf16 v[22:25], v[224:227], v[184:187], v[22:25]
	v_mfma_f32_16x16x32_bf16 v[18:21], v[216:219], v[200:203], v[18:21]
	v_mfma_f32_16x16x32_bf16 v[14:17], v[224:227], v[200:203], v[14:17]
	v_mfma_f32_16x16x32_bf16 v[10:13], v[216:219], v[208:211], v[10:13]
	v_mfma_f32_16x16x32_bf16 v[6:9], v[224:227], v[208:211], v[6:9]
	v_mfma_f32_16x16x32_bf16 v[34:37], v[220:223], v[160:163], v[34:37]
	v_mfma_f32_16x16x32_bf16 v[30:33], v[234:237], v[160:163], v[30:33]
	v_mfma_f32_16x16x32_bf16 v[26:29], v[220:223], v[196:199], v[26:29]
	v_mfma_f32_16x16x32_bf16 v[22:25], v[234:237], v[196:199], v[22:25]
	v_mfma_f32_16x16x32_bf16 v[18:21], v[220:223], v[204:207], v[18:21]
	v_mfma_f32_16x16x32_bf16 v[14:17], v[234:237], v[204:207], v[14:17]
	v_mfma_f32_16x16x32_bf16 v[10:13], v[220:223], v[212:215], v[10:13]
	v_mfma_f32_16x16x32_bf16 v[6:9], v[234:237], v[212:215], v[6:9]
	s_add_i32 s12, 0, 0x18000
	s_barrier
	s_add_u32 s10, s10, 0x80000
	s_addc_u32 s11, s11, 0
	s_mov_b32 m0, s55
	v_lshl_add_u64 v[216:217], s[10:11], 0, v[166:167]
	ds_read_b128 v[156:159], v230 offset:32768
	ds_read_b128 v[160:163], v230 offset:33792
	ds_read_b128 v[184:187], v230 offset:34816
	ds_read_b128 v[196:199], v230 offset:35840
	ds_read_b128 v[200:203], v230 offset:36864
	ds_read_b128 v[204:207], v230 offset:37888
	ds_read_b128 v[208:211], v230 offset:38912
	ds_read_b128 v[212:215], v230 offset:39936
	global_load_lds_dwordx4 v[216:217], off
	v_lshl_add_u64 v[216:217], s[10:11], 0, v[170:171]
	s_mov_b32 m0, s56
	s_nop 0
	global_load_lds_dwordx4 v[216:217], off
	s_waitcnt lgkmcnt(8)
	s_barrier
	s_waitcnt lgkmcnt(0)
	s_waitcnt lgkmcnt(0)
	v_mfma_f32_16x16x32_bf16 v[130:133], v[140:143], v[156:159], v[130:133]
	v_mfma_f32_16x16x32_bf16 v[126:129], v[148:151], v[156:159], v[126:129]
	v_mfma_f32_16x16x32_bf16 v[122:125], v[140:143], v[184:187], v[122:125]
	v_mfma_f32_16x16x32_bf16 v[118:121], v[148:151], v[184:187], v[118:121]
	v_mfma_f32_16x16x32_bf16 v[114:117], v[140:143], v[200:203], v[114:117]
	v_mfma_f32_16x16x32_bf16 v[110:113], v[148:151], v[200:203], v[110:113]
	v_mfma_f32_16x16x32_bf16 v[106:109], v[140:143], v[208:211], v[106:109]
	v_mfma_f32_16x16x32_bf16 v[102:105], v[148:151], v[208:211], v[102:105]
	v_mfma_f32_16x16x32_bf16 v[130:133], v[144:147], v[160:163], v[130:133]
	v_mfma_f32_16x16x32_bf16 v[126:129], v[152:155], v[160:163], v[126:129]
	v_mfma_f32_16x16x32_bf16 v[122:125], v[144:147], v[196:199], v[122:125]
	v_mfma_f32_16x16x32_bf16 v[118:121], v[152:155], v[196:199], v[118:121]
	v_mfma_f32_16x16x32_bf16 v[114:117], v[144:147], v[204:207], v[114:117]
	v_mfma_f32_16x16x32_bf16 v[110:113], v[152:155], v[204:207], v[110:113]
	v_mfma_f32_16x16x32_bf16 v[106:109], v[144:147], v[212:215], v[106:109]
	v_mfma_f32_16x16x32_bf16 v[102:105], v[152:155], v[212:215], v[102:105]
	s_barrier
	s_add_i32 s10, 0, 0x1c000
	s_add_i32 s11, s12, s52
	v_add_u32_e32 v3, s10, v228
	v_lshl_add_u64 v[164:165], v[164:165], 0, s[36:37]
	s_mov_b32 m0, s11
	ds_read_b128 v[216:219], v3
	ds_read_b128 v[220:223], v3 offset:1024
	ds_read_b128 v[224:227], v3 offset:2048
	ds_read_b128 v[234:237], v3 offset:3072
	global_load_lds_dwordx4 v[164:165], off
	v_lshl_add_u64 v[164:165], v[188:189], 0, s[36:37]
	s_add_i32 m0, s11, 0x2000
	s_nop 0
	global_load_lds_dwordx4 v[164:165], off
	s_barrier
	s_waitcnt lgkmcnt(0)
	s_waitcnt lgkmcnt(0)
	v_mfma_f32_16x16x32_bf16 v[98:101], v[216:219], v[156:159], v[98:101]
	v_mfma_f32_16x16x32_bf16 v[94:97], v[224:227], v[156:159], v[94:97]
	v_mfma_f32_16x16x32_bf16 v[90:93], v[216:219], v[184:187], v[90:93]
	v_mfma_f32_16x16x32_bf16 v[86:89], v[224:227], v[184:187], v[86:89]
	v_mfma_f32_16x16x32_bf16 v[82:85], v[216:219], v[200:203], v[82:85]
	v_mfma_f32_16x16x32_bf16 v[78:81], v[224:227], v[200:203], v[78:81]
	v_mfma_f32_16x16x32_bf16 v[74:77], v[216:219], v[208:211], v[74:77]
	v_mfma_f32_16x16x32_bf16 v[70:73], v[224:227], v[208:211], v[70:73]
	v_mfma_f32_16x16x32_bf16 v[98:101], v[220:223], v[160:163], v[98:101]
	v_mfma_f32_16x16x32_bf16 v[94:97], v[234:237], v[160:163], v[94:97]
	v_mfma_f32_16x16x32_bf16 v[90:93], v[220:223], v[196:199], v[90:93]
	v_mfma_f32_16x16x32_bf16 v[86:89], v[234:237], v[196:199], v[86:89]
	v_mfma_f32_16x16x32_bf16 v[82:85], v[220:223], v[204:207], v[82:85]
	v_mfma_f32_16x16x32_bf16 v[78:81], v[234:237], v[204:207], v[78:81]
	v_mfma_f32_16x16x32_bf16 v[74:77], v[220:223], v[212:215], v[74:77]
	v_mfma_f32_16x16x32_bf16 v[70:73], v[234:237], v[212:215], v[70:73]
	s_mov_b32 m0, s60
	v_lshl_add_u64 v[164:165], v[238:239], 0, s[36:37]
	s_barrier
	ds_read_b128 v[156:159], v230 offset:49152
	ds_read_b128 v[160:163], v230 offset:50176
	ds_read_b128 v[184:187], v230 offset:51200
	ds_read_b128 v[196:199], v230 offset:52224
	ds_read_b128 v[200:203], v230 offset:53248
	ds_read_b128 v[204:207], v230 offset:54272
	ds_read_b128 v[208:211], v230 offset:55296
	ds_read_b128 v[212:215], v230 offset:56320
	global_load_lds_dwordx4 v[164:165], off
	v_lshl_add_u64 v[164:165], v[240:241], 0, s[36:37]
	s_mov_b32 m0, s61
	s_nop 0
	global_load_lds_dwordx4 v[164:165], off
	s_waitcnt vmcnt(10)
	s_barrier
	s_waitcnt lgkmcnt(0)
	s_waitcnt lgkmcnt(0)
	v_mfma_f32_16x16x32_bf16 v[66:69], v[140:143], v[156:159], v[66:69]
	v_mfma_f32_16x16x32_bf16 v[62:65], v[148:151], v[156:159], v[62:65]
	v_mfma_f32_16x16x32_bf16 v[58:61], v[140:143], v[184:187], v[58:61]
	v_mfma_f32_16x16x32_bf16 v[54:57], v[148:151], v[184:187], v[54:57]
	v_mfma_f32_16x16x32_bf16 v[50:53], v[140:143], v[200:203], v[50:53]
	v_mfma_f32_16x16x32_bf16 v[46:49], v[148:151], v[200:203], v[46:49]
	v_mfma_f32_16x16x32_bf16 v[42:45], v[140:143], v[208:211], v[42:45]
	v_mfma_f32_16x16x32_bf16 v[38:41], v[148:151], v[208:211], v[38:41]
	v_mfma_f32_16x16x32_bf16 v[66:69], v[144:147], v[160:163], v[66:69]
	v_mfma_f32_16x16x32_bf16 v[62:65], v[152:155], v[160:163], v[62:65]
	v_mfma_f32_16x16x32_bf16 v[58:61], v[144:147], v[196:199], v[58:61]
	v_mfma_f32_16x16x32_bf16 v[54:57], v[152:155], v[196:199], v[54:57]
	v_mfma_f32_16x16x32_bf16 v[50:53], v[144:147], v[204:207], v[50:53]
	v_mfma_f32_16x16x32_bf16 v[46:49], v[152:155], v[204:207], v[46:49]
	v_mfma_f32_16x16x32_bf16 v[42:45], v[144:147], v[212:215], v[42:45]
	v_mfma_f32_16x16x32_bf16 v[38:41], v[152:155], v[212:215], v[38:41]
	s_barrier
	v_add_u32_e32 v3, 0x10000, v228
	ds_read_b128 v[140:143], v3
	ds_read_b128 v[144:147], v3 offset:1024
	ds_read_b128 v[148:151], v3 offset:2048
	ds_read_b128 v[152:155], v3 offset:3072
	s_add_i32 s10, s10, s52
	v_lshl_add_u64 v[242:243], v[242:243], 0, s[36:37]
	s_mov_b32 m0, s10
	s_nop 0
	global_load_lds_dwordx4 v[242:243], off
	v_lshl_add_u64 v[244:245], v[244:245], 0, s[36:37]
	s_add_i32 m0, s10, 0x2000
	s_nop 0
	global_load_lds_dwordx4 v[244:245], off
	s_waitcnt vmcnt(6)
	s_barrier
	v_mfma_f32_16x16x32_bf16 v[34:37], v[216:219], v[156:159], v[34:37]
	v_mfma_f32_16x16x32_bf16 v[30:33], v[224:227], v[156:159], v[30:33]
	v_mfma_f32_16x16x32_bf16 v[26:29], v[216:219], v[184:187], v[26:29]
	v_mfma_f32_16x16x32_bf16 v[22:25], v[224:227], v[184:187], v[22:25]
	v_mfma_f32_16x16x32_bf16 v[18:21], v[216:219], v[200:203], v[18:21]
	v_mfma_f32_16x16x32_bf16 v[14:17], v[224:227], v[200:203], v[14:17]
	v_mfma_f32_16x16x32_bf16 v[10:13], v[216:219], v[208:211], v[10:13]
	v_mfma_f32_16x16x32_bf16 v[6:9], v[224:227], v[208:211], v[6:9]
	v_mfma_f32_16x16x32_bf16 v[34:37], v[220:223], v[160:163], v[34:37]
	v_mfma_f32_16x16x32_bf16 v[30:33], v[234:237], v[160:163], v[30:33]
	v_mfma_f32_16x16x32_bf16 v[26:29], v[220:223], v[196:199], v[26:29]
	v_mfma_f32_16x16x32_bf16 v[22:25], v[234:237], v[196:199], v[22:25]
	v_mfma_f32_16x16x32_bf16 v[18:21], v[220:223], v[204:207], v[18:21]
	v_mfma_f32_16x16x32_bf16 v[14:17], v[234:237], v[204:207], v[14:17]
	v_mfma_f32_16x16x32_bf16 v[10:13], v[220:223], v[212:215], v[10:13]
	v_mfma_f32_16x16x32_bf16 v[6:9], v[234:237], v[212:215], v[6:9]
	s_add_u32 s6, s6, 0x100
	s_addc_u32 s7, s7, 0
	s_andn2_b64 s[0:1], s[0:1], exec
	s_and_b64 s[10:11], s[8:9], exec
	s_or_b64 s[0:1], s[0:1], s[10:11]
	s_cmp_ge_i32 s69, s57
	s_barrier
	s_cbranch_scc1 .LBB0_1598
	s_mov_b32 s12, s69
	s_branch .LBB0_1594
.LBB0_1598:
	s_waitcnt lgkmcnt(0)
	s_lshl_b32 s46, s66, 8
	v_add_u32_e32 v184, s46, v1
	v_ashrrev_i32_e32 v185, 31, v184
	v_lshlrev_b64 v[4:5], 2, v[184:185]
	v_lshl_add_u64 v[150:151], s[26:27], 0, v[4:5]
	v_lshl_add_u64 v[152:153], s[28:29], 0, v[4:5]
	global_load_dword v3, v[150:151], off
	global_load_dword v154, v[152:153], off
	v_or_b32_e32 v196, 16, v184
	v_ashrrev_i32_e32 v197, 31, v196
	v_or_b32_e32 v204, 32, v184
	v_or_b32_e32 v200, 48, v184
	v_lshlrev_b64 v[4:5], 2, v[196:197]
	v_ashrrev_i32_e32 v205, 31, v204
	v_ashrrev_i32_e32 v201, 31, v200
	v_lshl_add_u64 v[134:135], s[26:27], 0, v[4:5]
	v_lshlrev_b64 v[136:137], 2, v[204:205]
	v_lshlrev_b64 v[140:141], 2, v[200:201]
	v_lshl_add_u64 v[4:5], s[28:29], 0, v[4:5]
	v_lshl_add_u64 v[138:139], s[26:27], 0, v[136:137]
	v_lshl_add_u64 v[136:137], s[28:29], 0, v[136:137]
	v_lshl_add_u64 v[142:143], s[26:27], 0, v[140:141]
	global_load_dword v155, v[134:135], off
	global_load_dword v156, v[4:5], off
	global_load_dword v157, v[138:139], off
	global_load_dword v158, v[136:137], off
	global_load_dword v159, v[142:143], off
	v_lshl_add_u64 v[4:5], s[28:29], 0, v[140:141]
	global_load_dword v160, v[4:5], off
	global_load_dword v161, v[150:151], off offset:512
	global_load_dword v162, v[152:153], off offset:512
	v_lshl_or_b32 v188, s59, 8, v229
	v_ashrrev_i32_e32 v189, 31, v188
	v_lshl_add_u64 v[138:139], v[188:189], 2, s[34:35]
	global_load_dwordx4 v[142:145], v[138:139], off offset:16
	global_load_dwordx4 v[146:149], v[138:139], off
	global_load_dwordx4 v[134:137], v[138:139], off offset:528
	s_nop 0
	global_load_dwordx4 v[138:141], v[138:139], off offset:512
	s_nop 0
	global_load_dword v163, v[150:151], off offset:576
	global_load_dword v164, v[152:153], off offset:576
	global_load_dword v165, v[150:151], off offset:640
	global_load_dword v207, v[150:151], off offset:704
	global_load_dword v192, v[152:153], off offset:640
	global_load_dword v233, v[152:153], off offset:704
	v_add_u32_e32 v194, 0x80, v184
	v_add_u32_e32 v190, 0x90, v184
	v_add_u32_e32 v186, 0xa0, v184
	v_add_u32_e32 v4, 0xb0, v184
	v_ashrrev_i32_e32 v195, 31, v194
	v_ashrrev_i32_e32 v191, 31, v190
	v_ashrrev_i32_e32 v187, 31, v186
	v_ashrrev_i32_e32 v5, 31, v4
	s_waitcnt vmcnt(0)
	v_fmamk_f32 v3, v3, 0x3a000000, v231
	v_fmamk_f32 v150, v154, 0x3a000000, v231
	v_mul_f32_e32 v152, 0x4b800000, v150
	v_cmp_gt_f32_e64 s[6:7], s65, v150
	v_mul_f32_e32 v151, 0x4b800000, v3
	v_cmp_gt_f32_e64 s[0:1], s65, v3
	v_cndmask_b32_e64 v150, v150, v152, s[6:7]
	v_rsq_f32_e32 v150, v150
	v_cndmask_b32_e64 v3, v3, v151, s[0:1]
	v_rsq_f32_e32 v3, v3
	v_fmamk_f32 v153, v155, 0x3a000000, v231
	v_fmamk_f32 v154, v156, 0x3a000000, v231
	v_mul_f32_e32 v152, 0x4b800000, v154
	v_cmp_gt_f32_e64 s[10:11], s65, v154
	v_fmamk_f32 v155, v157, 0x3a000000, v231
	v_mul_f32_e32 v151, 0x4b800000, v153
	v_cmp_gt_f32_e64 s[8:9], s65, v153
	v_cndmask_b32_e64 v152, v154, v152, s[10:11]
	v_fmamk_f32 v156, v158, 0x3a000000, v231
	v_mul_f32_e32 v158, 0x4b800000, v155
	v_cndmask_b32_e64 v151, v153, v151, s[8:9]
	v_cmp_gt_f32_e64 s[12:13], s65, v155
	v_rsq_f32_e32 v152, v152
	v_rsq_f32_e32 v151, v151
	v_cndmask_b32_e64 v153, v155, v158, s[12:13]
	v_fmamk_f32 v157, v159, 0x3a000000, v231
	v_mul_f32_e32 v159, 0x4b800000, v156
	v_cmp_gt_f32_e32 vcc, s65, v156
	v_rsq_f32_e32 v153, v153
	v_mul_f32_e32 v155, 0x45800000, v3
	v_cndmask_b32_e32 v154, v156, v159, vcc
	v_mul_f32_e32 v156, 0x45800000, v150
	v_cndmask_b32_e64 v206, v150, v156, s[6:7]
	v_mul_f32_e32 v150, 0x45800000, v152
	v_cndmask_b32_e64 v237, v3, v155, s[0:1]
	v_mul_f32_e32 v3, 0x45800000, v151
	v_cndmask_b32_e64 v210, v152, v150, s[10:11]
	v_fmamk_f32 v150, v160, 0x3a000000, v231
	v_mul_f32_e32 v155, 0x45800000, v153
	v_cndmask_b32_e64 v211, v151, v3, s[8:9]
	v_mul_f32_e32 v151, 0x4b800000, v150
	v_cmp_gt_f32_e64 s[6:7], s65, v150
	v_cndmask_b32_e64 v209, v153, v155, s[12:13]
	v_mul_f32_e32 v193, 0x4b800000, v157
	v_cndmask_b32_e64 v155, v150, v151, s[6:7]
	v_lshlrev_b64 v[150:151], 11, v[184:185]
	v_lshl_add_u64 v[150:151], v[150:151], 0, v[188:189]
	v_lshlrev_b64 v[150:151], 1, v[150:151]
	v_lshl_add_u64 v[152:153], s[16:17], 0, v[150:151]
	global_load_dwordx4 v[216:219], v[152:153], off
	v_lshl_add_u64 v[152:153], s[90:91], 0, v[150:151]
	global_load_dwordx4 v[220:223], v[152:153], off nt
	global_load_dwordx4 v[224:227], v[152:153], off offset:256 nt
	v_cmp_gt_f32_e64 s[0:1], s65, v157
	v_rsq_f32_e32 v154, v154
	v_rsq_f32_e32 v155, v155
	v_cndmask_b32_e64 v3, v157, v193, s[0:1]
	v_rsq_f32_e32 v3, v3
	v_mul_f32_e32 v156, 0x45800000, v154
	v_cndmask_b32_e32 v208, v154, v156, vcc
	v_lshlrev_b64 v[152:153], 11, v[196:197]
	v_mul_f32_e32 v154, 0x45800000, v3
	v_cndmask_b32_e64 v203, v3, v154, s[0:1]
	v_fmamk_f32 v154, v161, 0x3a000000, v231
	v_mul_f32_e32 v156, 0x4b800000, v154
	v_cmp_gt_f32_e32 vcc, s65, v154
	v_mul_f32_e32 v3, 0x45800000, v155
	v_cndmask_b32_e64 v202, v155, v3, s[6:7]
	v_cndmask_b32_e32 v154, v154, v156, vcc
	v_rsq_f32_e32 v154, v154
	v_fmamk_f32 v156, v162, 0x3a000000, v231
	v_mul_f32_e32 v157, 0x4b800000, v156
	v_cmp_gt_f32_e64 s[0:1], s65, v156
	v_mul_f32_e32 v3, 0x45800000, v154
	v_cndmask_b32_e32 v199, v154, v3, vcc
	v_fmamk_f32 v154, v163, 0x3a000000, v231
	v_cndmask_b32_e64 v156, v156, v157, s[0:1]
	v_mul_f32_e32 v155, 0x4b800000, v154
	v_cmp_gt_f32_e32 vcc, s65, v154
	v_rsq_f32_e32 v156, v156
	v_or_b32_e32 v150, 0x100, v150
	v_cndmask_b32_e32 v154, v154, v155, vcc
	v_rsq_f32_e32 v154, v154
	v_mul_f32_e32 v3, 0x45800000, v156
	v_fmamk_f32 v155, v164, 0x3a000000, v231
	v_cndmask_b32_e64 v198, v156, v3, s[0:1]
	v_mul_f32_e32 v3, 0x45800000, v154
	v_mul_f32_e32 v157, 0x4b800000, v155
	v_cmp_gt_f32_e64 s[6:7], s65, v155
	v_cndmask_b32_e32 v193, v154, v3, vcc
	v_fmamk_f32 v154, v165, 0x3a000000, v231
	v_cndmask_b32_e64 v155, v155, v157, s[6:7]
	v_mul_f32_e32 v156, 0x4b800000, v154
	v_cmp_gt_f32_e64 s[0:1], s65, v154
	v_rsq_f32_e32 v155, v155
	v_lshl_add_u64 v[152:153], v[152:153], 0, v[188:189]
	v_cndmask_b32_e64 v154, v154, v156, s[0:1]
	v_rsq_f32_e32 v154, v154
	v_mul_f32_e32 v3, 0x45800000, v155
	v_fmamk_f32 v156, v192, 0x3a000000, v231
	v_cndmask_b32_e64 v192, v155, v3, s[6:7]
	v_mul_f32_e32 v3, 0x45800000, v154
	v_cndmask_b32_e64 v3, v154, v3, s[0:1]
	v_fmamk_f32 v154, v207, 0x3a000000, v231
	v_mul_f32_e32 v155, 0x4b800000, v154
	v_cmp_gt_f32_e64 s[6:7], s65, v154
	v_lshl_add_u64 v[150:151], s[16:17], 0, v[150:151]
	v_lshlrev_b64 v[152:153], 1, v[152:153]
	v_cndmask_b32_e64 v154, v154, v155, s[6:7]
	v_rsq_f32_e32 v236, v154
	v_lshl_add_u64 v[154:155], s[16:17], 0, v[152:153]
	global_load_dwordx4 v[238:241], v[150:151], off
	global_load_dwordx4 v[158:161], v[154:155], off
	v_mul_f32_e32 v157, 0x4b800000, v156
	v_cmp_gt_f32_e32 vcc, s65, v156
	v_lshl_add_u64 v[154:155], s[90:91], 0, v[152:153]
	v_or_b32_e32 v152, 0x100, v152
	v_cndmask_b32_e32 v156, v156, v157, vcc
	v_rsq_f32_e32 v234, v156
	v_mul_f32_e32 v156, v130, v237
	v_mul_f32_e32 v156, 0xbfb8aa3b, v156
	v_exp_f32_e32 v207, v156
	v_mul_f32_e32 v156, v131, v237
	v_lshl_add_u64 v[150:151], s[16:17], 0, v[152:153]
	v_mul_f32_e32 v156, 0xbfb8aa3b, v156
	global_load_dwordx4 v[150:153], v[150:151], off
	v_exp_f32_e32 v213, v156
	global_load_dwordx4 v[162:165], v[154:155], off nt
	s_nop 0
	global_load_dwordx4 v[154:157], v[154:155], off offset:256 nt
	v_add_f32_e32 v207, 1.0, v207
	v_rcp_f32_e32 v212, v207
	v_add_f32_e32 v207, 1.0, v213
	v_rcp_f32_e32 v213, v207
	s_waitcnt vmcnt(0)
	v_lshlrev_b32_e32 v242, 16, v220
	v_and_b32_e32 v243, 0xffff0000, v220
	v_pk_mul_f32 v[242:243], v[206:207], v[242:243] op_sel_hi:[0,1]
	v_mul_f32_e32 v207, v132, v237
	v_lshlrev_b32_e32 v214, 16, v216
	v_and_b32_e32 v215, 0xffff0000, v216
	v_mul_f32_e32 v207, 0xbfb8aa3b, v207
	v_mul_f32_e32 v216, v133, v237
	v_exp_f32_e32 v207, v207
	v_mul_f32_e32 v216, 0xbfb8aa3b, v216
	v_exp_f32_e32 v216, v216
	v_pk_mul_f32 v[242:243], v[146:147], v[242:243]
	v_add_f32_e32 v207, 1.0, v207
	v_pk_fma_f32 v[212:213], v[212:213], v[242:243], v[214:215]
	v_rcp_f32_e32 v214, v207
	v_add_f32_e32 v207, 1.0, v216
	v_lshlrev_b32_e32 v220, 16, v221
	v_and_b32_e32 v221, 0xffff0000, v221
	v_rcp_f32_e32 v215, v207
	v_pk_mul_f32 v[220:221], v[206:207], v[220:221] op_sel_hi:[0,1]
	v_mul_f32_e32 v207, v126, v237
	v_mul_f32_e32 v207, 0xbfb8aa3b, v207
	v_mul_f32_e32 v242, v127, v237
	v_exp_f32_e32 v207, v207
	v_mul_f32_e32 v242, 0xbfb8aa3b, v242
	v_exp_f32_e32 v242, v242
	v_lshlrev_b32_e32 v216, 16, v217
	v_and_b32_e32 v217, 0xffff0000, v217
	v_pk_mul_f32 v[220:221], v[148:149], v[220:221]
	v_add_f32_e32 v207, 1.0, v207
	v_pk_fma_f32 v[214:215], v[214:215], v[220:221], v[216:217]
	v_rcp_f32_e32 v216, v207
	v_add_f32_e32 v207, 1.0, v242
	v_lshlrev_b32_e32 v242, 16, v222
	v_and_b32_e32 v243, 0xffff0000, v222
	v_rcp_f32_e32 v217, v207
	v_pk_mul_f32 v[242:243], v[206:207], v[242:243] op_sel_hi:[0,1]
	v_mul_f32_e32 v207, v128, v237
	v_lshlrev_b32_e32 v220, 16, v218
	v_and_b32_e32 v221, 0xffff0000, v218
	v_mul_f32_e32 v207, 0xbfb8aa3b, v207
	v_mul_f32_e32 v218, v129, v237
	v_exp_f32_e32 v207, v207
	v_mul_f32_e32 v218, 0xbfb8aa3b, v218
	v_exp_f32_e32 v218, v218
	v_pk_mul_f32 v[242:243], v[142:143], v[242:243]
	v_add_f32_e32 v207, 1.0, v207
	v_pk_fma_f32 v[216:217], v[216:217], v[242:243], v[220:221]
	v_rcp_f32_e32 v220, v207
	v_add_f32_e32 v207, 1.0, v218
	v_lshlrev_b32_e32 v222, 16, v223
	v_and_b32_e32 v223, 0xffff0000, v223
	v_rcp_f32_e32 v221, v207
	v_pk_mul_f32 v[222:223], v[206:207], v[222:223] op_sel_hi:[0,1]
	v_mul_f32_e32 v207, v98, v237
	v_mul_f32_e32 v207, 0xbfb8aa3b, v207
	v_mul_f32_e32 v244, v99, v237
	v_exp_f32_e32 v207, v207
	v_mul_f32_e32 v244, 0xbfb8aa3b, v244
	v_exp_f32_e32 v244, v244
	v_lshlrev_b32_e32 v218, 16, v219
	v_and_b32_e32 v219, 0xffff0000, v219
	v_pk_mul_f32 v[222:223], v[144:145], v[222:223]
	v_lshlrev_b64 v[184:185], 12, v[184:185]
	v_pk_fma_f32 v[218:219], v[220:221], v[222:223], v[218:219]
	v_lshl_add_u64 v[242:243], s[30:31], 0, v[184:185]
	v_lshlrev_b64 v[184:185], 1, v[188:189]
	v_cvt_pk_bf16_f32 v220, v212, v213
	v_cvt_pk_bf16_f32 v221, v214, v215
	v_cvt_pk_bf16_f32 v222, v216, v217
	v_cvt_pk_bf16_f32 v223, v218, v219
	v_lshl_add_u64 v[242:243], v[242:243], 0, v[184:185]
	v_add_f32_e32 v207, 1.0, v207
	global_store_dwordx4 v[242:243], v[220:223], off
	v_and_b32_e32 v245, 0xffff0000, v224
	v_lshlrev_b64 v[196:197], 12, v[196:197]
	v_rcp_f32_e32 v220, v207
	v_add_f32_e32 v207, 1.0, v244
	v_lshlrev_b32_e32 v244, 16, v224
	v_rcp_f32_e32 v221, v207
	v_pk_mul_f32 v[244:245], v[206:207], v[244:245] op_sel_hi:[0,1]
	v_mul_f32_e32 v207, v100, v237
	v_mul_f32_e32 v207, 0xbfb8aa3b, v207
	v_mul_f32_e32 v224, v101, v237
	v_exp_f32_e32 v207, v207
	v_mul_f32_e32 v224, 0xbfb8aa3b, v224
	v_exp_f32_e32 v224, v224
	v_lshlrev_b32_e32 v222, 16, v238
	v_and_b32_e32 v223, 0xffff0000, v238
	v_pk_mul_f32 v[244:245], v[138:139], v[244:245]
	v_add_f32_e32 v207, 1.0, v207
	v_pk_fma_f32 v[220:221], v[220:221], v[244:245], v[222:223]
	v_rcp_f32_e32 v222, v207
	v_add_f32_e32 v207, 1.0, v224
	v_lshlrev_b32_e32 v224, 16, v225
	v_and_b32_e32 v225, 0xffff0000, v225
	v_rcp_f32_e32 v223, v207
	v_pk_mul_f32 v[224:225], v[206:207], v[224:225] op_sel_hi:[0,1]
	v_mul_f32_e32 v207, v94, v237
	v_mul_f32_e32 v207, 0xbfb8aa3b, v207
	v_mul_f32_e32 v244, v95, v237
	v_exp_f32_e32 v207, v207
	v_mul_f32_e32 v244, 0xbfb8aa3b, v244
	v_exp_f32_e32 v244, v244
	v_lshlrev_b32_e32 v238, 16, v239
	v_and_b32_e32 v239, 0xffff0000, v239
	v_pk_mul_f32 v[224:225], v[140:141], v[224:225]
	v_add_f32_e32 v207, 1.0, v207
	v_pk_fma_f32 v[222:223], v[222:223], v[224:225], v[238:239]
	v_rcp_f32_e32 v224, v207
	v_add_f32_e32 v207, 1.0, v244
	v_lshlrev_b32_e32 v244, 16, v226
	v_and_b32_e32 v245, 0xffff0000, v226
	v_rcp_f32_e32 v225, v207
	v_pk_mul_f32 v[244:245], v[206:207], v[244:245] op_sel_hi:[0,1]
	v_mul_f32_e32 v207, v96, v237
	v_mul_f32_e32 v207, 0xbfb8aa3b, v207
	v_mul_f32_e32 v226, v97, v237
	v_exp_f32_e32 v207, v207
	v_mul_f32_e32 v226, 0xbfb8aa3b, v226
	v_exp_f32_e32 v226, v226
	v_lshlrev_b32_e32 v238, 16, v240
	v_and_b32_e32 v239, 0xffff0000, v240
	v_pk_mul_f32 v[244:245], v[134:135], v[244:245]
	v_add_f32_e32 v207, 1.0, v207
	v_pk_fma_f32 v[224:225], v[224:225], v[244:245], v[238:239]
	v_rcp_f32_e32 v238, v207
	v_add_f32_e32 v207, 1.0, v226
	v_rcp_f32_e32 v239, v207
	v_lshlrev_b32_e32 v226, 16, v227
	v_and_b32_e32 v227, 0xffff0000, v227
	v_pk_mul_f32 v[206:207], v[206:207], v[226:227] op_sel_hi:[0,1]
	v_mul_f32_e32 v226, v122, v211
	v_mul_f32_e32 v227, v123, v211
	v_lshlrev_b32_e32 v240, 16, v241
	v_and_b32_e32 v241, 0xffff0000, v241
	v_pk_mul_f32 v[206:207], v[136:137], v[206:207]
	v_mul_f32_e32 v226, 0xbfb8aa3b, v226
	v_mul_f32_e32 v227, 0xbfb8aa3b, v227
	v_pk_fma_f32 v[206:207], v[238:239], v[206:207], v[240:241]
	v_exp_f32_e32 v226, v226
	v_exp_f32_e32 v227, v227
	v_cvt_pk_bf16_f32 v238, v220, v221
	v_cvt_pk_bf16_f32 v239, v222, v223
	v_cvt_pk_bf16_f32 v240, v224, v225
	v_cvt_pk_bf16_f32 v241, v206, v207
	global_store_dwordx4 v[242:243], v[238:241], off offset:256
	v_add_f32_e32 v226, 1.0, v226
	v_add_f32_e32 v227, 1.0, v227
	v_lshlrev_b32_e32 v238, 16, v158
	v_and_b32_e32 v239, 0xffff0000, v158
	v_mul_f32_e32 v158, v124, v211
	v_lshlrev_b32_e32 v240, 16, v162
	v_and_b32_e32 v241, 0xffff0000, v162
	v_mul_f32_e32 v158, 0xbfb8aa3b, v158
	v_mul_f32_e32 v162, v125, v211
	v_exp_f32_e32 v158, v158
	v_mul_f32_e32 v162, 0xbfb8aa3b, v162
	v_rcp_f32_e32 v226, v226
	v_rcp_f32_e32 v227, v227
	v_exp_f32_e32 v162, v162
	v_pk_mul_f32 v[240:241], v[210:211], v[240:241] op_sel_hi:[0,1]
	v_pk_mul_f32 v[240:241], v[146:147], v[240:241]
	v_add_f32_e32 v158, 1.0, v158
	v_pk_fma_f32 v[226:227], v[226:227], v[240:241], v[238:239]
	v_rcp_f32_e32 v238, v158
	v_add_f32_e32 v158, 1.0, v162
	v_mul_f32_e32 v240, v119, v211
	v_rcp_f32_e32 v239, v158
	v_mul_f32_e32 v237, v118, v211
	v_mul_f32_e32 v240, 0xbfb8aa3b, v240
	v_lshlrev_b32_e32 v162, 16, v163
	v_and_b32_e32 v163, 0xffff0000, v163
	v_mul_f32_e32 v237, 0xbfb8aa3b, v237
	v_exp_f32_e32 v240, v240
	v_pk_mul_f32 v[162:163], v[210:211], v[162:163] op_sel_hi:[0,1]
	v_exp_f32_e32 v237, v237
	v_lshlrev_b32_e32 v158, 16, v159
	v_and_b32_e32 v159, 0xffff0000, v159
	v_pk_mul_f32 v[162:163], v[148:149], v[162:163]
	v_and_b32_e32 v241, 0xffff0000, v164
	v_pk_fma_f32 v[158:159], v[238:239], v[162:163], v[158:159]
	v_lshlrev_b32_e32 v238, 16, v160
	v_and_b32_e32 v239, 0xffff0000, v160
	v_mul_f32_e32 v160, v120, v211
	v_add_f32_e32 v163, 1.0, v240
	v_lshlrev_b32_e32 v240, 16, v164
	v_mul_f32_e32 v160, 0xbfb8aa3b, v160
	v_mul_f32_e32 v164, v121, v211
	v_add_f32_e32 v162, 1.0, v237
	v_exp_f32_e32 v160, v160
	v_mul_f32_e32 v164, 0xbfb8aa3b, v164
	v_rcp_f32_e32 v162, v162
	v_rcp_f32_e32 v163, v163
	v_exp_f32_e32 v164, v164
	v_pk_mul_f32 v[240:241], v[210:211], v[240:241] op_sel_hi:[0,1]
	v_pk_mul_f32 v[240:241], v[142:143], v[240:241]
	v_add_f32_e32 v160, 1.0, v160
	v_pk_fma_f32 v[246:247], v[162:163], v[240:241], v[238:239]
	v_rcp_f32_e32 v162, v160
	v_add_f32_e32 v160, 1.0, v164
	v_rcp_f32_e32 v163, v160
	v_lshlrev_b32_e32 v164, 16, v165
	v_and_b32_e32 v165, 0xffff0000, v165
	v_mul_f32_e32 v237, v90, v211
	v_mul_f32_e32 v238, v91, v211
	v_pk_mul_f32 v[164:165], v[210:211], v[164:165] op_sel_hi:[0,1]
	v_mul_f32_e32 v237, 0xbfb8aa3b, v237
	v_mul_f32_e32 v238, 0xbfb8aa3b, v238
	v_lshlrev_b32_e32 v160, 16, v161
	v_and_b32_e32 v161, 0xffff0000, v161
	v_pk_mul_f32 v[164:165], v[144:145], v[164:165]
	v_exp_f32_e32 v237, v237
	v_exp_f32_e32 v238, v238
	v_pk_fma_f32 v[164:165], v[162:163], v[164:165], v[160:161]
	v_lshl_add_u64 v[196:197], s[30:31], 0, v[196:197]
	v_cvt_pk_bf16_f32 v160, v226, v227
	v_cvt_pk_bf16_f32 v161, v158, v159
	v_cvt_pk_bf16_f32 v162, v246, v247
	v_cvt_pk_bf16_f32 v163, v164, v165
	v_lshl_add_u64 v[196:197], v[196:197], 0, v[184:185]
	global_store_dwordx4 v[196:197], v[160:163], off
	v_and_b32_e32 v239, 0xffff0000, v154
	v_mul_f32_e32 v235, 0x45800000, v234
	v_lshlrev_b32_e32 v162, 16, v150
	v_and_b32_e32 v163, 0xffff0000, v150
	v_mul_f32_e32 v150, v92, v211
	v_add_f32_e32 v160, 1.0, v237
	v_add_f32_e32 v161, 1.0, v238
	v_lshlrev_b32_e32 v238, 16, v154
	v_mul_f32_e32 v150, 0xbfb8aa3b, v150
	v_mul_f32_e32 v154, v93, v211
	v_rcp_f32_e32 v160, v160
	v_rcp_f32_e32 v161, v161
	v_exp_f32_e32 v150, v150
	v_mul_f32_e32 v154, 0xbfb8aa3b, v154
	v_exp_f32_e32 v154, v154
	v_pk_mul_f32 v[238:239], v[210:211], v[238:239] op_sel_hi:[0,1]
	v_pk_mul_f32 v[238:239], v[138:139], v[238:239]
	v_add_f32_e32 v150, 1.0, v150
	v_pk_fma_f32 v[160:161], v[160:161], v[238:239], v[162:163]
	v_mul_f32_e32 v238, v87, v211
	v_rcp_f32_e32 v162, v150
	v_add_f32_e32 v150, 1.0, v154
	v_mul_f32_e32 v237, v86, v211
	v_mul_f32_e32 v238, 0xbfb8aa3b, v238
	v_rcp_f32_e32 v163, v150
	v_mul_f32_e32 v237, 0xbfb8aa3b, v237
	v_exp_f32_e32 v238, v238
	v_lshlrev_b32_e32 v154, 16, v155
	v_and_b32_e32 v155, 0xffff0000, v155
	v_exp_f32_e32 v237, v237
	v_pk_mul_f32 v[154:155], v[210:211], v[154:155] op_sel_hi:[0,1]
	v_lshlrev_b32_e32 v150, 16, v151
	v_and_b32_e32 v151, 0xffff0000, v151
	v_pk_mul_f32 v[154:155], v[140:141], v[154:155]
	v_and_b32_e32 v239, 0xffff0000, v156
	v_pk_fma_f32 v[154:155], v[162:163], v[154:155], v[150:151]
	v_add_f32_e32 v151, 1.0, v238
	v_lshlrev_b32_e32 v162, 16, v152
	v_and_b32_e32 v163, 0xffff0000, v152
	v_lshlrev_b32_e32 v238, 16, v156
	v_mul_f32_e32 v152, v88, v211
	v_mul_f32_e32 v156, v89, v211
	v_add_f32_e32 v150, 1.0, v237
	v_mul_f32_e32 v152, 0xbfb8aa3b, v152
	v_mul_f32_e32 v156, 0xbfb8aa3b, v156
	v_rcp_f32_e32 v150, v150
	v_rcp_f32_e32 v151, v151
	v_exp_f32_e32 v152, v152
	v_exp_f32_e32 v156, v156
	v_pk_mul_f32 v[238:239], v[210:211], v[238:239] op_sel_hi:[0,1]
	v_pk_mul_f32 v[238:239], v[134:135], v[238:239]
	v_mov_b32_e32 v237, v159
	v_pk_fma_f32 v[162:163], v[150:151], v[238:239], v[162:163]
	v_add_f32_e32 v150, 1.0, v152
	v_add_f32_e32 v151, 1.0, v156
	v_rcp_f32_e32 v150, v150
	v_rcp_f32_e32 v151, v151
	v_lshlrev_b32_e32 v156, 16, v157
	v_and_b32_e32 v157, 0xffff0000, v157
	v_pk_mul_f32 v[156:157], v[210:211], v[156:157] op_sel_hi:[0,1]
	v_lshlrev_b32_e32 v152, 16, v153
	v_and_b32_e32 v153, 0xffff0000, v153
	v_pk_mul_f32 v[156:157], v[136:137], v[156:157]
	v_mov_b32_e32 v159, v226
	v_pk_fma_f32 v[210:211], v[150:151], v[156:157], v[152:153]
	v_cvt_pk_bf16_f32 v150, v160, v161
	v_cvt_pk_bf16_f32 v151, v154, v155
	v_cvt_pk_bf16_f32 v152, v162, v163
	v_cvt_pk_bf16_f32 v153, v210, v211
	global_store_dwordx4 v[196:197], v[150:153], off offset:256
	v_mul_f32_e32 v156, 0x45800000, v236
	v_cndmask_b32_e32 v196, v234, v235, vcc
	v_lshlrev_b64 v[150:151], 11, v[204:205]
	v_lshl_add_u64 v[150:151], v[150:151], 0, v[188:189]
	v_lshlrev_b64 v[150:151], 1, v[150:151]
	v_lshl_add_u64 v[152:153], s[16:17], 0, v[150:151]
	global_load_dwordx4 v[238:241], v[152:153], off
	v_lshl_add_u64 v[152:153], s[90:91], 0, v[150:151]
	global_load_dwordx4 v[242:245], v[152:153], off nt
	v_cndmask_b32_e64 v234, v236, v156, s[6:7]
	v_fmamk_f32 v156, v233, 0x3a000000, v231
	v_mul_f32_e32 v157, 0x4b800000, v156
	v_cmp_gt_f32_e32 vcc, s65, v156
	v_mov_b32_e32 v226, v213
	v_mov_b32_e32 v236, v215
	v_cndmask_b32_e32 v156, v156, v157, vcc
	v_and_b32_e32 v157, 64, v232
	v_rsq_f32_e32 v197, v156
	v_xor_b32_e32 v156, 16, v232
	v_add_u32_e32 v235, 64, v157
	v_mov_b32_e32 v215, v158
	v_mov_b32_e32 v158, v212
	v_pk_mul_f32 v[212:213], v[226:227], v[226:227]
	v_cmp_lt_i32_e64 s[0:1], v156, v235
	v_pk_fma_f32 v[158:159], v[158:159], v[158:159], v[212:213]
	v_mov_b32_e32 v157, v165
	v_cndmask_b32_e64 v156, v232, v156, s[0:1]
	v_pk_fma_f32 v[158:159], v[214:215], v[214:215], v[158:159]
	v_lshlrev_b32_e32 v233, 2, v156
	v_mov_b32_e32 v156, v219
	v_mov_b32_e32 v219, v164
	v_mov_b32_e32 v164, v217
	v_mov_b32_e32 v217, v246
	v_pk_fma_f32 v[158:159], v[236:237], v[236:237], v[158:159]
	v_mov_b32_e32 v165, v247
	v_pk_fma_f32 v[158:159], v[216:217], v[216:217], v[158:159]
	v_or_b32_e32 v150, 0x100, v150
	v_pk_fma_f32 v[158:159], v[164:165], v[164:165], v[158:159]
	v_lshl_add_u64 v[150:151], s[16:17], 0, v[150:151]
	v_pk_fma_f32 v[158:159], v[218:219], v[218:219], v[158:159]
	v_lshlrev_b64 v[204:205], 12, v[204:205]
	v_pk_fma_f32 v[156:157], v[156:157], v[156:157], v[158:159]
	v_mov_b32_e32 v158, v220
	v_mov_b32_e32 v159, v160
	v_pk_fma_f32 v[156:157], v[158:159], v[158:159], v[156:157]
	v_mov_b32_e32 v160, v221
	v_pk_fma_f32 v[156:157], v[160:161], v[160:161], v[156:157]
	v_mov_b32_e32 v158, v222
	v_mov_b32_e32 v159, v154
	v_pk_fma_f32 v[156:157], v[158:159], v[158:159], v[156:157]
	v_mov_b32_e32 v154, v223
	v_pk_fma_f32 v[154:155], v[154:155], v[154:155], v[156:157]
	v_mov_b32_e32 v156, v224
	v_mov_b32_e32 v157, v162
	v_mov_b32_e32 v162, v225
	global_load_dwordx4 v[224:227], v[152:153], off offset:256 nt
	v_lshlrev_b64 v[152:153], 11, v[200:201]
	v_pk_fma_f32 v[154:155], v[156:157], v[156:157], v[154:155]
	v_lshl_add_u64 v[152:153], v[152:153], 0, v[188:189]
	v_pk_fma_f32 v[154:155], v[162:163], v[162:163], v[154:155]
	v_mov_b32_e32 v156, v206
	v_mov_b32_e32 v157, v210
	v_lshlrev_b64 v[152:153], 1, v[152:153]
	v_pk_fma_f32 v[212:213], v[156:157], v[156:157], v[154:155]
	v_lshl_add_u64 v[154:155], s[16:17], 0, v[152:153]
	global_load_dwordx4 v[246:249], v[150:151], off
	global_load_dwordx4 v[158:161], v[154:155], off
	v_mul_f32_e32 v156, v114, v209
	v_mul_f32_e32 v156, 0xbfb8aa3b, v156
	v_lshl_add_u64 v[154:155], s[90:91], 0, v[152:153]
	v_or_b32_e32 v152, 0x100, v152
	v_exp_f32_e32 v206, v156
	v_mul_f32_e32 v156, v115, v209
	v_lshl_add_u64 v[150:151], s[16:17], 0, v[152:153]
	v_mul_f32_e32 v156, 0xbfb8aa3b, v156
	global_load_dwordx4 v[150:153], v[150:151], off
	v_exp_f32_e32 v210, v156
	global_load_dwordx4 v[162:165], v[154:155], off nt
	s_nop 0
	global_load_dwordx4 v[154:157], v[154:155], off offset:256 nt
	v_add_f32_e32 v206, 1.0, v206
	v_rcp_f32_e32 v214, v206
	v_add_f32_e32 v206, 1.0, v210
	v_rcp_f32_e32 v215, v206
	v_mul_f32_e32 v206, v116, v209
	v_mul_f32_e32 v206, 0xbfb8aa3b, v206
	v_mul_f32_e32 v210, v117, v209
	v_exp_f32_e32 v206, v206
	v_mul_f32_e32 v210, 0xbfb8aa3b, v210
	v_exp_f32_e32 v210, v210
	s_waitcnt vmcnt(0)
	v_lshlrev_b32_e32 v216, 16, v238
	v_lshlrev_b32_e32 v218, 16, v242
	v_and_b32_e32 v219, 0xffff0000, v242
	v_pk_mul_f32 v[218:219], v[208:209], v[218:219] op_sel_hi:[0,1]
	v_and_b32_e32 v217, 0xffff0000, v238
	v_pk_mul_f32 v[218:219], v[146:147], v[218:219]
	v_add_f32_e32 v206, 1.0, v206
	v_pk_fma_f32 v[214:215], v[214:215], v[218:219], v[216:217]
	v_rcp_f32_e32 v216, v206
	v_add_f32_e32 v206, 1.0, v210
	v_rcp_f32_e32 v217, v206
	v_mul_f32_e32 v206, v110, v209
	v_mul_f32_e32 v206, 0xbfb8aa3b, v206
	v_mul_f32_e32 v210, v111, v209
	v_exp_f32_e32 v206, v206
	v_mul_f32_e32 v210, 0xbfb8aa3b, v210
	v_exp_f32_e32 v210, v210
	v_lshlrev_b32_e32 v220, 16, v243
	v_and_b32_e32 v221, 0xffff0000, v243
	v_pk_mul_f32 v[220:221], v[208:209], v[220:221] op_sel_hi:[0,1]
	v_lshlrev_b32_e32 v218, 16, v239
	v_and_b32_e32 v219, 0xffff0000, v239
	v_pk_mul_f32 v[220:221], v[148:149], v[220:221]
	v_add_f32_e32 v206, 1.0, v206
	v_pk_fma_f32 v[216:217], v[216:217], v[220:221], v[218:219]
	v_rcp_f32_e32 v218, v206
	v_add_f32_e32 v206, 1.0, v210
	v_rcp_f32_e32 v219, v206
	v_mul_f32_e32 v206, v112, v209
	v_mul_f32_e32 v206, 0xbfb8aa3b, v206
	v_mul_f32_e32 v210, v113, v209
	v_exp_f32_e32 v206, v206
	v_mul_f32_e32 v210, 0xbfb8aa3b, v210
	v_lshlrev_b32_e32 v222, 16, v244
	v_and_b32_e32 v223, 0xffff0000, v244
	v_exp_f32_e32 v210, v210
	v_pk_mul_f32 v[222:223], v[208:209], v[222:223] op_sel_hi:[0,1]
	v_lshlrev_b32_e32 v220, 16, v240
	v_and_b32_e32 v221, 0xffff0000, v240
	v_pk_mul_f32 v[222:223], v[142:143], v[222:223]
	v_lshl_add_u64 v[204:205], s[30:31], 0, v[204:205]
	v_pk_fma_f32 v[218:219], v[218:219], v[222:223], v[220:221]
	v_add_f32_e32 v206, 1.0, v206
	v_lshlrev_b32_e32 v222, 16, v241
	v_and_b32_e32 v223, 0xffff0000, v241
	v_lshl_add_u64 v[240:241], v[204:205], 0, v[184:185]
	v_mul_f32_e32 v204, v82, v209
	v_mul_f32_e32 v205, v83, v209
	v_rcp_f32_e32 v220, v206
	v_add_f32_e32 v206, 1.0, v210
	v_mul_f32_e32 v204, 0xbfb8aa3b, v204
	v_mul_f32_e32 v205, 0xbfb8aa3b, v205
	v_rcp_f32_e32 v221, v206
	v_exp_f32_e32 v204, v204
	v_exp_f32_e32 v205, v205
	v_lshlrev_b32_e32 v236, 16, v245
	v_and_b32_e32 v237, 0xffff0000, v245
	v_pk_mul_f32 v[236:237], v[208:209], v[236:237] op_sel_hi:[0,1]
	v_mul_f32_e32 v206, v84, v209
	v_pk_mul_f32 v[236:237], v[144:145], v[236:237]
	v_mul_f32_e32 v206, 0xbfb8aa3b, v206
	v_mul_f32_e32 v210, v85, v209
	v_pk_fma_f32 v[220:221], v[220:221], v[236:237], v[222:223]
	v_add_f32_e32 v204, 1.0, v204
	v_add_f32_e32 v205, 1.0, v205
	v_exp_f32_e32 v206, v206
	v_mul_f32_e32 v210, 0xbfb8aa3b, v210
	v_cvt_pk_bf16_f32 v236, v214, v215
	v_cvt_pk_bf16_f32 v237, v216, v217
	v_cvt_pk_bf16_f32 v238, v218, v219
	v_cvt_pk_bf16_f32 v239, v220, v221
	v_rcp_f32_e32 v204, v204
	v_rcp_f32_e32 v205, v205
	v_exp_f32_e32 v210, v210
	global_store_dwordx4 v[240:241], v[236:239], off
	v_lshlrev_b32_e32 v222, 16, v246
	v_and_b32_e32 v223, 0xffff0000, v246
	v_lshlrev_b32_e32 v236, 16, v224
	v_and_b32_e32 v237, 0xffff0000, v224
	v_pk_mul_f32 v[236:237], v[208:209], v[236:237] op_sel_hi:[0,1]
	v_pk_mul_f32 v[236:237], v[138:139], v[236:237]
	v_add_f32_e32 v206, 1.0, v206
	v_pk_fma_f32 v[204:205], v[204:205], v[236:237], v[222:223]
	v_rcp_f32_e32 v222, v206
	v_add_f32_e32 v206, 1.0, v210
	v_rcp_f32_e32 v223, v206
	v_mul_f32_e32 v206, v78, v209
	v_mul_f32_e32 v206, 0xbfb8aa3b, v206
	v_mul_f32_e32 v210, v79, v209
	v_exp_f32_e32 v206, v206
	v_mul_f32_e32 v210, 0xbfb8aa3b, v210
	v_exp_f32_e32 v210, v210
	v_lshlrev_b32_e32 v224, 16, v225
	v_and_b32_e32 v225, 0xffff0000, v225
	v_pk_mul_f32 v[224:225], v[208:209], v[224:225] op_sel_hi:[0,1]
	v_lshlrev_b32_e32 v236, 16, v247
	v_and_b32_e32 v237, 0xffff0000, v247
	v_pk_mul_f32 v[224:225], v[140:141], v[224:225]
	v_add_f32_e32 v206, 1.0, v206
	v_pk_fma_f32 v[222:223], v[222:223], v[224:225], v[236:237]
	v_rcp_f32_e32 v224, v206
	v_add_f32_e32 v206, 1.0, v210
	v_rcp_f32_e32 v225, v206
	v_lshlrev_b32_e32 v238, 16, v226
	v_and_b32_e32 v239, 0xffff0000, v226
	v_mul_f32_e32 v206, v80, v209
	v_pk_mul_f32 v[238:239], v[208:209], v[238:239] op_sel_hi:[0,1]
	v_mul_f32_e32 v206, 0xbfb8aa3b, v206
	v_mul_f32_e32 v209, v81, v209
	v_exp_f32_e32 v206, v206
	v_mul_f32_e32 v209, 0xbfb8aa3b, v209
	v_exp_f32_e32 v209, v209
	v_lshlrev_b32_e32 v236, 16, v248
	v_and_b32_e32 v237, 0xffff0000, v248
	v_pk_mul_f32 v[238:239], v[134:135], v[238:239]
	v_add_f32_e32 v206, 1.0, v206
	v_pk_fma_f32 v[224:225], v[224:225], v[238:239], v[236:237]
	v_rcp_f32_e32 v236, v206
	v_add_f32_e32 v206, 1.0, v209
	v_rcp_f32_e32 v237, v206
	v_lshlrev_b32_e32 v226, 16, v227
	v_and_b32_e32 v227, 0xffff0000, v227
	v_mul_f32_e32 v206, v106, v203
	v_pk_mul_f32 v[208:209], v[208:209], v[226:227] op_sel_hi:[0,1]
	v_mul_f32_e32 v206, 0xbfb8aa3b, v206
	v_mul_f32_e32 v210, v107, v203
	v_lshlrev_b32_e32 v238, 16, v249
	v_and_b32_e32 v239, 0xffff0000, v249
	v_pk_mul_f32 v[208:209], v[136:137], v[208:209]
	v_exp_f32_e32 v206, v206
	v_mul_f32_e32 v210, 0xbfb8aa3b, v210
	v_pk_fma_f32 v[208:209], v[236:237], v[208:209], v[238:239]
	v_exp_f32_e32 v210, v210
	v_cvt_pk_bf16_f32 v236, v204, v205
	v_cvt_pk_bf16_f32 v237, v222, v223
	v_cvt_pk_bf16_f32 v238, v224, v225
	v_cvt_pk_bf16_f32 v239, v208, v209
	global_store_dwordx4 v[240:241], v[236:239], off offset:256
	v_add_f32_e32 v206, 1.0, v206
	v_rcp_f32_e32 v226, v206
	v_lshlrev_b32_e32 v236, 16, v158
	v_and_b32_e32 v237, 0xffff0000, v158
	v_mul_f32_e32 v158, v108, v203
	v_lshlrev_b32_e32 v238, 16, v162
	v_and_b32_e32 v239, 0xffff0000, v162
	v_mul_f32_e32 v158, 0xbfb8aa3b, v158
	v_mul_f32_e32 v162, v109, v203
	v_add_f32_e32 v206, 1.0, v210
	v_exp_f32_e32 v158, v158
	v_mul_f32_e32 v162, 0xbfb8aa3b, v162
	v_rcp_f32_e32 v227, v206
	v_exp_f32_e32 v162, v162
	v_pk_mul_f32 v[238:239], v[202:203], v[238:239] op_sel_hi:[0,1]
	v_pk_mul_f32 v[238:239], v[146:147], v[238:239]
	v_add_f32_e32 v158, 1.0, v158
	v_pk_fma_f32 v[226:227], v[226:227], v[238:239], v[236:237]
	v_rcp_f32_e32 v236, v158
	v_add_f32_e32 v158, 1.0, v162
	v_rcp_f32_e32 v237, v158
	v_mul_f32_e32 v206, v102, v203
	v_mul_f32_e32 v210, v103, v203
	v_lshlrev_b32_e32 v162, 16, v163
	v_and_b32_e32 v163, 0xffff0000, v163
	v_mul_f32_e32 v206, 0xbfb8aa3b, v206
	v_mul_f32_e32 v210, 0xbfb8aa3b, v210
	v_pk_mul_f32 v[162:163], v[202:203], v[162:163] op_sel_hi:[0,1]
	v_exp_f32_e32 v206, v206
	v_exp_f32_e32 v210, v210
	v_lshlrev_b32_e32 v158, 16, v159
	v_and_b32_e32 v159, 0xffff0000, v159
	v_pk_mul_f32 v[162:163], v[148:149], v[162:163]
	v_lshlrev_b32_e32 v238, 16, v164
	v_pk_fma_f32 v[158:159], v[236:237], v[162:163], v[158:159]
	v_lshlrev_b32_e32 v236, 16, v160
	v_and_b32_e32 v237, 0xffff0000, v160
	v_mul_f32_e32 v160, v104, v203
	v_and_b32_e32 v239, 0xffff0000, v164
	v_mul_f32_e32 v160, 0xbfb8aa3b, v160
	v_mul_f32_e32 v164, v105, v203
	v_add_f32_e32 v162, 1.0, v206
	v_add_f32_e32 v163, 1.0, v210
	v_exp_f32_e32 v160, v160
	v_mul_f32_e32 v164, 0xbfb8aa3b, v164
	v_rcp_f32_e32 v162, v162
	v_rcp_f32_e32 v163, v163
	v_exp_f32_e32 v164, v164
	v_pk_mul_f32 v[238:239], v[202:203], v[238:239] op_sel_hi:[0,1]
	v_pk_mul_f32 v[238:239], v[142:143], v[238:239]
	v_add_f32_e32 v160, 1.0, v160
	v_pk_fma_f32 v[244:245], v[162:163], v[238:239], v[236:237]
	v_rcp_f32_e32 v162, v160
	v_add_f32_e32 v160, 1.0, v164
	v_rcp_f32_e32 v163, v160
	v_lshlrev_b32_e32 v164, 16, v165
	v_and_b32_e32 v165, 0xffff0000, v165
	v_pk_mul_f32 v[164:165], v[202:203], v[164:165] op_sel_hi:[0,1]
	v_mul_f32_e32 v206, v74, v203
	v_mul_f32_e32 v210, v75, v203
	v_lshlrev_b32_e32 v160, 16, v161
	v_and_b32_e32 v161, 0xffff0000, v161
	v_pk_mul_f32 v[164:165], v[144:145], v[164:165]
	v_lshlrev_b64 v[200:201], 12, v[200:201]
	v_mul_f32_e32 v206, 0xbfb8aa3b, v206
	v_mul_f32_e32 v210, 0xbfb8aa3b, v210
	v_pk_fma_f32 v[164:165], v[162:163], v[164:165], v[160:161]
	v_lshl_add_u64 v[200:201], s[30:31], 0, v[200:201]
	v_exp_f32_e32 v206, v206
	v_exp_f32_e32 v210, v210
	v_cvt_pk_bf16_f32 v160, v226, v227
	v_cvt_pk_bf16_f32 v161, v158, v159
	v_cvt_pk_bf16_f32 v162, v244, v245
	v_cvt_pk_bf16_f32 v163, v164, v165
	v_lshl_add_u64 v[200:201], v[200:201], 0, v[184:185]
	global_store_dwordx4 v[200:201], v[160:163], off
	v_lshlrev_b32_e32 v236, 16, v154
	v_and_b32_e32 v237, 0xffff0000, v154
	v_lshlrev_b32_e32 v162, 16, v150
	v_and_b32_e32 v163, 0xffff0000, v150
	v_mul_f32_e32 v150, v76, v203
	v_mul_f32_e32 v150, 0xbfb8aa3b, v150
	v_mul_f32_e32 v154, v77, v203
	v_add_f32_e32 v160, 1.0, v206
	v_add_f32_e32 v161, 1.0, v210
	v_exp_f32_e32 v150, v150
	v_mul_f32_e32 v154, 0xbfb8aa3b, v154
	v_rcp_f32_e32 v160, v160
	v_rcp_f32_e32 v161, v161
	v_exp_f32_e32 v154, v154
	v_pk_mul_f32 v[236:237], v[202:203], v[236:237] op_sel_hi:[0,1]
	v_pk_mul_f32 v[236:237], v[138:139], v[236:237]
	v_add_f32_e32 v150, 1.0, v150
	v_pk_fma_f32 v[160:161], v[160:161], v[236:237], v[162:163]
	v_rcp_f32_e32 v162, v150
	v_add_f32_e32 v150, 1.0, v154
	v_mul_f32_e32 v206, v70, v203
	v_mul_f32_e32 v210, v71, v203
	v_rcp_f32_e32 v163, v150
	v_mul_f32_e32 v206, 0xbfb8aa3b, v206
	v_mul_f32_e32 v210, 0xbfb8aa3b, v210
	v_lshlrev_b32_e32 v154, 16, v155
	v_and_b32_e32 v155, 0xffff0000, v155
	v_exp_f32_e32 v206, v206
	v_exp_f32_e32 v210, v210
	v_pk_mul_f32 v[154:155], v[202:203], v[154:155] op_sel_hi:[0,1]
	v_lshlrev_b32_e32 v150, 16, v151
	v_and_b32_e32 v151, 0xffff0000, v151
	v_pk_mul_f32 v[154:155], v[140:141], v[154:155]
	v_lshlrev_b32_e32 v236, 16, v156
	v_pk_fma_f32 v[154:155], v[162:163], v[154:155], v[150:151]
	v_lshlrev_b32_e32 v162, 16, v152
	v_and_b32_e32 v163, 0xffff0000, v152
	v_and_b32_e32 v237, 0xffff0000, v156
	v_mul_f32_e32 v152, v72, v203
	v_mul_f32_e32 v156, v73, v203
	v_add_f32_e32 v150, 1.0, v206
	v_add_f32_e32 v151, 1.0, v210
	v_mul_f32_e32 v152, 0xbfb8aa3b, v152
	v_mul_f32_e32 v156, 0xbfb8aa3b, v156
	v_rcp_f32_e32 v150, v150
	v_rcp_f32_e32 v151, v151
	v_exp_f32_e32 v152, v152
	v_exp_f32_e32 v156, v156
	v_pk_mul_f32 v[236:237], v[202:203], v[236:237] op_sel_hi:[0,1]
	v_pk_mul_f32 v[236:237], v[134:135], v[236:237]
	v_mov_b32_e32 v210, v207
	v_pk_fma_f32 v[162:163], v[150:151], v[236:237], v[162:163]
	v_add_f32_e32 v150, 1.0, v152
	v_add_f32_e32 v151, 1.0, v156
	v_rcp_f32_e32 v150, v150
	v_rcp_f32_e32 v151, v151
	v_lshlrev_b32_e32 v156, 16, v157
	v_and_b32_e32 v157, 0xffff0000, v157
	v_pk_mul_f32 v[156:157], v[202:203], v[156:157] op_sel_hi:[0,1]
	v_lshlrev_b32_e32 v152, 16, v153
	v_and_b32_e32 v153, 0xffff0000, v153
	v_pk_mul_f32 v[156:157], v[136:137], v[156:157]
	v_xor_b32_e32 v206, 32, v232
	v_pk_fma_f32 v[156:157], v[150:151], v[156:157], v[152:153]
	v_cvt_pk_bf16_f32 v150, v160, v161
	v_cvt_pk_bf16_f32 v151, v154, v155
	v_cvt_pk_bf16_f32 v152, v162, v163
	v_cvt_pk_bf16_f32 v153, v156, v157
	global_store_dwordx4 v[200:201], v[150:153], off offset:256
	v_pk_fma_f32 v[200:201], v[210:211], v[210:211], v[212:213]
	v_mov_b32_e32 v211, v159
	v_lshlrev_b64 v[150:151], 11, v[194:195]
	v_lshl_add_u64 v[150:151], v[150:151], 0, v[188:189]
	v_lshlrev_b64 v[150:151], 1, v[150:151]
	v_lshl_add_u64 v[152:153], s[16:17], 0, v[150:151]
	global_load_dwordx4 v[236:239], v[152:153], off
	v_lshl_add_u64 v[152:153], s[90:91], 0, v[150:151]
	global_load_dwordx4 v[240:243], v[152:153], off nt
	v_mov_b32_e32 v159, v226
	v_mov_b32_e32 v226, v215
	v_mov_b32_e32 v210, v217
	v_mov_b32_e32 v217, v158
	v_mov_b32_e32 v158, v214
	v_pk_mul_f32 v[212:213], v[226:227], v[226:227]
	v_cmp_lt_i32_e64 s[0:1], v206, v235
	v_pk_fma_f32 v[158:159], v[158:159], v[158:159], v[212:213]
	v_mov_b32_e32 v207, v165
	v_cndmask_b32_e64 v206, v232, v206, s[0:1]
	v_pk_fma_f32 v[158:159], v[216:217], v[216:217], v[158:159]
	v_lshlrev_b32_e32 v235, 2, v206
	v_mov_b32_e32 v206, v221
	v_mov_b32_e32 v221, v164
	v_mov_b32_e32 v164, v219
	v_mov_b32_e32 v219, v244
	v_pk_fma_f32 v[158:159], v[210:211], v[210:211], v[158:159]
	v_mov_b32_e32 v165, v245
	v_pk_fma_f32 v[158:159], v[218:219], v[218:219], v[158:159]
	v_or_b32_e32 v150, 0x100, v150
	v_pk_fma_f32 v[158:159], v[164:165], v[164:165], v[158:159]
	v_mov_b32_e32 v164, v204
	v_pk_fma_f32 v[158:159], v[220:221], v[220:221], v[158:159]
	v_mov_b32_e32 v165, v160
	v_pk_fma_f32 v[158:159], v[206:207], v[206:207], v[158:159]
	v_mov_b32_e32 v160, v205
	v_pk_fma_f32 v[158:159], v[164:165], v[164:165], v[158:159]
	global_load_dwordx4 v[218:221], v[152:153], off offset:256 nt
	v_pk_fma_f32 v[158:159], v[160:161], v[160:161], v[158:159]
	v_mov_b32_e32 v160, v222
	v_mov_b32_e32 v161, v154
	v_pk_fma_f32 v[158:159], v[160:161], v[160:161], v[158:159]
	v_mov_b32_e32 v154, v223
	v_pk_fma_f32 v[154:155], v[154:155], v[154:155], v[158:159]
	v_mov_b32_e32 v158, v224
	v_mov_b32_e32 v159, v162
	v_pk_fma_f32 v[154:155], v[158:159], v[158:159], v[154:155]
	v_mov_b32_e32 v162, v225
	v_lshlrev_b64 v[152:153], 11, v[190:191]
	v_pk_fma_f32 v[154:155], v[162:163], v[162:163], v[154:155]
	v_mov_b32_e32 v158, v208
	v_mov_b32_e32 v159, v156
	v_lshl_add_u64 v[152:153], v[152:153], 0, v[188:189]
	v_pk_fma_f32 v[154:155], v[158:159], v[158:159], v[154:155]
	v_mov_b32_e32 v156, v209
	v_lshl_add_u64 v[150:151], s[16:17], 0, v[150:151]
	v_lshlrev_b64 v[152:153], 1, v[152:153]
	v_pk_fma_f32 v[204:205], v[156:157], v[156:157], v[154:155]
	v_lshl_add_u64 v[154:155], s[16:17], 0, v[152:153]
	global_load_dwordx4 v[222:225], v[150:151], off
	global_load_dwordx4 v[158:161], v[154:155], off
	ds_bpermute_b32 v202, v233, v200
	ds_bpermute_b32 v203, v233, v201
	v_mul_f32_e32 v156, v66, v199
	v_mul_f32_e32 v156, 0xbfb8aa3b, v156
	v_lshl_add_u64 v[154:155], s[90:91], 0, v[152:153]
	v_or_b32_e32 v152, 0x100, v152
	s_waitcnt lgkmcnt(0)
	v_pk_add_f32 v[200:201], v[200:201], v[202:203]
	v_exp_f32_e32 v203, v156
	v_mul_f32_e32 v156, v67, v199
	v_lshl_add_u64 v[150:151], s[16:17], 0, v[152:153]
	v_mul_f32_e32 v156, 0xbfb8aa3b, v156
	global_load_dwordx4 v[150:153], v[150:151], off
	v_exp_f32_e32 v209, v156
	global_load_dwordx4 v[162:165], v[154:155], off nt
	s_nop 0
	global_load_dwordx4 v[154:157], v[154:155], off offset:256 nt
	v_add_f32_e32 v203, 1.0, v203
	v_rcp_f32_e32 v208, v203
	v_add_f32_e32 v203, 1.0, v209
	v_rcp_f32_e32 v209, v203
	v_mul_f32_e32 v203, v68, v199
	v_mul_f32_e32 v203, 0xbfb8aa3b, v203
	v_mul_f32_e32 v214, v69, v199
	v_exp_f32_e32 v203, v203
	v_mul_f32_e32 v214, 0xbfb8aa3b, v214
	v_exp_f32_e32 v214, v214
	v_mul_f32_e32 v216, v63, v199
	v_add_f32_e32 v203, 1.0, v203
	v_mul_f32_e32 v216, 0xbfb8aa3b, v216
	s_waitcnt vmcnt(7)
	v_lshlrev_b32_e32 v210, 16, v236
	v_and_b32_e32 v211, 0xffff0000, v236
	s_waitcnt vmcnt(6)
	v_lshlrev_b32_e32 v212, 16, v240
	v_and_b32_e32 v213, 0xffff0000, v240
	v_pk_mul_f32 v[212:213], v[198:199], v[212:213] op_sel_hi:[0,1]
	v_pk_mul_f32 v[212:213], v[146:147], v[212:213]
	v_exp_f32_e32 v216, v216
	v_pk_fma_f32 v[208:209], v[208:209], v[212:213], v[210:211]
	v_rcp_f32_e32 v210, v203
	v_add_f32_e32 v203, 1.0, v214
	v_rcp_f32_e32 v211, v203
	v_mul_f32_e32 v203, v62, v199
	v_mul_f32_e32 v203, 0xbfb8aa3b, v203
	v_exp_f32_e32 v203, v203
	v_lshlrev_b32_e32 v214, 16, v241
	v_and_b32_e32 v215, 0xffff0000, v241
	v_pk_mul_f32 v[214:215], v[198:199], v[214:215] op_sel_hi:[0,1]
	v_lshlrev_b32_e32 v212, 16, v237
	v_and_b32_e32 v213, 0xffff0000, v237
	v_pk_mul_f32 v[214:215], v[148:149], v[214:215]
	v_add_f32_e32 v203, 1.0, v203
	v_pk_fma_f32 v[210:211], v[210:211], v[214:215], v[212:213]
	v_rcp_f32_e32 v212, v203
	v_add_f32_e32 v203, 1.0, v216
	v_rcp_f32_e32 v213, v203
	v_mul_f32_e32 v203, v64, v199
	v_mul_f32_e32 v203, 0xbfb8aa3b, v203
	v_mul_f32_e32 v226, v65, v199
	v_exp_f32_e32 v203, v203
	v_mul_f32_e32 v226, 0xbfb8aa3b, v226
	v_exp_f32_e32 v226, v226
	v_lshlrev_b32_e32 v216, 16, v242
	v_and_b32_e32 v217, 0xffff0000, v242
	v_pk_mul_f32 v[216:217], v[198:199], v[216:217] op_sel_hi:[0,1]
	v_lshlrev_b32_e32 v214, 16, v238
	v_and_b32_e32 v215, 0xffff0000, v238
	v_pk_mul_f32 v[216:217], v[142:143], v[216:217]
	v_add_f32_e32 v203, 1.0, v203
	v_pk_fma_f32 v[212:213], v[212:213], v[216:217], v[214:215]
	v_rcp_f32_e32 v214, v203
	v_add_f32_e32 v203, 1.0, v226
	v_rcp_f32_e32 v215, v203
	v_lshlrev_b32_e32 v226, 16, v243
	v_and_b32_e32 v227, 0xffff0000, v243
	v_pk_mul_f32 v[226:227], v[198:199], v[226:227] op_sel_hi:[0,1]
	v_lshlrev_b64 v[194:195], 12, v[194:195]
	v_lshlrev_b32_e32 v216, 16, v239
	v_and_b32_e32 v217, 0xffff0000, v239
	v_pk_mul_f32 v[226:227], v[144:145], v[226:227]
	v_lshl_add_u64 v[194:195], s[30:31], 0, v[194:195]
	v_pk_fma_f32 v[214:215], v[214:215], v[226:227], v[216:217]
	v_lshl_add_u64 v[226:227], v[194:195], 0, v[184:185]
	v_mul_f32_e32 v194, v34, v199
	v_mul_f32_e32 v195, v35, v199
	v_mul_f32_e32 v194, 0xbfb8aa3b, v194
	v_mul_f32_e32 v195, 0xbfb8aa3b, v195
	v_exp_f32_e32 v194, v194
	v_exp_f32_e32 v195, v195
	v_cvt_pk_bf16_f32 v236, v208, v209
	v_cvt_pk_bf16_f32 v237, v210, v211
	v_cvt_pk_bf16_f32 v238, v212, v213
	v_cvt_pk_bf16_f32 v239, v214, v215
	v_mul_f32_e32 v203, v36, v199
	global_store_dwordx4 v[226:227], v[236:239], off
	v_mul_f32_e32 v203, 0xbfb8aa3b, v203
	v_add_f32_e32 v194, 1.0, v194
	s_waitcnt vmcnt(6)
	v_lshlrev_b32_e32 v236, 16, v218
	v_and_b32_e32 v237, 0xffff0000, v218
	v_mul_f32_e32 v218, v37, v199
	v_add_f32_e32 v195, 1.0, v195
	v_exp_f32_e32 v203, v203
	v_mul_f32_e32 v218, 0xbfb8aa3b, v218
	v_rcp_f32_e32 v194, v194
	v_rcp_f32_e32 v195, v195
	v_exp_f32_e32 v218, v218
	v_pk_mul_f32 v[236:237], v[198:199], v[236:237] op_sel_hi:[0,1]
	s_waitcnt vmcnt(5)
	v_lshlrev_b32_e32 v216, 16, v222
	v_and_b32_e32 v217, 0xffff0000, v222
	v_pk_mul_f32 v[236:237], v[138:139], v[236:237]
	v_add_f32_e32 v203, 1.0, v203
	v_pk_fma_f32 v[194:195], v[194:195], v[236:237], v[216:217]
	v_rcp_f32_e32 v216, v203
	v_add_f32_e32 v203, 1.0, v218
	v_rcp_f32_e32 v217, v203
	v_mul_f32_e32 v203, v30, v199
	v_mul_f32_e32 v203, 0xbfb8aa3b, v203
	v_mul_f32_e32 v236, v31, v199
	v_exp_f32_e32 v203, v203
	v_mul_f32_e32 v236, 0xbfb8aa3b, v236
	v_exp_f32_e32 v236, v236
	v_lshlrev_b32_e32 v218, 16, v219
	v_and_b32_e32 v219, 0xffff0000, v219
	v_pk_mul_f32 v[218:219], v[198:199], v[218:219] op_sel_hi:[0,1]
	v_lshlrev_b32_e32 v222, 16, v223
	v_and_b32_e32 v223, 0xffff0000, v223
	v_pk_mul_f32 v[218:219], v[140:141], v[218:219]
	v_add_f32_e32 v203, 1.0, v203
	v_pk_fma_f32 v[216:217], v[216:217], v[218:219], v[222:223]
	v_rcp_f32_e32 v218, v203
	v_add_f32_e32 v203, 1.0, v236
	v_lshlrev_b32_e32 v236, 16, v220
	v_and_b32_e32 v237, 0xffff0000, v220
	v_rcp_f32_e32 v219, v203
	v_pk_mul_f32 v[236:237], v[198:199], v[236:237] op_sel_hi:[0,1]
	v_mul_f32_e32 v203, v32, v199
	v_mul_f32_e32 v199, v33, v199
	v_mul_f32_e32 v203, 0xbfb8aa3b, v203
	v_mul_f32_e32 v199, 0xbfb8aa3b, v199
	v_exp_f32_e32 v203, v203
	v_exp_f32_e32 v199, v199
	v_lshlrev_b32_e32 v222, 16, v224
	v_and_b32_e32 v223, 0xffff0000, v224
	v_pk_mul_f32 v[236:237], v[134:135], v[236:237]
	v_add_f32_e32 v203, 1.0, v203
	v_add_f32_e32 v199, 1.0, v199
	v_pk_fma_f32 v[218:219], v[218:219], v[236:237], v[222:223]
	v_rcp_f32_e32 v222, v203
	v_rcp_f32_e32 v223, v199
	v_lshlrev_b32_e32 v220, 16, v221
	v_and_b32_e32 v221, 0xffff0000, v221
	v_pk_mul_f32 v[198:199], v[198:199], v[220:221] op_sel_hi:[0,1]
	v_lshlrev_b32_e32 v224, 16, v225
	v_and_b32_e32 v225, 0xffff0000, v225
	v_pk_mul_f32 v[198:199], v[136:137], v[198:199]
	v_mul_f32_e32 v203, v58, v193
	v_pk_fma_f32 v[198:199], v[222:223], v[198:199], v[224:225]
	v_mul_f32_e32 v203, 0xbfb8aa3b, v203
	v_mul_f32_e32 v224, v59, v193
	v_exp_f32_e32 v203, v203
	v_mul_f32_e32 v224, 0xbfb8aa3b, v224
	v_exp_f32_e32 v224, v224
	v_cvt_pk_bf16_f32 v220, v194, v195
	v_cvt_pk_bf16_f32 v221, v216, v217
	v_cvt_pk_bf16_f32 v222, v218, v219
	v_cvt_pk_bf16_f32 v223, v198, v199
	global_store_dwordx4 v[226:227], v[220:223], off offset:256
	v_add_f32_e32 v203, 1.0, v203
	s_waitcnt vmcnt(3)
	v_and_b32_e32 v225, 0xffff0000, v162
	v_lshlrev_b32_e32 v222, 16, v158
	v_and_b32_e32 v223, 0xffff0000, v158
	v_mul_f32_e32 v158, v60, v193
	v_rcp_f32_e32 v220, v203
	v_add_f32_e32 v203, 1.0, v224
	v_lshlrev_b32_e32 v224, 16, v162
	v_mul_f32_e32 v158, 0xbfb8aa3b, v158
	v_mul_f32_e32 v162, v61, v193
	v_rcp_f32_e32 v221, v203
	v_exp_f32_e32 v158, v158
	v_mul_f32_e32 v162, 0xbfb8aa3b, v162
	v_exp_f32_e32 v162, v162
	v_pk_mul_f32 v[224:225], v[192:193], v[224:225] op_sel_hi:[0,1]
	v_pk_mul_f32 v[224:225], v[146:147], v[224:225]
	v_add_f32_e32 v158, 1.0, v158
	v_pk_fma_f32 v[220:221], v[220:221], v[224:225], v[222:223]
	v_mul_f32_e32 v224, v55, v193
	v_rcp_f32_e32 v222, v158
	v_add_f32_e32 v158, 1.0, v162
	v_mul_f32_e32 v203, v54, v193
	v_mul_f32_e32 v224, 0xbfb8aa3b, v224
	v_rcp_f32_e32 v223, v158
	v_mul_f32_e32 v203, 0xbfb8aa3b, v203
	v_exp_f32_e32 v224, v224
	v_lshlrev_b32_e32 v162, 16, v163
	v_and_b32_e32 v163, 0xffff0000, v163
	v_exp_f32_e32 v203, v203
	v_pk_mul_f32 v[162:163], v[192:193], v[162:163] op_sel_hi:[0,1]
	v_lshlrev_b32_e32 v158, 16, v159
	v_and_b32_e32 v159, 0xffff0000, v159
	v_pk_mul_f32 v[162:163], v[148:149], v[162:163]
	v_and_b32_e32 v225, 0xffff0000, v164
	v_pk_fma_f32 v[162:163], v[222:223], v[162:163], v[158:159]
	v_add_f32_e32 v159, 1.0, v224
	v_lshlrev_b32_e32 v222, 16, v160
	v_and_b32_e32 v223, 0xffff0000, v160
	v_lshlrev_b32_e32 v224, 16, v164
	v_mul_f32_e32 v160, v56, v193
	v_mul_f32_e32 v164, v57, v193
	v_add_f32_e32 v158, 1.0, v203
	v_mul_f32_e32 v160, 0xbfb8aa3b, v160
	v_mul_f32_e32 v164, 0xbfb8aa3b, v164
	v_rcp_f32_e32 v158, v158
	v_rcp_f32_e32 v159, v159
	v_exp_f32_e32 v160, v160
	v_exp_f32_e32 v164, v164
	v_pk_mul_f32 v[224:225], v[192:193], v[224:225] op_sel_hi:[0,1]
	v_pk_mul_f32 v[224:225], v[142:143], v[224:225]
	v_mul_f32_e32 v203, v26, v193
	v_pk_fma_f32 v[226:227], v[158:159], v[224:225], v[222:223]
	v_add_f32_e32 v158, 1.0, v160
	v_add_f32_e32 v159, 1.0, v164
	v_rcp_f32_e32 v158, v158
	v_rcp_f32_e32 v159, v159
	v_lshlrev_b32_e32 v164, 16, v165
	v_and_b32_e32 v165, 0xffff0000, v165
	v_mul_f32_e32 v222, v27, v193
	v_pk_mul_f32 v[164:165], v[192:193], v[164:165] op_sel_hi:[0,1]
	v_mul_f32_e32 v203, 0xbfb8aa3b, v203
	v_mul_f32_e32 v222, 0xbfb8aa3b, v222
	v_lshlrev_b32_e32 v160, 16, v161
	v_and_b32_e32 v161, 0xffff0000, v161
	v_pk_mul_f32 v[164:165], v[144:145], v[164:165]
	v_lshlrev_b64 v[190:191], 12, v[190:191]
	v_exp_f32_e32 v203, v203
	v_exp_f32_e32 v222, v222
	v_pk_fma_f32 v[164:165], v[158:159], v[164:165], v[160:161]
	v_lshl_add_u64 v[190:191], s[30:31], 0, v[190:191]
	v_cvt_pk_bf16_f32 v158, v220, v221
	v_cvt_pk_bf16_f32 v159, v162, v163
	v_cvt_pk_bf16_f32 v160, v226, v227
	v_cvt_pk_bf16_f32 v161, v164, v165
	v_lshl_add_u64 v[190:191], v[190:191], 0, v[184:185]
	global_store_dwordx4 v[190:191], v[158:161], off
	s_waitcnt vmcnt(3)
	v_and_b32_e32 v223, 0xffff0000, v154
	ds_bpermute_b32 v206, v233, v204
	v_lshlrev_b32_e32 v160, 16, v150
	v_and_b32_e32 v161, 0xffff0000, v150
	v_mul_f32_e32 v150, v28, v193
	v_add_f32_e32 v158, 1.0, v203
	v_add_f32_e32 v159, 1.0, v222
	v_lshlrev_b32_e32 v222, 16, v154
	v_mul_f32_e32 v150, 0xbfb8aa3b, v150
	v_mul_f32_e32 v154, v29, v193
	v_rcp_f32_e32 v158, v158
	v_rcp_f32_e32 v159, v159
	v_exp_f32_e32 v150, v150
	v_mul_f32_e32 v154, 0xbfb8aa3b, v154
	v_exp_f32_e32 v154, v154
	v_pk_mul_f32 v[222:223], v[192:193], v[222:223] op_sel_hi:[0,1]
	v_pk_mul_f32 v[222:223], v[138:139], v[222:223]
	v_add_f32_e32 v150, 1.0, v150
	v_pk_fma_f32 v[158:159], v[158:159], v[222:223], v[160:161]
	v_mul_f32_e32 v222, v23, v193
	v_rcp_f32_e32 v160, v150
	v_add_f32_e32 v150, 1.0, v154
	v_mul_f32_e32 v203, v22, v193
	v_mul_f32_e32 v222, 0xbfb8aa3b, v222
	v_rcp_f32_e32 v161, v150
	v_mul_f32_e32 v203, 0xbfb8aa3b, v203
	v_exp_f32_e32 v222, v222
	v_lshlrev_b32_e32 v154, 16, v155
	v_and_b32_e32 v155, 0xffff0000, v155
	v_exp_f32_e32 v203, v203
	v_pk_mul_f32 v[154:155], v[192:193], v[154:155] op_sel_hi:[0,1]
	v_lshlrev_b32_e32 v150, 16, v151
	v_and_b32_e32 v151, 0xffff0000, v151
	v_pk_mul_f32 v[154:155], v[140:141], v[154:155]
	v_and_b32_e32 v223, 0xffff0000, v156
	v_pk_fma_f32 v[154:155], v[160:161], v[154:155], v[150:151]
	v_add_f32_e32 v151, 1.0, v222
	v_lshlrev_b32_e32 v160, 16, v152
	v_and_b32_e32 v161, 0xffff0000, v152
	v_lshlrev_b32_e32 v222, 16, v156
	v_mul_f32_e32 v152, v24, v193
	v_mul_f32_e32 v156, v25, v193
	v_add_f32_e32 v150, 1.0, v203
	v_mul_f32_e32 v152, 0xbfb8aa3b, v152
	v_mul_f32_e32 v156, 0xbfb8aa3b, v156
	v_rcp_f32_e32 v150, v150
	v_rcp_f32_e32 v151, v151
	v_exp_f32_e32 v152, v152
	v_exp_f32_e32 v156, v156
	v_pk_mul_f32 v[222:223], v[192:193], v[222:223] op_sel_hi:[0,1]
	v_pk_mul_f32 v[222:223], v[134:135], v[222:223]
	ds_bpermute_b32 v207, v233, v205
	v_pk_fma_f32 v[160:161], v[150:151], v[222:223], v[160:161]
	v_add_f32_e32 v150, 1.0, v152
	v_add_f32_e32 v151, 1.0, v156
	v_rcp_f32_e32 v150, v150
	v_rcp_f32_e32 v151, v151
	v_lshlrev_b32_e32 v156, 16, v157
	v_and_b32_e32 v157, 0xffff0000, v157
	v_pk_mul_f32 v[156:157], v[192:193], v[156:157] op_sel_hi:[0,1]
	v_lshlrev_b32_e32 v152, 16, v153
	v_and_b32_e32 v153, 0xffff0000, v153
	v_pk_mul_f32 v[156:157], v[136:137], v[156:157]
	ds_bpermute_b32 v202, v235, v200
	v_pk_fma_f32 v[156:157], v[150:151], v[156:157], v[152:153]
	v_cvt_pk_bf16_f32 v150, v158, v159
	v_cvt_pk_bf16_f32 v151, v154, v155
	v_cvt_pk_bf16_f32 v152, v160, v161
	v_cvt_pk_bf16_f32 v153, v156, v157
	global_store_dwordx4 v[190:191], v[150:153], off offset:256
	ds_bpermute_b32 v203, v235, v201
	s_nop 0
	v_lshlrev_b64 v[152:153], 11, v[186:187]
	v_lshl_add_u64 v[152:153], v[152:153], 0, v[188:189]
	v_lshlrev_b64 v[152:153], 1, v[152:153]
	v_lshl_add_u64 v[240:241], s[90:91], 0, v[152:153]
	global_load_dwordx4 v[236:239], v[240:241], off nt
	v_lshl_add_u64 v[190:191], s[16:17], 0, v[152:153]
	global_load_dwordx4 v[222:225], v[190:191], off
	v_mov_b32_e32 v191, v163
	v_mov_b32_e32 v163, v220
	v_mov_b32_e32 v220, v209
	v_mov_b32_e32 v190, v211
	v_mov_b32_e32 v211, v162
	v_mov_b32_e32 v162, v208
	v_pk_mul_f32 v[192:193], v[220:221], v[220:221]
	v_mov_b32_e32 v150, v215
	v_pk_fma_f32 v[162:163], v[162:163], v[162:163], v[192:193]
	v_mov_b32_e32 v215, v164
	v_pk_fma_f32 v[162:163], v[210:211], v[210:211], v[162:163]
	v_mov_b32_e32 v164, v213
	v_mov_b32_e32 v213, v226
	v_pk_fma_f32 v[162:163], v[190:191], v[190:191], v[162:163]
	v_mov_b32_e32 v151, v165
	v_mov_b32_e32 v165, v227
	v_pk_fma_f32 v[162:163], v[212:213], v[212:213], v[162:163]
	global_load_dwordx4 v[208:211], v[240:241], off offset:256 nt
	v_pk_fma_f32 v[162:163], v[164:165], v[164:165], v[162:163]
	v_or_b32_e32 v152, 0x100, v152
	v_pk_fma_f32 v[162:163], v[214:215], v[214:215], v[162:163]
	s_waitcnt lgkmcnt(0)
	v_pk_add_f32 v[190:191], v[200:201], v[202:203]
	v_pk_fma_f32 v[150:151], v[150:151], v[150:151], v[162:163]
	v_mov_b32_e32 v162, v194
	v_mov_b32_e32 v163, v158
	v_pk_fma_f32 v[150:151], v[162:163], v[162:163], v[150:151]
	v_mov_b32_e32 v158, v195
	v_pk_fma_f32 v[150:151], v[158:159], v[158:159], v[150:151]
	v_mov_b32_e32 v158, v216
	v_mov_b32_e32 v159, v154
	v_pk_fma_f32 v[150:151], v[158:159], v[158:159], v[150:151]
	v_mov_b32_e32 v154, v217
	v_pk_fma_f32 v[150:151], v[154:155], v[154:155], v[150:151]
	v_mov_b32_e32 v154, v218
	v_mov_b32_e32 v155, v160
	v_pk_fma_f32 v[150:151], v[154:155], v[154:155], v[150:151]
	v_mov_b32_e32 v160, v219
	v_pk_fma_f32 v[150:151], v[160:161], v[160:161], v[150:151]
	v_mov_b32_e32 v154, v198
	v_mov_b32_e32 v155, v156
	v_pk_fma_f32 v[150:151], v[154:155], v[154:155], v[150:151]
	v_mov_b32_e32 v156, v199
	v_pk_fma_f32 v[150:151], v[156:157], v[156:157], v[150:151]
	ds_bpermute_b32 v154, v233, v150
	ds_bpermute_b32 v155, v233, v151
	v_pk_add_f32 v[156:157], v[204:205], v[206:207]
	ds_bpermute_b32 v158, v235, v156
	ds_bpermute_b32 v159, v235, v157
	v_mul_f32_e32 v160, 0x45800000, v197
	s_waitcnt lgkmcnt(2)
	v_pk_add_f32 v[150:151], v[150:151], v[154:155]
	ds_bpermute_b32 v154, v235, v150
	ds_bpermute_b32 v155, v235, v151
	v_cndmask_b32_e32 v198, v197, v160, vcc
	s_waitcnt lgkmcnt(2)
	v_pk_add_f32 v[192:193], v[156:157], v[158:159]
	v_mul_f32_e32 v156, v50, v3
	v_mul_f32_e32 v156, 0xbfb8aa3b, v156
	s_waitcnt lgkmcnt(0)
	v_pk_add_f32 v[194:195], v[150:151], v[154:155]
	v_lshl_add_u64 v[150:151], s[16:17], 0, v[152:153]
	v_lshlrev_b64 v[152:153], 11, v[4:5]
	v_lshl_add_u64 v[152:153], v[152:153], 0, v[188:189]
	v_lshlrev_b64 v[152:153], 1, v[152:153]
	v_lshl_add_u64 v[154:155], s[16:17], 0, v[152:153]
	global_load_dwordx4 v[212:215], v[150:151], off
	global_load_dwordx4 v[158:161], v[154:155], off
	v_lshl_add_u64 v[154:155], s[90:91], 0, v[152:153]
	v_or_b32_e32 v152, 0x100, v152
	v_exp_f32_e32 v188, v156
	v_mul_f32_e32 v156, v51, v3
	v_lshl_add_u64 v[150:151], s[16:17], 0, v[152:153]
	v_mul_f32_e32 v156, 0xbfb8aa3b, v156
	global_load_dwordx4 v[150:153], v[150:151], off
	v_exp_f32_e32 v189, v156
	global_load_dwordx4 v[162:165], v[154:155], off nt
	s_nop 0
	global_load_dwordx4 v[154:157], v[154:155], off offset:256 nt
	v_mul_f32_e32 v199, v53, v3
	v_add_f32_e32 v188, 1.0, v188
	v_add_f32_e32 v189, 1.0, v189
	v_mul_f32_e32 v199, 0xbfb8aa3b, v199
	v_rcp_f32_e32 v188, v188
	s_waitcnt vmcnt(7)
	v_lshlrev_b32_e32 v202, 16, v236
	v_and_b32_e32 v203, 0xffff0000, v236
	v_pk_mul_f32 v[202:203], v[196:197], v[202:203] op_sel_hi:[0,1]
	v_mul_f32_e32 v197, v52, v3
	v_mul_f32_e32 v197, 0xbfb8aa3b, v197
	v_exp_f32_e32 v197, v197
	v_rcp_f32_e32 v189, v189
	v_exp_f32_e32 v199, v199
	s_waitcnt vmcnt(6)
	v_lshlrev_b32_e32 v200, 16, v222
	v_and_b32_e32 v201, 0xffff0000, v222
	v_pk_mul_f32 v[202:203], v[146:147], v[202:203]
	v_add_f32_e32 v197, 1.0, v197
	v_pk_fma_f32 v[188:189], v[188:189], v[202:203], v[200:201]
	v_rcp_f32_e32 v200, v197
	v_add_f32_e32 v197, 1.0, v199
	v_lshlrev_b32_e32 v204, 16, v237
	v_and_b32_e32 v205, 0xffff0000, v237
	v_rcp_f32_e32 v201, v197
	v_pk_mul_f32 v[204:205], v[196:197], v[204:205] op_sel_hi:[0,1]
	v_mul_f32_e32 v197, v46, v3
	v_mul_f32_e32 v197, 0xbfb8aa3b, v197
	v_mul_f32_e32 v199, v47, v3
	v_exp_f32_e32 v197, v197
	v_mul_f32_e32 v199, 0xbfb8aa3b, v199
	v_exp_f32_e32 v199, v199
	v_lshlrev_b32_e32 v202, 16, v223
	v_and_b32_e32 v203, 0xffff0000, v223
	v_pk_mul_f32 v[204:205], v[148:149], v[204:205]
	v_add_f32_e32 v197, 1.0, v197
	v_pk_fma_f32 v[200:201], v[200:201], v[204:205], v[202:203]
	v_rcp_f32_e32 v202, v197
	v_add_f32_e32 v197, 1.0, v199
	v_lshlrev_b32_e32 v206, 16, v238
	v_and_b32_e32 v207, 0xffff0000, v238
	v_rcp_f32_e32 v203, v197
	v_pk_mul_f32 v[206:207], v[196:197], v[206:207] op_sel_hi:[0,1]
	v_mul_f32_e32 v197, v48, v3
	v_mul_f32_e32 v197, 0xbfb8aa3b, v197
	v_mul_f32_e32 v199, v49, v3
	v_exp_f32_e32 v197, v197
	v_mul_f32_e32 v199, 0xbfb8aa3b, v199
	v_exp_f32_e32 v199, v199
	v_lshlrev_b32_e32 v204, 16, v224
	v_and_b32_e32 v205, 0xffff0000, v224
	v_pk_mul_f32 v[206:207], v[142:143], v[206:207]
	v_add_f32_e32 v197, 1.0, v197
	v_pk_fma_f32 v[202:203], v[202:203], v[206:207], v[204:205]
	v_rcp_f32_e32 v204, v197
	v_add_f32_e32 v197, 1.0, v199
	v_rcp_f32_e32 v205, v197
	v_lshlrev_b32_e32 v216, 16, v239
	v_and_b32_e32 v217, 0xffff0000, v239
	v_lshlrev_b64 v[186:187], 12, v[186:187]
	v_pk_mul_f32 v[216:217], v[196:197], v[216:217] op_sel_hi:[0,1]
	v_lshl_add_u64 v[186:187], s[30:31], 0, v[186:187]
	v_lshlrev_b32_e32 v206, 16, v225
	v_and_b32_e32 v207, 0xffff0000, v225
	v_pk_mul_f32 v[216:217], v[144:145], v[216:217]
	v_lshl_add_u64 v[220:221], v[186:187], 0, v[184:185]
	v_mul_f32_e32 v186, v18, v3
	v_mul_f32_e32 v187, v19, v3
	v_pk_fma_f32 v[204:205], v[204:205], v[216:217], v[206:207]
	v_mul_f32_e32 v186, 0xbfb8aa3b, v186
	v_mul_f32_e32 v187, 0xbfb8aa3b, v187
	v_cvt_pk_bf16_f32 v216, v188, v189
	v_cvt_pk_bf16_f32 v217, v200, v201
	v_cvt_pk_bf16_f32 v218, v202, v203
	v_cvt_pk_bf16_f32 v219, v204, v205
	v_exp_f32_e32 v186, v186
	v_exp_f32_e32 v187, v187
	global_store_dwordx4 v[220:221], v[216:219], off
	v_mul_f32_e32 v199, v21, v3
	v_add_f32_e32 v186, 1.0, v186
	s_waitcnt vmcnt(6)
	v_lshlrev_b32_e32 v216, 16, v208
	v_and_b32_e32 v217, 0xffff0000, v208
	v_pk_mul_f32 v[216:217], v[196:197], v[216:217] op_sel_hi:[0,1]
	v_mul_f32_e32 v197, v20, v3
	v_mul_f32_e32 v197, 0xbfb8aa3b, v197
	v_add_f32_e32 v187, 1.0, v187
	v_exp_f32_e32 v197, v197
	v_mul_f32_e32 v199, 0xbfb8aa3b, v199
	v_rcp_f32_e32 v186, v186
	v_rcp_f32_e32 v187, v187
	v_exp_f32_e32 v199, v199
	s_waitcnt vmcnt(5)
	v_lshlrev_b32_e32 v206, 16, v212
	v_and_b32_e32 v207, 0xffff0000, v212
	v_pk_mul_f32 v[216:217], v[138:139], v[216:217]
	v_add_f32_e32 v197, 1.0, v197
	v_pk_fma_f32 v[186:187], v[186:187], v[216:217], v[206:207]
	v_rcp_f32_e32 v206, v197
	v_add_f32_e32 v197, 1.0, v199
	v_lshlrev_b32_e32 v208, 16, v209
	v_and_b32_e32 v209, 0xffff0000, v209
	v_rcp_f32_e32 v207, v197
	v_pk_mul_f32 v[208:209], v[196:197], v[208:209] op_sel_hi:[0,1]
	v_mul_f32_e32 v197, v14, v3
	v_mul_f32_e32 v197, 0xbfb8aa3b, v197
	v_mul_f32_e32 v199, v15, v3
	v_exp_f32_e32 v197, v197
	v_mul_f32_e32 v199, 0xbfb8aa3b, v199
	v_exp_f32_e32 v199, v199
	v_lshlrev_b32_e32 v212, 16, v213
	v_and_b32_e32 v213, 0xffff0000, v213
	v_pk_mul_f32 v[208:209], v[140:141], v[208:209]
	v_add_f32_e32 v197, 1.0, v197
	v_pk_fma_f32 v[206:207], v[206:207], v[208:209], v[212:213]
	v_rcp_f32_e32 v208, v197
	v_add_f32_e32 v197, 1.0, v199
	v_lshlrev_b32_e32 v216, 16, v210
	v_and_b32_e32 v217, 0xffff0000, v210
	v_rcp_f32_e32 v209, v197
	v_pk_mul_f32 v[216:217], v[196:197], v[216:217] op_sel_hi:[0,1]
	v_mul_f32_e32 v197, v16, v3
	v_mul_f32_e32 v3, v17, v3
	v_mul_f32_e32 v3, 0xbfb8aa3b, v3
	v_mul_f32_e32 v197, 0xbfb8aa3b, v197
	v_exp_f32_e32 v3, v3
	v_exp_f32_e32 v197, v197
	v_lshlrev_b32_e32 v212, 16, v214
	v_and_b32_e32 v213, 0xffff0000, v214
	v_pk_mul_f32 v[216:217], v[134:135], v[216:217]
	v_add_f32_e32 v3, 1.0, v3
	v_pk_fma_f32 v[208:209], v[208:209], v[216:217], v[212:213]
	v_add_f32_e32 v197, 1.0, v197
	v_rcp_f32_e32 v213, v3
	v_mul_f32_e32 v3, v42, v234
	v_rcp_f32_e32 v212, v197
	v_mul_f32_e32 v3, 0xbfb8aa3b, v3
	v_mul_f32_e32 v199, v43, v234
	v_lshlrev_b32_e32 v210, 16, v211
	v_and_b32_e32 v211, 0xffff0000, v211
	v_exp_f32_e32 v3, v3
	v_mul_f32_e32 v199, 0xbfb8aa3b, v199
	v_pk_mul_f32 v[196:197], v[196:197], v[210:211] op_sel_hi:[0,1]
	v_exp_f32_e32 v199, v199
	v_lshlrev_b32_e32 v214, 16, v215
	v_and_b32_e32 v215, 0xffff0000, v215
	v_pk_mul_f32 v[196:197], v[136:137], v[196:197]
	v_cvt_pk_bf16_f32 v210, v186, v187
	v_pk_fma_f32 v[196:197], v[212:213], v[196:197], v[214:215]
	v_cvt_pk_bf16_f32 v211, v206, v207
	v_cvt_pk_bf16_f32 v212, v208, v209
	v_cvt_pk_bf16_f32 v213, v196, v197
	v_add_f32_e32 v3, 1.0, v3
	global_store_dwordx4 v[220:221], v[210:213], off offset:256
	s_waitcnt vmcnt(3)
	v_lshlrev_b32_e32 v214, 16, v162
	v_and_b32_e32 v215, 0xffff0000, v162
	v_rcp_f32_e32 v210, v3
	v_add_f32_e32 v3, 1.0, v199
	v_rcp_f32_e32 v211, v3
	v_mul_f32_e32 v3, v44, v234
	v_lshlrev_b32_e32 v212, 16, v158
	v_and_b32_e32 v213, 0xffff0000, v158
	v_mul_f32_e32 v3, 0xbfb8aa3b, v3
	v_mul_f32_e32 v158, v45, v234
	v_exp_f32_e32 v3, v3
	v_mul_f32_e32 v158, 0xbfb8aa3b, v158
	v_exp_f32_e32 v158, v158
	v_pk_mul_f32 v[214:215], v[198:199], v[214:215] op_sel_hi:[0,1]
	v_pk_mul_f32 v[146:147], v[146:147], v[214:215]
	v_add_f32_e32 v3, 1.0, v3
	v_pk_fma_f32 v[146:147], v[210:211], v[146:147], v[212:213]
	v_rcp_f32_e32 v210, v3
	v_add_f32_e32 v3, 1.0, v158
	v_lshlrev_b32_e32 v162, 16, v163
	v_and_b32_e32 v163, 0xffff0000, v163
	v_rcp_f32_e32 v211, v3
	v_pk_mul_f32 v[162:163], v[198:199], v[162:163] op_sel_hi:[0,1]
	v_mul_f32_e32 v3, v38, v234
	v_pk_mul_f32 v[148:149], v[148:149], v[162:163]
	v_mul_f32_e32 v3, 0xbfb8aa3b, v3
	v_mul_f32_e32 v162, v39, v234
	v_exp_f32_e32 v3, v3
	v_mul_f32_e32 v162, 0xbfb8aa3b, v162
	v_exp_f32_e32 v162, v162
	v_lshlrev_b32_e32 v158, 16, v159
	v_and_b32_e32 v159, 0xffff0000, v159
	v_add_f32_e32 v3, 1.0, v3
	v_pk_fma_f32 v[148:149], v[210:211], v[148:149], v[158:159]
	v_rcp_f32_e32 v158, v3
	v_add_f32_e32 v3, 1.0, v162
	v_rcp_f32_e32 v159, v3
	v_mul_f32_e32 v3, v40, v234
	v_lshlrev_b32_e32 v162, 16, v160
	v_and_b32_e32 v163, 0xffff0000, v160
	v_mul_f32_e32 v3, 0xbfb8aa3b, v3
	v_mul_f32_e32 v160, v41, v234
	v_exp_f32_e32 v3, v3
	v_mul_f32_e32 v160, 0xbfb8aa3b, v160
	v_exp_f32_e32 v160, v160
	v_lshlrev_b32_e32 v210, 16, v164
	v_and_b32_e32 v211, 0xffff0000, v164
	v_pk_mul_f32 v[210:211], v[198:199], v[210:211] op_sel_hi:[0,1]
	v_pk_mul_f32 v[142:143], v[142:143], v[210:211]
	v_add_f32_e32 v3, 1.0, v3
	v_pk_fma_f32 v[158:159], v[158:159], v[142:143], v[162:163]
	v_rcp_f32_e32 v142, v3
	v_add_f32_e32 v3, 1.0, v160
	v_rcp_f32_e32 v143, v3
	v_lshlrev_b32_e32 v162, 16, v165
	v_and_b32_e32 v163, 0xffff0000, v165
	v_pk_mul_f32 v[162:163], v[198:199], v[162:163] op_sel_hi:[0,1]
	v_lshlrev_b32_e32 v160, 16, v161
	v_and_b32_e32 v161, 0xffff0000, v161
	v_pk_mul_f32 v[144:145], v[144:145], v[162:163]
	v_mul_f32_e32 v3, v10, v234
	v_pk_fma_f32 v[160:161], v[142:143], v[144:145], v[160:161]
	v_mul_f32_e32 v3, 0xbfb8aa3b, v3
	v_mul_f32_e32 v142, v11, v234
	v_exp_f32_e32 v3, v3
	v_mul_f32_e32 v142, 0xbfb8aa3b, v142
	v_exp_f32_e32 v143, v142
	s_waitcnt vmcnt(2)
	v_lshlrev_b32_e32 v164, 16, v154
	v_add_f32_e32 v3, 1.0, v3
	v_rcp_f32_e32 v144, v3
	v_add_f32_e32 v3, 1.0, v143
	v_rcp_f32_e32 v145, v3
	v_mul_f32_e32 v3, v12, v234
	v_mul_f32_e32 v3, 0xbfb8aa3b, v3
	v_mul_f32_e32 v143, v13, v234
	v_exp_f32_e32 v3, v3
	v_mul_f32_e32 v143, 0xbfb8aa3b, v143
	v_exp_f32_e32 v143, v143
	v_and_b32_e32 v165, 0xffff0000, v154
	v_pk_mul_f32 v[164:165], v[198:199], v[164:165] op_sel_hi:[0,1]
	v_lshlrev_b32_e32 v162, 16, v150
	v_and_b32_e32 v163, 0xffff0000, v150
	v_pk_mul_f32 v[138:139], v[138:139], v[164:165]
	v_add_f32_e32 v3, 1.0, v3
	v_pk_fma_f32 v[138:139], v[144:145], v[138:139], v[162:163]
	v_rcp_f32_e32 v144, v3
	v_add_f32_e32 v3, 1.0, v143
	v_rcp_f32_e32 v145, v3
	v_mul_f32_e32 v3, v6, v234
	v_mul_f32_e32 v3, 0xbfb8aa3b, v3
	v_mul_f32_e32 v143, v7, v234
	v_exp_f32_e32 v3, v3
	v_mul_f32_e32 v143, 0xbfb8aa3b, v143
	v_exp_f32_e32 v143, v143
	v_lshlrev_b32_e32 v154, 16, v155
	v_and_b32_e32 v155, 0xffff0000, v155
	v_pk_mul_f32 v[154:155], v[198:199], v[154:155] op_sel_hi:[0,1]
	v_lshlrev_b32_e32 v150, 16, v151
	v_and_b32_e32 v151, 0xffff0000, v151
	v_pk_mul_f32 v[140:141], v[140:141], v[154:155]
	v_add_f32_e32 v3, 1.0, v3
	v_pk_fma_f32 v[140:141], v[144:145], v[140:141], v[150:151]
	v_rcp_f32_e32 v144, v3
	v_add_f32_e32 v3, 1.0, v143
	v_rcp_f32_e32 v145, v3
	v_mul_f32_e32 v3, v8, v234
	v_mul_f32_e32 v3, 0xbfb8aa3b, v3
	v_mul_f32_e32 v143, v9, v234
	v_exp_f32_e32 v3, v3
	v_mul_f32_e32 v143, 0xbfb8aa3b, v143
	v_cvt_pk_bf16_f32 v142, v146, v147
	v_lshlrev_b32_e32 v154, 16, v156
	v_and_b32_e32 v155, 0xffff0000, v156
	v_exp_f32_e32 v143, v143
	v_mov_b32_e32 v163, v146
	v_mov_b32_e32 v146, v189
	v_pk_mul_f32 v[154:155], v[198:199], v[154:155] op_sel_hi:[0,1]
	v_mov_b32_e32 v162, v188
	v_pk_mul_f32 v[146:147], v[146:147], v[146:147]
	v_lshlrev_b32_e32 v150, 16, v152
	v_and_b32_e32 v151, 0xffff0000, v152
	v_pk_mul_f32 v[134:135], v[134:135], v[154:155]
	v_mov_b32_e32 v156, v201
	v_mov_b32_e32 v201, v148
	v_pk_fma_f32 v[146:147], v[162:163], v[162:163], v[146:147]
	v_pk_fma_f32 v[144:145], v[144:145], v[134:135], v[150:151]
	v_add_f32_e32 v3, 1.0, v3
	v_lshlrev_b32_e32 v150, 16, v153
	v_and_b32_e32 v151, 0xffff0000, v153
	v_lshlrev_b32_e32 v152, 16, v157
	v_and_b32_e32 v153, 0xffff0000, v157
	v_mov_b32_e32 v157, v149
	v_pk_fma_f32 v[146:147], v[200:201], v[200:201], v[146:147]
	v_rcp_f32_e32 v134, v3
	v_add_f32_e32 v3, 1.0, v143
	v_mov_b32_e32 v154, v203
	v_mov_b32_e32 v203, v158
	v_pk_fma_f32 v[146:147], v[156:157], v[156:157], v[146:147]
	v_rcp_f32_e32 v135, v3
	v_pk_mul_f32 v[152:153], v[198:199], v[152:153] op_sel_hi:[0,1]
	v_mov_b32_e32 v155, v159
	v_pk_fma_f32 v[146:147], v[202:203], v[202:203], v[146:147]
	v_pk_mul_f32 v[136:137], v[136:137], v[152:153]
	v_mov_b32_e32 v152, v205
	v_mov_b32_e32 v205, v160
	v_pk_fma_f32 v[146:147], v[154:155], v[154:155], v[146:147]
	v_mov_b32_e32 v153, v161
	v_pk_fma_f32 v[146:147], v[204:205], v[204:205], v[146:147]
	v_pk_fma_f32 v[150:151], v[134:135], v[136:137], v[150:151]
	v_pk_fma_f32 v[146:147], v[152:153], v[152:153], v[146:147]
	v_mov_b32_e32 v152, v186
	v_mov_b32_e32 v153, v138
	v_cvt_pk_bf16_f32 v134, v138, v139
	v_pk_fma_f32 v[146:147], v[152:153], v[152:153], v[146:147]
	v_mov_b32_e32 v138, v187
	v_pk_fma_f32 v[138:139], v[138:139], v[138:139], v[146:147]
	v_mov_b32_e32 v146, v206
	v_mov_b32_e32 v147, v140
	v_cvt_pk_bf16_f32 v135, v140, v141
	v_pk_fma_f32 v[138:139], v[146:147], v[146:147], v[138:139]
	v_mov_b32_e32 v140, v207
	v_pk_fma_f32 v[138:139], v[140:141], v[140:141], v[138:139]
	v_mov_b32_e32 v140, v208
	v_mov_b32_e32 v141, v144
	v_cvt_pk_bf16_f32 v136, v144, v145
	v_pk_fma_f32 v[138:139], v[140:141], v[140:141], v[138:139]
	v_mov_b32_e32 v144, v209
	v_pk_fma_f32 v[138:139], v[144:145], v[144:145], v[138:139]
	v_mov_b32_e32 v140, v196
	v_mov_b32_e32 v141, v150
	v_cvt_pk_bf16_f32 v137, v150, v151
	v_pk_fma_f32 v[138:139], v[140:141], v[140:141], v[138:139]
	v_mov_b32_e32 v150, v197
	v_pk_fma_f32 v[138:139], v[150:151], v[150:151], v[138:139]
	ds_bpermute_b32 v140, v233, v138
	ds_bpermute_b32 v141, v233, v139
	v_lshlrev_b64 v[4:5], 12, v[4:5]
	v_lshl_add_u64 v[4:5], s[30:31], 0, v[4:5]
	v_cvt_pk_bf16_f32 v143, v148, v149
	v_cvt_pk_bf16_f32 v144, v158, v159
	s_waitcnt lgkmcnt(0)
	v_pk_add_f32 v[138:139], v[138:139], v[140:141]
	ds_bpermute_b32 v140, v235, v138
	ds_bpermute_b32 v141, v235, v139
	v_cvt_pk_bf16_f32 v145, v160, v161
	v_lshl_add_u64 v[4:5], v[4:5], 0, v[184:185]
	global_store_dwordx4 v[4:5], v[142:145], off
	global_store_dwordx4 v[4:5], v[134:137], off offset:256
	s_and_b64 vcc, exec, s[4:5]
	s_waitcnt lgkmcnt(0)
	v_pk_add_f32 v[134:135], v[138:139], v[140:141]
	s_cbranch_vccz .LBB0_1601
	s_and_saveexec_b64 s[0:1], s[2:3]
	s_cbranch_execz .LBB0_1583
	s_ashr_i32 s47, s46, 31
	v_lshl_add_u64 v[4:5], s[46:47], 2, v[174:175]
	global_atomic_add_f32 v[4:5], v190, off
	global_atomic_add_f32 v[4:5], v191, off offset:64
	global_atomic_add_f32 v[4:5], v192, off offset:128
	global_atomic_add_f32 v[4:5], v193, off offset:192
	global_atomic_add_f32 v[4:5], v194, off offset:512
	global_atomic_add_f32 v[4:5], v195, off offset:576
	global_atomic_add_f32 v[4:5], v134, off offset:640
	global_atomic_add_f32 v[4:5], v135, off offset:704
	s_branch .LBB0_1583
